# MLA tile: half-wave max exchange via v_permlane32_swap instead of LDS bpermute, all V fragments read at tile start into own registers
# speedup vs baseline: 1.0172x; 1.0025x over previous
; DI void gemm_mainloop(f32x16 (&acc)[2][2], const u16* A, int lda, const u16* Bt, int ldb, int K, unsigned char* smem) {
;   u16* s0 = (u16*)smem;
;   const int tid = TIDX(), lane = tid & 63, wave = tid >> 6, wm = wave >> 1, wn = wave & 1;
;   const int lr = tid >> 3, lc = (tid & 7) * 8;
;   unsigned offA[4], offB[4];
; #pragma unroll
;   for (int i = 0; i < 4; i++) { offA[i] = (unsigned)(((lr + 32 * i) * lda + lc) * 2); offB[i] = (unsigned)(((lr + 32 * i) * ldb + lc) * 2); }
;   const char* Ab = (const char*)A;
;   const char* Bb = (const char*)Bt;
;   u32x4 ra[4], rb[4];
;   const int nk = K >> 6;
;   const int r = lane & 31, hl = lane >> 5;
; #pragma unroll
;   for (int i = 0; i < 4; i++) { ra[i] = *(const u32x4*)(Ab + offA[i]); rb[i] = *(const u32x4*)(Bb + offB[i]); }
;   __syncthreads();
; #pragma unroll
;   for (int i = 0; i < 4; i++) { *(u32x4*)(s0 + (lr + 32 * i) * 72 + lc) = ra[i]; *(u32x4*)(s0 + 128 * 72 + (lr + 32 * i) * 72 + lc) = rb[i]; }
;   if (nk > 1) { Ab += 128; Bb += 128; }
; #pragma unroll
;   for (int i = 0; i < 4; i++) { ra[i] = *(const u32x4*)(Ab + offA[i]); rb[i] = *(const u32x4*)(Bb + offB[i]); }
;   __syncthreads();
;   for (int kt = 0; kt < nk; kt++) {
;     u16* sA = s0 + (kt & 1) * (256 * 72); u16* sB = sA + 128 * 72;
;     if (kt + 1 < nk) {
;       u16* nA = s0 + ((kt + 1) & 1) * (256 * 72); u16* nB = nA + 128 * 72;
; #pragma unroll
;       for (int i = 0; i < 4; i++) { *(u32x4*)(nA + (lr + 32 * i) * 72 + lc) = ra[i]; *(u32x4*)(nB + (lr + 32 * i) * 72 + lc) = rb[i]; }
;     }
;     if (kt + 2 < nk) { Ab += 128; Bb += 128; }
; #pragma unroll
;     for (int i = 0; i < 4; i++) { ra[i] = *(const u32x4*)(Ab + offA[i]); rb[i] = *(const u32x4*)(Bb + offB[i]); }
; #pragma unroll
;     for (int ks = 0; ks < 4; ks++) {
;       bf16x8 af[2], bfr[2];
; #pragma unroll
;       for (int b = 0; b < 2; b++) {
;         af[b] = *(const bf16x8*)(sA + (wm * 64 + b * 32 + r) * 72 + ks * 16 + hl * 8);
;         bfr[b] = *(const bf16x8*)(sB + (wn * 64 + b * 32 + r) * 72 + ks * 16 + hl * 8);
;       }
; #pragma unroll
;       for (int bm = 0; bm < 2; bm++)
; #pragma unroll
;         for (int bn = 0; bn < 2; bn++) acc[bm][bn] = MFMA32(af[bm], bfr[bn], acc[bm][bn]);
;     }
; DI void phase4(const Params& p, int l, unsigned char* smem) {
;     ...
;   while (true) {
;     __syncthreads();
;     if (TIDX() == 0) s_task4 = atomicAdd(ctr4, 1);
.LBB0_640:
	s_or_b64 exec, exec, s[2:3]
	s_waitcnt lgkmcnt(0)
	s_barrier
	ds_read_b32 v0, v201
	s_movk_i32 s2, 0xccd
	s_waitcnt lgkmcnt(0)
	v_cmp_lt_i32_e32 vcc, s2, v0
	v_readfirstlane_b32 s8, v0
	s_mov_b64 s[2:3], -1
	s_cbranch_vccnz .LBB0_635
	s_ashr_i32 s3, s8, 1
	s_and_b32 s2, s8, 1
	s_add_i32 s9, s3, 0x1c0
	s_cmp_eq_u32 s2, 0
	s_cselect_b32 s2, s3, s9
	s_cmpk_lt_i32 s8, 0x380
	s_cselect_b32 s16, s2, s8
	s_cmpk_gt_i32 s16, 0x1bf
	s_mov_b64 s[2:3], -1
	s_cbranch_scc0 .LBB0_718
	s_cmpk_gt_u32 s16, 0x4c5
	s_cbranch_scc0 .LBB0_712
	s_add_i32 s2, s16, 0xfb3a
	s_and_b32 s3, s2, 0xffff
	s_mul_i32 s3, s3, 0xff01
	s_lshr_b32 s17, s3, 24
	s_mul_i32 s3, s17, 0x101
	s_sub_i32 s2, s2, s3
	s_and_b32 s10, s2, 0xffff
	s_lshl_b32 s2, s2, 16
	v_mov_b32_e32 v67, v160
	s_add_u32 s2, s24, s2
	s_addc_u32 s3, s25, 0
	v_lshlrev_b32_e32 v0, 4, v67
	s_lshl_b32 s8, s17, 16
	v_ashrrev_i32_e32 v65, 3, v67
	v_and_b32_e32 v64, 0x70, v0
	s_add_u32 s8, s26, s8
	s_waitcnt vmcnt(11)
	v_lshl_or_b32 v120, v65, 9, v64
	s_addc_u32 s9, s27, 0
	v_add_u32_e32 v121, 0x4000, v120
	v_add_u32_e32 v122, 0x8000, v120
	v_add_u32_e32 v123, 0xc000, v120
	global_load_dwordx4 v[0:3], v120, s[2:3]
	global_load_dwordx4 v[4:7], v121, s[2:3]
	global_load_dwordx4 v[8:11], v122, s[2:3]
	global_load_dwordx4 v[12:15], v123, s[2:3]
	global_load_dwordx4 v[16:19], v120, s[8:9]
	global_load_dwordx4 v[20:23], v121, s[8:9]
	global_load_dwordx4 v[24:27], v122, s[8:9]
	global_load_dwordx4 v[28:31], v123, s[8:9]
	s_waitcnt vmcnt(63) expcnt(7) lgkmcnt(15)
	s_barrier
	global_load_dwordx4 v[32:35], v120, s[2:3] offset:128
	global_load_dwordx4 v[36:39], v120, s[8:9] offset:128
	global_load_dwordx4 v[40:43], v121, s[2:3] offset:128
	global_load_dwordx4 v[44:47], v121, s[8:9] offset:128
	global_load_dwordx4 v[48:51], v122, s[2:3] offset:128
	global_load_dwordx4 v[52:55], v122, s[8:9] offset:128
	global_load_dwordx4 v[56:59], v123, s[2:3] offset:128
	global_load_dwordx4 v[60:63], v123, s[8:9] offset:128
	v_and_b32_e32 v66, 31, v67
	v_lshrrev_b32_e32 v68, 1, v67
	v_and_or_b32 v69, v68, s45, v66
	v_and_b32_e32 v66, 16, v68
	v_mad_u64_u32 v[98:99], s[12:13], v65, s65, v[64:65]
	v_mad_u64_u32 v[64:65], s[12:13], v69, s65, v[66:67]
	v_add_u32_e32 v65, 0x1200, v98
	s_lshl_b32 s30, s10, 7
	s_waitcnt vmcnt(15)
	ds_write_b128 v98, v[0:3]
	s_waitcnt vmcnt(14)
	ds_write_b128 v98, v[4:7] offset:4608
	s_waitcnt vmcnt(13)
	ds_write_b128 v98, v[8:11] offset:9216
	s_waitcnt vmcnt(12)
	ds_write_b128 v98, v[12:15] offset:13824
	s_waitcnt vmcnt(11)
	ds_write_b128 v98, v[16:19] offset:18432
	s_waitcnt vmcnt(10)
	ds_write_b128 v98, v[20:23] offset:23040
	s_waitcnt vmcnt(9)
	ds_write_b128 v98, v[24:27] offset:27648
	s_waitcnt vmcnt(8)
	ds_write_b128 v98, v[28:31] offset:32256
	s_waitcnt lgkmcnt(0)
	s_barrier
	s_waitcnt vmcnt(7)
	ds_write_b128 v98, v[32:35] offset:36864
	s_waitcnt vmcnt(6)
	ds_write_b128 v98, v[36:39] offset:55296
	s_waitcnt vmcnt(5)
	ds_write_b128 v98, v[40:43] offset:41472
	s_waitcnt vmcnt(4)
	ds_write_b128 v98, v[44:47] offset:59904
	s_waitcnt vmcnt(3)
	ds_write_b128 v98, v[48:51] offset:46080
	s_waitcnt vmcnt(2)
	ds_write_b128 v98, v[52:55] offset:64512
	s_waitcnt vmcnt(1)
	ds_write_b128 v98, v[56:59] offset:50688
	s_waitcnt vmcnt(0)
	ds_write_b128 v65, v[60:63] offset:64512
	ds_read_b128 v[124:127], v64
	v_and_b32_e32 v4, 0x5f, v67
	v_mad_u32_u24 v99, v4, s65, v66
	global_load_dwordx4 v[66:69], v120, s[2:3] offset:256
	global_load_dwordx4 v[70:73], v120, s[8:9] offset:256
	global_load_dwordx4 v[74:77], v121, s[2:3] offset:256
	global_load_dwordx4 v[82:85], v121, s[8:9] offset:256
	global_load_dwordx4 v[94:97], v122, s[2:3] offset:256
	global_load_dwordx4 v[112:115], v122, s[8:9] offset:256
	global_load_dwordx4 v[78:81], v123, s[2:3] offset:256
	global_load_dwordx4 v[116:119], v123, s[8:9] offset:256
	ds_read_b128 v[128:131], v99 offset:18432
	ds_read_b128 v[132:135], v64 offset:32
	ds_read_b128 v[136:139], v99 offset:18464
	ds_read_b128 v[140:143], v99 offset:23040
	ds_read_b128 v[144:147], v99 offset:23072
	s_waitcnt lgkmcnt(4)
	ds_read_b128 v[148:151], v64 offset:4608
	ds_read_b128 v[152:155], v64 offset:4640
	ds_read_b128 v[156:159], v64 offset:64
	ds_read_b128 v[164:167], v99 offset:18496
	ds_read_b128 v[168:171], v64 offset:96
	ds_read_b128 v[172:175], v99 offset:18528
	ds_read_b128 v[176:179], v99 offset:23104
	ds_read_b128 v[86:89], v99 offset:23136
	ds_read_b128 v[180:183], v64 offset:4672
	ds_read_b128 v[90:93], v64 offset:4704
	v_mfma_f32_32x32x16_bf16 v[48:63], v[124:127], v[128:131], 0
	s_waitcnt lgkmcnt(11)
	v_mfma_f32_32x32x16_bf16 v[32:47], v[124:127], v[140:143], 0
	s_nop 1
	s_waitcnt lgkmcnt(9)
	v_mfma_f32_32x32x16_bf16 v[16:31], v[148:151], v[128:131], 0
	v_mfma_f32_32x32x16_bf16 v[0:15], v[148:151], v[140:143], 0
	v_mfma_f32_32x32x16_bf16 v[48:63], v[132:135], v[136:139], v[48:63]
	v_mfma_f32_32x32x16_bf16 v[32:47], v[132:135], v[144:147], v[32:47]
	s_waitcnt lgkmcnt(8)
	v_mfma_f32_32x32x16_bf16 v[16:31], v[152:155], v[136:139], v[16:31]
	v_mfma_f32_32x32x16_bf16 v[0:15], v[152:155], v[144:147], v[0:15]
	s_nop 5
	s_waitcnt lgkmcnt(6)
	v_mfma_f32_32x32x16_bf16 v[48:63], v[156:159], v[164:167], v[48:63]
	s_waitcnt lgkmcnt(3)
	v_mfma_f32_32x32x16_bf16 v[32:47], v[156:159], v[176:179], v[32:47]
	s_nop 1
	s_waitcnt lgkmcnt(1)
	v_mfma_f32_32x32x16_bf16 v[16:31], v[180:183], v[164:167], v[16:31]
	v_mfma_f32_32x32x16_bf16 v[0:15], v[180:183], v[176:179], v[0:15]
	v_mfma_f32_32x32x16_bf16 v[48:63], v[168:171], v[172:175], v[48:63]
	v_mfma_f32_32x32x16_bf16 v[32:47], v[168:171], v[86:89], v[32:47]
	s_nop 5
	s_waitcnt lgkmcnt(0)
	v_mfma_f32_32x32x16_bf16 v[16:31], v[90:93], v[172:175], v[16:31]
	s_nop 1
	s_barrier
; #define MFMA32(a, b, c) __builtin_amdgcn_mfma_f32_32x32x16_bf16((a), (b), (c), 0, 0, 0)
; DI void gemm_mainloop(f32x16 (&acc)[2][2], const u16* A, int lda, const u16* Bt, int ldb, int K, unsigned char* smem) {
;     ...
;   for (int kt = 0; kt < nk; kt++) {
;     u16* sA = s0 + (kt & 1) * (256 * 72); u16* sB = sA + 128 * 72;
;     if (kt + 1 < nk) {
;       u16* nA = s0 + ((kt + 1) & 1) * (256 * 72); u16* nB = nA + 128 * 72;
; #pragma unroll
;       for (int i = 0; i < 4; i++) { *(u32x4*)(nA + (lr + 32 * i) * 72 + lc) = ra[i]; *(u32x4*)(nB + (lr + 32 * i) * 72 + lc) = rb[i]; }
;     }
;     if (kt + 2 < nk) { Ab += 128; Bb += 128; }
; #pragma unroll
;     for (int i = 0; i < 4; i++) { ra[i] = *(const u32x4*)(Ab + offA[i]); rb[i] = *(const u32x4*)(Bb + offB[i]); }
; #pragma unroll
;     for (int ks = 0; ks < 4; ks++) {
;       bf16x8 af[2], bfr[2];
; #pragma unroll
;       for (int b = 0; b < 2; b++) {
;         af[b] = *(const bf16x8*)(sA + (wm * 64 + b * 32 + r) * 72 + ks * 16 + hl * 8);
;         bfr[b] = *(const bf16x8*)(sB + (wn * 64 + b * 32 + r) * 72 + ks * 16 + hl * 8);
;       }
; #pragma unroll
;       for (int bm = 0; bm < 2; bm++)
; #pragma unroll
;         for (int bn = 0; bn < 2; bn++) acc[bm][bn] = MFMA32(af[bm], bfr[bn], acc[bm][bn]);
;     }
	s_waitcnt vmcnt(7)
	ds_write_b128 v98, v[66:69]
	global_load_dwordx4 v[66:69], v120, s[2:3] offset:384
	s_waitcnt vmcnt(7)
	ds_write_b128 v98, v[70:73] offset:18432
	global_load_dwordx4 v[70:73], v120, s[8:9] offset:384
	s_waitcnt vmcnt(7)
	ds_write_b128 v98, v[74:77] offset:4608
	global_load_dwordx4 v[74:77], v121, s[2:3] offset:384
	s_waitcnt vmcnt(7)
	ds_write_b128 v98, v[82:85] offset:23040
	global_load_dwordx4 v[82:85], v121, s[8:9] offset:384
	s_waitcnt vmcnt(7)
	ds_write_b128 v98, v[94:97] offset:9216
	global_load_dwordx4 v[94:97], v122, s[2:3] offset:384
	s_waitcnt vmcnt(7)
	ds_write_b128 v98, v[112:115] offset:27648
	global_load_dwordx4 v[112:115], v122, s[8:9] offset:384
	s_waitcnt vmcnt(7)
	ds_write_b128 v98, v[78:81] offset:13824
	global_load_dwordx4 v[78:81], v123, s[2:3] offset:384
	s_waitcnt vmcnt(7)
	ds_write_b128 v98, v[116:119] offset:32256
	global_load_dwordx4 v[116:119], v123, s[8:9] offset:384
	ds_read_b128 v[124:127], v64 offset:36864
	ds_read_b128 v[128:131], v99 offset:55296
	ds_read_b128 v[132:135], v64 offset:36896
	ds_read_b128 v[136:139], v99 offset:55328
	ds_read_b128 v[140:143], v99 offset:59904
	ds_read_b128 v[144:147], v99 offset:59936
	v_mfma_f32_32x32x16_bf16 v[0:15], v[90:93], v[86:89], v[0:15]
	s_nop 5
	s_waitcnt lgkmcnt(4)
	ds_read_b128 v[148:151], v64 offset:41472
	ds_read_b128 v[152:155], v64 offset:41504
	ds_read_b128 v[156:159], v64 offset:36928
	ds_read_b128 v[164:167], v99 offset:55360
	ds_read_b128 v[168:171], v64 offset:36960
	ds_read_b128 v[172:175], v99 offset:55392
	ds_read_b128 v[176:179], v99 offset:59968
	v_mfma_f32_32x32x16_bf16 v[48:63], v[124:127], v[128:131], v[48:63]
	s_waitcnt lgkmcnt(8)
	v_mfma_f32_32x32x16_bf16 v[32:47], v[124:127], v[140:143], v[32:47]
	s_nop 1
	s_waitcnt lgkmcnt(6)
	v_mfma_f32_32x32x16_bf16 v[16:31], v[148:151], v[128:131], v[16:31]
	v_mfma_f32_32x32x16_bf16 v[0:15], v[148:151], v[140:143], v[0:15]
	v_mfma_f32_32x32x16_bf16 v[48:63], v[132:135], v[136:139], v[48:63]
	v_mfma_f32_32x32x16_bf16 v[32:47], v[132:135], v[144:147], v[32:47]
	s_waitcnt lgkmcnt(5)
	v_mfma_f32_32x32x16_bf16 v[16:31], v[152:155], v[136:139], v[16:31]
	s_nop 3
	v_mfma_f32_32x32x16_bf16 v[0:15], v[152:155], v[144:147], v[0:15]
	s_nop 0
	ds_read_b128 v[86:89], v99 offset:60000
	ds_read_b128 v[180:183], v64 offset:41536
	s_waitcnt lgkmcnt(5)
	v_mfma_f32_32x32x16_bf16 v[48:63], v[156:159], v[164:167], v[48:63]
	s_waitcnt lgkmcnt(2)
	v_mfma_f32_32x32x16_bf16 v[32:47], v[156:159], v[176:179], v[32:47]
	s_nop 0
	ds_read_b128 v[90:93], v64 offset:41568
	s_waitcnt lgkmcnt(1)
	v_mfma_f32_32x32x16_bf16 v[16:31], v[180:183], v[164:167], v[16:31]
	v_mfma_f32_32x32x16_bf16 v[0:15], v[180:183], v[176:179], v[0:15]
	v_mfma_f32_32x32x16_bf16 v[48:63], v[168:171], v[172:175], v[48:63]
	v_mfma_f32_32x32x16_bf16 v[32:47], v[168:171], v[86:89], v[32:47]
	s_nop 5
	s_waitcnt lgkmcnt(0)
	v_mfma_f32_32x32x16_bf16 v[16:31], v[90:93], v[172:175], v[16:31]
	s_nop 1
	s_barrier
	s_waitcnt vmcnt(7)
	ds_write_b128 v98, v[66:69] offset:36864
	s_waitcnt vmcnt(6)
	ds_write_b128 v98, v[70:73] offset:55296
	s_waitcnt vmcnt(5)
	ds_write_b128 v98, v[74:77] offset:41472
	s_waitcnt vmcnt(4)
	ds_write_b128 v98, v[82:85] offset:59904
	s_waitcnt vmcnt(3)
	ds_write_b128 v98, v[94:97] offset:46080
	s_waitcnt vmcnt(2)
	ds_write_b128 v98, v[112:115] offset:64512
	s_waitcnt vmcnt(1)
	ds_write_b128 v98, v[78:81] offset:50688
	s_waitcnt vmcnt(0)
	ds_write_b128 v65, v[116:119] offset:64512
	ds_read_b128 v[124:127], v64
	ds_read_b128 v[128:131], v99 offset:18432
	ds_read_b128 v[132:135], v64 offset:32
	ds_read_b128 v[136:139], v99 offset:18464
	ds_read_b128 v[140:143], v99 offset:23040
	ds_read_b128 v[144:147], v99 offset:23072
	v_mfma_f32_32x32x16_bf16 v[0:15], v[90:93], v[86:89], v[0:15]
	s_nop 5
	s_waitcnt lgkmcnt(4)
	ds_read_b128 v[148:151], v64 offset:4608
	ds_read_b128 v[152:155], v64 offset:4640
	ds_read_b128 v[156:159], v64 offset:64
	v_mfma_f32_32x32x16_bf16 v[48:63], v[124:127], v[128:131], v[48:63]
	s_waitcnt lgkmcnt(4)
	v_mfma_f32_32x32x16_bf16 v[32:47], v[124:127], v[140:143], v[32:47]
	s_nop 1
	s_waitcnt lgkmcnt(2)
	v_mfma_f32_32x32x16_bf16 v[16:31], v[148:151], v[128:131], v[16:31]
	v_mfma_f32_32x32x16_bf16 v[0:15], v[148:151], v[140:143], v[0:15]
	v_mfma_f32_32x32x16_bf16 v[48:63], v[132:135], v[136:139], v[48:63]
	v_mfma_f32_32x32x16_bf16 v[32:47], v[132:135], v[144:147], v[32:47]
	s_waitcnt lgkmcnt(1)
	v_mfma_f32_32x32x16_bf16 v[16:31], v[152:155], v[136:139], v[16:31]
	s_nop 0
	ds_read_b128 v[70:73], v99 offset:18496
	ds_read_b128 v[74:77], v64 offset:96
	ds_read_b128 v[78:81], v99 offset:18528
	v_mfma_f32_32x32x16_bf16 v[0:15], v[152:155], v[144:147], v[0:15]
	ds_read_b128 v[82:85], v99 offset:23104
	ds_read_b128 v[86:89], v99 offset:23136
	s_waitcnt lgkmcnt(4)
	v_mfma_f32_32x32x16_bf16 v[48:63], v[156:159], v[70:73], v[48:63]
	s_waitcnt lgkmcnt(1)
	v_mfma_f32_32x32x16_bf16 v[32:47], v[156:159], v[82:85], v[32:47]
	ds_read_b128 v[66:69], v64 offset:4672
	ds_read_b128 v[90:93], v64 offset:4704
	s_waitcnt lgkmcnt(0)
	s_barrier
; #define MFMA32(a, b, c) __builtin_amdgcn_mfma_f32_32x32x16_bf16((a), (b), (c), 0, 0, 0)
; DI unsigned pk2(float a, float b) { f2_t v = {a, b}; return __builtin_bit_cast(unsigned, __builtin_convertvector(v, bf2_t)); }
; DI void gemm_mainloop(f32x16 (&acc)[2][2], const u16* A, int lda, const u16* Bt, int ldb, int K, unsigned char* smem) {
;     ...
;   for (int kt = 0; kt < nk; kt++) {
;     u16* sA = s0 + (kt & 1) * (256 * 72); u16* sB = sA + 128 * 72;
;     if (kt + 1 < nk) {
;       u16* nA = s0 + ((kt + 1) & 1) * (256 * 72); u16* nB = nA + 128 * 72;
; #pragma unroll
;       for (int i = 0; i < 4; i++) { *(u32x4*)(nA + (lr + 32 * i) * 72 + lc) = ra[i]; *(u32x4*)(nB + (lr + 32 * i) * 72 + lc) = rb[i]; }
;     }
;     if (kt + 2 < nk) { Ab += 128; Bb += 128; }
; #pragma unroll
;     for (int i = 0; i < 4; i++) { ra[i] = *(const u32x4*)(Ab + offA[i]); rb[i] = *(const u32x4*)(Bb + offB[i]); }
; #pragma unroll
;     for (int ks = 0; ks < 4; ks++) {
;       bf16x8 af[2], bfr[2];
; #pragma unroll
;       for (int b = 0; b < 2; b++) {
;         af[b] = *(const bf16x8*)(sA + (wm * 64 + b * 32 + r) * 72 + ks * 16 + hl * 8);
;         bfr[b] = *(const bf16x8*)(sB + (wn * 64 + b * 32 + r) * 72 + ks * 16 + hl * 8);
;       }
; #pragma unroll
;       for (int bm = 0; bm < 2; bm++)
; #pragma unroll
;         for (int bn = 0; bn < 2; bn++) acc[bm][bn] = MFMA32(af[bm], bfr[bn], acc[bm][bn]);
;     }
; DI void phase4(const Params& p, int l, unsigned char* smem) {
;     ...
;       } else {
; #pragma unroll
;         for (int bm = 0; bm < 2; bm++)
; #pragma unroll
;           for (int bn = 0; bn < 2; bn++)
; #pragma unroll
;             for (int g4 = 0; g4 < 4; g4++) {
;               int krow = m0 + wm * 64 + bm * 32 + 8 * g4 + 4 * hl, d = bn * 32 + r;
;               uint2 o; o.x = pk2(acc[bm][bn][4 * g4], acc[bm][bn][4 * g4 + 1]); o.y = pk2(acc[bm][bn][4 * g4 + 2], acc[bm][bn][4 * g4 + 3]);
;               *(uint2*)(VT + vt_off(krow, head, d)) = o;
;             }
	ds_read_b128 v[124:127], v64 offset:36864
	ds_read_b128 v[128:131], v99 offset:55296
	ds_read_b128 v[132:135], v64 offset:36896
	ds_read_b128 v[136:139], v99 offset:55328
	ds_read_b128 v[140:143], v99 offset:59904
	ds_read_b128 v[144:147], v99 offset:59936
	ds_read_b128 v[148:151], v64 offset:41472
	ds_read_b128 v[152:155], v64 offset:41504
	ds_read_b128 v[156:159], v64 offset:36928
	v_mfma_f32_32x32x16_bf16 v[16:31], v[66:69], v[70:73], v[16:31]
	v_mfma_f32_32x32x16_bf16 v[0:15], v[66:69], v[82:85], v[0:15]
	v_mfma_f32_32x32x16_bf16 v[48:63], v[74:77], v[78:81], v[48:63]
	v_mfma_f32_32x32x16_bf16 v[32:47], v[74:77], v[86:89], v[32:47]
	v_mfma_f32_32x32x16_bf16 v[16:31], v[90:93], v[78:81], v[16:31]
	s_nop 3
	v_mfma_f32_32x32x16_bf16 v[0:15], v[90:93], v[86:89], v[0:15]
	s_nop 1
	s_waitcnt lgkmcnt(7)
	v_mfma_f32_32x32x16_bf16 v[48:63], v[124:127], v[128:131], v[48:63]
	s_waitcnt lgkmcnt(4)
	v_mfma_f32_32x32x16_bf16 v[32:47], v[124:127], v[140:143], v[32:47]
	s_nop 1
	s_waitcnt lgkmcnt(2)
	v_mfma_f32_32x32x16_bf16 v[16:31], v[148:151], v[128:131], v[16:31]
	v_mfma_f32_32x32x16_bf16 v[0:15], v[148:151], v[140:143], v[0:15]
	v_mfma_f32_32x32x16_bf16 v[48:63], v[132:135], v[136:139], v[48:63]
	v_mfma_f32_32x32x16_bf16 v[32:47], v[132:135], v[144:147], v[32:47]
	s_waitcnt lgkmcnt(1)
	v_mfma_f32_32x32x16_bf16 v[16:31], v[152:155], v[136:139], v[16:31]
	s_nop 0
	ds_read_b128 v[70:73], v99 offset:55360
	ds_read_b128 v[74:77], v64 offset:36960
	ds_read_b128 v[78:81], v99 offset:55392
	v_mfma_f32_32x32x16_bf16 v[0:15], v[152:155], v[144:147], v[0:15]
	ds_read_b128 v[82:85], v99 offset:59968
	ds_read_b128 v[86:89], v99 offset:60000
	s_waitcnt lgkmcnt(4)
	v_mfma_f32_32x32x16_bf16 v[48:63], v[156:159], v[70:73], v[48:63]
	s_waitcnt lgkmcnt(1)
	v_mfma_f32_32x32x16_bf16 v[32:47], v[156:159], v[82:85], v[32:47]
	ds_read_b128 v[66:69], v64 offset:41536
	ds_read_b128 v[90:93], v64 offset:41568
	s_waitcnt lgkmcnt(0)
	s_barrier
	v_mfma_f32_32x32x16_bf16 v[16:31], v[66:69], v[70:73], v[16:31]
	v_mfma_f32_32x32x16_bf16 v[0:15], v[66:69], v[82:85], v[0:15]
	v_mfma_f32_32x32x16_bf16 v[48:63], v[74:77], v[78:81], v[48:63]
	v_mfma_f32_32x32x16_bf16 v[32:47], v[74:77], v[86:89], v[32:47]
	v_mfma_f32_32x32x16_bf16 v[16:31], v[90:93], v[78:81], v[16:31]
	v_mfma_f32_32x32x16_bf16 v[0:15], v[90:93], v[86:89], v[0:15]
	s_and_saveexec_b64 s[2:3], s[4:5]
	s_xor_b64 s[2:3], exec, s[2:3]
	s_cbranch_execz .LBB0_709
	v_add_u32_e32 v64, s30, v208
	v_or_b32_e32 v69, v64, v209
	s_lshl_b32 s31, s17, 6
	v_add_u32_e32 v70, 0xffffc000, v69
	s_mov_b32 s8, 0xfe03f81
	v_or_b32_e32 v68, s31, v100
	v_cmp_lt_i32_e32 vcc, s64, v69
	v_mul_hi_u32 v71, v70, s8
	s_and_saveexec_b64 s[8:9], vcc
	s_xor_b64 s[8:9], exec, s[8:9]
	v_lshrrev_b32_e32 v65, 7, v71
	s_movk_i32 s10, 0xf7f0
	v_mad_i32_i24 v66, v65, s10, v70
	v_lshl_add_u32 v65, v65, 9, v68
	v_ashrrev_i32_e32 v67, 31, v66
	v_mad_u64_u32 v[66:67], s[10:11], v65, s95, v[66:67]
	s_mov_b64 s[10:11], 0x800000
	s_nop 0
	v_lshl_add_u64 v[66:67], v[66:67], 0, s[10:11]
	s_or_saveexec_b64 s[8:9], s[8:9]
	v_ashrrev_i32_e32 v64, 10, v64
	v_and_b32_e32 v64, 0x3fffff8, v64
	v_add_lshl_u32 v74, v64, s17, 6
	v_or_b32_e32 v64, v74, v100
	v_ashrrev_i32_e32 v65, 31, v64
	v_lshlrev_b64 v[64:65], 13, v[64:65]
	s_xor_b64 exec, exec, s[8:9]
	s_movk_i32 s10, 0x1fc4
	v_and_or_b32 v66, v69, s10, v64
	v_mov_b32_e32 v67, v65
	s_or_b64 exec, exec, s[8:9]
	v_cvt_pk_bf16_f32 v48, v48, v49
	v_cvt_pk_bf16_f32 v49, v50, v51
	v_lshl_add_u64 v[50:51], v[66:67], 1, s[56:57]
	v_or_b32_e32 v66, 8, v69
	v_add_u32_e32 v67, 0xffffc008, v69
	s_mov_b32 s10, 0xfe03f81
	v_cmp_lt_i32_e64 s[8:9], s64, v66
	v_mul_hi_u32 v72, v67, s10
	global_store_dwordx2 v[50:51], v[48:49], off
	s_and_saveexec_b64 s[10:11], s[8:9]
	s_xor_b64 s[10:11], exec, s[10:11]
	v_lshrrev_b32_e32 v49, 7, v72
	s_movk_i32 s12, 0xf7f0
	v_mad_i32_i24 v48, v49, s12, v67
	v_lshl_add_u32 v50, v49, 9, v68
	v_ashrrev_i32_e32 v49, 31, v48
	v_mad_u64_u32 v[48:49], s[12:13], v50, s95, v[48:49]
	s_mov_b64 s[12:13], 0x800000
	s_nop 0
	v_lshl_add_u64 v[48:49], v[48:49], 0, s[12:13]
	s_andn2_saveexec_b64 s[10:11], s[10:11]
	s_movk_i32 s12, 0x1fcc
	v_and_or_b32 v48, v66, s12, v64
	v_mov_b32_e32 v49, v65
	s_or_b64 exec, exec, s[10:11]
	v_cvt_pk_bf16_f32 v50, v52, v53
	v_cvt_pk_bf16_f32 v51, v54, v55
	v_or_b32_e32 v53, 16, v69
	v_add_u32_e32 v55, 0xffffc010, v69
	s_mov_b32 s12, 0xfe03f81
	v_lshl_add_u64 v[48:49], v[48:49], 1, s[56:57]
	v_cmp_lt_i32_e64 s[10:11], s64, v53
	v_mul_hi_u32 v73, v55, s12
	global_store_dwordx2 v[48:49], v[50:51], off
	s_and_saveexec_b64 s[12:13], s[10:11]
	s_xor_b64 s[12:13], exec, s[12:13]
	v_lshrrev_b32_e32 v49, 7, v73
	s_movk_i32 s14, 0xf7f0
	v_mad_i32_i24 v48, v49, s14, v55
	v_lshl_add_u32 v50, v49, 9, v68
	v_ashrrev_i32_e32 v49, 31, v48
	v_mad_u64_u32 v[48:49], s[14:15], v50, s95, v[48:49]
	s_mov_b64 s[14:15], 0x800000
	s_nop 0
	v_lshl_add_u64 v[48:49], v[48:49], 0, s[14:15]
	s_andn2_saveexec_b64 s[12:13], s[12:13]
	s_movk_i32 s14, 0x1fd4
	v_and_or_b32 v48, v53, s14, v64
	v_mov_b32_e32 v49, v65
	s_or_b64 exec, exec, s[12:13]
	v_cvt_pk_bf16_f32 v50, v56, v57
	v_or_b32_e32 v54, 24, v69
	v_add_u32_e32 v56, 0xffffc018, v69
	s_mov_b32 s14, 0xfe03f81
	v_cvt_pk_bf16_f32 v51, v58, v59
	v_lshl_add_u64 v[48:49], v[48:49], 1, s[56:57]
	v_cmp_lt_i32_e64 s[12:13], s64, v54
	v_mul_hi_u32 v57, v56, s14
	global_store_dwordx2 v[48:49], v[50:51], off
	s_and_saveexec_b64 s[14:15], s[12:13]
	s_xor_b64 s[14:15], exec, s[14:15]
	v_lshrrev_b32_e32 v49, 7, v57
	s_movk_i32 s34, 0xf7f0
	v_mad_i32_i24 v48, v49, s34, v56
	v_lshl_add_u32 v50, v49, 9, v68
	v_ashrrev_i32_e32 v49, 31, v48
	v_mad_u64_u32 v[48:49], s[34:35], v50, s95, v[48:49]
; DI unsigned pk2(float a, float b) { f2_t v = {a, b}; return __builtin_bit_cast(unsigned, __builtin_convertvector(v, bf2_t)); }
; DI size_t vt_off(int keyrow, int h, int d) {
;   if (keyrow < NP) { int b = keyrow >> 13, s = keyrow & 8191; return ((size_t)((b * 8 + h) * 64 + d)) * 8192 + s; }
;   int rr = keyrow - NP; int b = rr / SK, s = rr - b * SK; return VT_S_OFF + ((size_t)((b * 8 + h) * 64 + d)) * SK + s;
; }
; DI void phase4(const Params& p, int l, unsigned char* smem) {
;     ...
;       } else {
; #pragma unroll
;         for (int bm = 0; bm < 2; bm++)
; #pragma unroll
;           for (int bn = 0; bn < 2; bn++)
; #pragma unroll
;             for (int g4 = 0; g4 < 4; g4++) {
;               int krow = m0 + wm * 64 + bm * 32 + 8 * g4 + 4 * hl, d = bn * 32 + r;
;               uint2 o; o.x = pk2(acc[bm][bn][4 * g4], acc[bm][bn][4 * g4 + 1]); o.y = pk2(acc[bm][bn][4 * g4 + 2], acc[bm][bn][4 * g4 + 3]);
;               *(uint2*)(VT + vt_off(krow, head, d)) = o;
;             }
	s_mov_b64 s[34:35], 0x800000
	s_nop 0
	v_lshl_add_u64 v[48:49], v[48:49], 0, s[34:35]
	s_andn2_saveexec_b64 s[14:15], s[14:15]
	s_movk_i32 s34, 0x1fdc
	v_and_or_b32 v48, v54, s34, v64
	v_mov_b32_e32 v49, v65
	s_or_b64 exec, exec, s[14:15]
	v_cvt_pk_bf16_f32 v50, v60, v61
	v_cvt_pk_bf16_f32 v51, v62, v63
	v_lshl_add_u64 v[48:49], v[48:49], 1, s[56:57]
	v_or_b32_e32 v52, s31, v212
	global_store_dwordx2 v[48:49], v[50:51], off
	s_and_saveexec_b64 s[14:15], vcc
	s_xor_b64 s[14:15], exec, s[14:15]
	v_lshrrev_b32_e32 v49, 7, v71
	s_movk_i32 s31, 0xf7f0
	v_mad_i32_i24 v48, v49, s31, v70
	v_lshl_add_u32 v50, v49, 9, v52
	v_ashrrev_i32_e32 v49, 31, v48
	v_mad_u64_u32 v[48:49], s[34:35], v50, s95, v[48:49]
	s_mov_b64 s[34:35], 0x800000
	s_nop 0
	v_lshl_add_u64 v[50:51], v[48:49], 0, s[34:35]
	s_or_saveexec_b64 s[14:15], s[14:15]
	v_or_b32_e32 v48, v74, v212
	v_ashrrev_i32_e32 v49, 31, v48
	v_lshlrev_b64 v[48:49], 13, v[48:49]
	s_xor_b64 exec, exec, s[14:15]
	s_movk_i32 s31, 0x1fc4
	v_and_or_b32 v50, v69, s31, v48
	v_mov_b32_e32 v51, v49
	s_or_b64 exec, exec, s[14:15]
	v_cvt_pk_bf16_f32 v32, v32, v33
	v_cvt_pk_bf16_f32 v33, v34, v35
	v_lshl_add_u64 v[34:35], v[50:51], 1, s[56:57]
	global_store_dwordx2 v[34:35], v[32:33], off
	s_and_saveexec_b64 s[14:15], s[8:9]
	s_xor_b64 s[8:9], exec, s[14:15]
	v_lshrrev_b32_e32 v33, 7, v72
	s_movk_i32 s14, 0xf7f0
	v_mad_i32_i24 v32, v33, s14, v67
	v_lshl_add_u32 v34, v33, 9, v52
	v_ashrrev_i32_e32 v33, 31, v32
	v_mad_u64_u32 v[32:33], s[14:15], v34, s95, v[32:33]
	s_mov_b64 s[14:15], 0x800000
	s_nop 0
	v_lshl_add_u64 v[32:33], v[32:33], 0, s[14:15]
	s_andn2_saveexec_b64 s[8:9], s[8:9]
	s_movk_i32 s14, 0x1fcc
	v_and_or_b32 v32, v66, s14, v48
	v_mov_b32_e32 v33, v49
	s_or_b64 exec, exec, s[8:9]
	v_cvt_pk_bf16_f32 v34, v36, v37
	v_cvt_pk_bf16_f32 v35, v38, v39
	v_lshl_add_u64 v[32:33], v[32:33], 1, s[56:57]
	global_store_dwordx2 v[32:33], v[34:35], off
	s_and_saveexec_b64 s[8:9], s[10:11]
	s_xor_b64 s[8:9], exec, s[8:9]
	v_lshrrev_b32_e32 v33, 7, v73
	s_movk_i32 s10, 0xf7f0
	v_mad_i32_i24 v32, v33, s10, v55
	v_lshl_add_u32 v34, v33, 9, v52
	v_ashrrev_i32_e32 v33, 31, v32
	v_mad_u64_u32 v[32:33], s[10:11], v34, s95, v[32:33]
	s_mov_b64 s[10:11], 0x800000
	s_nop 0
	v_lshl_add_u64 v[32:33], v[32:33], 0, s[10:11]
	s_andn2_saveexec_b64 s[8:9], s[8:9]
	s_movk_i32 s10, 0x1fd4
	v_and_or_b32 v32, v53, s10, v48
	v_mov_b32_e32 v33, v49
	s_or_b64 exec, exec, s[8:9]
	v_cvt_pk_bf16_f32 v34, v40, v41
	v_cvt_pk_bf16_f32 v35, v42, v43
	v_lshl_add_u64 v[32:33], v[32:33], 1, s[56:57]
	global_store_dwordx2 v[32:33], v[34:35], off
	s_and_saveexec_b64 s[8:9], s[12:13]
	s_xor_b64 s[8:9], exec, s[8:9]
	v_lshrrev_b32_e32 v33, 7, v57
	s_movk_i32 s10, 0xf7f0
	v_mad_i32_i24 v32, v33, s10, v56
	v_lshl_add_u32 v34, v33, 9, v52
	v_ashrrev_i32_e32 v33, 31, v32
	v_mad_u64_u32 v[32:33], s[10:11], v34, s95, v[32:33]
	s_mov_b64 s[10:11], 0x800000
	s_nop 0
	v_lshl_add_u64 v[32:33], v[32:33], 0, s[10:11]
	s_andn2_saveexec_b64 s[8:9], s[8:9]
	s_movk_i32 s10, 0x1fdc
	v_and_or_b32 v32, v54, s10, v48
	v_mov_b32_e32 v33, v49
	s_or_b64 exec, exec, s[8:9]
	v_cvt_pk_bf16_f32 v34, v44, v45
	v_cvt_pk_bf16_f32 v35, v46, v47
	v_lshl_add_u64 v[32:33], v[32:33], 1, s[56:57]
	global_store_dwordx2 v[32:33], v[34:35], off
	v_or_b32_e32 v34, 32, v69
	v_add_u32_e32 v35, 0xffffc020, v69
	s_mov_b32 s8, 0xfe03f81
	v_cmp_lt_i32_e32 vcc, s64, v34
	v_mul_hi_u32 v36, v35, s8
	s_and_saveexec_b64 s[8:9], vcc
	s_xor_b64 s[8:9], exec, s[8:9]
	v_lshrrev_b32_e32 v33, 7, v36
	s_movk_i32 s10, 0xf7f0
	v_mad_i32_i24 v32, v33, s10, v35
	v_lshl_add_u32 v37, v33, 9, v68
	v_ashrrev_i32_e32 v33, 31, v32
	v_mad_u64_u32 v[32:33], s[10:11], v37, s95, v[32:33]
	s_mov_b64 s[10:11], 0x800000
	s_nop 0
	v_lshl_add_u64 v[32:33], v[32:33], 0, s[10:11]
	s_andn2_saveexec_b64 s[8:9], s[8:9]
	s_movk_i32 s10, 0x1fe4
	v_and_or_b32 v32, v34, s10, v64
	v_mov_b32_e32 v33, v65
	s_or_b64 exec, exec, s[8:9]
	v_cvt_pk_bf16_f32 v16, v16, v17
	v_cvt_pk_bf16_f32 v17, v18, v19
	v_lshl_add_u64 v[18:19], v[32:33], 1, s[56:57]
	global_store_dwordx2 v[18:19], v[16:17], off
	v_or_b32_e32 v18, 40, v69
	v_add_u32_e32 v32, 0xffffc028, v69
	s_mov_b32 s10, 0xfe03f81
	v_cmp_lt_i32_e64 s[8:9], s64, v18
	v_mul_hi_u32 v33, v32, s10
	s_and_saveexec_b64 s[10:11], s[8:9]
	s_xor_b64 s[10:11], exec, s[10:11]
	v_lshrrev_b32_e32 v17, 7, v33
	s_movk_i32 s12, 0xf7f0
	v_mad_i32_i24 v16, v17, s12, v32
	v_lshl_add_u32 v19, v17, 9, v68
	v_ashrrev_i32_e32 v17, 31, v16
	v_mad_u64_u32 v[16:17], s[12:13], v19, s95, v[16:17]
	s_mov_b64 s[12:13], 0x800000
	s_nop 0
; DI unsigned pk2(float a, float b) { f2_t v = {a, b}; return __builtin_bit_cast(unsigned, __builtin_convertvector(v, bf2_t)); }
; DI size_t vt_off(int keyrow, int h, int d) {
;   if (keyrow < NP) { int b = keyrow >> 13, s = keyrow & 8191; return ((size_t)((b * 8 + h) * 64 + d)) * 8192 + s; }
;   int rr = keyrow - NP; int b = rr / SK, s = rr - b * SK; return VT_S_OFF + ((size_t)((b * 8 + h) * 64 + d)) * SK + s;
; }
; DI void phase4(const Params& p, int l, unsigned char* smem) {
;     ...
;       } else {
; #pragma unroll
;         for (int bm = 0; bm < 2; bm++)
; #pragma unroll
;           for (int bn = 0; bn < 2; bn++)
; #pragma unroll
;             for (int g4 = 0; g4 < 4; g4++) {
;               int krow = m0 + wm * 64 + bm * 32 + 8 * g4 + 4 * hl, d = bn * 32 + r;
;               uint2 o; o.x = pk2(acc[bm][bn][4 * g4], acc[bm][bn][4 * g4 + 1]); o.y = pk2(acc[bm][bn][4 * g4 + 2], acc[bm][bn][4 * g4 + 3]);
;               *(uint2*)(VT + vt_off(krow, head, d)) = o;
;             }
	v_lshl_add_u64 v[16:17], v[16:17], 0, s[12:13]
	s_andn2_saveexec_b64 s[10:11], s[10:11]
	s_movk_i32 s12, 0x1fec
	v_and_or_b32 v16, v18, s12, v64
	v_mov_b32_e32 v17, v65
	s_or_b64 exec, exec, s[10:11]
	v_cvt_pk_bf16_f32 v20, v20, v21
	v_cvt_pk_bf16_f32 v21, v22, v23
	v_lshl_add_u64 v[16:17], v[16:17], 1, s[56:57]
	global_store_dwordx2 v[16:17], v[20:21], off
	v_or_b32_e32 v20, 48, v69
	v_add_u32_e32 v21, 0xffffc030, v69
	s_mov_b32 s12, 0xfe03f81
	v_cmp_lt_i32_e64 s[10:11], s64, v20
	v_mul_hi_u32 v23, v21, s12
	s_and_saveexec_b64 s[12:13], s[10:11]
	s_xor_b64 s[12:13], exec, s[12:13]
	v_lshrrev_b32_e32 v17, 7, v23
	s_movk_i32 s14, 0xf7f0
	v_mad_i32_i24 v16, v17, s14, v21
	v_lshl_add_u32 v19, v17, 9, v68
	v_ashrrev_i32_e32 v17, 31, v16
	v_mad_u64_u32 v[16:17], s[14:15], v19, s95, v[16:17]
	s_mov_b64 s[14:15], 0x800000
	s_nop 0
	v_lshl_add_u64 v[16:17], v[16:17], 0, s[14:15]
	s_andn2_saveexec_b64 s[12:13], s[12:13]
	s_movk_i32 s14, 0x1ff4
	v_and_or_b32 v16, v20, s14, v64
	v_mov_b32_e32 v17, v65
	s_or_b64 exec, exec, s[12:13]
	v_cvt_pk_bf16_f32 v24, v24, v25
	v_cvt_pk_bf16_f32 v25, v26, v27
	v_lshl_add_u64 v[16:17], v[16:17], 1, s[56:57]
	v_or_b32_e32 v19, 56, v69
	v_add_u32_e32 v22, 0xffffc038, v69
	s_mov_b32 s14, 0xfe03f81
	global_store_dwordx2 v[16:17], v[24:25], off
	v_cmp_lt_i32_e64 s[12:13], s64, v19
	v_mul_hi_u32 v24, v22, s14
	s_and_saveexec_b64 s[14:15], s[12:13]
	s_xor_b64 s[14:15], exec, s[14:15]
	v_lshrrev_b32_e32 v17, 7, v24
	s_movk_i32 s31, 0xf7f0
	v_mad_i32_i24 v16, v17, s31, v22
	v_lshl_add_u32 v25, v17, 9, v68
	v_ashrrev_i32_e32 v17, 31, v16
	v_mad_u64_u32 v[16:17], s[34:35], v25, s95, v[16:17]
	s_mov_b64 s[34:35], 0x800000
	s_nop 0
	v_lshl_add_u64 v[64:65], v[16:17], 0, s[34:35]
	s_andn2_saveexec_b64 s[14:15], s[14:15]
	s_movk_i32 s31, 0x1ffc
	v_and_or_b32 v64, v19, s31, v64
	s_or_b64 exec, exec, s[14:15]
	v_cvt_pk_bf16_f32 v16, v28, v29
	v_cvt_pk_bf16_f32 v17, v30, v31
	v_lshl_add_u64 v[26:27], v[64:65], 1, s[56:57]
	global_store_dwordx2 v[26:27], v[16:17], off
	s_and_saveexec_b64 s[14:15], vcc
	s_xor_b64 s[14:15], exec, s[14:15]
	v_lshrrev_b32_e32 v17, 7, v36
	s_movk_i32 s31, 0xf7f0
	v_mad_i32_i24 v16, v17, s31, v35
	v_lshl_add_u32 v25, v17, 9, v52
	v_ashrrev_i32_e32 v17, 31, v16
	v_mad_u64_u32 v[16:17], s[34:35], v25, s95, v[16:17]
	s_mov_b64 s[34:35], 0x800000
	s_nop 0
	v_lshl_add_u64 v[16:17], v[16:17], 0, s[34:35]
	s_andn2_saveexec_b64 s[14:15], s[14:15]
	s_movk_i32 s31, 0x1fe4
	v_and_or_b32 v16, v34, s31, v48
	v_mov_b32_e32 v17, v49
	s_or_b64 exec, exec, s[14:15]
	v_cvt_pk_bf16_f32 v0, v0, v1
	v_cvt_pk_bf16_f32 v1, v2, v3
	v_lshl_add_u64 v[2:3], v[16:17], 1, s[56:57]
	global_store_dwordx2 v[2:3], v[0:1], off
	s_and_saveexec_b64 s[14:15], s[8:9]
	s_xor_b64 s[8:9], exec, s[14:15]
	v_lshrrev_b32_e32 v1, 7, v33
	s_movk_i32 s14, 0xf7f0
	v_mad_i32_i24 v0, v1, s14, v32
	v_lshl_add_u32 v2, v1, 9, v52
	v_ashrrev_i32_e32 v1, 31, v0
	v_mad_u64_u32 v[0:1], s[14:15], v2, s95, v[0:1]
	s_mov_b64 s[14:15], 0x800000
	s_nop 0
	v_lshl_add_u64 v[0:1], v[0:1], 0, s[14:15]
	s_andn2_saveexec_b64 s[8:9], s[8:9]
	s_movk_i32 s14, 0x1fec
	v_and_or_b32 v0, v18, s14, v48
	v_mov_b32_e32 v1, v49
	s_or_b64 exec, exec, s[8:9]
	v_cvt_pk_bf16_f32 v2, v4, v5
	v_cvt_pk_bf16_f32 v3, v6, v7
	v_lshl_add_u64 v[0:1], v[0:1], 1, s[56:57]
	global_store_dwordx2 v[0:1], v[2:3], off
	s_and_saveexec_b64 s[8:9], s[10:11]
	s_xor_b64 s[8:9], exec, s[8:9]
	v_lshrrev_b32_e32 v1, 7, v23
	s_movk_i32 s10, 0xf7f0
	v_mad_i32_i24 v0, v1, s10, v21
	v_lshl_add_u32 v2, v1, 9, v52
	v_ashrrev_i32_e32 v1, 31, v0
	v_mad_u64_u32 v[0:1], s[10:11], v2, s95, v[0:1]
	s_mov_b64 s[10:11], 0x800000
	s_nop 0
	v_lshl_add_u64 v[0:1], v[0:1], 0, s[10:11]
	s_andn2_saveexec_b64 s[8:9], s[8:9]
	s_movk_i32 s10, 0x1ff4
	v_and_or_b32 v0, v20, s10, v48
	v_mov_b32_e32 v1, v49
	s_or_b64 exec, exec, s[8:9]
	v_cvt_pk_bf16_f32 v2, v8, v9
	v_cvt_pk_bf16_f32 v3, v10, v11
	v_lshl_add_u64 v[0:1], v[0:1], 1, s[56:57]
	global_store_dwordx2 v[0:1], v[2:3], off
	s_and_saveexec_b64 s[8:9], s[12:13]
	s_xor_b64 s[8:9], exec, s[8:9]
	v_lshrrev_b32_e32 v1, 7, v24
	s_movk_i32 s10, 0xf7f0
	v_mad_i32_i24 v0, v1, s10, v22
	v_lshl_add_u32 v2, v1, 9, v52
	v_ashrrev_i32_e32 v1, 31, v0
	v_mad_u64_u32 v[0:1], s[10:11], v2, s95, v[0:1]
	s_mov_b64 s[10:11], 0x800000
	s_nop 0
	v_lshl_add_u64 v[48:49], v[0:1], 0, s[10:11]
	s_andn2_saveexec_b64 s[8:9], s[8:9]
	s_movk_i32 s10, 0x1ffc
	v_and_or_b32 v48, v19, s10, v48
	s_or_b64 exec, exec, s[8:9]
	v_cvt_pk_bf16_f32 v0, v12, v13
	v_cvt_pk_bf16_f32 v1, v14, v15
	v_lshl_add_u64 v[2:3], v[48:49], 1, s[56:57]
	global_store_dwordx2 v[2:3], v[0:1], off

; DI void gemm_mainloop(f32x16 (&acc)[2][2], const u16* A, int lda, const u16* Bt, int ldb, int K, unsigned char* smem) {
;   u16* s0 = (u16*)smem;
;   const int tid = TIDX(), lane = tid & 63, wave = tid >> 6, wm = wave >> 1, wn = wave & 1;
;   const int lr = tid >> 3, lc = (tid & 7) * 8;
;   unsigned offA[4], offB[4];
; #pragma unroll
;   for (int i = 0; i < 4; i++) { offA[i] = (unsigned)(((lr + 32 * i) * lda + lc) * 2); offB[i] = (unsigned)(((lr + 32 * i) * ldb + lc) * 2); }
;   const char* Ab = (const char*)A;
;   const char* Bb = (const char*)Bt;
;   u32x4 ra[4], rb[4];
;   const int nk = K >> 6;
;   const int r = lane & 31, hl = lane >> 5;
; #pragma unroll
;   for (int i = 0; i < 4; i++) { ra[i] = *(const u32x4*)(Ab + offA[i]); rb[i] = *(const u32x4*)(Bb + offB[i]); }
;   __syncthreads();
; #pragma unroll
;   for (int i = 0; i < 4; i++) { *(u32x4*)(s0 + (lr + 32 * i) * 72 + lc) = ra[i]; *(u32x4*)(s0 + 128 * 72 + (lr + 32 * i) * 72 + lc) = rb[i]; }
;   if (nk > 1) { Ab += 128; Bb += 128; }
; #pragma unroll
;   for (int i = 0; i < 4; i++) { ra[i] = *(const u32x4*)(Ab + offA[i]); rb[i] = *(const u32x4*)(Bb + offB[i]); }
;   __syncthreads();
;   for (int kt = 0; kt < nk; kt++) {
;     u16* sA = s0 + (kt & 1) * (256 * 72); u16* sB = sA + 128 * 72;
;     if (kt + 1 < nk) {
;       u16* nA = s0 + ((kt + 1) & 1) * (256 * 72); u16* nB = nA + 128 * 72;
; #pragma unroll
;       for (int i = 0; i < 4; i++) { *(u32x4*)(nA + (lr + 32 * i) * 72 + lc) = ra[i]; *(u32x4*)(nB + (lr + 32 * i) * 72 + lc) = rb[i]; }
;     }
;     if (kt + 2 < nk) { Ab += 128; Bb += 128; }
; #pragma unroll
;     for (int i = 0; i < 4; i++) { ra[i] = *(const u32x4*)(Ab + offA[i]); rb[i] = *(const u32x4*)(Bb + offB[i]); }
; #pragma unroll
;     for (int ks = 0; ks < 4; ks++) {
;       bf16x8 af[2], bfr[2];
; #pragma unroll
;       for (int b = 0; b < 2; b++) {
;         af[b] = *(const bf16x8*)(sA + (wm * 64 + b * 32 + r) * 72 + ks * 16 + hl * 8);
;         bfr[b] = *(const bf16x8*)(sB + (wn * 64 + b * 32 + r) * 72 + ks * 16 + hl * 8);
;       }
; #pragma unroll
;       for (int bm = 0; bm < 2; bm++)
; #pragma unroll
;         for (int bn = 0; bn < 2; bn++) acc[bm][bn] = MFMA32(af[bm], bfr[bn], acc[bm][bn]);
;     }
; DI void phase4(const Params& p, int l, unsigned char* smem) {
;     ...
;     if (t < nQ) {
;       const int mt = t % 129, nt = t / 129, m0 = mt * 128;
.LBB0_712:
	s_andn2_b64 vcc, exec, s[2:3]
	s_cbranch_vccnz .LBB0_717
	s_add_i32 s12, s16, 0xfffffe40
	s_and_b32 s2, s12, 0xffff
	s_mulk_i32 s2, 0x3f81
	s_lshr_b32 s10, s2, 21
	s_mul_i32 s2, s10, 0x81
	s_sub_i32 s2, s12, s2
	s_and_b32 s11, s2, 0xffff
	s_mul_i32 s46, s11, 0xc000
	s_lshl_b64 s[2:3], s[46:47], 1
	s_add_u32 s2, s28, s2
	s_addc_u32 s3, s29, s3
	s_lshl_b32 s8, s10, 7
	s_add_u32 s8, s23, s8
	s_addc_u32 s9, s22, 0
	s_mulk_i32 s9, 0x300
	s_mul_hi_u32 s13, s8, 0x300
	s_add_i32 s13, s13, s9
	s_mulk_i32 s8, 0x300
	v_readlane_b32 s9, v254, 54
	s_add_u32 s8, s9, s8
	v_readlane_b32 s9, v254, 55
	v_mov_b32_e32 v67, v160
	s_addc_u32 s9, s9, s13
	s_movk_i32 s13, 0x180
	v_ashrrev_i32_e32 v64, 3, v67
	v_lshlrev_b32_e32 v0, 3, v67
	v_and_b32_e32 v65, 56, v0
	v_mul_lo_u32 v0, v64, s13
	v_or_b32_e32 v0, v0, v65
	v_lshlrev_b32_e32 v98, 1, v0
	v_add_u32_e32 v99, 0x6000, v98
	s_waitcnt vmcnt(11)
	v_add_u32_e32 v120, 0xc000, v98
	v_add_u32_e32 v121, 0x12000, v98
	global_load_dwordx4 v[0:3], v98, s[2:3]
	global_load_dwordx4 v[4:7], v99, s[2:3]
	global_load_dwordx4 v[8:11], v120, s[2:3]
	global_load_dwordx4 v[12:15], v121, s[2:3]
	global_load_dwordx4 v[16:19], v98, s[8:9]
	global_load_dwordx4 v[20:23], v99, s[8:9]
	global_load_dwordx4 v[24:27], v120, s[8:9]
	global_load_dwordx4 v[28:31], v121, s[8:9]
	s_waitcnt vmcnt(63) expcnt(7) lgkmcnt(15)
	s_barrier
	global_load_dwordx4 v[32:35], v98, s[2:3] offset:128
	global_load_dwordx4 v[36:39], v98, s[8:9] offset:128
	global_load_dwordx4 v[40:43], v99, s[2:3] offset:128
	global_load_dwordx4 v[44:47], v99, s[8:9] offset:128
	global_load_dwordx4 v[48:51], v120, s[2:3] offset:128
	global_load_dwordx4 v[52:55], v120, s[8:9] offset:128
	global_load_dwordx4 v[56:59], v121, s[2:3] offset:128
	global_load_dwordx4 v[60:63], v121, s[8:9] offset:128
	v_and_b32_e32 v66, 31, v67
	v_lshrrev_b32_e32 v68, 1, v67
	v_mul_lo_u32 v64, v64, s65
	v_and_or_b32 v69, v68, s45, v66
	v_and_b32_e32 v66, 16, v68
	v_lshl_add_u32 v122, v65, 1, v64
	v_mad_u64_u32 v[64:65], s[14:15], v69, s65, v[66:67]
	v_add_u32_e32 v123, 0x1200, v122
	s_lshl_b32 s11, s11, 7
	s_cmpk_gt_u32 s12, 0x203
	s_waitcnt vmcnt(15)
	ds_write_b128 v122, v[0:3]
	s_waitcnt vmcnt(14)
	ds_write_b128 v122, v[4:7] offset:4608
	s_waitcnt vmcnt(13)
	ds_write_b128 v122, v[8:11] offset:9216
	s_waitcnt vmcnt(12)
	ds_write_b128 v122, v[12:15] offset:13824
	s_waitcnt vmcnt(11)
	ds_write_b128 v122, v[16:19] offset:18432
	s_waitcnt vmcnt(10)
	ds_write_b128 v122, v[20:23] offset:23040
	s_waitcnt vmcnt(9)
	ds_write_b128 v122, v[24:27] offset:27648
	s_waitcnt vmcnt(8)
	ds_write_b128 v122, v[28:31] offset:32256
	s_waitcnt lgkmcnt(0)
	s_barrier
	s_waitcnt vmcnt(7)
	ds_write_b128 v122, v[32:35] offset:36864
	s_waitcnt vmcnt(6)
	ds_write_b128 v122, v[36:39] offset:55296
	s_waitcnt vmcnt(5)
	ds_write_b128 v122, v[40:43] offset:41472
	s_waitcnt vmcnt(4)
	ds_write_b128 v122, v[44:47] offset:59904
	s_waitcnt vmcnt(3)
	ds_write_b128 v122, v[48:51] offset:46080
	s_waitcnt vmcnt(2)
	ds_write_b128 v122, v[52:55] offset:64512
	s_waitcnt vmcnt(1)
	ds_write_b128 v122, v[56:59] offset:50688
	s_waitcnt vmcnt(0)
	ds_write_b128 v123, v[60:63] offset:64512
	ds_read_b128 v[124:127], v64
	v_and_b32_e32 v4, 0x5f, v67
	v_mad_u32_u24 v65, v4, s65, v66
	global_load_dwordx4 v[66:69], v98, s[2:3] offset:256
	global_load_dwordx4 v[70:73], v98, s[8:9] offset:256
	global_load_dwordx4 v[74:77], v99, s[2:3] offset:256
	global_load_dwordx4 v[82:85], v99, s[8:9] offset:256
	global_load_dwordx4 v[94:97], v120, s[2:3] offset:256
	global_load_dwordx4 v[112:115], v120, s[8:9] offset:256
	global_load_dwordx4 v[78:81], v121, s[2:3] offset:256
	global_load_dwordx4 v[116:119], v121, s[8:9] offset:256
	ds_read_b128 v[128:131], v65 offset:18432
	ds_read_b128 v[132:135], v64 offset:32
	ds_read_b128 v[136:139], v65 offset:18464
	ds_read_b128 v[140:143], v65 offset:23040
	ds_read_b128 v[144:147], v65 offset:23072
	s_waitcnt lgkmcnt(4)
	ds_read_b128 v[148:151], v64 offset:4608
	ds_read_b128 v[152:155], v64 offset:4640
	ds_read_b128 v[156:159], v64 offset:64
	ds_read_b128 v[164:167], v65 offset:18496
	ds_read_b128 v[168:171], v64 offset:96
	ds_read_b128 v[172:175], v65 offset:18528
	ds_read_b128 v[176:179], v65 offset:23104
	ds_read_b128 v[86:89], v65 offset:23136
	ds_read_b128 v[180:183], v64 offset:4672
	ds_read_b128 v[90:93], v64 offset:4704
	v_mfma_f32_32x32x16_bf16 v[32:47], v[124:127], v[128:131], 0
	s_waitcnt lgkmcnt(11)
	v_mfma_f32_32x32x16_bf16 v[48:63], v[124:127], v[140:143], 0
	s_nop 1
	s_waitcnt lgkmcnt(9)
	v_mfma_f32_32x32x16_bf16 v[16:31], v[148:151], v[128:131], 0
	v_mfma_f32_32x32x16_bf16 v[0:15], v[148:151], v[140:143], 0
	v_mfma_f32_32x32x16_bf16 v[32:47], v[132:135], v[136:139], v[32:47]
	v_mfma_f32_32x32x16_bf16 v[48:63], v[132:135], v[144:147], v[48:63]
	s_waitcnt lgkmcnt(8)
	v_mfma_f32_32x32x16_bf16 v[16:31], v[152:155], v[136:139], v[16:31]
	v_mfma_f32_32x32x16_bf16 v[0:15], v[152:155], v[144:147], v[0:15]
	s_nop 5
	s_waitcnt lgkmcnt(6)
	v_mfma_f32_32x32x16_bf16 v[32:47], v[156:159], v[164:167], v[32:47]
	s_waitcnt lgkmcnt(3)
	v_mfma_f32_32x32x16_bf16 v[48:63], v[156:159], v[176:179], v[48:63]
	s_nop 1
	s_waitcnt lgkmcnt(1)
	v_mfma_f32_32x32x16_bf16 v[16:31], v[180:183], v[164:167], v[16:31]
	v_mfma_f32_32x32x16_bf16 v[0:15], v[180:183], v[176:179], v[0:15]
	v_mfma_f32_32x32x16_bf16 v[32:47], v[168:171], v[172:175], v[32:47]
	v_mfma_f32_32x32x16_bf16 v[48:63], v[168:171], v[86:89], v[48:63]
	s_nop 5
	s_waitcnt lgkmcnt(0)
	v_mfma_f32_32x32x16_bf16 v[16:31], v[90:93], v[172:175], v[16:31]
	s_nop 1
	s_barrier
; #define MFMA32(a, b, c) __builtin_amdgcn_mfma_f32_32x32x16_bf16((a), (b), (c), 0, 0, 0)
; DI void gemm_mainloop(f32x16 (&acc)[2][2], const u16* A, int lda, const u16* Bt, int ldb, int K, unsigned char* smem) {
;     ...
;   for (int kt = 0; kt < nk; kt++) {
;     u16* sA = s0 + (kt & 1) * (256 * 72); u16* sB = sA + 128 * 72;
;     if (kt + 1 < nk) {
;       u16* nA = s0 + ((kt + 1) & 1) * (256 * 72); u16* nB = nA + 128 * 72;
; #pragma unroll
;       for (int i = 0; i < 4; i++) { *(u32x4*)(nA + (lr + 32 * i) * 72 + lc) = ra[i]; *(u32x4*)(nB + (lr + 32 * i) * 72 + lc) = rb[i]; }
;     }
;     if (kt + 2 < nk) { Ab += 128; Bb += 128; }
; #pragma unroll
;     for (int i = 0; i < 4; i++) { ra[i] = *(const u32x4*)(Ab + offA[i]); rb[i] = *(const u32x4*)(Bb + offB[i]); }
; #pragma unroll
;     for (int ks = 0; ks < 4; ks++) {
;       bf16x8 af[2], bfr[2];
; #pragma unroll
;       for (int b = 0; b < 2; b++) {
;         af[b] = *(const bf16x8*)(sA + (wm * 64 + b * 32 + r) * 72 + ks * 16 + hl * 8);
;         bfr[b] = *(const bf16x8*)(sB + (wn * 64 + b * 32 + r) * 72 + ks * 16 + hl * 8);
;       }
; #pragma unroll
;       for (int bm = 0; bm < 2; bm++)
; #pragma unroll
;         for (int bn = 0; bn < 2; bn++) acc[bm][bn] = MFMA32(af[bm], bfr[bn], acc[bm][bn]);
;     }
	s_waitcnt vmcnt(7)
	ds_write_b128 v122, v[66:69]
	global_load_dwordx4 v[66:69], v98, s[2:3] offset:384
	s_waitcnt vmcnt(7)
	ds_write_b128 v122, v[70:73] offset:18432
	global_load_dwordx4 v[70:73], v98, s[8:9] offset:384
	s_waitcnt vmcnt(7)
	ds_write_b128 v122, v[74:77] offset:4608
	global_load_dwordx4 v[74:77], v99, s[2:3] offset:384
	s_waitcnt vmcnt(7)
	ds_write_b128 v122, v[82:85] offset:23040
	global_load_dwordx4 v[82:85], v99, s[8:9] offset:384
	s_waitcnt vmcnt(7)
	ds_write_b128 v122, v[94:97] offset:9216
	global_load_dwordx4 v[94:97], v120, s[2:3] offset:384
	s_waitcnt vmcnt(7)
	ds_write_b128 v122, v[112:115] offset:27648
	global_load_dwordx4 v[112:115], v120, s[8:9] offset:384
	s_waitcnt vmcnt(7)
	ds_write_b128 v122, v[78:81] offset:13824
	global_load_dwordx4 v[78:81], v121, s[2:3] offset:384
	s_waitcnt vmcnt(7)
	ds_write_b128 v122, v[116:119] offset:32256
	global_load_dwordx4 v[116:119], v121, s[8:9] offset:384
	ds_read_b128 v[124:127], v64 offset:36864
	ds_read_b128 v[128:131], v65 offset:55296
	ds_read_b128 v[132:135], v64 offset:36896
	ds_read_b128 v[136:139], v65 offset:55328
	ds_read_b128 v[140:143], v65 offset:59904
	ds_read_b128 v[144:147], v65 offset:59936
	v_mfma_f32_32x32x16_bf16 v[0:15], v[90:93], v[86:89], v[0:15]
	s_nop 5
	s_waitcnt lgkmcnt(4)
	ds_read_b128 v[148:151], v64 offset:41472
	ds_read_b128 v[152:155], v64 offset:41504
	ds_read_b128 v[156:159], v64 offset:36928
	ds_read_b128 v[164:167], v65 offset:55360
	ds_read_b128 v[168:171], v64 offset:36960
	ds_read_b128 v[172:175], v65 offset:55392
	ds_read_b128 v[176:179], v65 offset:59968
	v_mfma_f32_32x32x16_bf16 v[32:47], v[124:127], v[128:131], v[32:47]
	s_waitcnt lgkmcnt(8)
	v_mfma_f32_32x32x16_bf16 v[48:63], v[124:127], v[140:143], v[48:63]
	s_nop 1
	s_waitcnt lgkmcnt(6)
	v_mfma_f32_32x32x16_bf16 v[16:31], v[148:151], v[128:131], v[16:31]
	v_mfma_f32_32x32x16_bf16 v[0:15], v[148:151], v[140:143], v[0:15]
	v_mfma_f32_32x32x16_bf16 v[32:47], v[132:135], v[136:139], v[32:47]
	v_mfma_f32_32x32x16_bf16 v[48:63], v[132:135], v[144:147], v[48:63]
	s_waitcnt lgkmcnt(5)
	v_mfma_f32_32x32x16_bf16 v[16:31], v[152:155], v[136:139], v[16:31]
	s_nop 3
	v_mfma_f32_32x32x16_bf16 v[0:15], v[152:155], v[144:147], v[0:15]
	s_nop 0
	ds_read_b128 v[86:89], v65 offset:60000
	ds_read_b128 v[180:183], v64 offset:41536
	s_waitcnt lgkmcnt(5)
	v_mfma_f32_32x32x16_bf16 v[32:47], v[156:159], v[164:167], v[32:47]
	s_waitcnt lgkmcnt(2)
	v_mfma_f32_32x32x16_bf16 v[48:63], v[156:159], v[176:179], v[48:63]
	s_nop 0
	ds_read_b128 v[90:93], v64 offset:41568
	s_waitcnt lgkmcnt(1)
	v_mfma_f32_32x32x16_bf16 v[16:31], v[180:183], v[164:167], v[16:31]
	v_mfma_f32_32x32x16_bf16 v[0:15], v[180:183], v[176:179], v[0:15]
	v_mfma_f32_32x32x16_bf16 v[32:47], v[168:171], v[172:175], v[32:47]
	v_mfma_f32_32x32x16_bf16 v[48:63], v[168:171], v[86:89], v[48:63]
	s_nop 5
	s_waitcnt lgkmcnt(0)
	v_mfma_f32_32x32x16_bf16 v[16:31], v[90:93], v[172:175], v[16:31]
	s_nop 1
	s_barrier
	s_waitcnt vmcnt(7)
	ds_write_b128 v122, v[66:69] offset:36864
	global_load_dwordx4 v[66:69], v98, s[2:3] offset:512
	s_waitcnt vmcnt(7)
	ds_write_b128 v122, v[70:73] offset:55296
	global_load_dwordx4 v[70:73], v98, s[8:9] offset:512
	s_waitcnt vmcnt(7)
	ds_write_b128 v122, v[74:77] offset:41472
	global_load_dwordx4 v[74:77], v99, s[2:3] offset:512
	s_waitcnt vmcnt(7)
	ds_write_b128 v122, v[82:85] offset:59904
	global_load_dwordx4 v[82:85], v99, s[8:9] offset:512
	s_waitcnt vmcnt(7)
	ds_write_b128 v122, v[94:97] offset:46080
	global_load_dwordx4 v[94:97], v120, s[2:3] offset:512
	s_waitcnt vmcnt(7)
	ds_write_b128 v122, v[112:115] offset:64512
	global_load_dwordx4 v[112:115], v120, s[8:9] offset:512
	s_waitcnt vmcnt(7)
	ds_write_b128 v122, v[78:81] offset:50688
	global_load_dwordx4 v[78:81], v121, s[2:3] offset:512
	s_waitcnt vmcnt(7)
	ds_write_b128 v123, v[116:119] offset:64512
	global_load_dwordx4 v[116:119], v121, s[8:9] offset:512
	ds_read_b128 v[124:127], v64
	ds_read_b128 v[128:131], v65 offset:18432
	ds_read_b128 v[132:135], v64 offset:32
	ds_read_b128 v[136:139], v65 offset:18464
	ds_read_b128 v[140:143], v65 offset:23040
	ds_read_b128 v[144:147], v65 offset:23072
	v_mfma_f32_32x32x16_bf16 v[0:15], v[90:93], v[86:89], v[0:15]
	s_nop 5
	s_waitcnt lgkmcnt(4)
	ds_read_b128 v[148:151], v64 offset:4608
	ds_read_b128 v[152:155], v64 offset:4640
	ds_read_b128 v[156:159], v64 offset:64
	ds_read_b128 v[164:167], v65 offset:18496
	ds_read_b128 v[168:171], v64 offset:96
	ds_read_b128 v[172:175], v65 offset:18528
	ds_read_b128 v[176:179], v65 offset:23104
	v_mfma_f32_32x32x16_bf16 v[32:47], v[124:127], v[128:131], v[32:47]
	s_waitcnt lgkmcnt(8)
	v_mfma_f32_32x32x16_bf16 v[48:63], v[124:127], v[140:143], v[48:63]
	s_nop 1
	s_waitcnt lgkmcnt(6)
	v_mfma_f32_32x32x16_bf16 v[16:31], v[148:151], v[128:131], v[16:31]
	v_mfma_f32_32x32x16_bf16 v[0:15], v[148:151], v[140:143], v[0:15]
	v_mfma_f32_32x32x16_bf16 v[32:47], v[132:135], v[136:139], v[32:47]
	v_mfma_f32_32x32x16_bf16 v[48:63], v[132:135], v[144:147], v[48:63]
	s_waitcnt lgkmcnt(5)
	v_mfma_f32_32x32x16_bf16 v[16:31], v[152:155], v[136:139], v[16:31]
	s_nop 3
	v_mfma_f32_32x32x16_bf16 v[0:15], v[152:155], v[144:147], v[0:15]
	s_nop 0
	ds_read_b128 v[86:89], v65 offset:23136
	ds_read_b128 v[180:183], v64 offset:4672
	s_waitcnt lgkmcnt(5)
	v_mfma_f32_32x32x16_bf16 v[32:47], v[156:159], v[164:167], v[32:47]
	s_waitcnt lgkmcnt(2)
	v_mfma_f32_32x32x16_bf16 v[48:63], v[156:159], v[176:179], v[48:63]
	s_nop 0
	ds_read_b128 v[90:93], v64 offset:4704
	s_waitcnt lgkmcnt(1)
	v_mfma_f32_32x32x16_bf16 v[16:31], v[180:183], v[164:167], v[16:31]
	v_mfma_f32_32x32x16_bf16 v[0:15], v[180:183], v[176:179], v[0:15]
	v_mfma_f32_32x32x16_bf16 v[32:47], v[168:171], v[172:175], v[32:47]
	v_mfma_f32_32x32x16_bf16 v[48:63], v[168:171], v[86:89], v[48:63]
	s_nop 5
	s_waitcnt lgkmcnt(0)
	v_mfma_f32_32x32x16_bf16 v[16:31], v[90:93], v[172:175], v[16:31]
	s_nop 1
	s_barrier
; #define MFMA32(a, b, c) __builtin_amdgcn_mfma_f32_32x32x16_bf16((a), (b), (c), 0, 0, 0)
; DI void gemm_mainloop(f32x16 (&acc)[2][2], const u16* A, int lda, const u16* Bt, int ldb, int K, unsigned char* smem) {
;     ...
;   for (int kt = 0; kt < nk; kt++) {
;     u16* sA = s0 + (kt & 1) * (256 * 72); u16* sB = sA + 128 * 72;
;     if (kt + 1 < nk) {
;       u16* nA = s0 + ((kt + 1) & 1) * (256 * 72); u16* nB = nA + 128 * 72;
; #pragma unroll
;       for (int i = 0; i < 4; i++) { *(u32x4*)(nA + (lr + 32 * i) * 72 + lc) = ra[i]; *(u32x4*)(nB + (lr + 32 * i) * 72 + lc) = rb[i]; }
;     }
;     if (kt + 2 < nk) { Ab += 128; Bb += 128; }
; #pragma unroll
;     for (int i = 0; i < 4; i++) { ra[i] = *(const u32x4*)(Ab + offA[i]); rb[i] = *(const u32x4*)(Bb + offB[i]); }
; #pragma unroll
;     for (int ks = 0; ks < 4; ks++) {
;       bf16x8 af[2], bfr[2];
; #pragma unroll
;       for (int b = 0; b < 2; b++) {
;         af[b] = *(const bf16x8*)(sA + (wm * 64 + b * 32 + r) * 72 + ks * 16 + hl * 8);
;         bfr[b] = *(const bf16x8*)(sB + (wn * 64 + b * 32 + r) * 72 + ks * 16 + hl * 8);
;       }
; #pragma unroll
;       for (int bm = 0; bm < 2; bm++)
; #pragma unroll
;         for (int bn = 0; bn < 2; bn++) acc[bm][bn] = MFMA32(af[bm], bfr[bn], acc[bm][bn]);
;     }
	s_waitcnt vmcnt(7)
	ds_write_b128 v122, v[66:69]
	global_load_dwordx4 v[66:69], v98, s[2:3] offset:640
	s_waitcnt vmcnt(7)
	ds_write_b128 v122, v[70:73] offset:18432
	global_load_dwordx4 v[70:73], v98, s[8:9] offset:640
	s_waitcnt vmcnt(7)
	ds_write_b128 v122, v[74:77] offset:4608
	global_load_dwordx4 v[74:77], v99, s[2:3] offset:640
	s_waitcnt vmcnt(7)
	ds_write_b128 v122, v[82:85] offset:23040
	global_load_dwordx4 v[82:85], v99, s[8:9] offset:640
	s_waitcnt vmcnt(7)
	ds_write_b128 v122, v[94:97] offset:9216
	global_load_dwordx4 v[94:97], v120, s[2:3] offset:640
	s_waitcnt vmcnt(7)
	ds_write_b128 v122, v[112:115] offset:27648
	global_load_dwordx4 v[112:115], v120, s[8:9] offset:640
	s_waitcnt vmcnt(7)
	ds_write_b128 v122, v[78:81] offset:13824
	global_load_dwordx4 v[78:81], v121, s[2:3] offset:640
	s_waitcnt vmcnt(7)
	ds_write_b128 v122, v[116:119] offset:32256
	global_load_dwordx4 v[116:119], v121, s[8:9] offset:640
	ds_read_b128 v[124:127], v64 offset:36864
	ds_read_b128 v[128:131], v65 offset:55296
	ds_read_b128 v[132:135], v64 offset:36896
	ds_read_b128 v[136:139], v65 offset:55328
	ds_read_b128 v[140:143], v65 offset:59904
	ds_read_b128 v[144:147], v65 offset:59936
	v_mfma_f32_32x32x16_bf16 v[0:15], v[90:93], v[86:89], v[0:15]
	s_nop 5
	s_waitcnt lgkmcnt(4)
	ds_read_b128 v[148:151], v64 offset:41472
	ds_read_b128 v[152:155], v64 offset:41504
	ds_read_b128 v[156:159], v64 offset:36928
	ds_read_b128 v[164:167], v65 offset:55360
	ds_read_b128 v[168:171], v64 offset:36960
	ds_read_b128 v[172:175], v65 offset:55392
	ds_read_b128 v[176:179], v65 offset:59968
	v_mfma_f32_32x32x16_bf16 v[32:47], v[124:127], v[128:131], v[32:47]
	s_waitcnt lgkmcnt(8)
	v_mfma_f32_32x32x16_bf16 v[48:63], v[124:127], v[140:143], v[48:63]
	s_nop 1
	s_waitcnt lgkmcnt(6)
	v_mfma_f32_32x32x16_bf16 v[16:31], v[148:151], v[128:131], v[16:31]
	v_mfma_f32_32x32x16_bf16 v[0:15], v[148:151], v[140:143], v[0:15]
	v_mfma_f32_32x32x16_bf16 v[32:47], v[132:135], v[136:139], v[32:47]
	v_mfma_f32_32x32x16_bf16 v[48:63], v[132:135], v[144:147], v[48:63]
	s_waitcnt lgkmcnt(5)
	v_mfma_f32_32x32x16_bf16 v[16:31], v[152:155], v[136:139], v[16:31]
	s_nop 3
	v_mfma_f32_32x32x16_bf16 v[0:15], v[152:155], v[144:147], v[0:15]
	s_nop 0
	ds_read_b128 v[86:89], v65 offset:60000
	ds_read_b128 v[180:183], v64 offset:41536
	s_waitcnt lgkmcnt(5)
	v_mfma_f32_32x32x16_bf16 v[32:47], v[156:159], v[164:167], v[32:47]
	s_waitcnt lgkmcnt(2)
	v_mfma_f32_32x32x16_bf16 v[48:63], v[156:159], v[176:179], v[48:63]
	s_nop 0
	ds_read_b128 v[90:93], v64 offset:41568
	s_waitcnt lgkmcnt(1)
	v_mfma_f32_32x32x16_bf16 v[16:31], v[180:183], v[164:167], v[16:31]
	v_mfma_f32_32x32x16_bf16 v[0:15], v[180:183], v[176:179], v[0:15]
	v_mfma_f32_32x32x16_bf16 v[32:47], v[168:171], v[172:175], v[32:47]
	v_mfma_f32_32x32x16_bf16 v[48:63], v[168:171], v[86:89], v[48:63]
	s_nop 5
	s_waitcnt lgkmcnt(0)
	v_mfma_f32_32x32x16_bf16 v[16:31], v[90:93], v[172:175], v[16:31]
	s_nop 1
	s_barrier
	s_waitcnt vmcnt(7)
	ds_write_b128 v122, v[66:69] offset:36864
	s_waitcnt vmcnt(6)
	ds_write_b128 v122, v[70:73] offset:55296
	s_waitcnt vmcnt(5)
	ds_write_b128 v122, v[74:77] offset:41472
	s_waitcnt vmcnt(4)
	ds_write_b128 v122, v[82:85] offset:59904
	s_waitcnt vmcnt(3)
	ds_write_b128 v122, v[94:97] offset:46080
	s_waitcnt vmcnt(2)
	ds_write_b128 v122, v[112:115] offset:64512
	s_waitcnt vmcnt(1)
	ds_write_b128 v122, v[78:81] offset:50688
	s_waitcnt vmcnt(0)
	ds_write_b128 v123, v[116:119] offset:64512
	ds_read_b128 v[124:127], v64
	ds_read_b128 v[128:131], v65 offset:18432
	ds_read_b128 v[132:135], v64 offset:32
	ds_read_b128 v[136:139], v65 offset:18464
	ds_read_b128 v[140:143], v65 offset:23040
	ds_read_b128 v[144:147], v65 offset:23072
	v_mfma_f32_32x32x16_bf16 v[0:15], v[90:93], v[86:89], v[0:15]
	s_nop 5
	s_mov_b64 s[2:3], -1
	s_waitcnt lgkmcnt(4)
	ds_read_b128 v[148:151], v64 offset:4608
	ds_read_b128 v[152:155], v64 offset:4640
	ds_read_b128 v[156:159], v64 offset:64
	v_mfma_f32_32x32x16_bf16 v[32:47], v[124:127], v[128:131], v[32:47]
	s_waitcnt lgkmcnt(4)
	v_mfma_f32_32x32x16_bf16 v[48:63], v[124:127], v[140:143], v[48:63]
	s_nop 1
	s_waitcnt lgkmcnt(2)
	v_mfma_f32_32x32x16_bf16 v[16:31], v[148:151], v[128:131], v[16:31]
	v_mfma_f32_32x32x16_bf16 v[0:15], v[148:151], v[140:143], v[0:15]
	v_mfma_f32_32x32x16_bf16 v[32:47], v[132:135], v[136:139], v[32:47]
	v_mfma_f32_32x32x16_bf16 v[48:63], v[132:135], v[144:147], v[48:63]
	s_waitcnt lgkmcnt(1)
	v_mfma_f32_32x32x16_bf16 v[16:31], v[152:155], v[136:139], v[16:31]
	s_nop 0
	ds_read_b128 v[70:73], v65 offset:18496
	ds_read_b128 v[74:77], v64 offset:96
	ds_read_b128 v[78:81], v65 offset:18528
	v_mfma_f32_32x32x16_bf16 v[0:15], v[152:155], v[144:147], v[0:15]
	ds_read_b128 v[82:85], v65 offset:23104
	ds_read_b128 v[86:89], v65 offset:23136
	s_waitcnt lgkmcnt(4)
	v_mfma_f32_32x32x16_bf16 v[32:47], v[156:159], v[70:73], v[32:47]
	s_waitcnt lgkmcnt(1)
	v_mfma_f32_32x32x16_bf16 v[48:63], v[156:159], v[82:85], v[48:63]
	ds_read_b128 v[66:69], v64 offset:4672
	ds_read_b128 v[90:93], v64 offset:4704
	s_waitcnt lgkmcnt(0)
	s_barrier
; #define MFMA32(a, b, c) __builtin_amdgcn_mfma_f32_32x32x16_bf16((a), (b), (c), 0, 0, 0)
; DI int crow(int i, int hl) { return (i & 3) + 8 * (i >> 2) + 4 * hl; }
; DI void gemm_mainloop(f32x16 (&acc)[2][2], const u16* A, int lda, const u16* Bt, int ldb, int K, unsigned char* smem) {
;     ...
;   for (int kt = 0; kt < nk; kt++) {
;     u16* sA = s0 + (kt & 1) * (256 * 72); u16* sB = sA + 128 * 72;
;     if (kt + 1 < nk) {
;       u16* nA = s0 + ((kt + 1) & 1) * (256 * 72); u16* nB = nA + 128 * 72;
; #pragma unroll
;       for (int i = 0; i < 4; i++) { *(u32x4*)(nA + (lr + 32 * i) * 72 + lc) = ra[i]; *(u32x4*)(nB + (lr + 32 * i) * 72 + lc) = rb[i]; }
;     }
;     if (kt + 2 < nk) { Ab += 128; Bb += 128; }
; #pragma unroll
;     for (int i = 0; i < 4; i++) { ra[i] = *(const u32x4*)(Ab + offA[i]); rb[i] = *(const u32x4*)(Bb + offB[i]); }
; #pragma unroll
;     for (int ks = 0; ks < 4; ks++) {
;       bf16x8 af[2], bfr[2];
; #pragma unroll
;       for (int b = 0; b < 2; b++) {
;         af[b] = *(const bf16x8*)(sA + (wm * 64 + b * 32 + r) * 72 + ks * 16 + hl * 8);
;         bfr[b] = *(const bf16x8*)(sB + (wn * 64 + b * 32 + r) * 72 + ks * 16 + hl * 8);
;       }
; #pragma unroll
;       for (int bm = 0; bm < 2; bm++)
; #pragma unroll
;         for (int bn = 0; bn < 2; bn++) acc[bm][bn] = MFMA32(af[bm], bfr[bn], acc[bm][bn]);
;     }
; DI void phase4(const Params& p, int l, unsigned char* smem) {
;     ...
;       } else {
;         float g = p.in[30][l * 32 + r] * QSCALE_MLA;
; #pragma unroll
;         for (int bm = 0; bm < 2; bm++)
; #pragma unroll
;           for (int bn = 0; bn < 2; bn++)
; #pragma unroll
;             for (int i = 0; i < 16; i++) {
;               const int head = (nt - 4) * 4 + wn * 2 + bn;
;               float a = acc[bm][bn][i];
;               float ss = red32(a * a); float rstd = rsqrtf(ss * (1.f / 32.f) + RMS_EPS);
;               float xn = a * rstd * g; float pt = __shfl_xor(xn, 16);
;               int row = m0 + wm * 64 + bm * 32 + crow(i, hl);
;               const float* rp = rope + pos_of(row) * 32;
;               float cs = rp[r & 15], sn = rp[16 + (r & 15)];
;               float o = (r & 16) ? (pt * sn + xn * cs) : (xn * cs - pt * sn);
;               QF[(size_t)row * 768 + head * 96 + 64 + r] = f2bf(o);
;             }
	ds_read_b128 v[124:127], v64 offset:36864
	ds_read_b128 v[128:131], v65 offset:55296
	ds_read_b128 v[132:135], v64 offset:36896
	ds_read_b128 v[136:139], v65 offset:55328
	ds_read_b128 v[140:143], v65 offset:59904
	ds_read_b128 v[144:147], v65 offset:59936
	ds_read_b128 v[148:151], v64 offset:41472
	ds_read_b128 v[152:155], v64 offset:41504
	ds_read_b128 v[156:159], v64 offset:36928
	v_mfma_f32_32x32x16_bf16 v[16:31], v[66:69], v[70:73], v[16:31]
	v_mfma_f32_32x32x16_bf16 v[0:15], v[66:69], v[82:85], v[0:15]
	v_mfma_f32_32x32x16_bf16 v[32:47], v[74:77], v[78:81], v[32:47]
	v_mfma_f32_32x32x16_bf16 v[48:63], v[74:77], v[86:89], v[48:63]
	v_mfma_f32_32x32x16_bf16 v[16:31], v[90:93], v[78:81], v[16:31]
	s_nop 3
	v_mfma_f32_32x32x16_bf16 v[0:15], v[90:93], v[86:89], v[0:15]
	s_nop 1
	s_waitcnt lgkmcnt(7)
	v_mfma_f32_32x32x16_bf16 v[32:47], v[124:127], v[128:131], v[32:47]
	s_waitcnt lgkmcnt(4)
	v_mfma_f32_32x32x16_bf16 v[48:63], v[124:127], v[140:143], v[48:63]
	s_nop 1
	s_waitcnt lgkmcnt(2)
	v_mfma_f32_32x32x16_bf16 v[16:31], v[148:151], v[128:131], v[16:31]
	v_mfma_f32_32x32x16_bf16 v[0:15], v[148:151], v[140:143], v[0:15]
	v_mfma_f32_32x32x16_bf16 v[32:47], v[132:135], v[136:139], v[32:47]
	v_mfma_f32_32x32x16_bf16 v[48:63], v[132:135], v[144:147], v[48:63]
	s_waitcnt lgkmcnt(1)
	v_mfma_f32_32x32x16_bf16 v[16:31], v[152:155], v[136:139], v[16:31]
	s_nop 0
	ds_read_b128 v[70:73], v65 offset:55360
	ds_read_b128 v[74:77], v64 offset:36960
	ds_read_b128 v[78:81], v65 offset:55392
	v_mfma_f32_32x32x16_bf16 v[0:15], v[152:155], v[144:147], v[0:15]
	ds_read_b128 v[82:85], v65 offset:59968
	ds_read_b128 v[86:89], v65 offset:60000
	s_waitcnt lgkmcnt(4)
	v_mfma_f32_32x32x16_bf16 v[32:47], v[156:159], v[70:73], v[32:47]
	s_waitcnt lgkmcnt(1)
	v_mfma_f32_32x32x16_bf16 v[48:63], v[156:159], v[82:85], v[48:63]
	ds_read_b128 v[66:69], v64 offset:41536
	ds_read_b128 v[90:93], v64 offset:41568
	s_waitcnt lgkmcnt(0)
	s_barrier
	v_mfma_f32_32x32x16_bf16 v[16:31], v[66:69], v[70:73], v[16:31]
	v_mfma_f32_32x32x16_bf16 v[0:15], v[66:69], v[82:85], v[0:15]
	v_mfma_f32_32x32x16_bf16 v[32:47], v[74:77], v[78:81], v[32:47]
	v_mfma_f32_32x32x16_bf16 v[48:63], v[74:77], v[86:89], v[48:63]
	v_mfma_f32_32x32x16_bf16 v[16:31], v[90:93], v[78:81], v[16:31]
	v_mfma_f32_32x32x16_bf16 v[0:15], v[90:93], v[86:89], v[0:15]
	s_cbranch_scc0 .LBB0_715
	v_readlane_b32 s2, v254, 33
	v_readlane_b32 s3, v254, 34
	s_load_dwordx2 s[2:3], s[2:3], 0xf0
	v_lshl_add_u32 v64, s10, 2, v211
	v_mul_i32_i24_e32 v162, 0x60, v64
	v_add_u32_e32 v120, s11, v208
	v_or_b32_e32 v90, v120, v209
	s_waitcnt lgkmcnt(0)
	v_lshl_add_u64 v[64:65], v[106:107], 2, s[2:3]
	global_load_dword v99, v[64:65], off
	s_movk_i32 s2, 0x1fc4
	v_bitop3_b32 v64, v120, s2, v209 bitop3:0xc8
	v_readlane_b32 s2, v254, 41
	v_cmp_gt_i32_e32 vcc, s50, v90
	v_readlane_b32 s3, v254, 42
	v_or_b32_e32 v94, v120, v214
	v_cndmask_b32_e32 v64, v213, v64, vcc
	v_lshl_add_u64 v[66:67], v[162:163], 1, s[2:3]
	v_lshlrev_b32_e32 v162, 7, v64
	v_lshl_add_u64 v[80:81], v[108:109], 0, v[162:163]
	global_load_dword v93, v[80:81], off offset:64
	global_load_dword v92, v[80:81], off
	v_cmp_lt_i32_e32 vcc, v200, v196
	s_movk_i32 s2, 0x1fc5
	v_mov_b32_e32 v69, v163
	v_cndmask_b32_e32 v68, v194, v200, vcc
	v_cmp_lt_i32_e32 vcc, v185, v196
	v_lshlrev_b32_e32 v115, 2, v68
	v_bitop3_b32 v68, v120, s2, v214 bitop3:0xc8
	v_cndmask_b32_e32 v82, v194, v185, vcc
	v_cmp_lt_i32_e32 vcc, v207, v196
	v_lshlrev_b32_e32 v114, 2, v82
	v_pk_mul_f32 v[64:65], v[32:33], v[32:33]
	v_cndmask_b32_e32 v97, v194, v207, vcc
	v_cmp_lt_i32_e32 vcc, v253, v196
	ds_bpermute_b32 v64, v115, v64
	ds_bpermute_b32 v65, v115, v65
	v_cndmask_b32_e32 v98, v194, v253, vcc
	v_cmp_lt_i32_e32 vcc, v204, v196
	v_lshlrev_b32_e32 v118, 2, v97
	v_lshlrev_b32_e32 v117, 2, v98
	v_cndmask_b32_e32 v112, v194, v204, vcc
	v_cmp_gt_i32_e32 vcc, s50, v94
	v_lshlrev_b32_e32 v116, 2, v112
	s_mov_b32 s2, 0x358637bd
	v_cndmask_b32_e32 v68, v215, v68, vcc
	v_lshlrev_b32_e32 v68, 7, v68
	v_lshl_add_u64 v[82:83], v[108:109], 0, v[68:69]
	global_load_dword v95, v[82:83], off
	global_load_dword v96, v[82:83], off offset:64
	s_waitcnt lgkmcnt(0)
	v_pk_fma_f32 v[68:69], v[32:33], v[32:33], v[64:65]
	ds_bpermute_b32 v86, v114, v68
	ds_bpermute_b32 v87, v114, v69
	v_mov_b64_e32 v[64:65], s[2:3]
	v_or_b32_e32 v98, v120, v216
	s_movk_i32 s2, 0x1fc6
	v_bitop3_b32 v97, v120, s2, v216 bitop3:0xc8
	s_waitcnt lgkmcnt(0)
	v_pk_add_f32 v[68:69], v[68:69], v[86:87]
	ds_bpermute_b32 v86, v118, v68
	ds_bpermute_b32 v87, v118, v69
	v_cmp_gt_i32_e32 vcc, s50, v98
	v_mov_b32_e32 v91, v163
	v_mad_i64_i32 v[122:123], s[2:3], v90, s33, v[66:67]
	s_waitcnt lgkmcnt(0)
	v_pk_add_f32 v[68:69], v[68:69], v[86:87]
	ds_bpermute_b32 v86, v117, v68
	ds_bpermute_b32 v87, v117, v69
	v_cndmask_b32_e32 v97, v217, v97, vcc
	v_lshlrev_b32_e32 v90, 7, v97
	s_mov_b32 s12, 0x3d000000
	v_pk_mul_f32 v[88:89], v[34:35], v[34:35]
	s_waitcnt lgkmcnt(0)
	v_pk_add_f32 v[68:69], v[68:69], v[86:87]
	ds_bpermute_b32 v112, v116, v68
	ds_bpermute_b32 v113, v116, v69
	v_lshl_add_u64 v[86:87], v[108:109], 0, v[90:91]
	ds_bpermute_b32 v88, v115, v88
	ds_bpermute_b32 v89, v115, v89
	v_lshlrev_b32_e32 v162, 1, v100
	s_waitcnt lgkmcnt(2)
	v_pk_add_f32 v[68:69], v[68:69], v[112:113]
	s_movk_i32 s2, 0x1fc7
	v_pk_fma_f32 v[90:91], v[68:69], s[12:13], v[64:65] op_sel_hi:[1,0,0]
	v_pk_mul_f32 v[84:85], v[36:37], v[36:37]
	v_mul_f32_e32 v68, 0x4b800000, v90
	v_cmp_gt_f32_e32 vcc, s75, v90
	ds_bpermute_b32 v84, v115, v84
	ds_bpermute_b32 v85, v115, v85
	v_cndmask_b32_e32 v68, v90, v68, vcc
	v_rsq_f32_e32 v112, v68
	v_lshl_add_u64 v[68:69], v[122:123], 0, v[162:163]
	global_load_dword v90, v[86:87], off
	global_load_dword v97, v[86:87], off offset:64
	global_load_dword v122, v[82:83], off offset:64
	global_load_dword v121, v[82:83], off
	global_load_dword v124, v[80:81], off offset:64
	global_load_dword v123, v[80:81], off
	v_mul_f32_e32 v113, 0x45800000, v112
	v_cndmask_b32_e32 v112, v112, v113, vcc
	v_mul_f32_e32 v112, v32, v112
	s_waitcnt vmcnt(10)
; DI int crow(int i, int hl) { return (i & 3) + 8 * (i >> 2) + 4 * hl; }
; DI void phase4(const Params& p, int l, unsigned char* smem) {
;     ...
;       } else {
;         float g = p.in[30][l * 32 + r] * QSCALE_MLA;
; #pragma unroll
;         for (int bm = 0; bm < 2; bm++)
; #pragma unroll
;           for (int bn = 0; bn < 2; bn++)
; #pragma unroll
;             for (int i = 0; i < 16; i++) {
;               const int head = (nt - 4) * 4 + wn * 2 + bn;
;               float a = acc[bm][bn][i];
;               float ss = red32(a * a); float rstd = rsqrtf(ss * (1.f / 32.f) + RMS_EPS);
;               float xn = a * rstd * g; float pt = __shfl_xor(xn, 16);
;               int row = m0 + wm * 64 + bm * 32 + crow(i, hl);
;               const float* rp = rope + pos_of(row) * 32;
;               float cs = rp[r & 15], sn = rp[16 + (r & 15)];
;               float o = (r & 16) ? (pt * sn + xn * cs) : (xn * cs - pt * sn);
;               QF[(size_t)row * 768 + head * 96 + 64 + r] = f2bf(o);
;             }
	v_mul_f32_e32 v119, 0x3e16c740, v99
	v_mul_f32_e32 v99, v119, v112
	ds_bpermute_b32 v112, v116, v99
	v_cmp_gt_f32_e32 vcc, s75, v91
	s_waitcnt lgkmcnt(1)
	v_pk_fma_f32 v[84:85], v[36:37], v[36:37], v[84:85]
	v_pk_mul_f32 v[78:79], v[38:39], v[38:39]
	ds_bpermute_b32 v78, v115, v78
	s_waitcnt vmcnt(9) lgkmcnt(1)
	v_mul_f32_e32 v80, v93, v112
	v_cndmask_b32_e64 v93, v80, -v80, s[6:7]
	v_mul_f32_e32 v80, 0x4b800000, v91
	v_cndmask_b32_e32 v80, v91, v80, vcc
	v_rsq_f32_e32 v91, v80
	v_pk_fma_f32 v[80:81], v[34:35], v[34:35], v[88:89]
	ds_bpermute_b32 v82, v114, v80
	ds_bpermute_b32 v83, v114, v81
	v_mul_f32_e32 v88, 0x45800000, v91
	v_cndmask_b32_e32 v88, v91, v88, vcc
	v_mul_f32_e32 v91, v33, v88
	s_waitcnt vmcnt(8)
	v_fmac_f32_e32 v93, v92, v99
	s_waitcnt lgkmcnt(0)
	v_pk_add_f32 v[80:81], v[80:81], v[82:83]
	ds_bpermute_b32 v82, v118, v80
	ds_bpermute_b32 v83, v118, v81
	v_mul_f32_e32 v91, v119, v91
	v_cvt_pk_bf16_f32 v92, v93, s0
	ds_bpermute_b32 v93, v116, v91
	global_store_short v[68:69], v92, off offset:128
	s_waitcnt lgkmcnt(1)
	v_pk_add_f32 v[80:81], v[80:81], v[82:83]
	ds_bpermute_b32 v82, v117, v80
	ds_bpermute_b32 v83, v117, v81
	v_or_b32_e32 v99, v120, v218
	v_bitop3_b32 v88, v120, s2, v218 bitop3:0xc8
	v_cmp_gt_i32_e32 vcc, s50, v99
	v_mov_b32_e32 v89, v163
	s_waitcnt lgkmcnt(0)
	v_pk_add_f32 v[80:81], v[80:81], v[82:83]
	v_cndmask_b32_e32 v88, v219, v88, vcc
	s_waitcnt vmcnt(7)
	v_mul_f32_e32 v92, v96, v93
	v_cndmask_b32_e64 v92, v92, -v92, s[6:7]
	v_fmac_f32_e32 v92, v95, v91
	v_cvt_pk_bf16_f32 v91, v92, s0
	ds_bpermute_b32 v92, v116, v80
	ds_bpermute_b32 v93, v116, v81
	v_mad_i64_i32 v[82:83], s[2:3], v94, s33, v[66:67]
	v_lshl_add_u64 v[82:83], v[82:83], 0, v[162:163]
	global_store_short v[82:83], v91, off offset:128
	s_waitcnt lgkmcnt(0)
	v_pk_add_f32 v[80:81], v[80:81], v[92:93]
	v_lshlrev_b32_e32 v88, 7, v88
	v_pk_fma_f32 v[92:93], v[80:81], s[12:13], v[64:65] op_sel_hi:[1,0,0]
	v_lshl_add_u64 v[88:89], v[108:109], 0, v[88:89]
	v_mul_f32_e32 v80, 0x4b800000, v92
	v_cmp_gt_f32_e32 vcc, s75, v92
	global_load_dword v112, v[88:89], off offset:64
	v_mov_b32_e32 v95, v163
	v_cndmask_b32_e32 v80, v92, v80, vcc
	v_rsq_f32_e32 v91, v80
	v_mad_i64_i32 v[80:81], s[2:3], v98, s33, v[66:67]
	s_movk_i32 s2, 0x1fcc
	v_mul_f32_e32 v92, 0x45800000, v91
	v_cndmask_b32_e32 v91, v91, v92, vcc
	v_or_b32_e32 v92, v120, v220
	v_bitop3_b32 v94, v120, s2, v220 bitop3:0xc8
	v_cmp_gt_i32_e32 vcc, s50, v92
	v_mul_f32_e32 v91, v34, v91
	v_mul_f32_e32 v91, v119, v91
	v_cndmask_b32_e32 v94, v221, v94, vcc
	v_lshlrev_b32_e32 v94, 7, v94
	v_lshl_add_u64 v[94:95], v[108:109], 0, v[94:95]
	global_load_dword v96, v[94:95], off offset:64
	global_load_dword v98, v[94:95], off
	global_load_dword v113, v[88:89], off
	ds_bpermute_b32 v129, v116, v91
	global_load_dword v126, v[88:89], off offset:64
	global_load_dword v125, v[88:89], off
	global_load_dword v128, v[86:87], off offset:64
	global_load_dword v127, v[86:87], off
	v_cmp_gt_f32_e32 vcc, s75, v93
	ds_bpermute_b32 v87, v114, v85
	v_lshl_add_u64 v[80:81], v[80:81], 0, v[162:163]
	s_waitcnt vmcnt(14) lgkmcnt(1)
	v_mul_f32_e32 v86, v97, v129
	v_cndmask_b32_e64 v88, v86, -v86, s[6:7]
	v_mul_f32_e32 v86, 0x4b800000, v93
	v_cndmask_b32_e32 v86, v93, v86, vcc
	v_rsq_f32_e32 v89, v86
	ds_bpermute_b32 v86, v114, v84
	v_fmac_f32_e32 v88, v90, v91
	v_cvt_pk_bf16_f32 v90, v88, s0
	v_mul_f32_e32 v88, 0x45800000, v89
	v_cndmask_b32_e32 v88, v89, v88, vcc
	s_waitcnt lgkmcnt(0)
	v_pk_add_f32 v[84:85], v[84:85], v[86:87]
	ds_bpermute_b32 v86, v118, v84
	ds_bpermute_b32 v87, v118, v85
	v_mul_f32_e32 v91, v35, v88
	v_mul_f32_e32 v91, v119, v91
	ds_bpermute_b32 v93, v116, v91
	global_store_short v[80:81], v90, off offset:128
	s_waitcnt lgkmcnt(1)
	v_pk_add_f32 v[84:85], v[84:85], v[86:87]
	ds_bpermute_b32 v86, v117, v84
	ds_bpermute_b32 v87, v117, v85
	v_or_b32_e32 v97, v120, v222
	s_movk_i32 s2, 0x1fcd
	v_bitop3_b32 v88, v120, s2, v222 bitop3:0xc8
	v_cmp_gt_i32_e32 vcc, s50, v97
	s_waitcnt lgkmcnt(0)
	v_pk_add_f32 v[84:85], v[84:85], v[86:87]
	v_mad_i64_i32 v[86:87], s[2:3], v99, s33, v[66:67]
	v_cndmask_b32_e32 v88, v223, v88, vcc
	v_or_b32_e32 v99, v120, v224
	v_lshlrev_b32_e32 v88, 7, v88
	v_mov_b32_e32 v89, v163
	v_lshl_add_u64 v[88:89], v[108:109], 0, v[88:89]
	v_lshl_add_u64 v[86:87], v[86:87], 0, v[162:163]
	global_load_dword v133, v[88:89], off offset:64
	ds_bpermute_b32 v79, v115, v79
	v_or_b32_e32 v139, v120, v228
	v_pk_mul_f32 v[76:77], v[40:41], v[40:41]
	ds_bpermute_b32 v76, v115, v76
	ds_bpermute_b32 v77, v115, v77
	s_waitcnt lgkmcnt(2)
	v_pk_fma_f32 v[78:79], v[38:39], v[38:39], v[78:79]
	v_or_b32_e32 v144, v120, v230
	v_pk_mul_f32 v[74:75], v[42:43], v[42:43]
	ds_bpermute_b32 v74, v115, v74
	s_waitcnt lgkmcnt(1)
	v_pk_fma_f32 v[76:77], v[40:41], v[40:41], v[76:77]
	ds_bpermute_b32 v75, v115, v75
	v_pk_mul_f32 v[72:73], v[44:45], v[44:45]
	ds_bpermute_b32 v72, v115, v72
	ds_bpermute_b32 v73, v115, v73
	v_or_b32_e32 v152, v120, v233
	s_waitcnt lgkmcnt(2)
	v_pk_fma_f32 v[74:75], v[42:43], v[42:43], v[74:75]
	v_or_b32_e32 v155, v120, v234
	v_or_b32_e32 v158, v120, v235
	s_waitcnt lgkmcnt(0)
	v_pk_fma_f32 v[72:73], v[44:45], v[44:45], v[72:73]
	v_pk_mul_f32 v[70:71], v[46:47], v[46:47]
	ds_bpermute_b32 v70, v115, v70
	s_waitcnt vmcnt(9)
	v_mul_f32_e32 v90, v112, v93
	v_cndmask_b32_e64 v90, v90, -v90, s[6:7]
	ds_bpermute_b32 v71, v115, v71
	s_waitcnt lgkmcnt(0)
	v_pk_fma_f32 v[70:71], v[46:47], v[46:47], v[70:71]
	s_waitcnt vmcnt(6)
	v_fmac_f32_e32 v90, v113, v91
	v_cvt_pk_bf16_f32 v93, v90, s0
	ds_bpermute_b32 v90, v116, v84
	ds_bpermute_b32 v91, v116, v85
	global_store_short v[86:87], v93, off offset:128
	v_mov_b32_e32 v93, v163
	s_waitcnt lgkmcnt(0)
; DI int crow(int i, int hl) { return (i & 3) + 8 * (i >> 2) + 4 * hl; }
; DI void phase4(const Params& p, int l, unsigned char* smem) {
;     ...
;       } else {
;         float g = p.in[30][l * 32 + r] * QSCALE_MLA;
; #pragma unroll
;         for (int bm = 0; bm < 2; bm++)
; #pragma unroll
;           for (int bn = 0; bn < 2; bn++)
; #pragma unroll
;             for (int i = 0; i < 16; i++) {
;               const int head = (nt - 4) * 4 + wn * 2 + bn;
;               float a = acc[bm][bn][i];
;               float ss = red32(a * a); float rstd = rsqrtf(ss * (1.f / 32.f) + RMS_EPS);
;               float xn = a * rstd * g; float pt = __shfl_xor(xn, 16);
;               int row = m0 + wm * 64 + bm * 32 + crow(i, hl);
;               const float* rp = rope + pos_of(row) * 32;
;               float cs = rp[r & 15], sn = rp[16 + (r & 15)];
;               float o = (r & 16) ? (pt * sn + xn * cs) : (xn * cs - pt * sn);
;               QF[(size_t)row * 768 + head * 96 + 64 + r] = f2bf(o);
;             }
	v_pk_add_f32 v[84:85], v[84:85], v[90:91]
	s_nop 0
	v_pk_fma_f32 v[90:91], v[84:85], s[12:13], v[64:65] op_sel_hi:[1,0,0]
	s_nop 0
	v_mul_f32_e32 v84, 0x4b800000, v90
	v_cmp_gt_f32_e32 vcc, s75, v90
	s_nop 1
	v_cndmask_b32_e32 v84, v90, v84, vcc
	v_rsq_f32_e32 v90, v84
	v_mad_i64_i32 v[84:85], s[2:3], v92, s33, v[66:67]
	s_movk_i32 s2, 0x1fce
	v_mul_f32_e32 v92, 0x45800000, v90
	v_cndmask_b32_e32 v90, v90, v92, vcc
	v_bitop3_b32 v92, v120, s2, v224 bitop3:0xc8
	v_cmp_gt_i32_e32 vcc, s50, v99
	v_mul_f32_e32 v90, v36, v90
	v_mul_f32_e32 v90, v119, v90
	v_cndmask_b32_e32 v92, v225, v92, vcc
	v_lshlrev_b32_e32 v92, 7, v92
	v_lshl_add_u64 v[92:93], v[108:109], 0, v[92:93]
	global_load_dword v112, v[92:93], off offset:64
	global_load_dword v113, v[92:93], off
	global_load_dword v134, v[88:89], off
	ds_bpermute_b32 v135, v116, v90
	global_load_dword v130, v[88:89], off offset:64
	global_load_dword v129, v[88:89], off
	global_load_dword v132, v[94:95], off offset:64
	global_load_dword v131, v[94:95], off
	v_cmp_gt_f32_e32 vcc, s75, v91
	ds_bpermute_b32 v89, v114, v79
	v_lshl_add_u64 v[84:85], v[84:85], 0, v[162:163]
	s_waitcnt lgkmcnt(1)
	v_mul_f32_e32 v88, v96, v135
	v_cndmask_b32_e64 v94, v88, -v88, s[6:7]
	v_mul_f32_e32 v88, 0x4b800000, v91
	v_cndmask_b32_e32 v88, v91, v88, vcc
	v_fmac_f32_e32 v94, v98, v90
	v_rsq_f32_e32 v90, v88
	ds_bpermute_b32 v88, v114, v78
	v_cvt_pk_bf16_f32 v94, v94, s0
	global_store_short v[84:85], v94, off offset:128
	v_mul_f32_e32 v91, 0x45800000, v90
	v_cndmask_b32_e32 v90, v90, v91, vcc
	s_waitcnt lgkmcnt(0)
	v_pk_add_f32 v[78:79], v[78:79], v[88:89]
	ds_bpermute_b32 v88, v118, v78
	ds_bpermute_b32 v89, v118, v79
	v_mul_f32_e32 v95, v37, v90
	v_mul_f32_e32 v95, v119, v95
	ds_bpermute_b32 v96, v116, v95
	v_or_b32_e32 v98, v120, v226
	s_waitcnt lgkmcnt(1)
	v_pk_add_f32 v[78:79], v[78:79], v[88:89]
	ds_bpermute_b32 v88, v117, v78
	ds_bpermute_b32 v89, v117, v79
	s_waitcnt vmcnt(9) lgkmcnt(2)
	v_mul_f32_e32 v94, v133, v96
	v_cndmask_b32_e64 v94, v94, -v94, s[6:7]
	s_movk_i32 s2, 0x1fcf
	v_bitop3_b32 v90, v120, s2, v226 bitop3:0xc8
	s_waitcnt lgkmcnt(0)
	v_pk_add_f32 v[78:79], v[78:79], v[88:89]
	v_cmp_gt_i32_e32 vcc, s50, v98
	v_mad_i64_i32 v[88:89], s[2:3], v97, s33, v[66:67]
	s_nop 0
	v_cndmask_b32_e32 v90, v227, v90, vcc
	v_lshl_add_u64 v[88:89], v[88:89], 0, v[162:163]
	v_lshlrev_b32_e32 v90, 7, v90
	v_mov_b32_e32 v91, v163
	v_lshl_add_u64 v[90:91], v[108:109], 0, v[90:91]
	global_load_dword v137, v[90:91], off offset:64
	v_mov_b32_e32 v97, v163
	s_waitcnt vmcnt(6)
	v_fmac_f32_e32 v94, v134, v95
	v_cvt_pk_bf16_f32 v96, v94, s0
	ds_bpermute_b32 v94, v116, v78
	ds_bpermute_b32 v95, v116, v79
	global_store_short v[88:89], v96, off offset:128
	s_waitcnt lgkmcnt(0)
	v_pk_add_f32 v[78:79], v[78:79], v[94:95]
	s_nop 0
	v_pk_fma_f32 v[94:95], v[78:79], s[12:13], v[64:65] op_sel_hi:[1,0,0]
	s_nop 0
	v_mul_f32_e32 v78, 0x4b800000, v94
	v_cmp_gt_f32_e32 vcc, s75, v94
	s_nop 1
	v_cndmask_b32_e32 v78, v94, v78, vcc
	v_rsq_f32_e32 v94, v78
	v_mad_i64_i32 v[78:79], s[2:3], v99, s33, v[66:67]
	s_movk_i32 s2, 0x1fd4
	v_mul_f32_e32 v96, 0x45800000, v94
	v_cndmask_b32_e32 v94, v94, v96, vcc
	v_bitop3_b32 v96, v120, s2, v228 bitop3:0xc8
	v_cmp_gt_i32_e32 vcc, s50, v139
	v_mul_f32_e32 v94, v38, v94
	v_mul_f32_e32 v94, v119, v94
	v_cndmask_b32_e32 v96, v213, v96, vcc
	v_lshlrev_b32_e32 v96, 7, v96
	v_lshl_add_u64 v[96:97], v[108:109], 0, v[96:97]
	global_load_dword v141, v[96:97], off offset:64
	global_load_dword v142, v[96:97], off
	global_load_dword v138, v[90:91], off
	ds_bpermute_b32 v99, v116, v94
	global_load_dword v134, v[90:91], off offset:64
	global_load_dword v133, v[90:91], off
	global_load_dword v136, v[92:93], off offset:64
	global_load_dword v135, v[92:93], off
	v_cmp_gt_f32_e32 vcc, s75, v95
	ds_bpermute_b32 v91, v114, v77
	s_movk_i32 s2, 0x1fd5
	s_waitcnt lgkmcnt(1)
	v_mul_f32_e32 v90, v112, v99
	v_cndmask_b32_e64 v92, v90, -v90, s[6:7]
	v_mul_f32_e32 v90, 0x4b800000, v95
	v_cndmask_b32_e32 v90, v95, v90, vcc
	v_rsq_f32_e32 v93, v90
	ds_bpermute_b32 v90, v114, v76
	v_fmac_f32_e32 v92, v113, v94
	v_cvt_pk_bf16_f32 v94, v92, s0
	v_mul_f32_e32 v92, 0x45800000, v93
	v_cndmask_b32_e32 v92, v93, v92, vcc
	v_or_b32_e32 v112, v120, v229
	v_mul_f32_e32 v95, v39, v92
	v_bitop3_b32 v92, v120, s2, v229 bitop3:0xc8
	v_cmp_gt_i32_e32 vcc, s50, v112
	s_waitcnt lgkmcnt(0)
	v_pk_add_f32 v[76:77], v[76:77], v[90:91]
	ds_bpermute_b32 v90, v118, v76
	v_cndmask_b32_e32 v92, v215, v92, vcc
	ds_bpermute_b32 v91, v118, v77
	v_lshlrev_b32_e32 v92, 7, v92
	v_mov_b32_e32 v93, v163
	v_lshl_add_u64 v[92:93], v[108:109], 0, v[92:93]
	global_load_dword v113, v[92:93], off offset:64
	global_load_dword v143, v[92:93], off
	v_mul_f32_e32 v95, v119, v95
	ds_bpermute_b32 v99, v116, v95
	s_waitcnt lgkmcnt(1)
	v_pk_add_f32 v[76:77], v[76:77], v[90:91]
	ds_bpermute_b32 v90, v117, v76
	ds_bpermute_b32 v91, v117, v77
	v_lshl_add_u64 v[78:79], v[78:79], 0, v[162:163]
	global_store_short v[78:79], v94, off offset:128
	s_waitcnt vmcnt(11) lgkmcnt(2)
	v_mul_f32_e32 v94, v137, v99
	v_cndmask_b32_e64 v94, v94, -v94, s[6:7]
	s_waitcnt lgkmcnt(0)
	v_pk_add_f32 v[90:91], v[76:77], v[90:91]
	v_mad_i64_i32 v[76:77], s[2:3], v98, s33, v[66:67]
	s_movk_i32 s2, 0x1fd6
	v_cmp_gt_i32_e32 vcc, s50, v144
	v_lshl_add_u64 v[76:77], v[76:77], 0, v[162:163]
	s_waitcnt vmcnt(7)
	v_fmac_f32_e32 v94, v138, v95
	v_cvt_pk_bf16_f32 v99, v94, s0
	ds_bpermute_b32 v94, v116, v90
	ds_bpermute_b32 v95, v116, v91
	global_store_short v[76:77], v99, off offset:128
	s_waitcnt lgkmcnt(0)
; DI int crow(int i, int hl) { return (i & 3) + 8 * (i >> 2) + 4 * hl; }
; DI void phase4(const Params& p, int l, unsigned char* smem) {
;     ...
;       } else {
;         float g = p.in[30][l * 32 + r] * QSCALE_MLA;
; #pragma unroll
;         for (int bm = 0; bm < 2; bm++)
; #pragma unroll
;           for (int bn = 0; bn < 2; bn++)
; #pragma unroll
;             for (int i = 0; i < 16; i++) {
;               const int head = (nt - 4) * 4 + wn * 2 + bn;
;               float a = acc[bm][bn][i];
;               float ss = red32(a * a); float rstd = rsqrtf(ss * (1.f / 32.f) + RMS_EPS);
;               float xn = a * rstd * g; float pt = __shfl_xor(xn, 16);
;               int row = m0 + wm * 64 + bm * 32 + crow(i, hl);
;               const float* rp = rope + pos_of(row) * 32;
;               float cs = rp[r & 15], sn = rp[16 + (r & 15)];
;               float o = (r & 16) ? (pt * sn + xn * cs) : (xn * cs - pt * sn);
;               QF[(size_t)row * 768 + head * 96 + 64 + r] = f2bf(o);
;             }
	v_pk_add_f32 v[90:91], v[90:91], v[94:95]
	s_nop 0
	v_pk_fma_f32 v[94:95], v[90:91], s[12:13], v[64:65] op_sel_hi:[1,0,0]
	v_bitop3_b32 v90, v120, s2, v230 bitop3:0xc8
	v_cndmask_b32_e32 v90, v217, v90, vcc
	v_mul_f32_e32 v137, 0x4b800000, v94
	v_lshlrev_b32_e32 v90, 7, v90
	v_mov_b32_e32 v91, v163
	v_cmp_gt_f32_e32 vcc, s75, v94
	v_lshl_add_u64 v[98:99], v[108:109], 0, v[90:91]
	global_load_dword v145, v[98:99], off offset:64
	global_load_dword v146, v[98:99], off
	v_cndmask_b32_e32 v90, v94, v137, vcc
	v_rsq_f32_e32 v94, v90
	v_mad_i64_i32 v[90:91], s[2:3], v139, s33, v[66:67]
	s_movk_i32 s2, 0x1fd7
	v_mul_f32_e32 v137, 0x45800000, v94
	v_cndmask_b32_e32 v94, v94, v137, vcc
	v_mul_f32_e32 v94, v40, v94
	v_mul_f32_e32 v94, v119, v94
	ds_bpermute_b32 v147, v116, v94
	global_load_dword v138, v[92:93], off offset:64
	global_load_dword v137, v[92:93], off
	global_load_dword v140, v[96:97], off offset:64
	global_load_dword v139, v[96:97], off
	v_cmp_gt_f32_e32 vcc, s75, v95
	ds_bpermute_b32 v93, v114, v75
	v_lshl_add_u64 v[90:91], v[90:91], 0, v[162:163]
	s_waitcnt lgkmcnt(1)
	v_mul_f32_e32 v92, v141, v147
	v_cndmask_b32_e64 v96, v92, -v92, s[6:7]
	v_mul_f32_e32 v92, 0x4b800000, v95
	v_cndmask_b32_e32 v92, v95, v92, vcc
	v_fmac_f32_e32 v96, v142, v94
	v_rsq_f32_e32 v94, v92
	v_or_b32_e32 v147, v120, v231
	ds_bpermute_b32 v92, v114, v74
	v_cvt_pk_bf16_f32 v96, v96, s0
	v_mul_f32_e32 v95, 0x45800000, v94
	v_cndmask_b32_e32 v94, v94, v95, vcc
	v_mul_f32_e32 v97, v41, v94
	v_bitop3_b32 v94, v120, s2, v231 bitop3:0xc8
	v_cmp_gt_i32_e32 vcc, s50, v147
	v_mov_b32_e32 v95, v163
	s_waitcnt lgkmcnt(0)
	v_pk_add_f32 v[74:75], v[74:75], v[92:93]
	v_cndmask_b32_e32 v94, v219, v94, vcc
	v_lshlrev_b32_e32 v94, 7, v94
	v_lshl_add_u64 v[94:95], v[108:109], 0, v[94:95]
	global_load_dword v148, v[94:95], off offset:64
	global_load_dword v149, v[94:95], off
	ds_bpermute_b32 v92, v118, v74
	ds_bpermute_b32 v93, v118, v75
	v_mul_f32_e32 v97, v119, v97
	ds_bpermute_b32 v141, v116, v97
	global_store_short v[90:91], v96, off offset:128
	s_waitcnt lgkmcnt(1)
	v_pk_add_f32 v[74:75], v[74:75], v[92:93]
	ds_bpermute_b32 v92, v117, v74
	ds_bpermute_b32 v93, v117, v75
	s_waitcnt vmcnt(12) lgkmcnt(2)
	v_mul_f32_e32 v96, v113, v141
	v_cndmask_b32_e64 v96, v96, -v96, s[6:7]
	s_waitcnt vmcnt(11)
	v_fmac_f32_e32 v96, v143, v97
	v_cvt_pk_bf16_f32 v113, v96, s0
	s_waitcnt lgkmcnt(0)
	v_pk_add_f32 v[74:75], v[74:75], v[92:93]
	ds_bpermute_b32 v96, v116, v74
	ds_bpermute_b32 v97, v116, v75
	v_mad_i64_i32 v[92:93], s[2:3], v112, s33, v[66:67]
	v_lshl_add_u64 v[92:93], v[92:93], 0, v[162:163]
	global_store_short v[92:93], v113, off offset:128
	s_waitcnt lgkmcnt(0)
	v_pk_add_f32 v[74:75], v[74:75], v[96:97]
	s_nop 0
	v_pk_fma_f32 v[96:97], v[74:75], s[12:13], v[64:65] op_sel_hi:[1,0,0]
	s_nop 0
	v_mul_f32_e32 v74, 0x4b800000, v96
	v_cmp_gt_f32_e32 vcc, s75, v96
	s_nop 1
	v_cndmask_b32_e32 v74, v96, v74, vcc
	v_rsq_f32_e32 v96, v74
	v_mad_i64_i32 v[74:75], s[2:3], v144, s33, v[66:67]
	global_load_dword v142, v[94:95], off offset:64
	global_load_dword v141, v[94:95], off
	global_load_dword v144, v[98:99], off offset:64
	global_load_dword v143, v[98:99], off
	v_mul_f32_e32 v112, 0x45800000, v96
	v_cndmask_b32_e32 v96, v96, v112, vcc
	v_mul_f32_e32 v96, v42, v96
	v_mul_f32_e32 v96, v119, v96
	ds_bpermute_b32 v112, v116, v96
	s_movk_i32 s2, 0x1fdc
	v_mov_b32_e32 v95, v163
	v_lshl_add_u64 v[74:75], v[74:75], 0, v[162:163]
	s_waitcnt vmcnt(13) lgkmcnt(0)
	v_mul_f32_e32 v94, v145, v112
	v_or_b32_e32 v145, v120, v232
	v_cndmask_b32_e64 v112, v94, -v94, s[6:7]
	v_bitop3_b32 v94, v120, s2, v232 bitop3:0xc8
	v_cmp_gt_i32_e32 vcc, s50, v145
	s_waitcnt vmcnt(12)
	v_fmac_f32_e32 v112, v146, v96
	v_cvt_pk_bf16_f32 v112, v112, s0
	v_cndmask_b32_e32 v94, v221, v94, vcc
	v_lshlrev_b32_e32 v94, 7, v94
	v_lshl_add_u64 v[98:99], v[108:109], 0, v[94:95]
	v_mul_f32_e32 v94, 0x4b800000, v97
	v_cmp_gt_f32_e32 vcc, s75, v97
	ds_bpermute_b32 v95, v114, v73
	global_store_short v[74:75], v112, off offset:128
	v_cndmask_b32_e32 v94, v97, v94, vcc
	v_rsq_f32_e32 v96, v94
	ds_bpermute_b32 v94, v114, v72
	s_movk_i32 s2, 0x1fdd
	global_load_dword v150, v[98:99], off offset:64
	v_mul_f32_e32 v97, 0x45800000, v96
	v_cndmask_b32_e32 v96, v96, v97, vcc
	s_waitcnt lgkmcnt(0)
	v_pk_add_f32 v[72:73], v[72:73], v[94:95]
	ds_bpermute_b32 v94, v118, v72
	ds_bpermute_b32 v95, v118, v73
	v_mul_f32_e32 v113, v43, v96
	v_mul_f32_e32 v113, v119, v113
	ds_bpermute_b32 v146, v116, v113
	v_bitop3_b32 v96, v120, s2, v233 bitop3:0xc8
	s_waitcnt lgkmcnt(1)
	v_pk_add_f32 v[72:73], v[72:73], v[94:95]
	ds_bpermute_b32 v94, v117, v72
	ds_bpermute_b32 v95, v117, v73
	v_cmp_gt_i32_e32 vcc, s50, v152
	v_mov_b32_e32 v97, v163
	s_waitcnt vmcnt(9) lgkmcnt(2)
	v_mul_f32_e32 v112, v148, v146
	v_cndmask_b32_e64 v112, v112, -v112, s[6:7]
	s_waitcnt vmcnt(8)
	v_fmac_f32_e32 v112, v149, v113
	s_waitcnt lgkmcnt(0)
	v_pk_add_f32 v[94:95], v[72:73], v[94:95]
	v_cvt_pk_bf16_f32 v146, v112, s0
	ds_bpermute_b32 v112, v116, v94
	ds_bpermute_b32 v113, v116, v95
	v_mad_i64_i32 v[72:73], s[2:3], v147, s33, v[66:67]
	s_movk_i32 s2, 0x1fde
	v_cndmask_b32_e32 v96, v223, v96, vcc
	s_waitcnt lgkmcnt(0)
; DI int crow(int i, int hl) { return (i & 3) + 8 * (i >> 2) + 4 * hl; }
; DI void phase4(const Params& p, int l, unsigned char* smem) {
;     ...
;       } else {
;         float g = p.in[30][l * 32 + r] * QSCALE_MLA;
; #pragma unroll
;         for (int bm = 0; bm < 2; bm++)
; #pragma unroll
;           for (int bn = 0; bn < 2; bn++)
; #pragma unroll
;             for (int i = 0; i < 16; i++) {
;               const int head = (nt - 4) * 4 + wn * 2 + bn;
;               float a = acc[bm][bn][i];
;               float ss = red32(a * a); float rstd = rsqrtf(ss * (1.f / 32.f) + RMS_EPS);
;               float xn = a * rstd * g; float pt = __shfl_xor(xn, 16);
;               int row = m0 + wm * 64 + bm * 32 + crow(i, hl);
;               const float* rp = rope + pos_of(row) * 32;
;               float cs = rp[r & 15], sn = rp[16 + (r & 15)];
;               float o = (r & 16) ? (pt * sn + xn * cs) : (xn * cs - pt * sn);
;               QF[(size_t)row * 768 + head * 96 + 64 + r] = f2bf(o);
;             }
	v_pk_add_f32 v[94:95], v[94:95], v[112:113]
	v_cmp_gt_i32_e32 vcc, s50, v155
	v_pk_fma_f32 v[112:113], v[94:95], s[12:13], v[64:65] op_sel_hi:[1,0,0]
	v_bitop3_b32 v94, v120, s2, v234 bitop3:0xc8
	v_cndmask_b32_e32 v94, v225, v94, vcc
	v_lshl_add_u64 v[72:73], v[72:73], 0, v[162:163]
	v_mul_f32_e32 v148, 0x4b800000, v112
	v_lshlrev_b32_e32 v94, 7, v94
	v_mov_b32_e32 v95, v163
	v_cmp_gt_f32_e32 vcc, s75, v112
	global_store_short v[72:73], v146, off offset:128
	v_lshl_add_u64 v[146:147], v[108:109], 0, v[94:95]
	v_cndmask_b32_e32 v94, v112, v148, vcc
	v_rsq_f32_e32 v112, v94
	v_mad_i64_i32 v[94:95], s[2:3], v145, s33, v[66:67]
	global_load_dword v156, v[146:147], off offset:64
	v_mul_f32_e32 v145, 0x45800000, v112
	v_cndmask_b32_e32 v112, v112, v145, vcc
	global_load_dword v145, v[146:147], off
	global_load_dword v151, v[98:99], off
	v_lshlrev_b32_e32 v96, 7, v96
	v_lshl_add_u64 v[96:97], v[108:109], 0, v[96:97]
	global_load_dword v153, v[96:97], off offset:64
	global_load_dword v154, v[96:97], off
	s_movk_i32 s2, 0x1fdf
	v_bitop3_b32 v148, v120, s2, v235 bitop3:0xc8
	v_cmp_gt_i32_e32 vcc, s50, v158
	v_mov_b32_e32 v149, v163
	v_mul_f32_e32 v112, v44, v112
	v_cndmask_b32_e32 v148, v227, v148, vcc
	v_lshlrev_b32_e32 v148, 7, v148
	v_lshl_add_u64 v[148:149], v[108:109], 0, v[148:149]
	global_load_dword v159, v[148:149], off
	global_load_dword v164, v[148:149], off offset:64
	global_load_dword v165, v[96:97], off offset:64
	global_load_dword v166, v[96:97], off
	global_load_dword v167, v[98:99], off offset:64
	global_load_dword v168, v[98:99], off
	v_mul_f32_e32 v112, v119, v112
	ds_bpermute_b32 v157, v116, v112
	v_cmp_gt_f32_e32 vcc, s75, v113
	ds_bpermute_b32 v97, v114, v71
	v_lshl_add_u64 v[94:95], v[94:95], 0, v[162:163]
	s_waitcnt vmcnt(12) lgkmcnt(1)
	v_mul_f32_e32 v96, v150, v157
	v_cndmask_b32_e64 v98, v96, -v96, s[6:7]
	v_mul_f32_e32 v96, 0x4b800000, v113
	v_cndmask_b32_e32 v96, v113, v96, vcc
	v_rsq_f32_e32 v99, v96
	ds_bpermute_b32 v96, v114, v70
	s_waitcnt lgkmcnt(0)
	v_pk_add_f32 v[70:71], v[70:71], v[96:97]
	ds_bpermute_b32 v96, v118, v70
	ds_bpermute_b32 v97, v118, v71
	s_waitcnt lgkmcnt(0)
	v_pk_add_f32 v[70:71], v[70:71], v[96:97]
	ds_bpermute_b32 v96, v117, v70
	ds_bpermute_b32 v97, v117, v71
	s_waitcnt lgkmcnt(0)
	v_pk_add_f32 v[70:71], v[70:71], v[96:97]
	v_mad_i64_i32 v[96:97], s[2:3], v152, s33, v[66:67]
	v_lshl_add_u64 v[96:97], v[96:97], 0, v[162:163]
	s_waitcnt vmcnt(8)
	v_fmac_f32_e32 v98, v151, v112
	v_mul_f32_e32 v112, 0x45800000, v99
	v_cndmask_b32_e32 v99, v99, v112, vcc
	v_mul_f32_e32 v99, v45, v99
	v_mul_f32_e32 v99, v119, v99
	ds_bpermute_b32 v112, v116, v99
	v_cvt_pk_bf16_f32 v98, v98, s0
	global_store_short v[94:95], v98, off offset:128
	v_pk_mul_f32 v[150:151], v[60:61], v[60:61]
	s_waitcnt vmcnt(8) lgkmcnt(0)
	v_mul_f32_e32 v98, v153, v112
	v_cndmask_b32_e64 v98, v98, -v98, s[6:7]
	s_waitcnt vmcnt(7)
	v_fmac_f32_e32 v98, v154, v99
	v_cvt_pk_bf16_f32 v112, v98, s0
	ds_bpermute_b32 v98, v116, v70
	ds_bpermute_b32 v99, v116, v71
	global_store_short v[96:97], v112, off offset:128
	global_load_dword v169, v[148:149], off offset:64
	global_load_dword v170, v[148:149], off
	global_load_dword v171, v[146:147], off offset:64
	global_load_dword v172, v[146:147], off
	v_pk_mul_f32 v[152:153], v[58:59], v[58:59]
	s_waitcnt lgkmcnt(0)
	v_pk_add_f32 v[70:71], v[70:71], v[98:99]
	s_nop 0
	v_pk_fma_f32 v[98:99], v[70:71], s[12:13], v[64:65] op_sel_hi:[1,0,0]
	s_nop 0
	v_mul_f32_e32 v70, 0x4b800000, v98
	v_cmp_gt_f32_e32 vcc, s75, v98
	s_nop 1
	v_cndmask_b32_e32 v70, v98, v70, vcc
	v_rsq_f32_e32 v98, v70
	v_mad_i64_i32 v[70:71], s[2:3], v155, s33, v[66:67]
	v_lshl_add_u64 v[70:71], v[70:71], 0, v[162:163]
	v_mul_f32_e32 v112, 0x45800000, v98
	v_cndmask_b32_e32 v98, v98, v112, vcc
	v_mul_f32_e32 v98, v46, v98
	v_mul_f32_e32 v112, v119, v98
	ds_bpermute_b32 v98, v116, v112
	v_cmp_gt_f32_e32 vcc, s75, v99
	v_pk_mul_f32 v[154:155], v[54:55], v[54:55]
	s_waitcnt lgkmcnt(0)
	v_mul_f32_e32 v113, v156, v98
	v_mul_f32_e32 v98, 0x4b800000, v99
	v_cndmask_b32_e32 v98, v99, v98, vcc
	v_rsq_f32_e32 v146, v98
	v_pk_mul_f32 v[98:99], v[48:49], v[48:49]
	ds_bpermute_b32 v98, v115, v98
	ds_bpermute_b32 v99, v115, v99
	v_cndmask_b32_e64 v113, v113, -v113, s[6:7]
	v_fmac_f32_e32 v113, v145, v112
	v_cvt_pk_bf16_f32 v145, v113, s0
	v_mul_f32_e32 v147, 0x45800000, v146
	s_waitcnt lgkmcnt(0)
	v_pk_fma_f32 v[98:99], v[48:49], v[48:49], v[98:99]
	ds_bpermute_b32 v112, v114, v98
	ds_bpermute_b32 v113, v114, v99
	v_cndmask_b32_e32 v146, v146, v147, vcc
	v_mul_f32_e32 v146, v47, v146
	v_mul_f32_e32 v146, v119, v146
	ds_bpermute_b32 v147, v116, v146
	s_waitcnt lgkmcnt(1)
	v_pk_add_f32 v[98:99], v[98:99], v[112:113]
	ds_bpermute_b32 v112, v118, v98
	ds_bpermute_b32 v113, v118, v99
	global_store_short v[70:71], v145, off offset:128
	s_waitcnt vmcnt(11) lgkmcnt(2)
	v_mul_f32_e32 v145, v164, v147
	v_cndmask_b32_e64 v145, v145, -v145, s[6:7]
	v_fmac_f32_e32 v145, v159, v146
	s_waitcnt lgkmcnt(0)
	v_pk_add_f32 v[112:113], v[98:99], v[112:113]
	ds_bpermute_b32 v146, v117, v112
	ds_bpermute_b32 v147, v117, v113
	v_pk_mul_f32 v[156:157], v[50:51], v[50:51]
	v_mad_i64_i32 v[98:99], s[2:3], v158, s33, v[66:67]
	ds_bpermute_b32 v156, v115, v156
	s_waitcnt lgkmcnt(1)
	v_pk_add_f32 v[146:147], v[112:113], v[146:147]
	ds_bpermute_b32 v148, v116, v146
	ds_bpermute_b32 v149, v116, v147
	ds_bpermute_b32 v157, v115, v157
	v_cvt_pk_bf16_f32 v145, v145, s0
	v_lshl_add_u64 v[98:99], v[98:99], 0, v[162:163]
	global_store_short v[98:99], v145, off offset:128
	s_waitcnt lgkmcnt(1)
	v_pk_add_f32 v[146:147], v[146:147], v[148:149]
	s_waitcnt lgkmcnt(0)
; DI int crow(int i, int hl) { return (i & 3) + 8 * (i >> 2) + 4 * hl; }
; DI void phase4(const Params& p, int l, unsigned char* smem) {
;     ...
;       } else {
;         float g = p.in[30][l * 32 + r] * QSCALE_MLA;
; #pragma unroll
;         for (int bm = 0; bm < 2; bm++)
; #pragma unroll
;           for (int bn = 0; bn < 2; bn++)
; #pragma unroll
;             for (int i = 0; i < 16; i++) {
;               const int head = (nt - 4) * 4 + wn * 2 + bn;
;               float a = acc[bm][bn][i];
;               float ss = red32(a * a); float rstd = rsqrtf(ss * (1.f / 32.f) + RMS_EPS);
;               float xn = a * rstd * g; float pt = __shfl_xor(xn, 16);
;               int row = m0 + wm * 64 + bm * 32 + crow(i, hl);
;               const float* rp = rope + pos_of(row) * 32;
;               float cs = rp[r & 15], sn = rp[16 + (r & 15)];
;               float o = (r & 16) ? (pt * sn + xn * cs) : (xn * cs - pt * sn);
;               QF[(size_t)row * 768 + head * 96 + 64 + r] = f2bf(o);
;             }
	v_pk_fma_f32 v[156:157], v[50:51], v[50:51], v[156:157]
	v_pk_fma_f32 v[146:147], v[146:147], s[12:13], v[64:65] op_sel_hi:[1,0,0]
	ds_bpermute_b32 v158, v114, v156
	v_mul_f32_e32 v145, 0x4b800000, v146
	v_cmp_gt_f32_e32 vcc, s75, v146
	ds_bpermute_b32 v159, v114, v157
	v_pk_mul_f32 v[148:149], v[56:57], v[56:57]
	v_cndmask_b32_e32 v145, v146, v145, vcc
	v_rsq_f32_e32 v145, v145
	v_pk_mul_f32 v[112:113], v[62:63], v[62:63]
	s_movk_i32 s2, 0x1fe4
	v_mul_f32_e32 v146, 0x45800000, v145
	v_cndmask_b32_e32 v145, v145, v146, vcc
	v_mul_f32_e32 v146, 0x4b800000, v147
	v_cmp_gt_f32_e32 vcc, s75, v147
	v_mul_f32_e32 v145, v48, v145
	v_mul_f32_e32 v145, v119, v145
	v_cndmask_b32_e32 v146, v147, v146, vcc
	v_rsq_f32_e32 v173, v146
	s_waitcnt lgkmcnt(0)
	v_pk_add_f32 v[146:147], v[156:157], v[158:159]
	ds_bpermute_b32 v156, v118, v146
	ds_bpermute_b32 v157, v118, v147
	ds_bpermute_b32 v164, v116, v145
	v_pk_mul_f32 v[158:159], v[52:53], v[52:53]
	s_waitcnt lgkmcnt(1)
	v_pk_add_f32 v[146:147], v[146:147], v[156:157]
	ds_bpermute_b32 v156, v117, v146
	ds_bpermute_b32 v157, v117, v147
	s_waitcnt lgkmcnt(2)
	v_mul_f32_e32 v124, v124, v164
	v_mul_f32_e32 v164, 0x45800000, v173
	v_cndmask_b32_e32 v164, v173, v164, vcc
	v_mul_f32_e32 v164, v49, v164
	v_mul_f32_e32 v164, v119, v164
	s_waitcnt lgkmcnt(0)
	v_pk_add_f32 v[146:147], v[146:147], v[156:157]
	ds_bpermute_b32 v173, v116, v164
	ds_bpermute_b32 v156, v116, v146
	ds_bpermute_b32 v157, v116, v147
	v_cndmask_b32_e64 v124, v124, -v124, s[6:7]
	v_fmac_f32_e32 v124, v123, v145
	v_cvt_pk_bf16_f32 v123, v124, s0
	global_store_short v[68:69], v123, off offset:320
	s_waitcnt lgkmcnt(2)
	v_mul_f32_e32 v122, v122, v173
	s_waitcnt lgkmcnt(0)
	v_pk_add_f32 v[68:69], v[146:147], v[156:157]
	v_cndmask_b32_e64 v122, v122, -v122, s[6:7]
	v_pk_fma_f32 v[68:69], v[68:69], s[12:13], v[64:65] op_sel_hi:[1,0,0]
	v_fmac_f32_e32 v122, v121, v164
	v_mul_f32_e32 v123, 0x4b800000, v68
	v_cmp_gt_f32_e32 vcc, s75, v68
	v_cvt_pk_bf16_f32 v121, v122, s0
	ds_bpermute_b32 v122, v115, v158
	v_cndmask_b32_e32 v68, v68, v123, vcc
	ds_bpermute_b32 v123, v115, v159
	v_rsq_f32_e32 v68, v68
	global_store_short v[82:83], v121, off offset:320
	s_waitcnt lgkmcnt(0)
	v_pk_fma_f32 v[122:123], v[52:53], v[52:53], v[122:123]
	v_mul_f32_e32 v124, 0x45800000, v68
	ds_bpermute_b32 v146, v114, v122
	ds_bpermute_b32 v147, v114, v123
	v_cndmask_b32_e32 v68, v68, v124, vcc
	v_mul_f32_e32 v68, v50, v68
	v_mul_f32_e32 v124, v119, v68
	v_mul_f32_e32 v68, 0x4b800000, v69
	v_cmp_gt_f32_e32 vcc, s75, v69
	ds_bpermute_b32 v145, v116, v124
	s_waitcnt lgkmcnt(0)
	v_mul_f32_e32 v82, v128, v145
	v_cndmask_b32_e32 v68, v69, v68, vcc
	v_rsq_f32_e32 v156, v68
	v_pk_add_f32 v[68:69], v[122:123], v[146:147]
	ds_bpermute_b32 v122, v118, v68
	ds_bpermute_b32 v123, v118, v69
	v_cndmask_b32_e64 v121, v82, -v82, s[6:7]
	v_mul_f32_e32 v128, 0x45800000, v156
	v_fmac_f32_e32 v121, v127, v124
	v_cvt_pk_bf16_f32 v121, v121, s0
	s_waitcnt lgkmcnt(0)
	v_pk_add_f32 v[68:69], v[68:69], v[122:123]
	ds_bpermute_b32 v82, v117, v68
	ds_bpermute_b32 v83, v117, v69
	v_cndmask_b32_e32 v122, v156, v128, vcc
	v_mul_f32_e32 v122, v51, v122
	v_mul_f32_e32 v122, v119, v122
	ds_bpermute_b32 v123, v116, v122
	s_waitcnt lgkmcnt(1)
	v_pk_add_f32 v[68:69], v[68:69], v[82:83]
	ds_bpermute_b32 v82, v116, v68
	ds_bpermute_b32 v83, v116, v69
	global_store_short v[80:81], v121, off offset:320
	s_waitcnt lgkmcnt(2)
	v_mul_f32_e32 v80, v126, v123
	v_cndmask_b32_e64 v80, v80, -v80, s[6:7]
	v_fmac_f32_e32 v80, v125, v122
	s_waitcnt lgkmcnt(0)
	v_pk_add_f32 v[68:69], v[68:69], v[82:83]
	v_cvt_pk_bf16_f32 v121, v80, s0
	v_pk_fma_f32 v[68:69], v[68:69], s[12:13], v[64:65] op_sel_hi:[1,0,0]
	ds_bpermute_b32 v80, v115, v154
	v_mul_f32_e32 v81, 0x4b800000, v68
	v_cmp_gt_f32_e32 vcc, s75, v68
	global_store_short v[86:87], v121, off offset:320
	s_nop 0
	v_cndmask_b32_e32 v68, v68, v81, vcc
	ds_bpermute_b32 v81, v115, v155
	v_rsq_f32_e32 v68, v68
	s_waitcnt lgkmcnt(0)
	v_pk_fma_f32 v[80:81], v[54:55], v[54:55], v[80:81]
	v_mul_f32_e32 v82, 0x45800000, v68
	v_cndmask_b32_e32 v68, v68, v82, vcc
	ds_bpermute_b32 v82, v114, v80
	ds_bpermute_b32 v83, v114, v81
	v_mul_f32_e32 v68, v52, v68
	v_mul_f32_e32 v122, v119, v68
	v_mul_f32_e32 v68, 0x4b800000, v69
	v_cmp_gt_f32_e32 vcc, s75, v69
	ds_bpermute_b32 v123, v116, v122
	s_nop 0
	v_cndmask_b32_e32 v68, v69, v68, vcc
	v_rsq_f32_e32 v124, v68
	s_waitcnt lgkmcnt(1)
	v_pk_add_f32 v[68:69], v[80:81], v[82:83]
	ds_bpermute_b32 v80, v118, v68
	ds_bpermute_b32 v81, v118, v69
	v_mul_f32_e32 v83, 0x45800000, v124
	v_cndmask_b32_e32 v83, v124, v83, vcc
	v_mul_f32_e32 v83, v53, v83
	v_mul_f32_e32 v83, v119, v83
	s_waitcnt lgkmcnt(0)
	v_pk_add_f32 v[68:69], v[68:69], v[80:81]
	ds_bpermute_b32 v80, v117, v68
	ds_bpermute_b32 v81, v117, v69
	ds_bpermute_b32 v86, v116, v83
	v_mul_f32_e32 v82, v132, v123
	v_cndmask_b32_e64 v82, v82, -v82, s[6:7]
	v_fmac_f32_e32 v82, v131, v122
	s_waitcnt lgkmcnt(1)
	v_pk_add_f32 v[68:69], v[68:69], v[80:81]
	ds_bpermute_b32 v80, v116, v68
	ds_bpermute_b32 v81, v116, v69
	v_cvt_pk_bf16_f32 v82, v82, s0
	global_store_short v[84:85], v82, off offset:320
	s_waitcnt lgkmcnt(2)
	v_mul_f32_e32 v82, v130, v86
	s_waitcnt lgkmcnt(0)
	v_pk_add_f32 v[68:69], v[68:69], v[80:81]
	s_nop 0
	v_pk_fma_f32 v[68:69], v[68:69], s[12:13], v[64:65] op_sel_hi:[1,0,0]
	ds_bpermute_b32 v81, v115, v149
	v_mul_f32_e32 v80, 0x4b800000, v68
	v_cmp_gt_f32_e32 vcc, s75, v68
	s_nop 1
	v_cndmask_b32_e32 v68, v68, v80, vcc
	v_cndmask_b32_e64 v80, v82, -v82, s[6:7]
	v_fmac_f32_e32 v80, v129, v83
	v_cvt_pk_bf16_f32 v84, v80, s0
	ds_bpermute_b32 v80, v115, v148
	v_rsq_f32_e32 v68, v68
	global_store_short v[88:89], v84, off offset:320
	v_mul_f32_e32 v82, 0x45800000, v68
	s_waitcnt lgkmcnt(0)
; DI int crow(int i, int hl) { return (i & 3) + 8 * (i >> 2) + 4 * hl; }
; DI void phase4(const Params& p, int l, unsigned char* smem) {
;     ...
;       } else {
;         float g = p.in[30][l * 32 + r] * QSCALE_MLA;
; #pragma unroll
;         for (int bm = 0; bm < 2; bm++)
; #pragma unroll
;           for (int bn = 0; bn < 2; bn++)
; #pragma unroll
;             for (int i = 0; i < 16; i++) {
;               const int head = (nt - 4) * 4 + wn * 2 + bn;
;               float a = acc[bm][bn][i];
;               float ss = red32(a * a); float rstd = rsqrtf(ss * (1.f / 32.f) + RMS_EPS);
;               float xn = a * rstd * g; float pt = __shfl_xor(xn, 16);
;               int row = m0 + wm * 64 + bm * 32 + crow(i, hl);
;               const float* rp = rope + pos_of(row) * 32;
;               float cs = rp[r & 15], sn = rp[16 + (r & 15)];
;               float o = (r & 16) ? (pt * sn + xn * cs) : (xn * cs - pt * sn);
;               QF[(size_t)row * 768 + head * 96 + 64 + r] = f2bf(o);
;             }
	v_pk_fma_f32 v[80:81], v[56:57], v[56:57], v[80:81]
	v_cndmask_b32_e32 v68, v68, v82, vcc
	ds_bpermute_b32 v82, v114, v80
	ds_bpermute_b32 v83, v114, v81
	v_mul_f32_e32 v68, v54, v68
	v_mul_f32_e32 v85, v119, v68
	v_mul_f32_e32 v68, 0x4b800000, v69
	v_cmp_gt_f32_e32 vcc, s75, v69
	ds_bpermute_b32 v86, v116, v85
	s_nop 0
	v_cndmask_b32_e32 v68, v69, v68, vcc
	v_rsq_f32_e32 v87, v68
	s_waitcnt lgkmcnt(1)
	v_pk_add_f32 v[68:69], v[80:81], v[82:83]
	ds_bpermute_b32 v80, v118, v68
	ds_bpermute_b32 v81, v118, v69
	v_mul_f32_e32 v83, 0x45800000, v87
	v_cndmask_b32_e32 v83, v87, v83, vcc
	v_mul_f32_e32 v83, v55, v83
	v_mul_f32_e32 v83, v119, v83
	s_waitcnt lgkmcnt(0)
	v_pk_add_f32 v[68:69], v[68:69], v[80:81]
	ds_bpermute_b32 v80, v117, v68
	ds_bpermute_b32 v81, v117, v69
	ds_bpermute_b32 v84, v116, v83
	v_mul_f32_e32 v82, v136, v86
	v_cndmask_b32_e64 v82, v82, -v82, s[6:7]
	v_fmac_f32_e32 v82, v135, v85
	s_waitcnt lgkmcnt(1)
	v_pk_add_f32 v[68:69], v[68:69], v[80:81]
	ds_bpermute_b32 v80, v116, v68
	ds_bpermute_b32 v81, v116, v69
	v_cvt_pk_bf16_f32 v82, v82, s0
	global_store_short v[78:79], v82, off offset:320
	s_waitcnt lgkmcnt(2)
	v_mul_f32_e32 v78, v134, v84
	v_cndmask_b32_e64 v78, v78, -v78, s[6:7]
	s_waitcnt lgkmcnt(0)
	v_pk_add_f32 v[68:69], v[68:69], v[80:81]
	v_fmac_f32_e32 v78, v133, v83
	v_pk_fma_f32 v[68:69], v[68:69], s[12:13], v[64:65] op_sel_hi:[1,0,0]
	v_cvt_pk_bf16_f32 v82, v78, s0
	v_mul_f32_e32 v79, 0x4b800000, v68
	v_cmp_gt_f32_e32 vcc, s75, v68
	ds_bpermute_b32 v78, v115, v152
	global_store_short v[76:77], v82, off offset:320
	v_cndmask_b32_e32 v68, v68, v79, vcc
	ds_bpermute_b32 v79, v115, v153
	v_rsq_f32_e32 v68, v68
	s_waitcnt lgkmcnt(0)
	v_pk_fma_f32 v[78:79], v[58:59], v[58:59], v[78:79]
	v_mul_f32_e32 v80, 0x45800000, v68
	v_cndmask_b32_e32 v68, v68, v80, vcc
	ds_bpermute_b32 v80, v114, v78
	ds_bpermute_b32 v81, v114, v79
	v_mul_f32_e32 v68, v56, v68
	v_mul_f32_e32 v83, v119, v68
	v_mul_f32_e32 v68, 0x4b800000, v69
	v_cmp_gt_f32_e32 vcc, s75, v69
	ds_bpermute_b32 v84, v116, v83
	s_waitcnt lgkmcnt(0)
	v_mul_f32_e32 v76, v140, v84
	v_cndmask_b32_e32 v68, v69, v68, vcc
	v_rsq_f32_e32 v85, v68
	v_pk_add_f32 v[68:69], v[78:79], v[80:81]
	ds_bpermute_b32 v78, v118, v68
	ds_bpermute_b32 v79, v118, v69
	v_cndmask_b32_e64 v80, v76, -v76, s[6:7]
	v_mul_f32_e32 v81, 0x45800000, v85
	v_fmac_f32_e32 v80, v139, v83
	v_cvt_pk_bf16_f32 v80, v80, s0
	s_waitcnt lgkmcnt(0)
	v_pk_add_f32 v[68:69], v[68:69], v[78:79]
	ds_bpermute_b32 v76, v117, v68
	ds_bpermute_b32 v77, v117, v69
	v_cndmask_b32_e32 v78, v85, v81, vcc
	v_mul_f32_e32 v78, v57, v78
	v_mul_f32_e32 v78, v119, v78
	ds_bpermute_b32 v79, v116, v78
	s_waitcnt lgkmcnt(1)
	v_pk_add_f32 v[68:69], v[68:69], v[76:77]
	ds_bpermute_b32 v76, v116, v68
	ds_bpermute_b32 v77, v116, v69
	global_store_short v[90:91], v80, off offset:320
	s_waitcnt lgkmcnt(2)
	v_mul_f32_e32 v79, v138, v79
	v_pk_mul_f32 v[90:91], v[18:19], v[18:19]
	s_waitcnt lgkmcnt(0)
	v_pk_add_f32 v[68:69], v[68:69], v[76:77]
	s_nop 0
	v_pk_fma_f32 v[68:69], v[68:69], s[12:13], v[64:65] op_sel_hi:[1,0,0]
	ds_bpermute_b32 v77, v115, v151
	v_mul_f32_e32 v76, 0x4b800000, v68
	v_cmp_gt_f32_e32 vcc, s75, v68
	s_nop 1
	v_cndmask_b32_e32 v68, v68, v76, vcc
	v_cndmask_b32_e64 v76, v79, -v79, s[6:7]
	v_fmac_f32_e32 v76, v137, v78
	v_cvt_pk_bf16_f32 v80, v76, s0
	ds_bpermute_b32 v76, v115, v150
	v_rsq_f32_e32 v68, v68
	global_store_short v[92:93], v80, off offset:320
	v_mul_f32_e32 v78, 0x45800000, v68
	s_waitcnt lgkmcnt(0)
	v_pk_fma_f32 v[76:77], v[60:61], v[60:61], v[76:77]
	v_cndmask_b32_e32 v68, v68, v78, vcc
	ds_bpermute_b32 v78, v114, v76
	ds_bpermute_b32 v79, v114, v77
	v_mul_f32_e32 v68, v58, v68
	v_mul_f32_e32 v81, v119, v68
	v_mul_f32_e32 v68, 0x4b800000, v69
	v_cmp_gt_f32_e32 vcc, s75, v69
	ds_bpermute_b32 v82, v116, v81
	s_nop 0
	v_cndmask_b32_e32 v68, v69, v68, vcc
	v_rsq_f32_e32 v83, v68
	s_waitcnt lgkmcnt(1)
	v_pk_add_f32 v[68:69], v[76:77], v[78:79]
	ds_bpermute_b32 v76, v118, v68
	ds_bpermute_b32 v77, v118, v69
	v_mul_f32_e32 v79, 0x45800000, v83
	v_cndmask_b32_e32 v79, v83, v79, vcc
	v_mul_f32_e32 v79, v59, v79
	v_mul_f32_e32 v79, v119, v79
	s_waitcnt lgkmcnt(0)
	v_pk_add_f32 v[68:69], v[68:69], v[76:77]
	ds_bpermute_b32 v76, v117, v68
	ds_bpermute_b32 v77, v117, v69
	ds_bpermute_b32 v80, v116, v79
	v_mul_f32_e32 v78, v144, v82
	v_cndmask_b32_e64 v78, v78, -v78, s[6:7]
	v_fmac_f32_e32 v78, v143, v81
	s_waitcnt lgkmcnt(1)
	v_pk_add_f32 v[68:69], v[68:69], v[76:77]
	ds_bpermute_b32 v76, v116, v68
	ds_bpermute_b32 v77, v116, v69
	v_cvt_pk_bf16_f32 v78, v78, s0
	global_store_short v[74:75], v78, off offset:320
	s_waitcnt lgkmcnt(2)
	v_mul_f32_e32 v74, v142, v80
	v_cndmask_b32_e64 v74, v74, -v74, s[6:7]
	s_waitcnt lgkmcnt(0)
	v_pk_add_f32 v[68:69], v[68:69], v[76:77]
	v_fmac_f32_e32 v74, v141, v79
	v_pk_fma_f32 v[68:69], v[68:69], s[12:13], v[64:65] op_sel_hi:[1,0,0]
	v_cvt_pk_bf16_f32 v78, v74, s0
	v_mul_f32_e32 v75, 0x4b800000, v68
	v_cmp_gt_f32_e32 vcc, s75, v68
	ds_bpermute_b32 v74, v115, v112
	global_store_short v[72:73], v78, off offset:320
	v_cndmask_b32_e32 v68, v68, v75, vcc
	ds_bpermute_b32 v75, v115, v113
	v_rsq_f32_e32 v68, v68
	v_or_b32_e32 v112, 32, v120
	v_or_b32_e32 v131, v112, v222
	v_or_b32_e32 v139, v112, v228
	v_mul_f32_e32 v76, 0x45800000, v68
	s_waitcnt lgkmcnt(0)
	v_pk_fma_f32 v[74:75], v[62:63], v[62:63], v[74:75]
	v_cndmask_b32_e32 v68, v68, v76, vcc
	ds_bpermute_b32 v76, v114, v74
	ds_bpermute_b32 v77, v114, v75
	v_mul_f32_e32 v68, v60, v68
	v_mul_f32_e32 v79, v119, v68
	v_mul_f32_e32 v68, 0x4b800000, v69
	v_cmp_gt_f32_e32 vcc, s75, v69
	ds_bpermute_b32 v80, v116, v79
	v_or_b32_e32 v142, v112, v229
	v_cndmask_b32_e32 v68, v69, v68, vcc
	v_rsq_f32_e32 v81, v68
	s_waitcnt lgkmcnt(1)
; DI int crow(int i, int hl) { return (i & 3) + 8 * (i >> 2) + 4 * hl; }
; DI void phase4(const Params& p, int l, unsigned char* smem) {
;     ...
;       } else {
;         float g = p.in[30][l * 32 + r] * QSCALE_MLA;
; #pragma unroll
;         for (int bm = 0; bm < 2; bm++)
; #pragma unroll
;           for (int bn = 0; bn < 2; bn++)
; #pragma unroll
;             for (int i = 0; i < 16; i++) {
;               const int head = (nt - 4) * 4 + wn * 2 + bn;
;               float a = acc[bm][bn][i];
;               float ss = red32(a * a); float rstd = rsqrtf(ss * (1.f / 32.f) + RMS_EPS);
;               float xn = a * rstd * g; float pt = __shfl_xor(xn, 16);
;               int row = m0 + wm * 64 + bm * 32 + crow(i, hl);
;               const float* rp = rope + pos_of(row) * 32;
;               float cs = rp[r & 15], sn = rp[16 + (r & 15)];
;               float o = (r & 16) ? (pt * sn + xn * cs) : (xn * cs - pt * sn);
;               QF[(size_t)row * 768 + head * 96 + 64 + r] = f2bf(o);
;             }
	v_pk_add_f32 v[68:69], v[74:75], v[76:77]
	ds_bpermute_b32 v74, v118, v68
	ds_bpermute_b32 v75, v118, v69
	s_waitcnt vmcnt(21) lgkmcnt(2)
	v_mul_f32_e32 v72, v167, v80
	v_cndmask_b32_e64 v76, v72, -v72, s[6:7]
	v_mul_f32_e32 v77, 0x45800000, v81
	s_waitcnt vmcnt(20)
	v_fmac_f32_e32 v76, v168, v79
	s_waitcnt lgkmcnt(0)
	v_pk_add_f32 v[68:69], v[68:69], v[74:75]
	ds_bpermute_b32 v72, v117, v68
	ds_bpermute_b32 v73, v117, v69
	v_cndmask_b32_e32 v74, v81, v77, vcc
	v_mul_f32_e32 v74, v61, v74
	v_mul_f32_e32 v74, v119, v74
	ds_bpermute_b32 v75, v116, v74
	s_waitcnt lgkmcnt(1)
	v_pk_add_f32 v[68:69], v[68:69], v[72:73]
	ds_bpermute_b32 v72, v116, v68
	ds_bpermute_b32 v73, v116, v69
	v_cvt_pk_bf16_f32 v76, v76, s0
	s_waitcnt lgkmcnt(2)
	v_mul_f32_e32 v75, v165, v75
	global_store_short v[94:95], v76, off offset:320
	v_or_b32_e32 v76, v112, v209
	s_waitcnt lgkmcnt(0)
	v_pk_add_f32 v[68:69], v[68:69], v[72:73]
	v_mov_b32_e32 v73, v163
	v_pk_fma_f32 v[68:69], v[68:69], s[12:13], v[64:65] op_sel_hi:[1,0,0]
	v_or_b32_e32 v95, v112, v214
	v_mul_f32_e32 v72, 0x4b800000, v68
	v_cmp_gt_f32_e32 vcc, s75, v68
	v_or_b32_e32 v145, v112, v230
	v_or_b32_e32 v148, v112, v231
	v_cndmask_b32_e32 v68, v68, v72, vcc
	v_rsq_f32_e32 v68, v68
	v_cndmask_b32_e64 v72, v75, -v75, s[6:7]
	v_fmac_f32_e32 v72, v166, v74
	v_cvt_pk_bf16_f32 v74, v72, s0
	v_mul_f32_e32 v72, 0x45800000, v68
	v_cndmask_b32_e32 v68, v68, v72, vcc
	v_mul_f32_e32 v68, v62, v68
	v_mul_f32_e32 v75, v119, v68
	ds_bpermute_b32 v68, v116, v75
	v_bitop3_b32 v72, v112, s2, v209 bitop3:0xc8
	v_cmp_gt_i32_e32 vcc, s50, v76
	global_store_short v[96:97], v74, off offset:320
	s_movk_i32 s2, 0x1fe5
	v_cndmask_b32_e32 v72, v213, v72, vcc
	v_lshlrev_b32_e32 v72, 7, v72
	v_lshl_add_u64 v[78:79], v[108:109], 0, v[72:73]
	v_mul_f32_e32 v72, 0x4b800000, v69
	v_cmp_gt_f32_e32 vcc, s75, v69
	s_waitcnt vmcnt(17) lgkmcnt(0)
	v_mul_f32_e32 v68, v171, v68
	v_cndmask_b32_e64 v74, v68, -v68, s[6:7]
	v_cndmask_b32_e32 v69, v69, v72, vcc
	v_rsq_f32_e32 v72, v69
	v_pk_mul_f32 v[68:69], v[16:17], v[16:17]
	ds_bpermute_b32 v68, v115, v68
	ds_bpermute_b32 v69, v115, v69
	v_mul_f32_e32 v73, 0x45800000, v72
	v_cndmask_b32_e32 v72, v72, v73, vcc
	v_mul_f32_e32 v72, v63, v72
	v_mul_f32_e32 v77, v119, v72
	s_waitcnt lgkmcnt(0)
	v_pk_fma_f32 v[68:69], v[16:17], v[16:17], v[68:69]
	ds_bpermute_b32 v72, v114, v68
	ds_bpermute_b32 v73, v114, v69
	ds_bpermute_b32 v80, v116, v77
	s_waitcnt vmcnt(16)
	v_fmac_f32_e32 v74, v172, v75
	v_cvt_pk_bf16_f32 v74, v74, s0
	global_store_short v[70:71], v74, off offset:320
	s_waitcnt lgkmcnt(1)
	v_pk_add_f32 v[68:69], v[68:69], v[72:73]
	ds_bpermute_b32 v70, v118, v68
	ds_bpermute_b32 v71, v118, v69
	v_bitop3_b32 v72, v112, s2, v214 bitop3:0xc8
	v_cmp_gt_i32_e32 vcc, s50, v95
	s_waitcnt lgkmcnt(2)
	v_mul_f32_e32 v74, v169, v80
	v_mov_b32_e32 v73, v163
	v_cndmask_b32_e32 v72, v215, v72, vcc
	v_lshlrev_b32_e32 v72, 7, v72
	v_lshl_add_u64 v[80:81], v[108:109], 0, v[72:73]
	v_cndmask_b32_e64 v72, v74, -v74, s[6:7]
	v_fmac_f32_e32 v72, v170, v77
	s_waitcnt lgkmcnt(0)
	v_pk_add_f32 v[70:71], v[68:69], v[70:71]
	v_cvt_pk_bf16_f32 v74, v72, s0
	ds_bpermute_b32 v72, v117, v70
	ds_bpermute_b32 v73, v117, v71
	global_load_dword v92, v[78:79], off offset:64
	global_load_dword v96, v[80:81], off offset:64
	v_mad_i64_i32 v[68:69], s[2:3], v76, s33, v[66:67]
	s_waitcnt lgkmcnt(0)
	v_pk_add_f32 v[82:83], v[70:71], v[72:73]
	ds_bpermute_b32 v84, v116, v82
	ds_bpermute_b32 v85, v116, v83
	global_store_short v[98:99], v74, off offset:320
	v_or_b32_e32 v98, v112, v216
	s_movk_i32 s2, 0x1fe6
	v_lshl_add_u64 v[68:69], v[68:69], 0, v[162:163]
	s_waitcnt lgkmcnt(0)
	v_pk_add_f32 v[82:83], v[82:83], v[84:85]
	v_pk_mul_f32 v[84:85], v[20:21], v[20:21]
	v_pk_fma_f32 v[88:89], v[82:83], s[12:13], v[64:65] op_sel_hi:[1,0,0]
	ds_bpermute_b32 v84, v115, v84
	v_mul_f32_e32 v82, 0x4b800000, v88
	v_cmp_gt_f32_e32 vcc, s75, v88
	ds_bpermute_b32 v85, v115, v85
	v_pk_mul_f32 v[76:77], v[24:25], v[24:25]
	v_cndmask_b32_e32 v82, v88, v82, vcc
	v_rsq_f32_e32 v86, v82
	v_pk_mul_f32 v[82:83], v[22:23], v[22:23]
	s_waitcnt lgkmcnt(0)
	v_pk_fma_f32 v[84:85], v[20:21], v[20:21], v[84:85]
	ds_bpermute_b32 v82, v115, v82
	v_mul_f32_e32 v87, 0x45800000, v86
	v_cndmask_b32_e32 v86, v86, v87, vcc
	v_mul_f32_e32 v94, v16, v86
	v_bitop3_b32 v86, v112, s2, v216 bitop3:0xc8
	v_cmp_gt_i32_e32 vcc, s50, v98
	v_mov_b32_e32 v87, v163
	v_mul_f32_e32 v99, v119, v94
	v_cndmask_b32_e32 v86, v217, v86, vcc
	v_lshlrev_b32_e32 v86, 7, v86
	v_lshl_add_u64 v[86:87], v[108:109], 0, v[86:87]
	global_load_dword v88, v[86:87], off offset:64
	global_load_dword v94, v[86:87], off
	global_load_dword v97, v[80:81], off
	global_load_dword v93, v[78:79], off
	ds_bpermute_b32 v123, v116, v99
	global_load_dword v120, v[80:81], off offset:64
	global_load_dword v113, v[80:81], off
	global_load_dword v122, v[78:79], off offset:64
	global_load_dword v121, v[78:79], off
	ds_bpermute_b32 v79, v115, v91
	v_mul_f32_e32 v80, 0x4b800000, v89
	v_cmp_gt_f32_e32 vcc, s75, v89
	s_movk_i32 s2, 0x1fe7
	v_mov_b32_e32 v91, v163
	v_cndmask_b32_e32 v80, v89, v80, vcc
	v_rsq_f32_e32 v89, v80
	ds_bpermute_b32 v83, v115, v83
	ds_bpermute_b32 v76, v115, v76
	ds_bpermute_b32 v77, v115, v77
	v_pk_mul_f32 v[74:75], v[26:27], v[26:27]
	ds_bpermute_b32 v74, v115, v74
	s_waitcnt lgkmcnt(3)
	v_pk_fma_f32 v[82:83], v[22:23], v[22:23], v[82:83]
	ds_bpermute_b32 v75, v115, v75
	s_waitcnt lgkmcnt(2)
	v_pk_fma_f32 v[76:77], v[24:25], v[24:25], v[76:77]
	v_pk_mul_f32 v[72:73], v[28:29], v[28:29]
	ds_bpermute_b32 v72, v115, v72
	ds_bpermute_b32 v73, v115, v73
	s_waitcnt lgkmcnt(2)
; DI int crow(int i, int hl) { return (i & 3) + 8 * (i >> 2) + 4 * hl; }
; DI void phase4(const Params& p, int l, unsigned char* smem) {
;     ...
;         float g = p.in[30][l * 32 + r] * QSCALE_MLA;
; #pragma unroll
;         for (int bm = 0; bm < 2; bm++)
; #pragma unroll
;           for (int bn = 0; bn < 2; bn++)
; #pragma unroll
;             for (int i = 0; i < 16; i++) {
;               const int head = (nt - 4) * 4 + wn * 2 + bn;
;               float a = acc[bm][bn][i];
;               float ss = red32(a * a); float rstd = rsqrtf(ss * (1.f / 32.f) + RMS_EPS);
;               float xn = a * rstd * g; float pt = __shfl_xor(xn, 16);
;               int row = m0 + wm * 64 + bm * 32 + crow(i, hl);
;               const float* rp = rope + pos_of(row) * 32;
;               float cs = rp[r & 15], sn = rp[16 + (r & 15)];
;               float o = (r & 16) ? (pt * sn + xn * cs) : (xn * cs - pt * sn);
;               QF[(size_t)row * 768 + head * 96 + 64 + r] = f2bf(o);
;             }
	v_pk_fma_f32 v[74:75], v[26:27], v[26:27], v[74:75]
	v_or_b32_e32 v153, v112, v233
	v_or_b32_e32 v158, v112, v235
	v_pk_mul_f32 v[70:71], v[30:31], v[30:31]
	s_waitcnt lgkmcnt(0)
	v_pk_fma_f32 v[72:73], v[28:29], v[28:29], v[72:73]
	ds_bpermute_b32 v70, v115, v70
	ds_bpermute_b32 v71, v115, v71
	s_waitcnt lgkmcnt(0)
	v_pk_fma_f32 v[70:71], v[30:31], v[30:31], v[70:71]
	s_waitcnt vmcnt(10)
	v_mul_f32_e32 v78, v92, v123
	v_cndmask_b32_e64 v92, v78, -v78, s[6:7]
	ds_bpermute_b32 v78, v115, v90
	v_mul_f32_e32 v90, 0x45800000, v89
	v_cndmask_b32_e32 v89, v89, v90, vcc
	v_mul_f32_e32 v89, v17, v89
	v_mul_f32_e32 v89, v119, v89
	s_waitcnt lgkmcnt(0)
	v_pk_fma_f32 v[78:79], v[18:19], v[18:19], v[78:79]
	ds_bpermute_b32 v80, v114, v78
	ds_bpermute_b32 v81, v114, v79
	v_bitop3_b32 v90, v112, s2, v218 bitop3:0xc8
	s_waitcnt lgkmcnt(0)
	v_pk_add_f32 v[78:79], v[78:79], v[80:81]
	ds_bpermute_b32 v80, v118, v78
	ds_bpermute_b32 v81, v118, v79
	s_waitcnt lgkmcnt(0)
	v_pk_add_f32 v[78:79], v[78:79], v[80:81]
	ds_bpermute_b32 v80, v117, v78
	ds_bpermute_b32 v81, v117, v79
	s_waitcnt lgkmcnt(0)
	v_pk_add_f32 v[78:79], v[78:79], v[80:81]
	v_mad_i64_i32 v[80:81], s[2:3], v95, s33, v[66:67]
	v_lshl_add_u64 v[80:81], v[80:81], 0, v[162:163]
	s_waitcnt vmcnt(4)
	v_fmac_f32_e32 v92, v93, v99
	ds_bpermute_b32 v93, v116, v89
	v_cvt_pk_bf16_f32 v92, v92, s0
	global_store_short v[68:69], v92, off offset:128
	v_or_b32_e32 v99, v112, v218
	v_cmp_gt_i32_e32 vcc, s50, v99
	s_waitcnt lgkmcnt(0)
	v_mul_f32_e32 v92, v96, v93
	v_cndmask_b32_e64 v92, v92, -v92, s[6:7]
	v_fmac_f32_e32 v92, v97, v89
	v_cvt_pk_bf16_f32 v89, v92, s0
	ds_bpermute_b32 v92, v116, v78
	ds_bpermute_b32 v93, v116, v79
	v_cndmask_b32_e32 v90, v219, v90, vcc
	global_store_short v[80:81], v89, off offset:128
	v_lshlrev_b32_e32 v90, 7, v90
	v_lshl_add_u64 v[90:91], v[108:109], 0, v[90:91]
	s_waitcnt lgkmcnt(0)
	v_pk_add_f32 v[78:79], v[78:79], v[92:93]
	global_load_dword v127, v[90:91], off offset:64
	v_pk_fma_f32 v[92:93], v[78:79], s[12:13], v[64:65] op_sel_hi:[1,0,0]
	v_mov_b32_e32 v97, v163
	v_mul_f32_e32 v78, 0x4b800000, v92
	v_cmp_gt_f32_e32 vcc, s75, v92
	s_nop 1
	v_cndmask_b32_e32 v78, v92, v78, vcc
	v_rsq_f32_e32 v89, v78
	v_mad_i64_i32 v[78:79], s[2:3], v98, s33, v[66:67]
	s_movk_i32 s2, 0x1fec
	v_mul_f32_e32 v92, 0x45800000, v89
	v_cndmask_b32_e32 v89, v89, v92, vcc
	v_or_b32_e32 v92, v112, v220
	v_bitop3_b32 v95, v112, s2, v220 bitop3:0xc8
	v_cmp_gt_i32_e32 vcc, s50, v92
	v_mul_f32_e32 v89, v18, v89
	v_mul_f32_e32 v89, v119, v89
	v_cndmask_b32_e32 v95, v221, v95, vcc
	v_lshlrev_b32_e32 v96, 7, v95
	v_lshl_add_u64 v[96:97], v[108:109], 0, v[96:97]
	global_load_dword v95, v[96:97], off offset:64
	global_load_dword v98, v[96:97], off
	global_load_dword v128, v[90:91], off
	ds_bpermute_b32 v129, v116, v89
	global_load_dword v124, v[90:91], off offset:64
	global_load_dword v123, v[90:91], off
	global_load_dword v126, v[86:87], off offset:64
	global_load_dword v125, v[86:87], off
	v_cmp_gt_f32_e32 vcc, s75, v93
	ds_bpermute_b32 v87, v114, v85
	v_lshl_add_u64 v[78:79], v[78:79], 0, v[162:163]
	s_waitcnt lgkmcnt(1)
	v_mul_f32_e32 v86, v88, v129
	v_cndmask_b32_e64 v88, v86, -v86, s[6:7]
	v_mul_f32_e32 v86, 0x4b800000, v93
	v_cndmask_b32_e32 v86, v93, v86, vcc
	v_fmac_f32_e32 v88, v94, v89
	v_rsq_f32_e32 v89, v86
	ds_bpermute_b32 v86, v114, v84
	v_cvt_pk_bf16_f32 v90, v88, s0
	global_store_short v[78:79], v90, off offset:128
	v_mul_f32_e32 v88, 0x45800000, v89
	v_cndmask_b32_e32 v88, v89, v88, vcc
	s_waitcnt lgkmcnt(0)
	v_pk_add_f32 v[84:85], v[84:85], v[86:87]
	ds_bpermute_b32 v86, v118, v84
	ds_bpermute_b32 v87, v118, v85
	v_mul_f32_e32 v91, v19, v88
	v_mul_f32_e32 v91, v119, v91
	ds_bpermute_b32 v93, v116, v91
	s_movk_i32 s2, 0x1fed
	s_waitcnt lgkmcnt(1)
	v_pk_add_f32 v[84:85], v[84:85], v[86:87]
	ds_bpermute_b32 v86, v117, v84
	ds_bpermute_b32 v87, v117, v85
	v_bitop3_b32 v88, v112, s2, v222 bitop3:0xc8
	v_cmp_gt_i32_e32 vcc, s50, v131
	v_mov_b32_e32 v89, v163
	s_waitcnt lgkmcnt(0)
	v_pk_add_f32 v[84:85], v[84:85], v[86:87]
	v_cndmask_b32_e32 v88, v223, v88, vcc
	v_mad_i64_i32 v[86:87], s[2:3], v99, s33, v[66:67]
	v_or_b32_e32 v99, v112, v224
	v_lshlrev_b32_e32 v88, 7, v88
	v_lshl_add_u64 v[88:89], v[108:109], 0, v[88:89]
	v_lshl_add_u64 v[86:87], v[86:87], 0, v[162:163]
	global_load_dword v94, v[88:89], off offset:64
	s_waitcnt vmcnt(9)
	v_mul_f32_e32 v90, v127, v93
	v_cndmask_b32_e64 v90, v90, -v90, s[6:7]
	s_waitcnt vmcnt(6)
	v_fmac_f32_e32 v90, v128, v91
	v_cvt_pk_bf16_f32 v93, v90, s0
	ds_bpermute_b32 v90, v116, v84
	ds_bpermute_b32 v91, v116, v85
	global_store_short v[86:87], v93, off offset:128
	v_mov_b32_e32 v93, v163
	s_waitcnt lgkmcnt(0)
	v_pk_add_f32 v[84:85], v[84:85], v[90:91]
	s_nop 0
	v_pk_fma_f32 v[90:91], v[84:85], s[12:13], v[64:65] op_sel_hi:[1,0,0]
	s_nop 0
	v_mul_f32_e32 v84, 0x4b800000, v90
	v_cmp_gt_f32_e32 vcc, s75, v90
	s_nop 1
	v_cndmask_b32_e32 v84, v90, v84, vcc
	v_rsq_f32_e32 v90, v84
	v_mad_i64_i32 v[84:85], s[2:3], v92, s33, v[66:67]
	s_movk_i32 s2, 0x1fee
	v_mul_f32_e32 v92, 0x45800000, v90
	v_cndmask_b32_e32 v90, v90, v92, vcc
	v_bitop3_b32 v92, v112, s2, v224 bitop3:0xc8
	v_cmp_gt_i32_e32 vcc, s50, v99
	v_mul_f32_e32 v90, v20, v90
	v_mul_f32_e32 v90, v119, v90
	v_cndmask_b32_e32 v92, v225, v92, vcc
	v_lshlrev_b32_e32 v92, 7, v92
	v_lshl_add_u64 v[92:93], v[108:109], 0, v[92:93]
	global_load_dword v135, v[92:93], off offset:64
	global_load_dword v136, v[92:93], off
	global_load_dword v132, v[88:89], off
	ds_bpermute_b32 v133, v116, v90
	global_load_dword v128, v[88:89], off offset:64
	global_load_dword v127, v[88:89], off
	global_load_dword v130, v[96:97], off offset:64
	global_load_dword v129, v[96:97], off
	v_cmp_gt_f32_e32 vcc, s75, v91
	ds_bpermute_b32 v89, v114, v83
	v_lshl_add_u64 v[84:85], v[84:85], 0, v[162:163]
	s_waitcnt lgkmcnt(1)
; DI int crow(int i, int hl) { return (i & 3) + 8 * (i >> 2) + 4 * hl; }
; DI void phase4(const Params& p, int l, unsigned char* smem) {
;     ...
;         float g = p.in[30][l * 32 + r] * QSCALE_MLA;
; #pragma unroll
;         for (int bm = 0; bm < 2; bm++)
; #pragma unroll
;           for (int bn = 0; bn < 2; bn++)
; #pragma unroll
;             for (int i = 0; i < 16; i++) {
;               const int head = (nt - 4) * 4 + wn * 2 + bn;
;               float a = acc[bm][bn][i];
;               float ss = red32(a * a); float rstd = rsqrtf(ss * (1.f / 32.f) + RMS_EPS);
;               float xn = a * rstd * g; float pt = __shfl_xor(xn, 16);
;               int row = m0 + wm * 64 + bm * 32 + crow(i, hl);
;               const float* rp = rope + pos_of(row) * 32;
;               float cs = rp[r & 15], sn = rp[16 + (r & 15)];
;               float o = (r & 16) ? (pt * sn + xn * cs) : (xn * cs - pt * sn);
;               QF[(size_t)row * 768 + head * 96 + 64 + r] = f2bf(o);
;             }
	v_mul_f32_e32 v88, v95, v133
	v_cndmask_b32_e64 v95, v88, -v88, s[6:7]
	v_mul_f32_e32 v88, 0x4b800000, v91
	v_cndmask_b32_e32 v88, v91, v88, vcc
	v_fmac_f32_e32 v95, v98, v90
	v_rsq_f32_e32 v90, v88
	ds_bpermute_b32 v88, v114, v82
	v_cvt_pk_bf16_f32 v95, v95, s0
	global_store_short v[84:85], v95, off offset:128
	v_mul_f32_e32 v91, 0x45800000, v90
	v_cndmask_b32_e32 v90, v90, v91, vcc
	s_waitcnt lgkmcnt(0)
	v_pk_add_f32 v[82:83], v[82:83], v[88:89]
	ds_bpermute_b32 v88, v118, v82
	ds_bpermute_b32 v89, v118, v83
	v_mul_f32_e32 v96, v21, v90
	v_mul_f32_e32 v96, v119, v96
	ds_bpermute_b32 v97, v116, v96
	v_or_b32_e32 v98, v112, v226
	s_waitcnt lgkmcnt(1)
	v_pk_add_f32 v[82:83], v[82:83], v[88:89]
	ds_bpermute_b32 v88, v117, v82
	ds_bpermute_b32 v89, v117, v83
	s_waitcnt vmcnt(9) lgkmcnt(2)
	v_mul_f32_e32 v94, v94, v97
	v_cndmask_b32_e64 v94, v94, -v94, s[6:7]
	s_movk_i32 s2, 0x1fef
	v_bitop3_b32 v90, v112, s2, v226 bitop3:0xc8
	s_waitcnt lgkmcnt(0)
	v_pk_add_f32 v[82:83], v[82:83], v[88:89]
	ds_bpermute_b32 v95, v116, v83
	v_cmp_gt_i32_e32 vcc, s50, v98
	v_mad_i64_i32 v[88:89], s[2:3], v131, s33, v[66:67]
	s_nop 0
	v_cndmask_b32_e32 v90, v227, v90, vcc
	v_lshl_add_u64 v[88:89], v[88:89], 0, v[162:163]
	v_lshlrev_b32_e32 v90, 7, v90
	v_mov_b32_e32 v91, v163
	v_lshl_add_u64 v[90:91], v[108:109], 0, v[90:91]
	global_load_dword v137, v[90:91], off offset:64
	v_mov_b32_e32 v97, v163
	s_waitcnt vmcnt(6)
	v_fmac_f32_e32 v94, v132, v96
	v_cvt_pk_bf16_f32 v96, v94, s0
	ds_bpermute_b32 v94, v116, v82
	global_store_short v[88:89], v96, off offset:128
	s_waitcnt lgkmcnt(0)
	v_pk_add_f32 v[82:83], v[82:83], v[94:95]
	s_nop 0
	v_pk_fma_f32 v[94:95], v[82:83], s[12:13], v[64:65] op_sel_hi:[1,0,0]
	s_nop 0
	v_mul_f32_e32 v82, 0x4b800000, v94
	v_cmp_gt_f32_e32 vcc, s75, v94
	s_nop 1
	v_cndmask_b32_e32 v82, v94, v82, vcc
	v_rsq_f32_e32 v94, v82
	v_mad_i64_i32 v[82:83], s[2:3], v99, s33, v[66:67]
	s_movk_i32 s2, 0x1ff4
	v_mul_f32_e32 v96, 0x45800000, v94
	v_cndmask_b32_e32 v94, v94, v96, vcc
	v_bitop3_b32 v96, v112, s2, v228 bitop3:0xc8
	v_cmp_gt_i32_e32 vcc, s50, v139
	v_mul_f32_e32 v94, v22, v94
	v_mul_f32_e32 v94, v119, v94
	v_cndmask_b32_e32 v96, v213, v96, vcc
	v_lshlrev_b32_e32 v96, 7, v96
	v_lshl_add_u64 v[96:97], v[108:109], 0, v[96:97]
	global_load_dword v140, v[96:97], off offset:64
	global_load_dword v141, v[96:97], off
	global_load_dword v138, v[90:91], off
	ds_bpermute_b32 v99, v116, v94
	global_load_dword v132, v[90:91], off offset:64
	global_load_dword v131, v[90:91], off
	global_load_dword v134, v[92:93], off offset:64
	global_load_dword v133, v[92:93], off
	v_cmp_gt_f32_e32 vcc, s75, v95
	ds_bpermute_b32 v91, v114, v77
	v_lshl_add_u64 v[82:83], v[82:83], 0, v[162:163]
	s_waitcnt lgkmcnt(1)
	v_mul_f32_e32 v90, v135, v99
	v_cndmask_b32_e64 v92, v90, -v90, s[6:7]
	v_mul_f32_e32 v90, 0x4b800000, v95
	v_cndmask_b32_e32 v90, v95, v90, vcc
	v_rsq_f32_e32 v93, v90
	ds_bpermute_b32 v90, v114, v76
	v_fmac_f32_e32 v92, v136, v94
	v_cvt_pk_bf16_f32 v94, v92, s0
	v_mul_f32_e32 v92, 0x45800000, v93
	v_cndmask_b32_e32 v92, v93, v92, vcc
	s_waitcnt lgkmcnt(0)
	v_pk_add_f32 v[76:77], v[76:77], v[90:91]
	ds_bpermute_b32 v90, v118, v76
	ds_bpermute_b32 v91, v118, v77
	v_mul_f32_e32 v95, v23, v92
	v_mul_f32_e32 v95, v119, v95
	ds_bpermute_b32 v99, v116, v95
	global_store_short v[82:83], v94, off offset:128
	s_waitcnt lgkmcnt(1)
	v_pk_add_f32 v[76:77], v[76:77], v[90:91]
	ds_bpermute_b32 v90, v117, v76
	ds_bpermute_b32 v91, v117, v77
	s_waitcnt vmcnt(9) lgkmcnt(2)
	v_mul_f32_e32 v94, v137, v99
	v_cndmask_b32_e64 v94, v94, -v94, s[6:7]
	s_movk_i32 s2, 0x1ff5
	v_bitop3_b32 v92, v112, s2, v229 bitop3:0xc8
	s_waitcnt lgkmcnt(0)
	v_pk_add_f32 v[90:91], v[76:77], v[90:91]
	v_cmp_gt_i32_e32 vcc, s50, v142
	v_mad_i64_i32 v[76:77], s[2:3], v98, s33, v[66:67]
	s_nop 0
	v_cndmask_b32_e32 v92, v215, v92, vcc
	s_movk_i32 s2, 0x1ff6
	v_lshlrev_b32_e32 v92, 7, v92
	v_mov_b32_e32 v93, v163
	v_cmp_gt_i32_e32 vcc, s50, v145
	v_lshl_add_u64 v[92:93], v[108:109], 0, v[92:93]
	global_load_dword v143, v[92:93], off offset:64
	v_lshl_add_u64 v[76:77], v[76:77], 0, v[162:163]
	s_waitcnt vmcnt(6)
	v_fmac_f32_e32 v94, v138, v95
	v_cvt_pk_bf16_f32 v99, v94, s0
	ds_bpermute_b32 v94, v116, v90
	ds_bpermute_b32 v95, v116, v91
	global_store_short v[76:77], v99, off offset:128
	s_waitcnt lgkmcnt(0)
	v_pk_add_f32 v[90:91], v[90:91], v[94:95]
	s_nop 0
	v_pk_fma_f32 v[94:95], v[90:91], s[12:13], v[64:65] op_sel_hi:[1,0,0]
	v_bitop3_b32 v90, v112, s2, v230 bitop3:0xc8
	v_cndmask_b32_e32 v90, v217, v90, vcc
	v_lshlrev_b32_e32 v90, 7, v90
	v_mov_b32_e32 v91, v163
	v_lshl_add_u64 v[98:99], v[108:109], 0, v[90:91]
	global_load_dword v146, v[98:99], off offset:64
	global_load_dword v147, v[98:99], off
	global_load_dword v144, v[92:93], off
	v_mul_f32_e32 v135, 0x4b800000, v94
	v_cmp_gt_f32_e32 vcc, s75, v94
	s_nop 1
	v_cndmask_b32_e32 v90, v94, v135, vcc
	v_rsq_f32_e32 v94, v90
	v_mad_i64_i32 v[90:91], s[2:3], v139, s33, v[66:67]
	s_movk_i32 s2, 0x1ff7
	v_mul_f32_e32 v135, 0x45800000, v94
	v_cndmask_b32_e32 v94, v94, v135, vcc
	v_mul_f32_e32 v94, v24, v94
	v_mul_f32_e32 v94, v119, v94
	ds_bpermute_b32 v139, v116, v94
	global_load_dword v136, v[92:93], off offset:64
	global_load_dword v135, v[92:93], off
	global_load_dword v138, v[96:97], off offset:64
	global_load_dword v137, v[96:97], off
	v_cmp_gt_f32_e32 vcc, s75, v95
	ds_bpermute_b32 v93, v114, v75
	v_lshl_add_u64 v[90:91], v[90:91], 0, v[162:163]
	s_waitcnt lgkmcnt(1)
; DI int crow(int i, int hl) { return (i & 3) + 8 * (i >> 2) + 4 * hl; }
; DI void phase4(const Params& p, int l, unsigned char* smem) {
;     ...
;         float g = p.in[30][l * 32 + r] * QSCALE_MLA;
; #pragma unroll
;         for (int bm = 0; bm < 2; bm++)
; #pragma unroll
;           for (int bn = 0; bn < 2; bn++)
; #pragma unroll
;             for (int i = 0; i < 16; i++) {
;               const int head = (nt - 4) * 4 + wn * 2 + bn;
;               float a = acc[bm][bn][i];
;               float ss = red32(a * a); float rstd = rsqrtf(ss * (1.f / 32.f) + RMS_EPS);
;               float xn = a * rstd * g; float pt = __shfl_xor(xn, 16);
;               int row = m0 + wm * 64 + bm * 32 + crow(i, hl);
;               const float* rp = rope + pos_of(row) * 32;
;               float cs = rp[r & 15], sn = rp[16 + (r & 15)];
;               float o = (r & 16) ? (pt * sn + xn * cs) : (xn * cs - pt * sn);
;               QF[(size_t)row * 768 + head * 96 + 64 + r] = f2bf(o);
;             }
	v_mul_f32_e32 v92, v140, v139
	v_cndmask_b32_e64 v96, v92, -v92, s[6:7]
	v_mul_f32_e32 v92, 0x4b800000, v95
	v_cndmask_b32_e32 v92, v95, v92, vcc
	v_fmac_f32_e32 v96, v141, v94
	v_rsq_f32_e32 v94, v92
	ds_bpermute_b32 v92, v114, v74
	v_cvt_pk_bf16_f32 v96, v96, s0
	global_store_short v[90:91], v96, off offset:128
	v_mul_f32_e32 v95, 0x45800000, v94
	v_cndmask_b32_e32 v94, v94, v95, vcc
	v_mul_f32_e32 v97, v25, v94
	v_bitop3_b32 v94, v112, s2, v231 bitop3:0xc8
	v_cmp_gt_i32_e32 vcc, s50, v148
	v_mov_b32_e32 v95, v163
	s_waitcnt lgkmcnt(0)
	v_pk_add_f32 v[74:75], v[74:75], v[92:93]
	v_cndmask_b32_e32 v94, v219, v94, vcc
	v_lshlrev_b32_e32 v94, 7, v94
	v_lshl_add_u64 v[94:95], v[108:109], 0, v[94:95]
	global_load_dword v149, v[94:95], off offset:64
	global_load_dword v150, v[94:95], off
	ds_bpermute_b32 v92, v118, v74
	ds_bpermute_b32 v93, v118, v75
	v_mul_f32_e32 v97, v119, v97
	ds_bpermute_b32 v139, v116, v97
	s_waitcnt lgkmcnt(1)
	v_pk_add_f32 v[74:75], v[74:75], v[92:93]
	ds_bpermute_b32 v92, v117, v74
	ds_bpermute_b32 v93, v117, v75
	s_waitcnt vmcnt(11) lgkmcnt(2)
	v_mul_f32_e32 v96, v143, v139
	v_cndmask_b32_e64 v96, v96, -v96, s[6:7]
	s_waitcnt lgkmcnt(0)
	v_pk_add_f32 v[74:75], v[74:75], v[92:93]
	v_mad_i64_i32 v[92:93], s[2:3], v142, s33, v[66:67]
	v_lshl_add_u64 v[92:93], v[92:93], 0, v[162:163]
	s_waitcnt vmcnt(7)
	v_fmac_f32_e32 v96, v144, v97
	v_cvt_pk_bf16_f32 v139, v96, s0
	ds_bpermute_b32 v96, v116, v74
	ds_bpermute_b32 v97, v116, v75
	global_store_short v[92:93], v139, off offset:128
	s_waitcnt lgkmcnt(0)
	v_pk_add_f32 v[74:75], v[74:75], v[96:97]
	s_nop 0
	v_pk_fma_f32 v[96:97], v[74:75], s[12:13], v[64:65] op_sel_hi:[1,0,0]
	s_nop 0
	v_mul_f32_e32 v74, 0x4b800000, v96
	v_cmp_gt_f32_e32 vcc, s75, v96
	s_nop 1
	v_cndmask_b32_e32 v74, v96, v74, vcc
	v_rsq_f32_e32 v96, v74
	v_mad_i64_i32 v[74:75], s[2:3], v145, s33, v[66:67]
	s_movk_i32 s2, 0x1ffc
	v_mul_f32_e32 v139, 0x45800000, v96
	v_cndmask_b32_e32 v96, v96, v139, vcc
	v_mul_f32_e32 v96, v26, v96
	v_mul_f32_e32 v96, v119, v96
	ds_bpermute_b32 v143, v116, v96
	global_load_dword v140, v[94:95], off offset:64
	global_load_dword v139, v[94:95], off
	global_load_dword v142, v[98:99], off offset:64
	global_load_dword v141, v[98:99], off
	v_mov_b32_e32 v95, v163
	v_lshl_add_u64 v[74:75], v[74:75], 0, v[162:163]
	s_waitcnt lgkmcnt(0)
	v_mul_f32_e32 v94, v146, v143
	v_or_b32_e32 v146, v112, v232
	v_cndmask_b32_e64 v143, v94, -v94, s[6:7]
	v_bitop3_b32 v94, v112, s2, v232 bitop3:0xc8
	v_cmp_gt_i32_e32 vcc, s50, v146
	v_fmac_f32_e32 v143, v147, v96
	v_cvt_pk_bf16_f32 v143, v143, s0
	v_cndmask_b32_e32 v94, v221, v94, vcc
	v_lshlrev_b32_e32 v94, 7, v94
	v_lshl_add_u64 v[98:99], v[108:109], 0, v[94:95]
	v_mul_f32_e32 v94, 0x4b800000, v97
	v_cmp_gt_f32_e32 vcc, s75, v97
	ds_bpermute_b32 v95, v114, v73
	global_load_dword v151, v[98:99], off offset:64
	v_cndmask_b32_e32 v94, v97, v94, vcc
	v_rsq_f32_e32 v96, v94
	ds_bpermute_b32 v94, v114, v72
	global_store_short v[74:75], v143, off offset:128
	s_movk_i32 s2, 0x1ffd
	v_mul_f32_e32 v97, 0x45800000, v96
	v_cndmask_b32_e32 v96, v96, v97, vcc
	s_waitcnt lgkmcnt(0)
	v_pk_add_f32 v[72:73], v[72:73], v[94:95]
	ds_bpermute_b32 v94, v118, v72
	ds_bpermute_b32 v95, v118, v73
	v_mul_f32_e32 v144, v27, v96
	v_mul_f32_e32 v144, v119, v144
	ds_bpermute_b32 v145, v116, v144
	v_bitop3_b32 v96, v112, s2, v233 bitop3:0xc8
	s_waitcnt lgkmcnt(1)
	v_pk_add_f32 v[72:73], v[72:73], v[94:95]
	ds_bpermute_b32 v94, v117, v72
	ds_bpermute_b32 v95, v117, v73
	s_waitcnt vmcnt(8) lgkmcnt(2)
	v_mul_f32_e32 v143, v149, v145
	v_cndmask_b32_e64 v143, v143, -v143, s[6:7]
	s_waitcnt vmcnt(7)
	v_fmac_f32_e32 v143, v150, v144
	v_cmp_gt_i32_e32 vcc, s50, v153
	s_waitcnt lgkmcnt(0)
	v_pk_add_f32 v[72:73], v[72:73], v[94:95]
	ds_bpermute_b32 v144, v116, v72
	ds_bpermute_b32 v145, v116, v73
	v_cndmask_b32_e32 v96, v223, v96, vcc
	v_mad_i64_i32 v[94:95], s[2:3], v148, s33, v[66:67]
	v_cvt_pk_bf16_f32 v143, v143, s0
	s_waitcnt lgkmcnt(0)
	v_pk_add_f32 v[72:73], v[72:73], v[144:145]
	v_lshl_add_u64 v[94:95], v[94:95], 0, v[162:163]
	v_pk_fma_f32 v[144:145], v[72:73], s[12:13], v[64:65] op_sel_hi:[1,0,0]
	global_store_short v[94:95], v143, off offset:128
	v_mul_f32_e32 v72, 0x4b800000, v144
	v_cmp_gt_f32_e32 vcc, s75, v144
	v_or_b32_e32 v150, v112, v234
	v_cmp_gt_i32_e64 s[8:9], s50, v150
	v_cndmask_b32_e32 v72, v144, v72, vcc
	v_rsq_f32_e32 v143, v72
	v_mad_i64_i32 v[72:73], s[2:3], v146, s33, v[66:67]
	s_movk_i32 s2, 0x1ffe
	s_nop 0
	v_bitop3_b32 v146, v112, s2, v234 bitop3:0xc8
	v_cndmask_b32_e64 v146, v225, v146, s[8:9]
	v_lshlrev_b32_e32 v146, 7, v146
	v_mov_b32_e32 v147, v163
	v_mul_f32_e32 v144, 0x45800000, v143
	v_lshl_add_u64 v[146:147], v[108:109], 0, v[146:147]
	global_load_dword v156, v[146:147], off offset:64
	v_cndmask_b32_e32 v143, v143, v144, vcc
	global_load_dword v144, v[146:147], off
	global_load_dword v152, v[98:99], off
	v_lshlrev_b32_e32 v96, 7, v96
	v_mov_b32_e32 v97, v163
	v_lshl_add_u64 v[96:97], v[108:109], 0, v[96:97]
	global_load_dword v154, v[96:97], off offset:64
	global_load_dword v155, v[96:97], off
	v_mul_f32_e32 v143, v28, v143
	v_mul_f32_e32 v143, v119, v143
	s_movk_i32 s2, 0x1fff
	ds_bpermute_b32 v157, v116, v143
	v_bitop3_b32 v112, v112, s2, v235 bitop3:0xc8
	v_cmp_gt_i32_e32 vcc, s50, v158
	v_mov_b32_e32 v149, v163
	v_lshl_add_u64 v[72:73], v[72:73], 0, v[162:163]
	v_cndmask_b32_e32 v112, v227, v112, vcc
	v_lshlrev_b32_e32 v148, 7, v112
	v_lshl_add_u64 v[148:149], v[108:109], 0, v[148:149]
	global_load_dword v112, v[148:149], off offset:64
	global_load_dword v164, v[96:97], off offset:64
	global_load_dword v165, v[96:97], off
	global_load_dword v166, v[98:99], off offset:64
	global_load_dword v167, v[98:99], off
	v_cmp_gt_f32_e32 vcc, s75, v145
	ds_bpermute_b32 v97, v114, v71
	s_waitcnt vmcnt(12) lgkmcnt(1)
; DI int crow(int i, int hl) { return (i & 3) + 8 * (i >> 2) + 4 * hl; }
; DI void phase4(const Params& p, int l, unsigned char* smem) {
;     ...
;         float g = p.in[30][l * 32 + r] * QSCALE_MLA;
; #pragma unroll
;         for (int bm = 0; bm < 2; bm++)
; #pragma unroll
;           for (int bn = 0; bn < 2; bn++)
; #pragma unroll
;             for (int i = 0; i < 16; i++) {
;               const int head = (nt - 4) * 4 + wn * 2 + bn;
;               float a = acc[bm][bn][i];
;               float ss = red32(a * a); float rstd = rsqrtf(ss * (1.f / 32.f) + RMS_EPS);
;               float xn = a * rstd * g; float pt = __shfl_xor(xn, 16);
;               int row = m0 + wm * 64 + bm * 32 + crow(i, hl);
;               const float* rp = rope + pos_of(row) * 32;
;               float cs = rp[r & 15], sn = rp[16 + (r & 15)];
;               float o = (r & 16) ? (pt * sn + xn * cs) : (xn * cs - pt * sn);
;               QF[(size_t)row * 768 + head * 96 + 64 + r] = f2bf(o);
;             }
	v_mul_f32_e32 v96, v151, v157
	global_load_dword v151, v[148:149], off
	v_cndmask_b32_e64 v98, v96, -v96, s[6:7]
	v_mul_f32_e32 v96, 0x4b800000, v145
	v_cndmask_b32_e32 v96, v145, v96, vcc
	v_rsq_f32_e32 v99, v96
	ds_bpermute_b32 v96, v114, v70
	s_waitcnt lgkmcnt(0)
	v_pk_add_f32 v[70:71], v[70:71], v[96:97]
	ds_bpermute_b32 v96, v118, v70
	ds_bpermute_b32 v97, v118, v71
	s_waitcnt lgkmcnt(0)
	v_pk_add_f32 v[70:71], v[70:71], v[96:97]
	ds_bpermute_b32 v96, v117, v70
	ds_bpermute_b32 v97, v117, v71
	s_waitcnt lgkmcnt(0)
	v_pk_add_f32 v[70:71], v[70:71], v[96:97]
	v_mad_i64_i32 v[96:97], s[2:3], v153, s33, v[66:67]
	v_lshl_add_u64 v[96:97], v[96:97], 0, v[162:163]
	s_waitcnt vmcnt(8)
	v_fmac_f32_e32 v98, v152, v143
	v_mul_f32_e32 v143, 0x45800000, v99
	v_cndmask_b32_e32 v99, v99, v143, vcc
	v_mul_f32_e32 v99, v29, v99
	v_mul_f32_e32 v99, v119, v99
	ds_bpermute_b32 v143, v116, v99
	v_cvt_pk_bf16_f32 v98, v98, s0
	global_store_short v[72:73], v98, off offset:128
	v_pk_mul_f32 v[152:153], v[2:3], v[2:3]
	ds_bpermute_b32 v152, v115, v152
	s_waitcnt vmcnt(8) lgkmcnt(1)
	v_mul_f32_e32 v98, v154, v143
	v_cndmask_b32_e64 v98, v98, -v98, s[6:7]
	s_waitcnt vmcnt(7)
	v_fmac_f32_e32 v98, v155, v99
	v_cvt_pk_bf16_f32 v143, v98, s0
	ds_bpermute_b32 v98, v116, v70
	ds_bpermute_b32 v99, v116, v71
	global_store_short v[96:97], v143, off offset:128
	global_load_dword v168, v[148:149], off offset:64
	global_load_dword v169, v[148:149], off
	global_load_dword v170, v[146:147], off offset:64
	global_load_dword v171, v[146:147], off
	ds_bpermute_b32 v153, v115, v153
	v_pk_mul_f32 v[148:149], v[12:13], v[12:13]
	s_waitcnt lgkmcnt(1)
	v_pk_add_f32 v[70:71], v[70:71], v[98:99]
	s_waitcnt lgkmcnt(0)
	v_pk_fma_f32 v[152:153], v[2:3], v[2:3], v[152:153]
	v_pk_fma_f32 v[98:99], v[70:71], s[12:13], v[64:65] op_sel_hi:[1,0,0]
	ds_bpermute_b32 v154, v114, v152
	v_mul_f32_e32 v70, 0x4b800000, v98
	v_cmp_gt_f32_e32 vcc, s75, v98
	ds_bpermute_b32 v155, v114, v153
	s_waitcnt lgkmcnt(0)
	v_pk_add_f32 v[152:153], v[152:153], v[154:155]
	v_cndmask_b32_e32 v70, v98, v70, vcc
	v_rsq_f32_e32 v98, v70
	v_mad_i64_i32 v[70:71], s[2:3], v150, s33, v[66:67]
	v_lshl_add_u64 v[70:71], v[70:71], 0, v[162:163]
	v_mul_f32_e32 v143, 0x45800000, v98
	v_cndmask_b32_e32 v98, v98, v143, vcc
	v_mul_f32_e32 v98, v30, v98
	v_mul_f32_e32 v143, v119, v98
	v_mul_f32_e32 v98, 0x4b800000, v99
	v_cmp_gt_f32_e32 vcc, s75, v99
	ds_bpermute_b32 v145, v116, v143
	v_mad_i64_i32 v[66:67], s[2:3], v158, s33, v[66:67]
	v_cndmask_b32_e32 v98, v99, v98, vcc
	v_rsq_f32_e32 v150, v98
	v_pk_mul_f32 v[98:99], v[0:1], v[0:1]
	ds_bpermute_b32 v98, v115, v98
	ds_bpermute_b32 v99, v115, v99
	s_waitcnt lgkmcnt(2)
	v_mul_f32_e32 v145, v156, v145
	v_cndmask_b32_e64 v146, v145, -v145, s[6:7]
	v_fmac_f32_e32 v146, v144, v143
	v_mul_f32_e32 v143, 0x45800000, v150
	s_waitcnt lgkmcnt(0)
	v_pk_fma_f32 v[98:99], v[0:1], v[0:1], v[98:99]
	ds_bpermute_b32 v144, v114, v98
	ds_bpermute_b32 v145, v114, v99
	v_cndmask_b32_e32 v143, v150, v143, vcc
	v_mul_f32_e32 v143, v31, v143
	v_mul_f32_e32 v143, v119, v143
	ds_bpermute_b32 v147, v116, v143
	s_waitcnt lgkmcnt(1)
	v_pk_add_f32 v[98:99], v[98:99], v[144:145]
	ds_bpermute_b32 v144, v118, v98
	ds_bpermute_b32 v145, v118, v99
	v_cvt_pk_bf16_f32 v146, v146, s0
	global_store_short v[70:71], v146, off offset:128
	s_waitcnt vmcnt(12) lgkmcnt(2)
	v_mul_f32_e32 v112, v112, v147
	v_cndmask_b32_e64 v112, v112, -v112, s[6:7]
	s_waitcnt lgkmcnt(0)
	v_pk_add_f32 v[98:99], v[98:99], v[144:145]
	ds_bpermute_b32 v144, v117, v98
	ds_bpermute_b32 v145, v117, v99
	s_waitcnt vmcnt(7)
	v_fmac_f32_e32 v112, v151, v143
	v_cvt_pk_bf16_f32 v112, v112, s0
	v_lshl_add_u64 v[66:67], v[66:67], 0, v[162:163]
	global_store_short v[66:67], v112, off offset:128
	s_waitcnt lgkmcnt(0)
	v_pk_add_f32 v[144:145], v[98:99], v[144:145]
	ds_bpermute_b32 v146, v116, v144
	ds_bpermute_b32 v147, v116, v145
	ds_bpermute_b32 v154, v118, v152
	ds_bpermute_b32 v155, v118, v153
	v_pk_mul_f32 v[158:159], v[4:5], v[4:5]
	v_pk_mul_f32 v[156:157], v[6:7], v[6:7]
	s_waitcnt lgkmcnt(2)
	v_pk_add_f32 v[144:145], v[144:145], v[146:147]
	v_pk_mul_f32 v[150:151], v[8:9], v[8:9]
	v_pk_fma_f32 v[144:145], v[144:145], s[12:13], v[64:65] op_sel_hi:[1,0,0]
	v_pk_mul_f32 v[146:147], v[10:11], v[10:11]
	v_mul_f32_e32 v112, 0x4b800000, v144
	v_cmp_gt_f32_e32 vcc, s75, v144
	v_pk_mul_f32 v[98:99], v[14:15], v[14:15]
	s_mov_b64 s[2:3], 0
	v_cndmask_b32_e32 v112, v144, v112, vcc
	v_rsq_f32_e32 v112, v112
	s_nop 0
	v_mul_f32_e32 v143, 0x45800000, v112
	v_cndmask_b32_e32 v112, v112, v143, vcc
	v_mul_f32_e32 v112, v0, v112
	v_mul_f32_e32 v112, v119, v112
	ds_bpermute_b32 v143, v116, v112
	v_cmp_gt_f32_e32 vcc, s75, v145
	s_waitcnt lgkmcnt(0)
	v_mul_f32_e32 v122, v122, v143
	v_mul_f32_e32 v143, 0x4b800000, v145
	v_cndmask_b32_e32 v143, v145, v143, vcc
	v_pk_add_f32 v[144:145], v[152:153], v[154:155]
	v_rsq_f32_e32 v143, v143
	ds_bpermute_b32 v152, v117, v144
	ds_bpermute_b32 v153, v117, v145
	v_cndmask_b32_e64 v122, v122, -v122, s[6:7]
	v_fmac_f32_e32 v122, v121, v112
	v_cvt_pk_bf16_f32 v112, v122, s0
	global_store_short v[68:69], v112, off offset:320
	v_mul_f32_e32 v112, 0x45800000, v143
	s_waitcnt lgkmcnt(0)
	v_pk_add_f32 v[68:69], v[144:145], v[152:153]
	v_cndmask_b32_e32 v112, v143, v112, vcc
	ds_bpermute_b32 v144, v116, v68
	ds_bpermute_b32 v145, v116, v69
	v_mul_f32_e32 v112, v1, v112
	v_mul_f32_e32 v112, v119, v112
	ds_bpermute_b32 v121, v116, v112
	s_waitcnt lgkmcnt(1)
	v_pk_add_f32 v[68:69], v[68:69], v[144:145]
	s_nop 0
	v_pk_fma_f32 v[68:69], v[68:69], s[12:13], v[64:65] op_sel_hi:[1,0,0]
	s_waitcnt lgkmcnt(0)
; DI int crow(int i, int hl) { return (i & 3) + 8 * (i >> 2) + 4 * hl; }
; DI void phase4(const Params& p, int l, unsigned char* smem) {
;     ...
;         float g = p.in[30][l * 32 + r] * QSCALE_MLA;
; #pragma unroll
;         for (int bm = 0; bm < 2; bm++)
; #pragma unroll
;           for (int bn = 0; bn < 2; bn++)
; #pragma unroll
;             for (int i = 0; i < 16; i++) {
;               const int head = (nt - 4) * 4 + wn * 2 + bn;
;               float a = acc[bm][bn][i];
;               float ss = red32(a * a); float rstd = rsqrtf(ss * (1.f / 32.f) + RMS_EPS);
;               float xn = a * rstd * g; float pt = __shfl_xor(xn, 16);
;               int row = m0 + wm * 64 + bm * 32 + crow(i, hl);
;               const float* rp = rope + pos_of(row) * 32;
;               float cs = rp[r & 15], sn = rp[16 + (r & 15)];
;               float o = (r & 16) ? (pt * sn + xn * cs) : (xn * cs - pt * sn);
;               QF[(size_t)row * 768 + head * 96 + 64 + r] = f2bf(o);
;             }
	v_mul_f32_e32 v120, v120, v121
	v_mul_f32_e32 v122, 0x4b800000, v68
	v_cmp_gt_f32_e32 vcc, s75, v68
	s_nop 1
	v_cndmask_b32_e32 v68, v68, v122, vcc
	v_cndmask_b32_e64 v122, v120, -v120, s[6:7]
	v_fmac_f32_e32 v122, v113, v112
	ds_bpermute_b32 v112, v115, v158
	ds_bpermute_b32 v113, v115, v159
	v_rsq_f32_e32 v68, v68
	v_cvt_pk_bf16_f32 v122, v122, s0
	global_store_short v[80:81], v122, off offset:320
	v_mul_f32_e32 v120, 0x45800000, v68
	s_waitcnt lgkmcnt(0)
	v_pk_fma_f32 v[112:113], v[4:5], v[4:5], v[112:113]
	v_cndmask_b32_e32 v68, v68, v120, vcc
	ds_bpermute_b32 v120, v114, v112
	ds_bpermute_b32 v121, v114, v113
	v_mul_f32_e32 v68, v2, v68
	v_mul_f32_e32 v143, v119, v68
	ds_bpermute_b32 v68, v116, v143
	v_cmp_gt_f32_e32 vcc, s75, v69
	s_waitcnt lgkmcnt(1)
	v_pk_add_f32 v[80:81], v[112:113], v[120:121]
	ds_bpermute_b32 v112, v118, v80
	ds_bpermute_b32 v113, v118, v81
	s_waitcnt lgkmcnt(2)
	v_mul_f32_e32 v68, v126, v68
	v_cndmask_b32_e64 v122, v68, -v68, s[6:7]
	v_mul_f32_e32 v68, 0x4b800000, v69
	v_cndmask_b32_e32 v68, v69, v68, vcc
	v_rsq_f32_e32 v120, v68
	s_waitcnt lgkmcnt(0)
	v_pk_add_f32 v[68:69], v[80:81], v[112:113]
	ds_bpermute_b32 v80, v117, v68
	ds_bpermute_b32 v81, v117, v69
	v_fmac_f32_e32 v122, v125, v143
	v_cvt_pk_bf16_f32 v112, v122, s0
	global_store_short v[78:79], v112, off offset:320
	v_mul_f32_e32 v112, 0x45800000, v120
	s_waitcnt lgkmcnt(0)
	v_pk_add_f32 v[68:69], v[68:69], v[80:81]
	ds_bpermute_b32 v78, v116, v68
	ds_bpermute_b32 v79, v116, v69
	v_cndmask_b32_e32 v80, v120, v112, vcc
	v_mul_f32_e32 v80, v3, v80
	v_mul_f32_e32 v80, v119, v80
	ds_bpermute_b32 v81, v116, v80
	s_waitcnt lgkmcnt(1)
	v_pk_add_f32 v[68:69], v[68:69], v[78:79]
	ds_bpermute_b32 v79, v115, v157
	v_pk_fma_f32 v[68:69], v[68:69], s[12:13], v[64:65] op_sel_hi:[1,0,0]
	s_nop 0
	v_mul_f32_e32 v78, 0x4b800000, v68
	v_cmp_gt_f32_e32 vcc, s75, v68
	s_nop 1
	v_cndmask_b32_e32 v68, v68, v78, vcc
	s_waitcnt lgkmcnt(1)
	v_mul_f32_e32 v78, v124, v81
	v_cndmask_b32_e64 v112, v78, -v78, s[6:7]
	ds_bpermute_b32 v78, v115, v156
	v_rsq_f32_e32 v68, v68
	v_fmac_f32_e32 v112, v123, v80
	v_cvt_pk_bf16_f32 v112, v112, s0
	global_store_short v[86:87], v112, off offset:320
	v_mul_f32_e32 v80, 0x45800000, v68
	s_waitcnt lgkmcnt(0)
	v_pk_fma_f32 v[78:79], v[6:7], v[6:7], v[78:79]
	v_cndmask_b32_e32 v68, v68, v80, vcc
	ds_bpermute_b32 v80, v114, v78
	ds_bpermute_b32 v81, v114, v79
	v_mul_f32_e32 v68, v4, v68
	v_mul_f32_e32 v113, v119, v68
	ds_bpermute_b32 v68, v116, v113
	v_cmp_gt_f32_e32 vcc, s75, v69
	s_waitcnt lgkmcnt(1)
	v_pk_add_f32 v[78:79], v[78:79], v[80:81]
	ds_bpermute_b32 v80, v118, v78
	ds_bpermute_b32 v81, v118, v79
	s_waitcnt lgkmcnt(2)
	v_mul_f32_e32 v68, v130, v68
	v_cndmask_b32_e64 v86, v68, -v68, s[6:7]
	v_mul_f32_e32 v68, 0x4b800000, v69
	v_cndmask_b32_e32 v68, v69, v68, vcc
	v_rsq_f32_e32 v87, v68
	s_waitcnt lgkmcnt(0)
	v_pk_add_f32 v[68:69], v[78:79], v[80:81]
	ds_bpermute_b32 v78, v117, v68
	ds_bpermute_b32 v79, v117, v69
	v_fmac_f32_e32 v86, v129, v113
	v_cvt_pk_bf16_f32 v80, v86, s0
	global_store_short v[84:85], v80, off offset:320
	v_mul_f32_e32 v80, 0x45800000, v87
	s_waitcnt lgkmcnt(0)
	v_pk_add_f32 v[68:69], v[68:69], v[78:79]
	ds_bpermute_b32 v78, v116, v68
	ds_bpermute_b32 v79, v116, v69
	v_cndmask_b32_e32 v80, v87, v80, vcc
	v_mul_f32_e32 v80, v5, v80
	v_mul_f32_e32 v80, v119, v80
	ds_bpermute_b32 v81, v116, v80
	s_waitcnt lgkmcnt(1)
	v_pk_add_f32 v[68:69], v[68:69], v[78:79]
	ds_bpermute_b32 v79, v115, v151
	v_pk_fma_f32 v[68:69], v[68:69], s[12:13], v[64:65] op_sel_hi:[1,0,0]
	s_nop 0
	v_mul_f32_e32 v78, 0x4b800000, v68
	v_cmp_gt_f32_e32 vcc, s75, v68
	s_nop 1
	v_cndmask_b32_e32 v68, v68, v78, vcc
	s_waitcnt lgkmcnt(1)
	v_mul_f32_e32 v78, v128, v81
	v_cndmask_b32_e64 v84, v78, -v78, s[6:7]
	ds_bpermute_b32 v78, v115, v150
	v_rsq_f32_e32 v68, v68
	v_fmac_f32_e32 v84, v127, v80
	v_cvt_pk_bf16_f32 v84, v84, s0
	global_store_short v[88:89], v84, off offset:320
	v_mul_f32_e32 v80, 0x45800000, v68
	s_waitcnt lgkmcnt(0)
	v_pk_fma_f32 v[78:79], v[8:9], v[8:9], v[78:79]
	v_cndmask_b32_e32 v68, v68, v80, vcc
	ds_bpermute_b32 v80, v114, v78
	ds_bpermute_b32 v81, v114, v79
	v_mul_f32_e32 v68, v6, v68
	v_mul_f32_e32 v85, v119, v68
	ds_bpermute_b32 v68, v116, v85
	v_cmp_gt_f32_e32 vcc, s75, v69
	s_waitcnt lgkmcnt(1)
	v_pk_add_f32 v[78:79], v[78:79], v[80:81]
	ds_bpermute_b32 v80, v118, v78
	ds_bpermute_b32 v81, v118, v79
	s_waitcnt lgkmcnt(2)
	v_mul_f32_e32 v68, v134, v68
	v_cndmask_b32_e64 v84, v68, -v68, s[6:7]
	v_mul_f32_e32 v68, 0x4b800000, v69
	v_cndmask_b32_e32 v68, v69, v68, vcc
	v_rsq_f32_e32 v86, v68
	s_waitcnt lgkmcnt(0)
	v_pk_add_f32 v[68:69], v[78:79], v[80:81]
	ds_bpermute_b32 v78, v117, v68
	ds_bpermute_b32 v79, v117, v69
	v_fmac_f32_e32 v84, v133, v85
	v_cvt_pk_bf16_f32 v80, v84, s0
	global_store_short v[82:83], v80, off offset:320
	v_mul_f32_e32 v80, 0x45800000, v86
	s_waitcnt lgkmcnt(0)
	v_pk_add_f32 v[68:69], v[68:69], v[78:79]
	ds_bpermute_b32 v78, v116, v68
	ds_bpermute_b32 v79, v116, v69
	v_cndmask_b32_e32 v80, v86, v80, vcc
	v_mul_f32_e32 v80, v7, v80
	v_mul_f32_e32 v80, v119, v80
	ds_bpermute_b32 v81, v116, v80
	s_waitcnt lgkmcnt(1)
	v_pk_add_f32 v[68:69], v[68:69], v[78:79]
	ds_bpermute_b32 v79, v115, v147
	v_pk_fma_f32 v[68:69], v[68:69], s[12:13], v[64:65] op_sel_hi:[1,0,0]
	s_nop 0
	v_mul_f32_e32 v78, 0x4b800000, v68
	v_cmp_gt_f32_e32 vcc, s75, v68
	s_nop 1
	v_cndmask_b32_e32 v68, v68, v78, vcc
	s_waitcnt lgkmcnt(1)
	v_mul_f32_e32 v78, v132, v81
	v_cndmask_b32_e64 v82, v78, -v78, s[6:7]
	ds_bpermute_b32 v78, v115, v146
	v_rsq_f32_e32 v68, v68
	v_fmac_f32_e32 v82, v131, v80
	v_cvt_pk_bf16_f32 v82, v82, s0
	global_store_short v[76:77], v82, off offset:320
	v_mul_f32_e32 v80, 0x45800000, v68
	s_waitcnt lgkmcnt(0)
; DI int crow(int i, int hl) { return (i & 3) + 8 * (i >> 2) + 4 * hl; }
; DI void phase4(const Params& p, int l, unsigned char* smem) {
;     ...
;         float g = p.in[30][l * 32 + r] * QSCALE_MLA;
; #pragma unroll
;         for (int bm = 0; bm < 2; bm++)
; #pragma unroll
;           for (int bn = 0; bn < 2; bn++)
; #pragma unroll
;             for (int i = 0; i < 16; i++) {
;               const int head = (nt - 4) * 4 + wn * 2 + bn;
;               float a = acc[bm][bn][i];
;               float ss = red32(a * a); float rstd = rsqrtf(ss * (1.f / 32.f) + RMS_EPS);
;               float xn = a * rstd * g; float pt = __shfl_xor(xn, 16);
;               int row = m0 + wm * 64 + bm * 32 + crow(i, hl);
;               const float* rp = rope + pos_of(row) * 32;
;               float cs = rp[r & 15], sn = rp[16 + (r & 15)];
;               float o = (r & 16) ? (pt * sn + xn * cs) : (xn * cs - pt * sn);
;               QF[(size_t)row * 768 + head * 96 + 64 + r] = f2bf(o);
;             }
	v_pk_fma_f32 v[78:79], v[10:11], v[10:11], v[78:79]
	v_cndmask_b32_e32 v68, v68, v80, vcc
	ds_bpermute_b32 v80, v114, v78
	ds_bpermute_b32 v81, v114, v79
	v_mul_f32_e32 v68, v8, v68
	v_mul_f32_e32 v83, v119, v68
	ds_bpermute_b32 v68, v116, v83
	v_cmp_gt_f32_e32 vcc, s75, v69
	s_waitcnt lgkmcnt(1)
	v_pk_add_f32 v[76:77], v[78:79], v[80:81]
	ds_bpermute_b32 v78, v118, v76
	ds_bpermute_b32 v79, v118, v77
	s_waitcnt lgkmcnt(2)
	v_mul_f32_e32 v68, v138, v68
	v_cndmask_b32_e64 v82, v68, -v68, s[6:7]
	v_mul_f32_e32 v68, 0x4b800000, v69
	v_cndmask_b32_e32 v68, v69, v68, vcc
	v_rsq_f32_e32 v80, v68
	s_waitcnt lgkmcnt(0)
	v_pk_add_f32 v[68:69], v[76:77], v[78:79]
	ds_bpermute_b32 v76, v117, v68
	ds_bpermute_b32 v77, v117, v69
	v_fmac_f32_e32 v82, v137, v83
	v_cvt_pk_bf16_f32 v78, v82, s0
	global_store_short v[90:91], v78, off offset:320
	v_mul_f32_e32 v78, 0x45800000, v80
	s_waitcnt lgkmcnt(0)
	v_pk_add_f32 v[68:69], v[68:69], v[76:77]
	ds_bpermute_b32 v76, v116, v68
	ds_bpermute_b32 v77, v116, v69
	v_cndmask_b32_e32 v78, v80, v78, vcc
	v_mul_f32_e32 v78, v9, v78
	v_mul_f32_e32 v78, v119, v78
	ds_bpermute_b32 v79, v116, v78
	s_waitcnt lgkmcnt(1)
	v_pk_add_f32 v[68:69], v[68:69], v[76:77]
	ds_bpermute_b32 v77, v115, v149
	v_pk_fma_f32 v[68:69], v[68:69], s[12:13], v[64:65] op_sel_hi:[1,0,0]
	s_nop 0
	v_mul_f32_e32 v76, 0x4b800000, v68
	v_cmp_gt_f32_e32 vcc, s75, v68
	s_nop 1
	v_cndmask_b32_e32 v68, v68, v76, vcc
	s_waitcnt lgkmcnt(1)
	v_mul_f32_e32 v76, v136, v79
	v_cndmask_b32_e64 v80, v76, -v76, s[6:7]
	ds_bpermute_b32 v76, v115, v148
	v_rsq_f32_e32 v68, v68
	v_fmac_f32_e32 v80, v135, v78
	v_cvt_pk_bf16_f32 v80, v80, s0
	global_store_short v[92:93], v80, off offset:320
	v_mul_f32_e32 v78, 0x45800000, v68
	s_waitcnt lgkmcnt(0)
	v_pk_fma_f32 v[76:77], v[12:13], v[12:13], v[76:77]
	v_cndmask_b32_e32 v68, v68, v78, vcc
	ds_bpermute_b32 v78, v114, v76
	ds_bpermute_b32 v79, v114, v77
	v_mul_f32_e32 v68, v10, v68
	v_mul_f32_e32 v81, v119, v68
	ds_bpermute_b32 v68, v116, v81
	v_cmp_gt_f32_e32 vcc, s75, v69
	s_waitcnt lgkmcnt(1)
	v_pk_add_f32 v[76:77], v[76:77], v[78:79]
	ds_bpermute_b32 v78, v118, v76
	ds_bpermute_b32 v79, v118, v77
	s_waitcnt lgkmcnt(2)
	v_mul_f32_e32 v68, v142, v68
	v_cndmask_b32_e64 v80, v68, -v68, s[6:7]
	v_mul_f32_e32 v68, 0x4b800000, v69
	v_cndmask_b32_e32 v68, v69, v68, vcc
	v_rsq_f32_e32 v82, v68
	s_waitcnt lgkmcnt(0)
	v_pk_add_f32 v[68:69], v[76:77], v[78:79]
	ds_bpermute_b32 v76, v117, v68
	ds_bpermute_b32 v77, v117, v69
	v_fmac_f32_e32 v80, v141, v81
	v_cvt_pk_bf16_f32 v78, v80, s0
	global_store_short v[74:75], v78, off offset:320
	v_mul_f32_e32 v78, 0x45800000, v82
	s_waitcnt lgkmcnt(0)
	v_pk_add_f32 v[68:69], v[68:69], v[76:77]
	ds_bpermute_b32 v74, v116, v68
	ds_bpermute_b32 v75, v116, v69
	v_cndmask_b32_e32 v76, v82, v78, vcc
	v_mul_f32_e32 v76, v11, v76
	v_mul_f32_e32 v76, v119, v76
	ds_bpermute_b32 v77, v116, v76
	s_waitcnt lgkmcnt(1)
	v_pk_add_f32 v[68:69], v[68:69], v[74:75]
	ds_bpermute_b32 v75, v115, v99
	v_pk_fma_f32 v[68:69], v[68:69], s[12:13], v[64:65] op_sel_hi:[1,0,0]
	s_nop 0
	v_mul_f32_e32 v74, 0x4b800000, v68
	v_cmp_gt_f32_e32 vcc, s75, v68
	s_nop 1
	v_cndmask_b32_e32 v68, v68, v74, vcc
	s_waitcnt lgkmcnt(1)
	v_mul_f32_e32 v74, v140, v77
	v_cndmask_b32_e64 v78, v74, -v74, s[6:7]
	ds_bpermute_b32 v74, v115, v98
	v_rsq_f32_e32 v68, v68
	v_fmac_f32_e32 v78, v139, v76
	v_cvt_pk_bf16_f32 v78, v78, s0
	global_store_short v[94:95], v78, off offset:320
	v_mul_f32_e32 v76, 0x45800000, v68
	s_waitcnt lgkmcnt(0)
	v_pk_fma_f32 v[74:75], v[14:15], v[14:15], v[74:75]
	v_cndmask_b32_e32 v68, v68, v76, vcc
	ds_bpermute_b32 v76, v114, v74
	ds_bpermute_b32 v77, v114, v75
	v_mul_f32_e32 v68, v12, v68
	v_mul_f32_e32 v79, v119, v68
	ds_bpermute_b32 v68, v116, v79
	v_cmp_gt_f32_e32 vcc, s75, v69
	s_waitcnt lgkmcnt(1)
	v_pk_add_f32 v[74:75], v[74:75], v[76:77]
	ds_bpermute_b32 v76, v118, v74
	ds_bpermute_b32 v77, v118, v75
	s_waitcnt lgkmcnt(2)
	v_mul_f32_e32 v68, v166, v68
	v_cndmask_b32_e64 v78, v68, -v68, s[6:7]
	v_mul_f32_e32 v68, 0x4b800000, v69
	v_cndmask_b32_e32 v68, v69, v68, vcc
	v_rsq_f32_e32 v80, v68
	s_waitcnt lgkmcnt(0)
	v_pk_add_f32 v[68:69], v[74:75], v[76:77]
	ds_bpermute_b32 v74, v117, v68
	ds_bpermute_b32 v75, v117, v69
	v_fmac_f32_e32 v78, v167, v79
	v_cvt_pk_bf16_f32 v76, v78, s0
	global_store_short v[72:73], v76, off offset:320
	v_mul_f32_e32 v76, 0x45800000, v80
	s_waitcnt lgkmcnt(0)
	v_pk_add_f32 v[68:69], v[68:69], v[74:75]
	ds_bpermute_b32 v72, v116, v68
	ds_bpermute_b32 v73, v116, v69
	v_cndmask_b32_e32 v74, v80, v76, vcc
	v_mul_f32_e32 v74, v13, v74
	v_mul_f32_e32 v74, v119, v74
	ds_bpermute_b32 v75, v116, v74
	s_waitcnt lgkmcnt(1)
	v_pk_add_f32 v[68:69], v[68:69], v[72:73]
	s_nop 0
	v_pk_fma_f32 v[64:65], v[68:69], s[12:13], v[64:65] op_sel_hi:[1,0,0]
	s_nop 0
	v_mul_f32_e32 v68, 0x4b800000, v64
	v_cmp_gt_f32_e32 vcc, s75, v64
	v_mul_f32_e32 v72, 0x4b800000, v65
	s_nop 0
	v_cndmask_b32_e32 v64, v64, v68, vcc
	v_rsq_f32_e32 v64, v64
	s_waitcnt lgkmcnt(0)
	v_mul_f32_e32 v68, v164, v75
	v_cndmask_b32_e64 v68, v68, -v68, s[6:7]
	v_fmac_f32_e32 v68, v165, v74
	v_mul_f32_e32 v69, 0x45800000, v64
	v_cndmask_b32_e32 v64, v64, v69, vcc
	v_mul_f32_e32 v64, v14, v64
	v_mul_f32_e32 v64, v119, v64
	v_cmp_gt_f32_e32 vcc, s75, v65
	ds_bpermute_b32 v69, v116, v64
	v_cvt_pk_bf16_f32 v68, v68, s0
	v_cndmask_b32_e32 v65, v65, v72, vcc
	v_rsq_f32_e32 v65, v65
	global_store_short v[96:97], v68, off offset:320
	s_waitcnt vmcnt(17) lgkmcnt(0)
	v_mul_f32_e32 v68, v170, v69
	v_cndmask_b32_e64 v68, v68, -v68, s[6:7]
	v_mul_f32_e32 v69, 0x45800000, v65
	v_cndmask_b32_e32 v65, v65, v69, vcc
	v_mul_f32_e32 v65, v15, v65
	v_mul_f32_e32 v65, v119, v65
	ds_bpermute_b32 v69, v116, v65
	s_waitcnt vmcnt(16)
	v_fmac_f32_e32 v68, v171, v64
	v_cvt_pk_bf16_f32 v64, v68, s0
	global_store_short v[70:71], v64, off offset:320
	s_waitcnt lgkmcnt(0)
	v_mul_f32_e32 v64, v168, v69
	v_cndmask_b32_e64 v64, v64, -v64, s[6:7]
	v_fmac_f32_e32 v64, v169, v65
	v_cvt_pk_bf16_f32 v64, v64, s0
	global_store_short v[66:67], v64, off offset:320

; #define MFMA32(a, b, c) __builtin_amdgcn_mfma_f32_32x32x16_bf16((a), (b), (c), 0, 0, 0)
; template <int DK, bool SB> ...
;     ...
;     f32x16 S[2];
; #pragma unroll
;     for (int kb = 0; kb < 2; kb++) {
; #pragma unroll
;       for (int i = 0; i < 16; i++) S[kb][i] = 0.f;
; #pragma unroll
;       for (int ks = 0; ks < KS; ks++) {
;         bf16x8 kf = *(const bf16x8*)(sK + (kb * 32 + r) * KSTR + ks * 16 + hl * 8);
;         S[kb] = MFMA32(kf, qf[ks], S[kb]);
;       }
;     }
;     const int key0 = kt * 64 + 4 * hl;
;     if (!SB) {
;       const bool need_mask = (kt + 1) * 64 > nkeys;
;       if (need_mask) {
; #pragma unroll
;         for (int kb = 0; kb < 2; kb++)
; #pragma unroll
;           for (int i = 0; i < 16; i++) { int key = key0 + kb * 32 + (i & 3) + 8 * (i >> 2); if (key >= nkeys) S[kb][i] = -1e30f; }
.LBB0_802:
	s_bitcmp1_b32 s46, 0
	s_cselect_b32 s6, 0x5800, 0
	v_or_b32_e32 v133, s6, v118
	v_add_u32_e32 v134, v133, v127
	ds_read_b128 v[176:179], v134
	ds_read_b128 v[180:183], v134 offset:32
	ds_read_b128 v[190:193], v134 offset:64
	ds_read_b128 v[208:211], v134 offset:6688
	ds_read_b128 v[212:215], v134 offset:96
	ds_read_b128 v[216:219], v134 offset:128
	ds_read_b128 v[220:223], v134 offset:160
	ds_read_b128 v[224:227], v134 offset:6656
	ds_read_b128 v[228:231], v134 offset:6720
	s_cmp_le_i32 s42, s51
	s_waitcnt vmcnt(10) lgkmcnt(8)
	v_mfma_f32_32x32x16_bf16 v[48:63], v[176:179], v[64:67], 0
	ds_read_b128 v[176:179], v134 offset:6752
	s_nop 1
	s_waitcnt vmcnt(9) lgkmcnt(8)
	v_mfma_f32_32x32x16_bf16 v[48:63], v[180:183], v[68:71], v[48:63]
	ds_read_b128 v[180:183], v134 offset:6784
	ds_read_b128 v[136:139], v134 offset:6816
	s_waitcnt vmcnt(8) lgkmcnt(9)
	v_mfma_f32_32x32x16_bf16 v[48:63], v[190:193], v[72:75], v[48:63]
	s_nop 0
	s_waitcnt vmcnt(7) lgkmcnt(7)
	v_mfma_f32_32x32x16_bf16 v[48:63], v[212:215], v[76:79], v[48:63]
	s_nop 0
	s_waitcnt vmcnt(6) lgkmcnt(6)
	v_mfma_f32_32x32x16_bf16 v[48:63], v[216:219], v[80:83], v[48:63]
	s_nop 0
	s_waitcnt vmcnt(5) lgkmcnt(5)
	v_mfma_f32_32x32x16_bf16 v[48:63], v[220:223], v[84:87], v[48:63]
	s_nop 0
	s_waitcnt lgkmcnt(4)
	v_mfma_f32_32x32x16_bf16 v[32:47], v[224:227], v[64:67], 0
	v_mfma_f32_32x32x16_bf16 v[32:47], v[208:211], v[68:71], v[32:47]
	s_nop 0
	s_waitcnt lgkmcnt(3)
	v_mfma_f32_32x32x16_bf16 v[32:47], v[228:231], v[72:75], v[32:47]
	s_nop 0
	s_waitcnt lgkmcnt(2)
	v_mfma_f32_32x32x16_bf16 v[32:47], v[176:179], v[76:79], v[32:47]
	s_nop 0
	s_waitcnt lgkmcnt(1)
	v_mfma_f32_32x32x16_bf16 v[32:47], v[180:183], v[80:83], v[32:47]
	s_nop 0
	s_waitcnt lgkmcnt(0)
	v_mfma_f32_32x32x16_bf16 v[32:47], v[136:139], v[84:87], v[32:47]
	s_cbranch_scc1 .LBB0_804
	v_add_u32_e32 v134, s42, v119
	v_subrev_u32_e32 v136, 64, v134
	v_cmp_gt_u32_e64 s[6:7], s51, v136
	v_subrev_u32_e32 v136, 63, v134
	v_cmp_gt_u32_e64 s[8:9], s51, v136
	s_or_b64 s[6:7], s[8:9], s[6:7]
	v_subrev_u32_e32 v136, 62, v134
	v_cndmask_b32_e64 v48, v206, v48, s[6:7]
	v_cmp_gt_u32_e64 s[6:7], s51, v136
	v_subrev_u32_e32 v136, 61, v134
	v_cndmask_b32_e64 v49, v206, v49, s[8:9]
	v_cndmask_b32_e64 v50, v206, v50, s[6:7]
	v_cmp_gt_u32_e64 s[6:7], s51, v136
	v_subrev_u32_e32 v136, 56, v134
	s_nop 0
	v_cndmask_b32_e64 v51, v206, v51, s[6:7]
	v_cmp_gt_u32_e64 s[6:7], s51, v136
	v_subrev_u32_e32 v136, 55, v134
	s_nop 0
	v_cndmask_b32_e64 v52, v206, v52, s[6:7]
	v_cmp_gt_u32_e64 s[6:7], s51, v136
	v_subrev_u32_e32 v136, 54, v134
	s_nop 0
	v_cndmask_b32_e64 v53, v206, v53, s[6:7]
	v_cmp_gt_u32_e64 s[6:7], s51, v136
	v_subrev_u32_e32 v136, 53, v134
	s_nop 0
	v_cndmask_b32_e64 v54, v206, v54, s[6:7]
	v_cmp_gt_u32_e64 s[6:7], s51, v136
	v_subrev_u32_e32 v136, 48, v134
	s_nop 0
	v_cndmask_b32_e64 v55, v206, v55, s[6:7]
	v_cmp_gt_u32_e64 s[6:7], s51, v136
	v_subrev_u32_e32 v136, 47, v134
	s_nop 0
	v_cndmask_b32_e64 v56, v206, v56, s[6:7]
	v_cmp_gt_u32_e64 s[6:7], s51, v136
	v_subrev_u32_e32 v136, 46, v134
	s_nop 0
	v_cndmask_b32_e64 v57, v206, v57, s[6:7]
	v_cmp_gt_u32_e64 s[6:7], s51, v136
	v_subrev_u32_e32 v136, 45, v134
	s_nop 0
	v_cndmask_b32_e64 v58, v206, v58, s[6:7]
	v_cmp_gt_u32_e64 s[6:7], s51, v136
	v_subrev_u32_e32 v136, 40, v134
	s_nop 0
	v_cndmask_b32_e64 v59, v206, v59, s[6:7]
	v_cmp_gt_u32_e64 s[6:7], s51, v136
	v_subrev_u32_e32 v136, 39, v134
	s_nop 0
	v_cndmask_b32_e64 v60, v206, v60, s[6:7]
	v_cmp_gt_u32_e64 s[6:7], s51, v136
	v_subrev_u32_e32 v136, 38, v134
	s_nop 0
	v_cndmask_b32_e64 v61, v206, v61, s[6:7]
	v_cmp_gt_u32_e64 s[6:7], s51, v136
	v_subrev_u32_e32 v136, 37, v134
	s_nop 0
	v_cndmask_b32_e64 v62, v206, v62, s[6:7]
	v_cmp_gt_u32_e64 s[6:7], s51, v136
	v_subrev_u32_e32 v136, 32, v134
	v_cmp_gt_u32_e64 s[8:9], s51, v136
	v_subrev_u32_e32 v136, 31, v134
	v_cmp_gt_u32_e64 s[10:11], s51, v136
	v_subrev_u32_e32 v136, 30, v134
	v_cmp_gt_u32_e64 s[12:13], s51, v136
	v_subrev_u32_e32 v136, 29, v134
	v_cmp_gt_u32_e64 s[14:15], s51, v136
	v_subrev_u32_e32 v136, 24, v134
	v_cmp_gt_u32_e64 s[16:17], s51, v136
	v_subrev_u32_e32 v136, 23, v134
	v_cmp_gt_u32_e64 s[18:19], s51, v136
	v_subrev_u32_e32 v136, 22, v134
	v_cmp_gt_u32_e64 s[20:21], s51, v136
	v_subrev_u32_e32 v136, 21, v134
	v_cmp_gt_u32_e64 s[22:23], s51, v136
	v_add_u32_e32 v136, -16, v134
	v_cmp_gt_u32_e64 s[24:25], s51, v136
	v_add_u32_e32 v136, -15, v134
	v_cmp_gt_u32_e64 s[26:27], s51, v136
	v_add_u32_e32 v136, -14, v134
	v_cmp_gt_u32_e64 s[28:29], s51, v136
	v_add_u32_e32 v136, -13, v134
	v_cmp_gt_u32_e64 s[30:31], s51, v136
	v_add_u32_e32 v136, -8, v134
	v_cmp_gt_u32_e64 s[34:35], s51, v136
	v_add_u32_e32 v136, -7, v134
	v_cmp_gt_u32_e64 s[36:37], s51, v136
	v_add_u32_e32 v136, -6, v134
	v_add_u32_e32 v134, -5, v134
	v_cmp_gt_u32_e64 s[38:39], s51, v136
	v_cmp_gt_u32_e64 s[40:41], s51, v134
	s_or_b64 s[38:39], s[40:41], s[38:39]
	s_or_b64 s[36:37], s[38:39], s[36:37]
	s_or_b64 s[34:35], s[36:37], s[34:35]
	s_or_b64 s[30:31], s[34:35], s[30:31]
	s_or_b64 s[28:29], s[30:31], s[28:29]
	s_or_b64 s[26:27], s[28:29], s[26:27]
	s_or_b64 s[24:25], s[26:27], s[24:25]
	s_or_b64 s[22:23], s[24:25], s[22:23]
	s_or_b64 s[20:21], s[22:23], s[20:21]
	s_or_b64 s[18:19], s[20:21], s[18:19]
	s_or_b64 s[16:17], s[18:19], s[16:17]
	s_or_b64 s[14:15], s[16:17], s[14:15]
	s_or_b64 s[12:13], s[14:15], s[12:13]
	s_or_b64 s[10:11], s[12:13], s[10:11]
	s_or_b64 s[8:9], s[10:11], s[8:9]
	s_or_b64 s[6:7], s[8:9], s[6:7]
	v_cndmask_b32_e64 v47, v206, v47, s[40:41]
	v_cndmask_b32_e64 v46, v206, v46, s[38:39]
	v_cndmask_b32_e64 v45, v206, v45, s[36:37]
	v_cndmask_b32_e64 v44, v206, v44, s[34:35]
	v_cndmask_b32_e64 v43, v206, v43, s[30:31]
	v_cndmask_b32_e64 v42, v206, v42, s[28:29]
	s_mov_b32 s29, 0x2aaaaaab
	v_cndmask_b32_e64 v41, v206, v41, s[26:27]
	v_cndmask_b32_e64 v40, v206, v40, s[24:25]
	v_cndmask_b32_e64 v39, v206, v39, s[22:23]
	v_cndmask_b32_e64 v38, v206, v38, s[20:21]
	v_cndmask_b32_e64 v37, v206, v37, s[18:19]
	v_cndmask_b32_e64 v36, v206, v36, s[16:17]
	v_cndmask_b32_e64 v35, v206, v35, s[14:15]
	v_cndmask_b32_e64 v34, v206, v34, s[12:13]
	v_cndmask_b32_e64 v33, v206, v33, s[10:11]
	v_cndmask_b32_e64 v32, v206, v32, s[8:9]
	v_cndmask_b32_e64 v63, v206, v63, s[6:7]
; template <int DK, bool SB> ...
;     ...
;       float tmax = -1e30f;
; #pragma unroll
;       for (int kb = 0; kb < 2; kb++)
; #pragma unroll
;         for (int i = 0; i < 16; i++) tmax = fmaxf(tmax, S[kb][i]);
;       tmax = fmaxf(tmax, __shfl_xor(tmax, 32));
;       float m_new = fmaxf(m_run, tmax);
;       float alpha = ex2(m_run - m_new);
;       m_run = m_new;
;       float ps = 0.f;
; #pragma unroll
;       for (int kb = 0; kb < 2; kb++)
; #pragma unroll
;         for (int i = 0; i < 16; i++) { float pv = ex2(S[kb][i] - m_new); S[kb][i] = pv; ps += pv; }
;       l_run = l_run * alpha + ps;
; #pragma unroll
;       for (int b = 0; b < 2; b++)
; #pragma unroll
;         for (int i = 0; i < 16; i++) O[b][i] *= alpha;
;     } else {
;       const bool need_mask = (kt * 64 + 63 >= wave_q0) || ((kt + 1) * 64 > nkeys);
; #pragma unroll
;       for (int kb = 0; kb < 2; kb++)
; #pragma unroll
;         for (int i = 0; i < 16; i++) {
;           float d = __builtin_amdgcn_rcpf(1.f + ex2(S[kb][i]));
;           if (need_mask) { int key = key0 + kb * 32 + (i & 3) + 8 * (i >> 2); if (!(key < nkeys && key < qpos)) d = 1.f; }
;           S[kb][i] = d;
;         }
;       float gs[8], pg[8], sa[8];
; #pragma unroll
;       for (int o = 0; o < 8; o++) { int kb = o >> 2, g = o & 3; gs[o] = (S[kb][4 * g] * S[kb][4 * g + 1]) * (S[kb][4 * g + 2] * S[kb][4 * g + 3]); }
; #pragma unroll
;       for (int o = 0; o < 8; o++) pg[o] = __shfl_xor(gs[o], 32);
;       sa[7] = R;
; #pragma unroll
;       for (int o = 6; o >= 0; o--) sa[o] = sa[o + 1] * (gs[o + 1] * pg[o + 1]);
;       const float total = sa[0] * (gs[0] * pg[0]);
; #pragma unroll
;       for (int o = 0; o < 8; o++) {
;         int kb = o >> 2, g = o & 3;
;         float c = hl == 0 ? sa[o] * pg[o] : sa[o];
; #pragma unroll
;         for (int e = 3; e >= 0; e--) {
;           float d = S[kb][4 * g + e];
;           S[kb][4 * g + e] = c - d * c;
;           c *= d;
;         }
;       }
;       R = total;
;     }
; #pragma unroll
;     for (int kb = 0; kb < 2; kb++)
; #pragma unroll
;       for (int s2 = 0; s2 < 2; s2++) {
;         uint4 u;
;         u.x = pk2(S[kb][8 * s2], S[kb][8 * s2 + 1]); u.y = pk2(S[kb][8 * s2 + 2], S[kb][8 * s2 + 3]);
;         u.z = pk2(S[kb][8 * s2 + 4], S[kb][8 * s2 + 5]); u.w = pk2(S[kb][8 * s2 + 6], S[kb][8 * s2 + 7]);
;         bf16x8 pf = __builtin_bit_cast(bf16x8, u);
; #pragma unroll
.LBB0_804:
	v_add3_u32 v237, v133, v128, v129
	v_add_u32_e32 v238, 0x3000, v237
	ds_read2_b64 v[150:153], v238 offset0:128 offset1:130
	ds_read2_b64 v[154:157], v238 offset0:132 offset1:134
	v_add_u32_e32 v239, 0x4000, v237
	ds_read2_b64 v[164:167], v239 offset0:192 offset1:194
	ds_read2_b64 v[168:171], v239 offset0:196 offset1:198
	ds_read2_b64 v[172:175], v238 offset0:136 offset1:138
	ds_read2_b64 v[232:235], v239 offset0:200 offset1:202
	ds_read2_b64 v[244:247], v238 offset0:140 offset1:142
	ds_read2_b64 v[248:251], v239 offset0:204 offset1:206
	s_mov_b32 s6, 0xf149f2ca
	v_max3_f32 v134, v48, s6, v49
	v_max3_f32 v134, v134, v50, v51
	v_max3_f32 v134, v134, v52, v53
	v_max3_f32 v134, v134, v54, v55
	v_max3_f32 v134, v134, v56, v57
	v_max3_f32 v134, v134, v58, v59
	v_max3_f32 v134, v134, v60, v61
	v_max3_f32 v134, v134, v62, v63
	s_nop 1
	v_max3_f32 v134, v134, v32, v33
	v_max3_f32 v134, v134, v34, v35
	v_max3_f32 v134, v134, v36, v37
	v_max3_f32 v134, v134, v38, v39
	v_max3_f32 v134, v134, v40, v41
	v_max3_f32 v134, v134, v42, v43
	v_max3_f32 v134, v134, v44, v45
	v_max3_f32 v134, v134, v46, v47
	v_mov_b32_e32 v136, v134
	s_nop 1
	v_permlane32_swap_b32_e32 v136, v134
	v_max3_f32 v134, v135, v134, v136
	v_sub_f32_e32 v48, v48, v134
	v_exp_f32_e32 v48, v48
	v_sub_f32_e32 v49, v49, v134
	v_exp_f32_e32 v49, v49
	v_sub_f32_e32 v50, v50, v134
	v_exp_f32_e32 v50, v50
	v_sub_f32_e32 v51, v51, v134
	v_exp_f32_e32 v51, v51
	v_sub_f32_e32 v52, v52, v134
	v_add_f32_e32 v136, 0, v48
	v_exp_f32_e32 v52, v52
	v_sub_f32_e32 v53, v53, v134
	v_add_f32_e32 v136, v49, v136
	v_exp_f32_e32 v53, v53
	v_sub_f32_e32 v54, v54, v134
	v_add_f32_e32 v136, v50, v136
	v_exp_f32_e32 v54, v54
	v_sub_f32_e32 v55, v55, v134
	v_add_f32_e32 v136, v51, v136
	v_exp_f32_e32 v55, v55
	v_sub_f32_e32 v56, v56, v134
	v_add_f32_e32 v136, v52, v136
	v_exp_f32_e32 v56, v56
	v_sub_f32_e32 v57, v57, v134
	v_add_f32_e32 v136, v53, v136
	v_exp_f32_e32 v57, v57
	v_sub_f32_e32 v58, v58, v134
	v_add_f32_e32 v136, v54, v136
	v_exp_f32_e32 v58, v58
	v_sub_f32_e32 v59, v59, v134
	v_add_f32_e32 v136, v55, v136
	v_exp_f32_e32 v59, v59
	v_sub_f32_e32 v60, v60, v134
	v_add_f32_e32 v136, v56, v136
	v_exp_f32_e32 v60, v60
	v_sub_f32_e32 v61, v61, v134
	v_add_f32_e32 v136, v57, v136
	v_exp_f32_e32 v61, v61
	v_sub_f32_e32 v62, v62, v134
	v_add_f32_e32 v136, v58, v136
	v_exp_f32_e32 v62, v62
	v_sub_f32_e32 v63, v63, v134
	v_add_f32_e32 v136, v59, v136
	v_exp_f32_e32 v63, v63
	v_sub_f32_e32 v32, v32, v134
	v_add_f32_e32 v136, v60, v136
	v_exp_f32_e32 v137, v32
	v_sub_f32_e32 v32, v33, v134
	v_add_f32_e32 v136, v61, v136
	v_exp_f32_e32 v33, v32
	v_sub_f32_e32 v32, v34, v134
	v_add_f32_e32 v136, v62, v136
	v_exp_f32_e32 v138, v32
	v_sub_f32_e32 v32, v35, v134
	v_add_f32_e32 v136, v63, v136
	v_exp_f32_e32 v139, v32
	v_sub_f32_e32 v32, v36, v134
	v_exp_f32_e32 v140, v32
	v_sub_f32_e32 v32, v37, v134
	v_add_f32_e32 v34, v137, v136
	v_exp_f32_e32 v141, v32
	v_sub_f32_e32 v32, v38, v134
	v_add_f32_e32 v34, v33, v34
	v_exp_f32_e32 v142, v32
	v_sub_f32_e32 v32, v39, v134
	v_add_f32_e32 v34, v138, v34
	v_exp_f32_e32 v143, v32
	v_sub_f32_e32 v32, v40, v134
	v_add_f32_e32 v34, v139, v34
	v_exp_f32_e32 v144, v32
	v_sub_f32_e32 v32, v41, v134
	v_add_f32_e32 v34, v140, v34
	v_exp_f32_e32 v145, v32
	v_sub_f32_e32 v32, v42, v134
	v_add_f32_e32 v34, v141, v34
	v_exp_f32_e32 v146, v32
	v_sub_f32_e32 v32, v43, v134
	v_add_f32_e32 v34, v142, v34
	v_exp_f32_e32 v147, v32
	v_sub_f32_e32 v32, v44, v134
	v_add_f32_e32 v34, v143, v34
	v_exp_f32_e32 v148, v32
	v_sub_f32_e32 v32, v45, v134
	v_add_f32_e32 v34, v144, v34
	v_exp_f32_e32 v149, v32
	v_sub_f32_e32 v32, v46, v134
	v_add_f32_e32 v34, v145, v34
	v_exp_f32_e32 v46, v32
	v_sub_f32_e32 v32, v47, v134
	v_add_f32_e32 v34, v146, v34
	v_exp_f32_e32 v47, v32
	v_add_f32_e32 v34, v147, v34
	v_add_f32_e32 v34, v148, v34
	v_add_f32_e32 v34, v149, v34
	v_add_f32_e32 v34, v46, v34
	v_sub_f32_e32 v135, v135, v134
	v_add_f32_e32 v136, v47, v34
	v_cvt_pk_bf16_f32 v34, v48, v49
	v_add3_u32 v48, v133, v128, v129
	v_exp_f32_e32 v32, v135
	v_add_u32_e32 v49, 0x3000, v48
	s_nop 1
	v_cvt_pk_bf16_f32 v35, v50, v51
	v_pk_mul_f32 v[30:31], v[30:31], v[32:33] op_sel_hi:[1,0]
	v_pk_mul_f32 v[28:29], v[28:29], v[32:33] op_sel_hi:[1,0]
	v_pk_mul_f32 v[26:27], v[26:27], v[32:33] op_sel_hi:[1,0]
	v_pk_mul_f32 v[24:25], v[24:25], v[32:33] op_sel_hi:[1,0]
	v_pk_mul_f32 v[22:23], v[22:23], v[32:33] op_sel_hi:[1,0]
	v_pk_mul_f32 v[20:21], v[20:21], v[32:33] op_sel_hi:[1,0]
	v_pk_mul_f32 v[18:19], v[18:19], v[32:33] op_sel_hi:[1,0]
	v_pk_mul_f32 v[16:17], v[16:17], v[32:33] op_sel_hi:[1,0]
	v_cvt_pk_bf16_f32 v36, v52, v53
	v_cvt_pk_bf16_f32 v37, v54, v55
	v_add_u32_e32 v48, 0x4000, v48
	v_pk_mul_f32 v[14:15], v[14:15], v[32:33] op_sel_hi:[1,0]
	s_waitcnt lgkmcnt(7)
	v_mfma_f32_32x32x16_bf16 v[16:31], v[150:153], v[34:37], v[16:31]
	s_nop 0
	v_mul_f32_e64 v12, v12, v32
	v_mul_f32_e64 v13, v13, v32
	v_mul_f32_e64 v10, v10, v32
	v_mul_f32_e64 v11, v11, v32
	v_pk_mul_f32 v[8:9], v[8:9], v[32:33] op_sel_hi:[1,0]
	v_pk_mul_f32 v[6:7], v[6:7], v[32:33] op_sel_hi:[1,0]
	v_pk_mul_f32 v[4:5], v[4:5], v[32:33] op_sel_hi:[1,0]
	v_pk_mul_f32 v[2:3], v[2:3], v[32:33] op_sel_hi:[1,0]
	v_pk_mul_f32 v[0:1], v[0:1], v[32:33] op_sel_hi:[1,0]
	v_fmac_f32_e32 v136, v124, v32
	v_mov_b32_e32 v135, v134
	s_waitcnt lgkmcnt(5)
	v_mfma_f32_32x32x16_bf16 v[0:15], v[164:167], v[34:37], v[0:15]
	s_nop 0
	v_cvt_pk_bf16_f32 v34, v56, v57
	v_cvt_pk_bf16_f32 v35, v58, v59
	v_cvt_pk_bf16_f32 v36, v60, v61
	v_cvt_pk_bf16_f32 v37, v62, v63
	v_mov_b32_e32 v124, v136
	s_waitcnt lgkmcnt(4)
	v_mfma_f32_32x32x16_bf16 v[0:15], v[168:171], v[34:37], v[0:15]
	s_nop 0
	v_mfma_f32_32x32x16_bf16 v[16:31], v[154:157], v[34:37], v[16:31]
	v_cvt_pk_bf16_f32 v34, v137, v33
	v_cvt_pk_bf16_f32 v35, v138, v139
	v_cvt_pk_bf16_f32 v36, v140, v141
	v_cvt_pk_bf16_f32 v37, v142, v143
	s_waitcnt lgkmcnt(3)
	s_nop 0
	v_mfma_f32_32x32x16_bf16 v[16:31], v[172:175], v[34:37], v[16:31]
	s_nop 0
	s_waitcnt lgkmcnt(2)
	v_mfma_f32_32x32x16_bf16 v[0:15], v[232:235], v[34:37], v[0:15]
	s_nop 0
	v_cvt_pk_bf16_f32 v34, v144, v145
	v_cvt_pk_bf16_f32 v35, v146, v147
	v_cvt_pk_bf16_f32 v36, v148, v149
	v_cvt_pk_bf16_f32 v37, v46, v47
	s_waitcnt lgkmcnt(1)
	s_nop 0
	v_mfma_f32_32x32x16_bf16 v[16:31], v[244:247], v[34:37], v[16:31]
	s_nop 0
	s_waitcnt lgkmcnt(0)
	v_mfma_f32_32x32x16_bf16 v[0:15], v[248:251], v[34:37], v[0:15]

; #define MFMA32(a, b, c) __builtin_amdgcn_mfma_f32_32x32x16_bf16((a), (b), (c), 0, 0, 0)
; DI float ex2(float x) { return __builtin_amdgcn_exp2f(x); }
; template <int DK, bool SB> ...
;     ...
;     f32x16 S[2];
; #pragma unroll
;     for (int kb = 0; kb < 2; kb++) {
; #pragma unroll
;       for (int i = 0; i < 16; i++) S[kb][i] = 0.f;
; #pragma unroll
;       for (int ks = 0; ks < KS; ks++) {
;         bf16x8 kf = *(const bf16x8*)(sK + (kb * 32 + r) * KSTR + ks * 16 + hl * 8);
;         S[kb] = MFMA32(kf, qf[ks], S[kb]);
;       }
;     }
;     const int key0 = kt * 64 + 4 * hl;
;     if (!SB) {
;       const bool need_mask = (kt + 1) * 64 > nkeys;
;       if (need_mask) {
; #pragma unroll
;         for (int kb = 0; kb < 2; kb++)
; #pragma unroll
;           for (int i = 0; i < 16; i++) { int key = key0 + kb * 32 + (i & 3) + 8 * (i >> 2); if (key >= nkeys) S[kb][i] = -1e30f; }
;       }
;       float tmax = -1e30f;
; #pragma unroll
;       for (int kb = 0; kb < 2; kb++)
; #pragma unroll
;         for (int i = 0; i < 16; i++) tmax = fmaxf(tmax, S[kb][i]);
;       tmax = fmaxf(tmax, __shfl_xor(tmax, 32));
;       float m_new = fmaxf(m_run, tmax);
;       float alpha = ex2(m_run - m_new);
;       m_run = m_new;
;       float ps = 0.f;
; #pragma unroll
;       for (int kb = 0; kb < 2; kb++)
; #pragma unroll
;         for (int i = 0; i < 16; i++) { float pv = ex2(S[kb][i] - m_new); S[kb][i] = pv; ps += pv; }
;       l_run = l_run * alpha + ps;
; #pragma unroll
;       for (int b = 0; b < 2; b++)
; #pragma unroll
;         for (int i = 0; i < 16; i++) O[b][i] *= alpha;
;     } else {
;       const bool need_mask = (kt * 64 + 63 >= wave_q0) || ((kt + 1) * 64 > nkeys);
; #pragma unroll
;       for (int kb = 0; kb < 2; kb++)
; #pragma unroll
;         for (int i = 0; i < 16; i++) {
;           float d = __builtin_amdgcn_rcpf(1.f + ex2(S[kb][i]));
;           if (need_mask) { int key = key0 + kb * 32 + (i & 3) + 8 * (i >> 2); if (!(key < nkeys && key < qpos)) d = 1.f; }
;           S[kb][i] = d;
;         }
.LBB0_815:
	s_sub_i32 s23, s8, 64
	v_cmp_lt_i32_e32 vcc, s23, v117
	s_and_b64 s[26:27], s[4:5], vcc
	s_and_saveexec_b64 s[14:15], s[26:27]
	s_cbranch_execz .LBB0_817
	s_bitcmp1_b32 s24, 0
	s_cselect_b32 s9, 0x4800, 0
	v_or_b32_e32 v32, s9, v104
	v_lshl_add_u32 v121, v119, 1, v32
	ds_read_b128 v[176:179], v121
	ds_read_b128 v[180:183], v121 offset:32
	ds_read_b128 v[190:193], v121 offset:64
	ds_read_b128 v[208:211], v121 offset:96
	ds_read_b128 v[212:215], v121 offset:4608
	ds_read_b128 v[216:219], v121 offset:4640
	ds_read_b128 v[220:223], v121 offset:4672
	ds_read_b128 v[224:227], v121 offset:4704
	v_add_u32_e32 v108, s8, v106
	s_add_i32 s9, s8, -1
	v_subrev_u32_e32 v110, 64, v108
	s_waitcnt vmcnt(7) lgkmcnt(7)
	v_mfma_f32_32x32x16_bf16 v[48:63], v[176:179], v[64:67], 0
	s_nop 1
	v_subrev_u32_e32 v111, 63, v108
	v_cmp_ge_i32_e32 vcc, s9, v97
	s_cmp_gt_i32 s8, s51
	v_cmp_lt_i32_e64 s[8:9], v110, v118
	v_subrev_u32_e32 v134, 62, v108
	v_subrev_u32_e32 v135, 61, v108
	s_waitcnt vmcnt(6) lgkmcnt(6)
	v_mfma_f32_32x32x16_bf16 v[48:63], v[180:183], v[68:71], v[48:63]
	s_cselect_b64 s[26:27], -1, 0
	s_or_b64 vcc, vcc, s[26:27]
	s_waitcnt vmcnt(5) lgkmcnt(5)
	v_mfma_f32_32x32x16_bf16 v[48:63], v[190:193], v[72:75], v[48:63]
	s_nop 1
	s_waitcnt vmcnt(4) lgkmcnt(4)
	v_mfma_f32_32x32x16_bf16 v[48:63], v[208:211], v[76:79], v[48:63]
	s_nop 1
	s_waitcnt lgkmcnt(3)
	v_mfma_f32_32x32x16_bf16 v[32:47], v[212:215], v[64:67], 0
	s_nop 7
	v_exp_f32_e32 v48, v48
	v_exp_f32_e32 v49, v49
	v_exp_f32_e32 v50, v50
	v_exp_f32_e32 v51, v51
	v_add_f32_e32 v48, 1.0, v48
	v_add_f32_e32 v49, 1.0, v49
	v_rcp_f32_e32 v48, v48
	v_add_f32_e32 v50, 1.0, v50
	v_rcp_f32_e32 v49, v49
	s_waitcnt lgkmcnt(2)
	v_mfma_f32_32x32x16_bf16 v[32:47], v[216:219], v[68:71], v[32:47]
	v_exp_f32_e32 v52, v52
	v_add_f32_e32 v51, 1.0, v51
	v_rcp_f32_e32 v126, v50
	v_rcp_f32_e32 v51, v51
	v_cndmask_b32_e64 v50, 1.0, v48, s[8:9]
	v_cmp_lt_i32_e64 s[8:9], v111, v118
	v_add_f32_e32 v52, 1.0, v52
	v_rcp_f32_e32 v127, v52
	v_cndmask_b32_e64 v110, 1.0, v49, s[8:9]
	v_cmp_lt_i32_e64 s[8:9], v134, v118
	v_cndmask_b32_e32 v52, v48, v50, vcc
	v_cndmask_b32_e32 v50, v49, v110, vcc
	v_cndmask_b32_e64 v111, 1.0, v126, s[8:9]
	v_cmp_lt_i32_e64 s[8:9], v135, v118
	v_subrev_u32_e32 v49, 56, v108
	v_cndmask_b32_e32 v110, v126, v111, vcc
	v_cndmask_b32_e64 v128, 1.0, v51, s[8:9]
	v_cndmask_b32_e32 v48, v51, v128, vcc
	v_exp_f32_e32 v51, v53
	v_cmp_lt_i32_e64 s[8:9], v49, v118
	v_exp_f32_e32 v53, v54
	s_waitcnt lgkmcnt(1)
	v_mfma_f32_32x32x16_bf16 v[32:47], v[220:223], v[72:75], v[32:47]
	v_cndmask_b32_e64 v49, 1.0, v127, s[8:9]
	v_cndmask_b32_e32 v126, v127, v49, vcc
	v_add_f32_e32 v49, 1.0, v51
	v_rcp_f32_e32 v49, v49
	v_subrev_u32_e32 v51, 55, v108
	v_cmp_lt_i32_e64 s[8:9], v51, v118
	s_waitcnt lgkmcnt(0)
	v_mfma_f32_32x32x16_bf16 v[32:47], v[224:227], v[76:79], v[32:47]
	v_cndmask_b32_e64 v51, 1.0, v49, s[8:9]
	v_cndmask_b32_e32 v127, v49, v51, vcc
	v_add_f32_e32 v49, 1.0, v53
	v_rcp_f32_e32 v49, v49
	v_exp_f32_e32 v53, v55
	v_subrev_u32_e32 v51, 54, v108
	v_cmp_lt_i32_e64 s[8:9], v51, v118
	s_nop 4
	v_exp_f32_e32 v32, v32
	v_exp_f32_e32 v33, v33
	v_cndmask_b32_e64 v51, 1.0, v49, s[8:9]
	v_cndmask_b32_e32 v128, v49, v51, vcc
	v_add_f32_e32 v49, 1.0, v53
	v_rcp_f32_e32 v49, v49
	v_exp_f32_e32 v53, v56
	v_subrev_u32_e32 v51, 53, v108
	v_cmp_lt_i32_e64 s[8:9], v51, v118
	v_add_f32_e32 v32, 1.0, v32
	v_rcp_f32_e32 v32, v32
	v_cndmask_b32_e64 v51, 1.0, v49, s[8:9]
	v_cndmask_b32_e32 v129, v49, v51, vcc
	v_add_f32_e32 v49, 1.0, v53
	v_rcp_f32_e32 v49, v49
	v_exp_f32_e32 v53, v57
	v_subrev_u32_e32 v51, 48, v108
	v_cmp_lt_i32_e64 s[8:9], v51, v118
	v_exp_f32_e32 v34, v34
	s_nop 0
	v_cndmask_b32_e64 v51, 1.0, v49, s[8:9]
	v_cndmask_b32_e32 v130, v49, v51, vcc
	v_add_f32_e32 v49, 1.0, v53
	v_rcp_f32_e32 v49, v49
	v_exp_f32_e32 v53, v58
	v_subrev_u32_e32 v51, 47, v108
	v_cmp_lt_i32_e64 s[8:9], v51, v118
	s_nop 1
	v_cndmask_b32_e64 v51, 1.0, v49, s[8:9]
	v_cndmask_b32_e32 v131, v49, v51, vcc
	v_add_f32_e32 v49, 1.0, v53
	v_rcp_f32_e32 v49, v49
	v_exp_f32_e32 v53, v59
	v_subrev_u32_e32 v51, 46, v108
	v_cmp_lt_i32_e64 s[8:9], v51, v118
	s_nop 1
	v_cndmask_b32_e64 v51, 1.0, v49, s[8:9]
	v_cndmask_b32_e32 v132, v49, v51, vcc
	v_add_f32_e32 v49, 1.0, v53
	v_rcp_f32_e32 v49, v49
	v_exp_f32_e32 v53, v60
	v_subrev_u32_e32 v51, 45, v108
	v_cmp_lt_i32_e64 s[8:9], v51, v118
	s_nop 1
	v_cndmask_b32_e64 v51, 1.0, v49, s[8:9]
	v_cndmask_b32_e32 v133, v49, v51, vcc
	v_add_f32_e32 v49, 1.0, v53
	v_rcp_f32_e32 v49, v49
	v_exp_f32_e32 v53, v61
	v_subrev_u32_e32 v51, 40, v108
	v_cmp_lt_i32_e64 s[8:9], v51, v118
	s_nop 1
	v_cndmask_b32_e64 v51, 1.0, v49, s[8:9]
	v_cndmask_b32_e32 v54, v49, v51, vcc
	v_add_f32_e32 v49, 1.0, v53
	v_rcp_f32_e32 v49, v49
	v_exp_f32_e32 v53, v62
	v_subrev_u32_e32 v51, 39, v108
	v_cmp_lt_i32_e64 s[8:9], v51, v118
	s_nop 1
	v_cndmask_b32_e64 v51, 1.0, v49, s[8:9]
	v_cndmask_b32_e32 v56, v49, v51, vcc
	v_add_f32_e32 v49, 1.0, v53
	v_rcp_f32_e32 v49, v49
	v_exp_f32_e32 v53, v63
	v_subrev_u32_e32 v51, 38, v108
	v_cmp_lt_i32_e64 s[8:9], v51, v118
	s_nop 1
	v_cndmask_b32_e64 v51, 1.0, v49, s[8:9]
	v_cndmask_b32_e32 v58, v49, v51, vcc
	v_add_f32_e32 v49, 1.0, v53
	v_rcp_f32_e32 v49, v49
	v_subrev_u32_e32 v51, 37, v108
	v_cmp_lt_i32_e64 s[8:9], v51, v118
	s_nop 1
	v_cndmask_b32_e64 v51, 1.0, v49, s[8:9]
	v_cndmask_b32_e32 v60, v49, v51, vcc
	v_subrev_u32_e32 v49, 32, v108
	v_cmp_lt_i32_e64 s[8:9], v49, v118
	v_mul_f32_e32 v51, v132, v133
	s_nop 0
	v_cndmask_b32_e64 v49, 1.0, v32, s[8:9]
	v_cndmask_b32_e32 v134, v32, v49, vcc
	v_add_f32_e32 v32, 1.0, v33
	v_rcp_f32_e32 v32, v32
	v_subrev_u32_e32 v33, 31, v108
; DI float ex2(float x) { return __builtin_amdgcn_exp2f(x); }
; template <int DK, bool SB> ...
;     ...
;         for (int i = 0; i < 16; i++) {
;           float d = __builtin_amdgcn_rcpf(1.f + ex2(S[kb][i]));
;           if (need_mask) { int key = key0 + kb * 32 + (i & 3) + 8 * (i >> 2); if (!(key < nkeys && key < qpos)) d = 1.f; }
;           S[kb][i] = d;
;         }
;       float gs[8], pg[8], sa[8];
; #pragma unroll
;       for (int o = 0; o < 8; o++) { int kb = o >> 2, g = o & 3; gs[o] = (S[kb][4 * g] * S[kb][4 * g + 1]) * (S[kb][4 * g + 2] * S[kb][4 * g + 3]); }
; #pragma unroll
;       for (int o = 0; o < 8; o++) pg[o] = __shfl_xor(gs[o], 32);
;       sa[7] = R;
; #pragma unroll
;       for (int o = 6; o >= 0; o--) sa[o] = sa[o + 1] * (gs[o + 1] * pg[o + 1]);
;       const float total = sa[0] * (gs[0] * pg[0]);
	v_cmp_lt_i32_e64 s[8:9], v33, v118
	v_mul_f32_e32 v49, v130, v131
	s_nop 0
	v_cndmask_b32_e64 v33, 1.0, v32, s[8:9]
	v_cndmask_b32_e32 v135, v32, v33, vcc
	v_add_f32_e32 v32, 1.0, v34
	v_rcp_f32_e32 v32, v32
	v_exp_f32_e32 v34, v35
	v_subrev_u32_e32 v33, 30, v108
	v_cmp_lt_i32_e64 s[8:9], v33, v118
	v_exp_f32_e32 v35, v42
	s_nop 0
	v_cndmask_b32_e64 v33, 1.0, v32, s[8:9]
	v_cndmask_b32_e32 v136, v32, v33, vcc
	v_add_f32_e32 v32, 1.0, v34
	v_rcp_f32_e32 v32, v32
	v_exp_f32_e32 v34, v36
	v_subrev_u32_e32 v33, 29, v108
	v_cmp_lt_i32_e64 s[8:9], v33, v118
	v_exp_f32_e32 v36, v43
	s_nop 0
	v_cndmask_b32_e64 v33, 1.0, v32, s[8:9]
	v_cndmask_b32_e32 v137, v32, v33, vcc
	v_add_f32_e32 v32, 1.0, v34
	v_rcp_f32_e32 v32, v32
	v_exp_f32_e32 v34, v37
	v_subrev_u32_e32 v33, 24, v108
	v_cmp_lt_i32_e64 s[8:9], v33, v118
	s_nop 1
	v_cndmask_b32_e64 v33, 1.0, v32, s[8:9]
	v_cndmask_b32_e32 v138, v32, v33, vcc
	v_add_f32_e32 v32, 1.0, v34
	v_rcp_f32_e32 v32, v32
	v_exp_f32_e32 v34, v38
	v_subrev_u32_e32 v33, 23, v108
	v_cmp_lt_i32_e64 s[8:9], v33, v118
	s_nop 1
	v_cndmask_b32_e64 v33, 1.0, v32, s[8:9]
	v_cndmask_b32_e32 v139, v32, v33, vcc
	v_add_f32_e32 v32, 1.0, v34
	v_rcp_f32_e32 v32, v32
	v_exp_f32_e32 v34, v39
	v_subrev_u32_e32 v33, 22, v108
	v_cmp_lt_i32_e64 s[8:9], v33, v118
	s_nop 1
	v_cndmask_b32_e64 v33, 1.0, v32, s[8:9]
	v_cndmask_b32_e32 v140, v32, v33, vcc
	v_add_f32_e32 v32, 1.0, v34
	v_rcp_f32_e32 v32, v32
	v_exp_f32_e32 v34, v40
	v_subrev_u32_e32 v33, 21, v108
	v_cmp_lt_i32_e64 s[8:9], v33, v118
	v_mul_f32_e32 v40, v134, v135
	s_nop 0
	v_cndmask_b32_e64 v33, 1.0, v32, s[8:9]
	v_cndmask_b32_e32 v141, v32, v33, vcc
	v_add_f32_e32 v32, 1.0, v34
	v_rcp_f32_e32 v32, v32
	v_exp_f32_e32 v34, v41
	v_add_u32_e32 v33, -16, v108
	v_cmp_lt_i32_e64 s[8:9], v33, v118
	v_mul_f32_e32 v41, v140, v141
	s_nop 0
	v_cndmask_b32_e64 v33, 1.0, v32, s[8:9]
	v_cndmask_b32_e32 v32, v32, v33, vcc
	v_add_f32_e32 v33, 1.0, v34
	v_rcp_f32_e32 v33, v33
	v_add_u32_e32 v34, -15, v108
	v_cmp_lt_i32_e64 s[8:9], v34, v118
	s_nop 1
	v_cndmask_b32_e64 v34, 1.0, v33, s[8:9]
	v_cndmask_b32_e32 v34, v33, v34, vcc
	v_add_f32_e32 v33, 1.0, v35
	v_rcp_f32_e32 v33, v33
	v_add_u32_e32 v35, -14, v108
	v_cmp_lt_i32_e64 s[8:9], v35, v118
	s_nop 1
	v_cndmask_b32_e64 v35, 1.0, v33, s[8:9]
	v_cndmask_b32_e32 v142, v33, v35, vcc
	v_add_f32_e32 v33, 1.0, v36
	v_rcp_f32_e32 v33, v33
	v_exp_f32_e32 v36, v44
	v_add_u32_e32 v35, -13, v108
	v_cmp_lt_i32_e64 s[8:9], v35, v118
	s_nop 1
	v_cndmask_b32_e64 v35, 1.0, v33, s[8:9]
	v_cndmask_b32_e32 v143, v33, v35, vcc
	v_add_f32_e32 v33, 1.0, v36
	v_rcp_f32_e32 v33, v33
	v_exp_f32_e32 v36, v45
	v_add_u32_e32 v35, -8, v108
	v_cmp_lt_i32_e64 s[8:9], v35, v118
	v_mul_f32_e32 v38, v142, v143
	s_nop 0
	v_cndmask_b32_e64 v35, 1.0, v33, s[8:9]
	v_cndmask_b32_e32 v144, v33, v35, vcc
	v_add_f32_e32 v33, 1.0, v36
	v_rcp_f32_e32 v33, v33
	v_add_u32_e32 v35, -7, v108
	v_exp_f32_e32 v36, v46
	v_cmp_lt_i32_e64 s[8:9], v35, v118
	v_mul_f32_e32 v46, v126, v127
	s_nop 0
	v_cndmask_b32_e64 v35, 1.0, v33, s[8:9]
	v_cndmask_b32_e32 v145, v33, v35, vcc
	v_exp_f32_e32 v35, v47
	v_add_f32_e32 v33, 1.0, v36
	v_rcp_f32_e32 v33, v33
	v_add_u32_e32 v36, -6, v108
	v_add_f32_e32 v35, 1.0, v35
	v_cmp_lt_i32_e64 s[8:9], v36, v118
	v_rcp_f32_e32 v35, v35
	v_mul_f32_e32 v47, v128, v129
	v_cndmask_b32_e64 v36, 1.0, v33, s[8:9]
	v_cndmask_b32_e32 v146, v33, v36, vcc
	v_add_u32_e32 v33, -5, v108
	v_cmp_lt_i32_e64 s[8:9], v33, v118
	v_mul_f32_e32 v53, v46, v47
	s_nop 0
	v_cndmask_b32_e64 v33, 1.0, v35, s[8:9]
	v_cndmask_b32_e32 v147, v35, v33, vcc
	v_cmp_lt_i32_e32 vcc, v197, v196
	v_mul_f32_e32 v33, v144, v145
	v_mul_f32_e32 v35, v146, v147
	v_cndmask_b32_e32 v36, v194, v197, vcc
	v_lshlrev_b32_e32 v122, 2, v36
	v_pk_mul_f32 v[36:37], v[32:33], v[34:35]
	ds_bpermute_b32 v39, v122, v37
	v_mul_f32_e32 v35, v138, v139
	v_mul_f32_e32 v33, v136, v137
	v_mul_f32_e32 v35, v35, v41
	v_mul_f32_e32 v55, v40, v33
	s_waitcnt lgkmcnt(0)
	v_pk_mul_f32 v[36:37], v[36:37], v[38:39]
	ds_bpermute_b32 v108, v122, v36
	ds_bpermute_b32 v38, v122, v35
	ds_bpermute_b32 v57, v122, v55
	s_waitcnt lgkmcnt(2)
	v_pk_mul_f32 v[62:63], v[36:37], v[108:109]
	s_nop 0
	v_pk_mul_f32 v[40:41], v[62:63], v[62:63] op_sel:[0,1] op_sel_hi:[1,0]
	s_waitcnt lgkmcnt(1)
	v_mul_f32_e32 v59, v35, v38
	v_mov_b32_e32 v61, v40
	v_pk_mul_f32 v[42:43], v[58:59], v[60:61]
	s_waitcnt lgkmcnt(0)
	v_pk_mul_f32 v[36:37], v[54:55], v[56:57]
	v_mul_f32_e32 v35, v49, v51
	v_pk_mul_f32 v[44:45], v[36:37], v[42:43]
	ds_bpermute_b32 v33, v122, v44
	ds_bpermute_b32 v41, v122, v35
	ds_bpermute_b32 v51, v122, v53
	s_waitcnt lgkmcnt(2)
	v_mul_f32_e32 v36, v44, v33
	v_mul_f32_e32 v49, v36, v45
	s_waitcnt lgkmcnt(1)
	v_mul_f32_e32 v111, v35, v41
	v_pk_mul_f32 v[46:47], v[110:111], v[48:49]
	s_waitcnt lgkmcnt(0)
	v_pk_mul_f32 v[36:37], v[52:53], v[50:51]
	v_mul_f32_e32 v33, v45, v33
	v_pk_mul_f32 v[36:37], v[36:37], v[46:47]
	ds_bpermute_b32 v148, v122, v36
	v_cndmask_b32_e64 v45, v45, v33, s[6:7]
	v_mul_f32_e32 v44, v60, v45
	v_mul_f32_e32 v33, v43, v57
	v_cndmask_b32_e64 v43, v43, v33, s[6:7]
	s_waitcnt lgkmcnt(0)
; #define MFMA32(a, b, c) __builtin_amdgcn_mfma_f32_32x32x16_bf16((a), (b), (c), 0, 0, 0)
; DI unsigned pk2(float a, float b) { f2_t v = {a, b}; return __builtin_bit_cast(unsigned, __builtin_convertvector(v, bf2_t)); }
; template <int DK, bool SB> ...
;     ...
;       sa[7] = R;
; #pragma unroll
;       for (int o = 6; o >= 0; o--) sa[o] = sa[o + 1] * (gs[o + 1] * pg[o + 1]);
;       const float total = sa[0] * (gs[0] * pg[0]);
; #pragma unroll
;       for (int o = 0; o < 8; o++) {
;         int kb = o >> 2, g = o & 3;
;         float c = hl == 0 ? sa[o] * pg[o] : sa[o];
; #pragma unroll
;         for (int e = 3; e >= 0; e--) {
;           float d = S[kb][4 * g + e];
;           S[kb][4 * g + e] = c - d * c;
;           c *= d;
;         }
;       }
;       R = total;
;     }
; #pragma unroll
;     for (int kb = 0; kb < 2; kb++)
; #pragma unroll
;       for (int s2 = 0; s2 < 2; s2++) {
;         uint4 u;
;         u.x = pk2(S[kb][8 * s2], S[kb][8 * s2 + 1]); u.y = pk2(S[kb][8 * s2 + 2], S[kb][8 * s2 + 3]);
;         u.z = pk2(S[kb][8 * s2 + 4], S[kb][8 * s2 + 5]); u.w = pk2(S[kb][8 * s2 + 6], S[kb][8 * s2 + 7]);
;         bf16x8 pf = __builtin_bit_cast(bf16x8, u);
; #pragma unroll
;         for (int bd = 0; bd < 2; bd++) {
;           const u16* vp = sV + (bd * 32 + r) * 72 + kb * 32 + s2 * 16 + hl * 4;
;           uint2 lo = *(const uint2*)vp, hi = *(const uint2*)(vp + 8);
;           uint4 vv; vv.x = lo.x; vv.y = lo.y; vv.z = hi.x; vv.w = hi.y;
;           O[bd] = MFMA32(__builtin_bit_cast(bf16x8, vv), pf, O[bd]);
;         }
;       }
	v_mul_f32_e32 v35, v37, v148
	v_cndmask_b32_e64 v123, v37, v35, s[6:7]
	v_mul_f32_e32 v35, v47, v51
	v_mul_f32_e32 v122, v48, v123
	v_cndmask_b32_e64 v47, v47, v35, s[6:7]
	v_mul_f32_e32 v110, v110, v122
	v_mul_f32_e32 v46, v129, v47
	v_mul_f32_e32 v35, v49, v41
	v_mov_b32_e32 v111, v122
	v_mul_f32_e32 v124, v50, v110
	v_mul_f32_e32 v50, v128, v46
	v_mov_b32_e32 v51, v46
	v_cndmask_b32_e64 v49, v49, v35, s[6:7]
	v_pk_add_f32 v[122:123], v[122:123], v[110:111] neg_lo:[0,1] neg_hi:[0,1]
	v_mul_f32_e32 v52, v52, v124
	v_mov_b32_e32 v125, v110
	v_mov_b32_e32 v53, v124
	v_pk_add_f32 v[110:111], v[46:47], v[50:51] neg_lo:[0,1] neg_hi:[0,1]
	v_mul_f32_e32 v46, v127, v50
	v_mul_f32_e32 v48, v133, v49
	v_pk_add_f32 v[52:53], v[124:125], v[52:53] neg_lo:[0,1] neg_hi:[0,1]
	v_mul_f32_e32 v124, v126, v46
	v_mov_b32_e32 v47, v50
	v_mov_b32_e32 v125, v46
	v_mul_f32_e32 v50, v132, v48
	v_mov_b32_e32 v51, v48
	v_pk_add_f32 v[46:47], v[46:47], v[124:125] neg_lo:[0,1] neg_hi:[0,1]
	v_pk_add_f32 v[124:125], v[48:49], v[50:51] neg_lo:[0,1] neg_hi:[0,1]
	v_mul_f32_e32 v48, v131, v50
	v_mul_f32_e32 v126, v130, v48
	v_mov_b32_e32 v49, v50
	v_mov_b32_e32 v127, v48
	v_pk_add_f32 v[126:127], v[48:49], v[126:127] neg_lo:[0,1] neg_hi:[0,1]
	v_mul_f32_e32 v48, v58, v44
	v_mov_b32_e32 v49, v44
	v_pk_add_f32 v[58:59], v[44:45], v[48:49] neg_lo:[0,1] neg_hi:[0,1]
	v_mul_f32_e32 v44, v56, v48
	v_mul_f32_e32 v50, v54, v44
	v_mov_b32_e32 v45, v48
	v_mov_b32_e32 v51, v44
	v_mul_f32_e32 v42, v137, v43
	v_mul_f32_e32 v33, v40, v38
	v_pk_add_f32 v[54:55], v[44:45], v[50:51] neg_lo:[0,1] neg_hi:[0,1]
	v_mul_f32_e32 v44, v136, v42
	v_mov_b32_e32 v45, v42
	v_cndmask_b32_e64 v41, v40, v33, s[6:7]
	v_pk_add_f32 v[56:57], v[42:43], v[44:45] neg_lo:[0,1] neg_hi:[0,1]
	v_mul_f32_e32 v42, v135, v44
	v_mul_f32_e32 v40, v141, v41
	v_add_u32_e32 v33, v121, v120
	v_mul_f32_e32 v48, v134, v42
	v_mov_b32_e32 v43, v44
	v_mov_b32_e32 v49, v42
	v_mul_f32_e32 v128, v140, v40
	v_mov_b32_e32 v129, v40
	v_add_u32_e32 v121, 0x2000, v33
	ds_read2_b64 v[228:231], v121 offset0:128 offset1:130
	v_pk_add_f32 v[60:61], v[42:43], v[48:49] neg_lo:[0,1] neg_hi:[0,1]
	v_pk_add_f32 v[130:131], v[40:41], v[128:129] neg_lo:[0,1] neg_hi:[0,1]
	s_nop 0
	v_cvt_pk_bf16_f32 v45, v122, v123
	v_add_u32_e32 v122, 0x3000, v33
	ds_read2_b64 v[176:179], v122 offset0:192 offset1:194
	ds_read2_b64 v[180:183], v121 offset0:132 offset1:134
	ds_read2_b64 v[190:193], v122 offset0:196 offset1:198
	ds_read2_b64 v[208:211], v121 offset0:136 offset1:138
	v_cvt_pk_bf16_f32 v44, v52, v53
	v_cvt_pk_bf16_f32 v46, v46, v47
	v_cvt_pk_bf16_f32 v47, v110, v111
	v_mul_f32_e32 v33, v63, v108
	v_cndmask_b32_e64 v63, v63, v33, s[6:7]
	s_waitcnt lgkmcnt(4)
	v_mfma_f32_32x32x16_bf16 v[16:31], v[228:231], v[44:47], v[16:31]
	s_nop 0
	v_mul_f32_e32 v62, v143, v63
	v_mul_f32_e32 v110, v142, v62
	v_mul_f32_e32 v34, v34, v110
	v_mul_f32_e32 v32, v32, v34
	v_mov_b32_e32 v35, v110
	v_mov_b32_e32 v33, v34
	s_waitcnt lgkmcnt(3)
	v_mfma_f32_32x32x16_bf16 v[0:15], v[176:179], v[44:47], v[0:15]
	s_nop 0
	v_cvt_pk_bf16_f32 v44, v126, v127
	v_cvt_pk_bf16_f32 v45, v124, v125
	v_cvt_pk_bf16_f32 v46, v54, v55
	v_cvt_pk_bf16_f32 v47, v58, v59
	v_pk_add_f32 v[58:59], v[34:35], v[32:33] neg_lo:[0,1] neg_hi:[0,1]
	s_nop 0
	s_waitcnt lgkmcnt(2)
	v_mfma_f32_32x32x16_bf16 v[16:31], v[180:183], v[44:47], v[16:31]
	v_mul_f32_e32 v132, v139, v128
	v_mul_f32_e32 v134, v138, v132
	v_mov_b32_e32 v133, v128
	v_mov_b32_e32 v135, v132
	v_add_f32_e64 v52, v132, -v134
	v_add_f32_e64 v53, v133, -v135
	v_mul_f32_e32 v38, v109, v39
	v_cvt_pk_bf16_f32 v39, v56, v57
	s_waitcnt lgkmcnt(1)
	v_mfma_f32_32x32x16_bf16 v[0:15], v[190:193], v[44:47], v[0:15]
	ds_read2_b64 v[42:45], v122 offset0:200 offset1:202
	ds_read2_b64 v[212:215], v121 offset0:140 offset1:142
	v_cndmask_b32_e64 v47, v109, v38, s[6:7]
	v_cvt_pk_bf16_f32 v38, v60, v61
	v_cvt_pk_bf16_f32 v40, v52, v53
	v_cvt_pk_bf16_f32 v41, v130, v131
	v_mul_f32_e32 v46, v147, v47
	v_mul_f32_e32 v48, v146, v46
	s_waitcnt lgkmcnt(2)
	v_mfma_f32_32x32x16_bf16 v[16:31], v[208:211], v[38:41], v[16:31]
	s_nop 0
	v_mul_f32_e32 v50, v145, v48
	v_mov_b32_e32 v111, v62
	v_mov_b32_e32 v49, v46
	v_mul_f32_e32 v52, v144, v50
	v_mov_b32_e32 v51, v48
	v_mov_b32_e32 v53, v50
	v_pk_add_f32 v[54:55], v[62:63], v[110:111] neg_lo:[0,1] neg_hi:[0,1]
	v_pk_add_f32 v[46:47], v[46:47], v[48:49] neg_lo:[0,1] neg_hi:[0,1]
	s_waitcnt lgkmcnt(1)
	v_mfma_f32_32x32x16_bf16 v[0:15], v[42:45], v[38:41], v[0:15]
	v_add_f32_e64 v40, v50, -v52
	v_add_f32_e64 v41, v51, -v53
	v_cvt_pk_bf16_f32 v38, v58, v59
	v_cvt_pk_bf16_f32 v39, v54, v55
	v_cvt_pk_bf16_f32 v40, v40, v41
	v_cvt_pk_bf16_f32 v41, v46, v47
	v_mul_f32_e32 v36, v36, v148
	v_mul_f32_e32 v109, v36, v37
	s_waitcnt lgkmcnt(0)
	v_mfma_f32_32x32x16_bf16 v[16:31], v[212:215], v[38:41], v[16:31]
	ds_read2_b64 v[32:35], v122 offset0:204 offset1:206
	s_waitcnt lgkmcnt(0)
	v_mfma_f32_32x32x16_bf16 v[0:15], v[32:35], v[38:41], v[0:15]

; #define SCAN_PREFETCH(slot, cc) { int c_ = (cc) < nch ? (cc) : nch - 1; size_t row = (size_t)(srow0 + c_ * 16 + lstep); \
;     pw[slot] = *(const f32x4v*)(RWW + row * 512 + h * 64 + lpart); \
;     _Pragma("unroll") for (int c = 0; c < 5; c++) px[slot][c] = *(const u32x2*)(RWX + row * 2560 + c * 512 + h * 64 + lpart); }
; DI void rwkv_scan_task(const Params& p, int srow0, int T, int h, int rq, const float* S0, float* Sout, int comb_bh, int comb_seg, unsigned char* smem) {
;     ...
;         SCAN_PREFETCH((k & 1), cc + 2)
; #pragma unroll
;         for (int j = 0; j < 2; j++) {
;           float yk = 0.f;
; #pragma unroll
;           for (int u = 0; u < 8; u++) {
;             const float* o = ops + (bsel * 16 + j * 8 + u) * 384;
;             const float v = o[192 + Rr];
;             const float br = sc[(bsel * 16 + j * 8 + u) * 2], kr = sc[(bsel * 16 + j * 8 + u) * 2 + 1];
;             f32x4v d1v = S[0] * *(const f32x4v*)(o + 256 + c0) + S[1] * *(const f32x4v*)(o + 256 + c0 + 4);
;             f32x4v d2v = S[0] * *(const f32x4v*)(o + 64 + c0) + S[1] * *(const f32x4v*)(o + 64 + c0 + 4);
;             float d1 = (d1v.x + d1v.y) + (d1v.z + d1v.w), d2 = (d2v.x + d2v.y) + (d2v.z + d2v.w);
;             d1 = dpp_add<0xB1>(d1); d2 = dpp_add<0xB1>(d2); d1 = dpp_add<0x4E>(d1); d2 = dpp_add<0x4E>(d2);
;             d1 = dpp_add<0x141>(d1); d2 = dpp_add<0x141>(d2);
; #pragma unroll
;             for (int m = 0; m < 2; m++) {
;               const f32x4v w = *(const f32x4v*)(o + c0 + 4 * m), kp = *(const f32x4v*)(o + 128 + c0 + 4 * m), bb = *(const f32x4v*)(o + 320 + c0 + 4 * m);
;               S[m] = S[m] * w + (kp * v - bb * d1);
;             }
;             const float y = d2 - d1 * br + v * kr;
;             yk = (u == c8) ? y : yk;
.LBB0_847:
	ds_read2st64_b32 v[32:33], v77 offset0:3 offset1:9
	ds_read_b128 v[96:99], v163 offset:49152
	ds_read_b128 v[100:103], v163 offset:49168
	ds_read_b128 v[104:107], v163 offset:49184
	ds_read_b128 v[108:111], v163 offset:49200
	ds_read_b128 v[112:115], v36 offset:1024
	ds_read_b128 v[116:119], v36 offset:1040
	ds_read_b128 v[120:123], v36 offset:256
	ds_read_b128 v[124:127], v36 offset:272
	ds_read_b128 v[128:131], v36
	ds_read_b128 v[132:135], v36 offset:16
	ds_read_b128 v[136:139], v36 offset:512
	ds_read_b128 v[90:93], v36 offset:1280
	ds_read_b128 v[140:143], v36 offset:528
	v_add_u32_e32 v85, s27, v82
	v_add_u32_e32 v8, 32, v85
	v_ashrrev_i32_e32 v9, 31, v8
	v_lshlrev_b64 v[4:5], 11, v[8:9]
	v_lshl_add_u64 v[4:5], v[40:41], 0, v[4:5]
	v_mad_i64_i32 v[8:9], s[2:3], v8, s97, v[42:43]
	global_load_dwordx4 v[4:7], v[4:5], off
	s_nop 0
	global_load_dwordx2 v[64:65], v[8:9], off
	global_load_dwordx2 v[56:57], v[8:9], off offset:1024
	global_load_dwordx2 v[62:63], v[8:9], off offset:2048
	global_load_dwordx2 v[60:61], v[8:9], off offset:3072
	v_add_co_u32_e64 v8, s[22:23], s60, v8
	s_nop 1
	v_addc_co_u32_e64 v9, s[22:23], 0, v9, s[22:23]
	global_load_dwordx2 v[58:59], v[8:9], off
	s_nop 6
	s_waitcnt lgkmcnt(7)
	ds_read_b128 v[144:147], v36 offset:1296
	ds_read_b128 v[148:151], v36 offset:2560
	ds_read_b128 v[152:155], v36 offset:2576
	ds_read_b128 v[164:167], v36 offset:1792
	ds_read_b128 v[168:171], v36 offset:1808
	ds_read_b128 v[172:175], v36 offset:1536
	ds_read_b128 v[176:179], v36 offset:2048
	v_pk_mul_f32 v[34:35], v[18:19], v[118:119]
	v_pk_mul_f32 v[70:71], v[16:17], v[116:117]
	v_pk_fma_f32 v[34:35], v[22:23], v[114:115], v[34:35]
	v_pk_fma_f32 v[74:75], v[20:21], v[112:113], v[70:71]
	s_nop 1
	s_waitcnt lgkmcnt(12)
	ds_read_b128 v[180:183], v36 offset:2816
	ds_read_b128 v[190:193], v36 offset:1552
	v_pk_mul_f32 v[70:71], v[16:17], v[124:125]
	v_pk_mul_f32 v[72:73], v[18:19], v[126:127]
	v_pk_fma_f32 v[66:67], v[20:21], v[120:121], v[70:71]
	v_pk_mov_b32 v[70:71], v[74:75], v[34:35] op_sel:[1,0]
	v_mov_b32_e32 v75, v35
	v_pk_fma_f32 v[68:69], v[22:23], v[122:123], v[72:73]
	v_pk_add_f32 v[34:35], v[70:71], v[74:75]
	s_nop 0
	v_add_f32_e32 v34, v34, v35
	v_add_f32_e32 v35, v66, v67
	v_add_f32_e32 v66, v68, v69
	v_add_f32_e32 v35, v35, v66
	s_nop 3
	v_add_f32_dpp v34, v34, v34 quad_perm:[1,0,3,2] row_mask:0xf bank_mask:0xf bound_ctrl:1
	v_add_f32_dpp v35, v35, v35 quad_perm:[1,0,3,2] row_mask:0xf bank_mask:0xf bound_ctrl:1
	s_nop 0
	v_add_f32_dpp v34, v34, v34 quad_perm:[2,3,0,1] row_mask:0xf bank_mask:0xf bound_ctrl:1
	v_add_f32_dpp v35, v35, v35 quad_perm:[2,3,0,1] row_mask:0xf bank_mask:0xf bound_ctrl:1
	s_nop 0
	v_add_f32_dpp v34, v34, v34 row_half_mirror row_mask:0xf bank_mask:0xf bound_ctrl:1
	s_waitcnt lgkmcnt(10)
	ds_read_b128 v[208:211], v36 offset:2064
	v_pk_mul_f32 v[74:75], v[34:35], v[90:91] op_sel_hi:[0,1]
	v_pk_mul_f32 v[90:91], v[34:35], v[92:93] op_sel_hi:[0,1]
	v_pk_fma_f32 v[88:89], v[32:33], v[138:139], v[90:91] op_sel_hi:[0,1,1] neg_lo:[0,0,1] neg_hi:[0,0,1]
	v_pk_fma_f32 v[74:75], v[32:33], v[136:137], v[74:75] op_sel_hi:[0,1,1] neg_lo:[0,0,1] neg_hi:[0,0,1]
	v_pk_fma_f32 v[74:75], v[20:21], v[128:129], v[74:75]
	v_pk_fma_f32 v[86:87], v[22:23], v[130:131], v[88:89]
	s_nop 1
	v_mov_b32_dpp v94, v35 row_half_mirror row_mask:0xf bank_mask:0xf bound_ctrl:1
	s_waitcnt vmcnt(7)
	v_and_b32_e32 v93, 0xffff0000, v53
	s_waitcnt lgkmcnt(9)
	v_pk_mul_f32 v[66:67], v[34:35], v[144:145] op_sel_hi:[0,1]
	v_pk_fma_f32 v[20:21], v[32:33], v[140:141], v[66:67] op_sel_hi:[0,1,1] neg_lo:[0,0,1] neg_hi:[0,0,1]
	v_pk_fma_f32 v[70:71], v[16:17], v[132:133], v[20:21]
	v_add_f32_e32 v16, v35, v94
	v_pk_mul_f32 v[68:69], v[34:35], v[146:147] op_sel_hi:[0,1]
	v_fma_f32 v16, -v96, v34, v16
	v_pk_fma_f32 v[22:23], v[32:33], v[142:143], v[68:69] op_sel_hi:[0,1,1] neg_lo:[0,0,1] neg_hi:[0,0,1]
	v_fmac_f32_e32 v16, v32, v97
	v_pk_fma_f32 v[72:73], v[18:19], v[134:135], v[22:23]
	v_cndmask_b32_e64 v88, 0, v16, s[6:7]
	s_nop 1
	v_mov_b32_e32 v32, v33
	s_waitcnt lgkmcnt(7)
	v_pk_mul_f32 v[20:21], v[70:71], v[152:153]
	v_pk_mul_f32 v[22:23], v[72:73], v[154:155]
	v_pk_fma_f32 v[34:35], v[74:75], v[148:149], v[20:21]
	v_pk_fma_f32 v[28:29], v[86:87], v[150:151], v[22:23]
	s_nop 1
	s_waitcnt lgkmcnt(5)
	v_pk_mul_f32 v[20:21], v[70:71], v[168:169]
	v_pk_mul_f32 v[22:23], v[72:73], v[170:171]
	v_pk_fma_f32 v[16:17], v[74:75], v[164:165], v[20:21]
	v_pk_mov_b32 v[20:21], v[34:35], v[28:29] op_sel:[1,0]
	v_mov_b32_e32 v35, v29
	v_pk_fma_f32 v[18:19], v[86:87], v[166:167], v[22:23]
	v_pk_add_f32 v[20:21], v[20:21], v[34:35]
	v_add_f32_e32 v16, v16, v17
	v_add_f32_e32 v20, v20, v21
	v_add_f32_e32 v17, v18, v19
	v_add_f32_e32 v16, v16, v17
	s_nop 0
	v_add_f32_dpp v17, v20, v20 quad_perm:[1,0,3,2] row_mask:0xf bank_mask:0xf bound_ctrl:1
	v_add_f32_dpp v16, v16, v16 quad_perm:[1,0,3,2] row_mask:0xf bank_mask:0xf bound_ctrl:1
	s_nop 0
	v_add_f32_dpp v17, v17, v17 quad_perm:[2,3,0,1] row_mask:0xf bank_mask:0xf bound_ctrl:1
	v_add_f32_dpp v29, v16, v16 quad_perm:[2,3,0,1] row_mask:0xf bank_mask:0xf bound_ctrl:1
	s_nop 0
	v_add_f32_dpp v28, v17, v17 row_half_mirror row_mask:0xf bank_mask:0xf bound_ctrl:1
	s_nop 2
	v_mov_b32_dpp v89, v29 row_half_mirror row_mask:0xf bank_mask:0xf bound_ctrl:1
	s_waitcnt lgkmcnt(2)
	v_pk_mul_f32 v[34:35], v[28:29], v[180:181] op_sel_hi:[0,1]
	v_pk_mul_f32 v[66:67], v[28:29], v[182:183] op_sel_hi:[0,1]
	v_pk_fma_f32 v[22:23], v[32:33], v[178:179], v[66:67] op_sel_hi:[0,1,1] neg_lo:[0,0,1] neg_hi:[0,0,1]
	v_pk_fma_f32 v[20:21], v[32:33], v[176:177], v[34:35] op_sel_hi:[0,1,1] neg_lo:[0,0,1] neg_hi:[0,0,1]
	v_pk_fma_f32 v[74:75], v[74:75], v[172:173], v[20:21]
	v_pk_fma_f32 v[86:87], v[86:87], v[174:175], v[22:23]
	s_nop 1
	ds_read_b128 v[66:69], v36 offset:2832
	s_waitcnt lgkmcnt(0)
; DI void rwkv_scan_task(const Params& p, int srow0, int T, int h, int rq, const float* S0, float* Sout, int comb_bh, int comb_seg, unsigned char* smem) {
;     ...
;           for (int u = 0; u < 8; u++) {
;             const float* o = ops + (bsel * 16 + j * 8 + u) * 384;
;             const float v = o[192 + Rr];
;             const float br = sc[(bsel * 16 + j * 8 + u) * 2], kr = sc[(bsel * 16 + j * 8 + u) * 2 + 1];
;             f32x4v d1v = S[0] * *(const f32x4v*)(o + 256 + c0) + S[1] * *(const f32x4v*)(o + 256 + c0 + 4);
;             f32x4v d2v = S[0] * *(const f32x4v*)(o + 64 + c0) + S[1] * *(const f32x4v*)(o + 64 + c0 + 4);
;             float d1 = (d1v.x + d1v.y) + (d1v.z + d1v.w), d2 = (d2v.x + d2v.y) + (d2v.z + d2v.w);
;             d1 = dpp_add<0xB1>(d1); d2 = dpp_add<0xB1>(d2); d1 = dpp_add<0x4E>(d1); d2 = dpp_add<0x4E>(d2);
;             d1 = dpp_add<0x141>(d1); d2 = dpp_add<0x141>(d2);
; #pragma unroll
;             for (int m = 0; m < 2; m++) {
;               const f32x4v w = *(const f32x4v*)(o + c0 + 4 * m), kp = *(const f32x4v*)(o + 128 + c0 + 4 * m), bb = *(const f32x4v*)(o + 320 + c0 + 4 * m);
;               S[m] = S[m] * w + (kp * v - bb * d1);
;             }
;             const float y = d2 - d1 * br + v * kr;
;             yk = (u == c8) ? y : yk;
	v_pk_mul_f32 v[66:67], v[28:29], v[66:67] op_sel_hi:[0,1]
	v_pk_fma_f32 v[20:21], v[32:33], v[208:209], v[66:67] op_sel_hi:[0,1,1] neg_lo:[0,0,1] neg_hi:[0,0,1]
	v_pk_fma_f32 v[66:67], v[70:71], v[190:191], v[20:21]
	v_add_f32_e32 v16, v29, v89
	v_pk_mul_f32 v[34:35], v[28:29], v[68:69] op_sel_hi:[0,1]
	v_fma_f32 v16, -v98, v28, v16
	v_pk_fma_f32 v[22:23], v[32:33], v[210:211], v[34:35] op_sel_hi:[0,1,1] neg_lo:[0,0,1] neg_hi:[0,0,1]
	v_fmac_f32_e32 v16, v33, v99
	v_pk_fma_f32 v[22:23], v[72:73], v[192:193], v[22:23]
	v_cndmask_b32_e64 v69, v88, v16, s[8:9]
	ds_read2st64_b32 v[16:17], v77 offset0:15 offset1:21
	ds_read_b128 v[212:215], v36 offset:4096
	ds_read_b128 v[216:219], v36 offset:4112
	ds_read_b128 v[116:119], v36 offset:3328
	ds_read_b128 v[112:115], v36 offset:3344
	ds_read_b128 v[124:127], v36 offset:3072
	ds_read_b128 v[120:123], v36 offset:3584
	ds_read_b128 v[136:139], v36 offset:4352
	ds_read_b128 v[128:131], v36 offset:3088
	ds_read_b128 v[144:147], v36 offset:3600
	ds_read_b128 v[140:143], v36 offset:4368
	ds_read_b128 v[132:135], v36 offset:5632
	ds_read_b128 v[152:155], v36 offset:5648
	ds_read_b128 v[148:151], v36 offset:4864
	s_waitcnt lgkmcnt(11)
	ds_read_b128 v[168:171], v36 offset:4880
	ds_read_b128 v[164:167], v36 offset:4608
	ds_read_b128 v[180:183], v36 offset:5120
	v_pk_mul_f32 v[28:29], v[66:67], v[216:217]
	v_pk_mul_f32 v[30:31], v[22:23], v[218:219]
	v_pk_fma_f32 v[34:35], v[74:75], v[212:213], v[28:29]
	v_pk_fma_f32 v[32:33], v[86:87], v[214:215], v[30:31]
	s_nop 1
	s_waitcnt lgkmcnt(12)
	ds_read_b128 v[176:179], v36 offset:5888
	ds_read_b128 v[172:175], v36 offset:4624
	v_pk_mul_f32 v[28:29], v[66:67], v[112:113]
	v_pk_mul_f32 v[30:31], v[22:23], v[114:115]
	v_pk_fma_f32 v[18:19], v[74:75], v[116:117], v[28:29]
	v_pk_mov_b32 v[28:29], v[34:35], v[32:33] op_sel:[1,0]
	v_mov_b32_e32 v35, v33
	v_pk_fma_f32 v[20:21], v[86:87], v[118:119], v[30:31]
	v_pk_add_f32 v[28:29], v[28:29], v[34:35]
	v_add_f32_e32 v18, v18, v19
	v_add_f32_e32 v28, v28, v29
	v_add_f32_e32 v19, v20, v21
	v_add_f32_e32 v18, v18, v19
	s_nop 0
	v_add_f32_dpp v19, v28, v28 quad_perm:[1,0,3,2] row_mask:0xf bank_mask:0xf bound_ctrl:1
	v_add_f32_dpp v18, v18, v18 quad_perm:[1,0,3,2] row_mask:0xf bank_mask:0xf bound_ctrl:1
	s_nop 0
	v_add_f32_dpp v19, v19, v19 quad_perm:[2,3,0,1] row_mask:0xf bank_mask:0xf bound_ctrl:1
	v_add_f32_dpp v88, v18, v18 quad_perm:[2,3,0,1] row_mask:0xf bank_mask:0xf bound_ctrl:1
	s_nop 0
	v_add_f32_dpp v68, v19, v19 row_half_mirror row_mask:0xf bank_mask:0xf bound_ctrl:1
	s_nop 2
	v_mov_b32_dpp v89, v88 row_half_mirror row_mask:0xf bank_mask:0xf bound_ctrl:1
	s_waitcnt lgkmcnt(11)
	ds_read_b128 v[208:211], v36 offset:5136
	ds_read_b128 v[96:99], v36 offset:5904
	v_pk_mul_f32 v[32:33], v[68:69], v[136:137] op_sel_hi:[0,1]
	v_pk_mul_f32 v[34:35], v[68:69], v[138:139] op_sel_hi:[0,1]
	v_pk_fma_f32 v[30:31], v[16:17], v[122:123], v[34:35] op_sel_hi:[0,1,1] neg_lo:[0,0,1] neg_hi:[0,0,1]
	v_pk_fma_f32 v[28:29], v[16:17], v[120:121], v[32:33] op_sel_hi:[0,1,1] neg_lo:[0,0,1] neg_hi:[0,0,1]
	v_pk_fma_f32 v[70:71], v[74:75], v[124:125], v[28:29]
	v_pk_fma_f32 v[72:73], v[86:87], v[126:127], v[30:31]
	s_nop 2
	s_waitcnt lgkmcnt(10)
	v_pk_mul_f32 v[32:33], v[68:69], v[140:141] op_sel_hi:[0,1]
	v_pk_mul_f32 v[34:35], v[68:69], v[142:143] op_sel_hi:[0,1]
	v_pk_fma_f32 v[28:29], v[16:17], v[144:145], v[32:33] op_sel_hi:[0,1,1] neg_lo:[0,0,1] neg_hi:[0,0,1]
	v_pk_fma_f32 v[30:31], v[16:17], v[146:147], v[34:35] op_sel_hi:[0,1,1] neg_lo:[0,0,1] neg_hi:[0,0,1]
	v_pk_fma_f32 v[34:35], v[66:67], v[128:129], v[28:29]
	v_add_f32_e32 v18, v88, v89
	v_fma_f32 v18, -v100, v68, v18
	v_fmac_f32_e32 v18, v16, v101
	v_pk_fma_f32 v[32:33], v[22:23], v[130:131], v[30:31]
	v_cndmask_b32_e64 v67, v69, v18, s[10:11]
	s_nop 1
	v_mov_b32_e32 v66, v17
	s_waitcnt lgkmcnt(8)
	v_pk_mul_f32 v[22:23], v[34:35], v[152:153]
	v_pk_mul_f32 v[24:25], v[32:33], v[154:155]
	v_pk_fma_f32 v[30:31], v[70:71], v[132:133], v[22:23]
	v_pk_fma_f32 v[28:29], v[72:73], v[134:135], v[24:25]
	s_nop 1
	s_waitcnt lgkmcnt(6)
	v_pk_mul_f32 v[22:23], v[34:35], v[168:169]
	v_pk_mul_f32 v[24:25], v[32:33], v[170:171]
	v_pk_fma_f32 v[18:19], v[70:71], v[148:149], v[22:23]
	v_pk_fma_f32 v[20:21], v[72:73], v[150:151], v[24:25]
	v_add_f32_e32 v18, v18, v19
	v_add_f32_e32 v19, v20, v21
	v_pk_mov_b32 v[22:23], v[30:31], v[28:29] op_sel:[1,0]
	v_mov_b32_e32 v31, v29
	v_add_f32_e32 v18, v18, v19
	v_pk_add_f32 v[22:23], v[22:23], v[30:31]
	s_nop 0
	v_add_f32_dpp v18, v18, v18 quad_perm:[1,0,3,2] row_mask:0xf bank_mask:0xf bound_ctrl:1
	v_add_f32_e32 v16, v22, v23
	s_nop 0
	v_add_f32_dpp v74, v18, v18 quad_perm:[2,3,0,1] row_mask:0xf bank_mask:0xf bound_ctrl:1
	s_nop 2
	v_add_f32_dpp v16, v16, v16 quad_perm:[1,0,3,2] row_mask:0xf bank_mask:0xf bound_ctrl:1
	v_mov_b32_dpp v75, v74 row_half_mirror row_mask:0xf bank_mask:0xf bound_ctrl:1
	s_nop 0
	v_add_f32_dpp v16, v16, v16 quad_perm:[2,3,0,1] row_mask:0xf bank_mask:0xf bound_ctrl:1
	s_nop 1
	v_add_f32_dpp v16, v16, v16 row_half_mirror row_mask:0xf bank_mask:0xf bound_ctrl:1
	s_waitcnt lgkmcnt(3)
	v_pk_mul_f32 v[28:29], v[16:17], v[176:177] op_sel_hi:[0,1]
	v_pk_mul_f32 v[30:31], v[16:17], v[178:179] op_sel_hi:[0,1]
	v_pk_fma_f32 v[24:25], v[66:67], v[182:183], v[30:31] op_sel_hi:[0,1,1] neg_lo:[0,0,1] neg_hi:[0,0,1]
	v_pk_fma_f32 v[22:23], v[66:67], v[180:181], v[28:29] op_sel_hi:[0,1,1] neg_lo:[0,0,1] neg_hi:[0,0,1]
	v_pk_fma_f32 v[68:69], v[70:71], v[164:165], v[22:23]
	v_pk_fma_f32 v[70:71], v[72:73], v[166:167], v[24:25]
	s_nop 2
	s_waitcnt lgkmcnt(0)
; DI void rwkv_scan_task(const Params& p, int srow0, int T, int h, int rq, const float* S0, float* Sout, int comb_bh, int comb_seg, unsigned char* smem) {
;     ...
;           for (int u = 0; u < 8; u++) {
;             const float* o = ops + (bsel * 16 + j * 8 + u) * 384;
;             const float v = o[192 + Rr];
;             const float br = sc[(bsel * 16 + j * 8 + u) * 2], kr = sc[(bsel * 16 + j * 8 + u) * 2 + 1];
;             f32x4v d1v = S[0] * *(const f32x4v*)(o + 256 + c0) + S[1] * *(const f32x4v*)(o + 256 + c0 + 4);
;             f32x4v d2v = S[0] * *(const f32x4v*)(o + 64 + c0) + S[1] * *(const f32x4v*)(o + 64 + c0 + 4);
;             float d1 = (d1v.x + d1v.y) + (d1v.z + d1v.w), d2 = (d2v.x + d2v.y) + (d2v.z + d2v.w);
;             d1 = dpp_add<0xB1>(d1); d2 = dpp_add<0xB1>(d2); d1 = dpp_add<0x4E>(d1); d2 = dpp_add<0x4E>(d2);
;             d1 = dpp_add<0x141>(d1); d2 = dpp_add<0x141>(d2);
; #pragma unroll
;             for (int m = 0; m < 2; m++) {
;               const f32x4v w = *(const f32x4v*)(o + c0 + 4 * m), kp = *(const f32x4v*)(o + 128 + c0 + 4 * m), bb = *(const f32x4v*)(o + 320 + c0 + 4 * m);
;               S[m] = S[m] * w + (kp * v - bb * d1);
;             }
;             const float y = d2 - d1 * br + v * kr;
;             yk = (u == c8) ? y : yk;
	v_pk_mul_f32 v[30:31], v[16:17], v[98:99] op_sel_hi:[0,1]
	v_pk_mul_f32 v[28:29], v[16:17], v[96:97] op_sel_hi:[0,1]
	v_pk_fma_f32 v[22:23], v[66:67], v[208:209], v[28:29] op_sel_hi:[0,1,1] neg_lo:[0,0,1] neg_hi:[0,0,1]
	v_pk_fma_f32 v[24:25], v[66:67], v[210:211], v[30:31] op_sel_hi:[0,1,1] neg_lo:[0,0,1] neg_hi:[0,0,1]
	v_pk_fma_f32 v[30:31], v[32:33], v[174:175], v[24:25]
	v_pk_fma_f32 v[32:33], v[34:35], v[172:173], v[22:23]
	v_add_f32_e32 v18, v74, v75
	v_fma_f32 v16, -v102, v16, v18
	v_fmac_f32_e32 v16, v17, v103
	v_cndmask_b32_e64 v35, v67, v16, s[12:13]
	ds_read2st64_b32 v[16:17], v77 offset0:27 offset1:33
	ds_read_b128 v[190:193], v36 offset:7168
	ds_read_b128 v[216:219], v36 offset:7184
	ds_read_b128 v[212:215], v36 offset:6400
	ds_read_b128 v[112:115], v36 offset:6416
	ds_read_b128 v[116:119], v36 offset:6144
	ds_read_b128 v[136:139], v36 offset:6656
	ds_read_b128 v[120:123], v36 offset:7424
	ds_read_b128 v[124:127], v36 offset:6160
	ds_read_b128 v[140:143], v36 offset:6672
	ds_read_b128 v[144:147], v36 offset:7440
	ds_read_b128 v[128:131], v36 offset:8704
	ds_read_b128 v[152:155], v36 offset:8720
	ds_read_b128 v[132:135], v36 offset:7936
	s_waitcnt lgkmcnt(11)
	ds_read_b128 v[168:171], v36 offset:7952
	ds_read_b128 v[148:151], v36 offset:7680
	ds_read_b128 v[176:179], v36 offset:8192
	v_pk_mul_f32 v[22:23], v[32:33], v[216:217]
	v_pk_mul_f32 v[24:25], v[30:31], v[218:219]
	v_pk_fma_f32 v[28:29], v[68:69], v[190:191], v[22:23]
	v_pk_fma_f32 v[26:27], v[70:71], v[192:193], v[24:25]
	s_nop 1
	s_waitcnt lgkmcnt(12)
	ds_read_b128 v[180:183], v36 offset:8960
	ds_read_b128 v[164:167], v36 offset:7696
	v_pk_mul_f32 v[22:23], v[32:33], v[112:113]
	v_pk_mul_f32 v[24:25], v[30:31], v[114:115]
	v_pk_fma_f32 v[18:19], v[68:69], v[212:213], v[22:23]
	v_pk_mov_b32 v[22:23], v[28:29], v[26:27] op_sel:[1,0]
	v_mov_b32_e32 v29, v27
	v_pk_fma_f32 v[20:21], v[70:71], v[214:215], v[24:25]
	v_pk_add_f32 v[22:23], v[22:23], v[28:29]
	v_add_f32_e32 v18, v18, v19
	v_add_f32_e32 v22, v22, v23
	v_add_f32_e32 v19, v20, v21
	v_add_f32_e32 v18, v18, v19
	s_nop 0
	v_add_f32_dpp v19, v22, v22 quad_perm:[1,0,3,2] row_mask:0xf bank_mask:0xf bound_ctrl:1
	v_add_f32_dpp v18, v18, v18 quad_perm:[1,0,3,2] row_mask:0xf bank_mask:0xf bound_ctrl:1
	s_nop 0
	v_add_f32_dpp v19, v19, v19 quad_perm:[2,3,0,1] row_mask:0xf bank_mask:0xf bound_ctrl:1
	v_add_f32_dpp v72, v18, v18 quad_perm:[2,3,0,1] row_mask:0xf bank_mask:0xf bound_ctrl:1
	s_nop 0
	v_add_f32_dpp v34, v19, v19 row_half_mirror row_mask:0xf bank_mask:0xf bound_ctrl:1
	s_nop 2
	v_mov_b32_dpp v73, v72 row_half_mirror row_mask:0xf bank_mask:0xf bound_ctrl:1
	s_waitcnt lgkmcnt(11)
	ds_read_b128 v[96:99], v36 offset:8208
	ds_read_b128 v[208:211], v36 offset:8976
	v_pk_mul_f32 v[26:27], v[34:35], v[120:121] op_sel_hi:[0,1]
	v_pk_mul_f32 v[28:29], v[34:35], v[122:123] op_sel_hi:[0,1]
	v_pk_fma_f32 v[24:25], v[16:17], v[138:139], v[28:29] op_sel_hi:[0,1,1] neg_lo:[0,0,1] neg_hi:[0,0,1]
	v_pk_fma_f32 v[22:23], v[16:17], v[136:137], v[26:27] op_sel_hi:[0,1,1] neg_lo:[0,0,1] neg_hi:[0,0,1]
	v_pk_fma_f32 v[66:67], v[68:69], v[116:117], v[22:23]
	v_pk_fma_f32 v[68:69], v[70:71], v[118:119], v[24:25]
	s_nop 2
	s_waitcnt lgkmcnt(10)
	v_pk_mul_f32 v[26:27], v[34:35], v[144:145] op_sel_hi:[0,1]
	v_pk_mul_f32 v[28:29], v[34:35], v[146:147] op_sel_hi:[0,1]
	v_pk_fma_f32 v[22:23], v[16:17], v[140:141], v[26:27] op_sel_hi:[0,1,1] neg_lo:[0,0,1] neg_hi:[0,0,1]
	v_pk_fma_f32 v[24:25], v[16:17], v[142:143], v[28:29] op_sel_hi:[0,1,1] neg_lo:[0,0,1] neg_hi:[0,0,1]
	v_pk_fma_f32 v[32:33], v[32:33], v[124:125], v[22:23]
	v_add_f32_e32 v18, v72, v73
	v_pk_fma_f32 v[30:31], v[30:31], v[126:127], v[24:25]
	v_fma_f32 v12, -v104, v34, v18
	s_nop 1
	v_fmac_f32_e32 v12, v16, v105
	v_cndmask_b32_e64 v70, v35, v12, s[14:15]
	s_waitcnt lgkmcnt(8)
	v_pk_mul_f32 v[12:13], v[32:33], v[152:153]
	v_pk_mul_f32 v[22:23], v[30:31], v[154:155]
	v_pk_fma_f32 v[12:13], v[66:67], v[128:129], v[12:13]
	v_pk_fma_f32 v[26:27], v[68:69], v[130:131], v[22:23]
	s_nop 1
	s_waitcnt lgkmcnt(6)
	v_pk_mul_f32 v[22:23], v[32:33], v[168:169]
	v_pk_mul_f32 v[24:25], v[30:31], v[170:171]
	v_pk_fma_f32 v[18:19], v[66:67], v[132:133], v[22:23]
	v_pk_mov_b32 v[22:23], v[12:13], v[26:27] op_sel:[1,0]
	v_mov_b32_e32 v13, v27
	v_pk_fma_f32 v[20:21], v[68:69], v[134:135], v[24:25]
	v_pk_add_f32 v[12:13], v[22:23], v[12:13]
	v_add_f32_e32 v16, v20, v21
	v_add_f32_e32 v12, v12, v13
	v_add_f32_e32 v13, v18, v19
	s_nop 2
	v_add_f32_e32 v13, v13, v16
	v_add_f32_dpp v12, v12, v12 quad_perm:[1,0,3,2] row_mask:0xf bank_mask:0xf bound_ctrl:1
	v_mov_b32_e32 v16, v17
	v_add_f32_dpp v13, v13, v13 quad_perm:[1,0,3,2] row_mask:0xf bank_mask:0xf bound_ctrl:1
	v_add_f32_dpp v12, v12, v12 quad_perm:[2,3,0,1] row_mask:0xf bank_mask:0xf bound_ctrl:1
	s_nop 0
	v_add_f32_dpp v13, v13, v13 quad_perm:[2,3,0,1] row_mask:0xf bank_mask:0xf bound_ctrl:1
	v_add_f32_dpp v12, v12, v12 row_half_mirror row_mask:0xf bank_mask:0xf bound_ctrl:1
	s_waitcnt lgkmcnt(3)
	v_pk_mul_f32 v[26:27], v[12:13], v[180:181] op_sel_hi:[0,1]
	v_pk_mul_f32 v[28:29], v[12:13], v[182:183] op_sel_hi:[0,1]
	v_pk_fma_f32 v[24:25], v[16:17], v[178:179], v[28:29] op_sel_hi:[0,1,1] neg_lo:[0,0,1] neg_hi:[0,0,1]
	v_pk_fma_f32 v[22:23], v[16:17], v[176:177], v[26:27] op_sel_hi:[0,1,1] neg_lo:[0,0,1] neg_hi:[0,0,1]
	v_pk_fma_f32 v[34:35], v[66:67], v[148:149], v[22:23]
	v_pk_fma_f32 v[66:67], v[68:69], v[150:151], v[24:25]
	s_nop 2
	v_mov_b32_dpp v71, v13 row_half_mirror row_mask:0xf bank_mask:0xf bound_ctrl:1
	s_waitcnt lgkmcnt(0)
; DI void rwkv_scan_task(const Params& p, int srow0, int T, int h, int rq, const float* S0, float* Sout, int comb_bh, int comb_seg, unsigned char* smem) {
;     ...
;           for (int u = 0; u < 8; u++) {
;             const float* o = ops + (bsel * 16 + j * 8 + u) * 384;
;             const float v = o[192 + Rr];
;             const float br = sc[(bsel * 16 + j * 8 + u) * 2], kr = sc[(bsel * 16 + j * 8 + u) * 2 + 1];
;             f32x4v d1v = S[0] * *(const f32x4v*)(o + 256 + c0) + S[1] * *(const f32x4v*)(o + 256 + c0 + 4);
;             f32x4v d2v = S[0] * *(const f32x4v*)(o + 64 + c0) + S[1] * *(const f32x4v*)(o + 64 + c0 + 4);
;             float d1 = (d1v.x + d1v.y) + (d1v.z + d1v.w), d2 = (d2v.x + d2v.y) + (d2v.z + d2v.w);
;             d1 = dpp_add<0xB1>(d1); d2 = dpp_add<0xB1>(d2); d1 = dpp_add<0x4E>(d1); d2 = dpp_add<0x4E>(d2);
;             d1 = dpp_add<0x141>(d1); d2 = dpp_add<0x141>(d2);
; #pragma unroll
;             for (int m = 0; m < 2; m++) {
;               const f32x4v w = *(const f32x4v*)(o + c0 + 4 * m), kp = *(const f32x4v*)(o + 128 + c0 + 4 * m), bb = *(const f32x4v*)(o + 320 + c0 + 4 * m);
;               S[m] = S[m] * w + (kp * v - bb * d1);
;             }
;             const float y = d2 - d1 * br + v * kr;
;             yk = (u == c8) ? y : yk;
	v_pk_mul_f32 v[28:29], v[12:13], v[210:211] op_sel_hi:[0,1]
	v_pk_mul_f32 v[26:27], v[12:13], v[208:209] op_sel_hi:[0,1]
	v_add_f32_e32 v13, v13, v71
	v_fma_f32 v12, -v106, v12, v13
	v_pk_fma_f32 v[22:23], v[16:17], v[96:97], v[26:27] op_sel_hi:[0,1,1] neg_lo:[0,0,1] neg_hi:[0,0,1]
	v_pk_fma_f32 v[24:25], v[16:17], v[98:99], v[28:29] op_sel_hi:[0,1,1] neg_lo:[0,0,1] neg_hi:[0,0,1]
	v_fmac_f32_e32 v12, v17, v107
	v_pk_fma_f32 v[26:27], v[30:31], v[166:167], v[24:25]
	v_pk_fma_f32 v[28:29], v[32:33], v[164:165], v[22:23]
	v_cndmask_b32_e64 v31, v70, v12, s[16:17]
	ds_read2st64_b32 v[12:13], v77 offset0:39 offset1:45
	ds_read_b128 v[172:175], v36 offset:10240
	ds_read_b128 v[100:103], v36 offset:10256
	ds_read_b128 v[216:219], v36 offset:9472
	ds_read_b128 v[190:193], v36 offset:9488
	ds_read_b128 v[112:115], v36 offset:9216
	ds_read_b128 v[212:215], v36 offset:9728
	ds_read_b128 v[120:123], v36 offset:10496
	ds_read_b128 v[136:139], v36 offset:9232
	ds_read_b128 v[116:119], v36 offset:9744
	ds_read_b128 v[144:147], v36 offset:10512
	ds_read_b128 v[140:143], v36 offset:11776
	ds_read_b128 v[124:127], v36 offset:11792
	ds_read_b128 v[152:155], v36 offset:11008
	s_waitcnt lgkmcnt(11)
	ds_read_b128 v[128:131], v36 offset:11024
	ds_read_b128 v[168:171], v36 offset:10752
	ds_read_b128 v[132:135], v36 offset:11264
	v_pk_mul_f32 v[18:19], v[28:29], v[100:101]
	v_pk_mul_f32 v[20:21], v[26:27], v[102:103]
	v_pk_fma_f32 v[24:25], v[34:35], v[172:173], v[18:19]
	v_pk_fma_f32 v[22:23], v[66:67], v[174:175], v[20:21]
	s_nop 1
	s_waitcnt lgkmcnt(12)
	ds_read_b128 v[180:183], v36 offset:12032
	ds_read_b128 v[176:179], v36 offset:10768
	v_pk_mul_f32 v[18:19], v[28:29], v[190:191]
	v_pk_mul_f32 v[20:21], v[26:27], v[192:193]
	v_pk_fma_f32 v[14:15], v[34:35], v[216:217], v[18:19]
	v_pk_mov_b32 v[18:19], v[24:25], v[22:23] op_sel:[1,0]
	v_mov_b32_e32 v25, v23
	v_pk_fma_f32 v[16:17], v[66:67], v[218:219], v[20:21]
	v_pk_add_f32 v[18:19], v[18:19], v[24:25]
	v_add_f32_e32 v14, v14, v15
	v_add_f32_e32 v18, v18, v19
	v_add_f32_e32 v15, v16, v17
	v_add_f32_e32 v14, v14, v15
	s_nop 0
	v_add_f32_dpp v15, v18, v18 quad_perm:[1,0,3,2] row_mask:0xf bank_mask:0xf bound_ctrl:1
	v_add_f32_dpp v14, v14, v14 quad_perm:[1,0,3,2] row_mask:0xf bank_mask:0xf bound_ctrl:1
	s_nop 0
	v_add_f32_dpp v15, v15, v15 quad_perm:[2,3,0,1] row_mask:0xf bank_mask:0xf bound_ctrl:1
	v_add_f32_dpp v68, v14, v14 quad_perm:[2,3,0,1] row_mask:0xf bank_mask:0xf bound_ctrl:1
	s_nop 0
	v_add_f32_dpp v30, v15, v15 row_half_mirror row_mask:0xf bank_mask:0xf bound_ctrl:1
	s_nop 2
	v_mov_b32_dpp v69, v68 row_half_mirror row_mask:0xf bank_mask:0xf bound_ctrl:1
	s_waitcnt lgkmcnt(11)
	ds_read_b128 v[148:151], v36 offset:11280
	ds_read_b128 v[208:211], v36 offset:12048
	v_pk_mul_f32 v[22:23], v[30:31], v[120:121] op_sel_hi:[0,1]
	v_pk_mul_f32 v[24:25], v[30:31], v[122:123] op_sel_hi:[0,1]
	v_pk_fma_f32 v[20:21], v[12:13], v[214:215], v[24:25] op_sel_hi:[0,1,1] neg_lo:[0,0,1] neg_hi:[0,0,1]
	v_pk_fma_f32 v[18:19], v[12:13], v[212:213], v[22:23] op_sel_hi:[0,1,1] neg_lo:[0,0,1] neg_hi:[0,0,1]
	v_pk_fma_f32 v[32:33], v[34:35], v[112:113], v[18:19]
	v_pk_fma_f32 v[34:35], v[66:67], v[114:115], v[20:21]
	s_nop 2
	s_waitcnt lgkmcnt(10)
	v_pk_mul_f32 v[22:23], v[30:31], v[144:145] op_sel_hi:[0,1]
	v_pk_mul_f32 v[24:25], v[30:31], v[146:147] op_sel_hi:[0,1]
	v_pk_fma_f32 v[18:19], v[12:13], v[116:117], v[22:23] op_sel_hi:[0,1,1] neg_lo:[0,0,1] neg_hi:[0,0,1]
	v_pk_fma_f32 v[20:21], v[12:13], v[118:119], v[24:25] op_sel_hi:[0,1,1] neg_lo:[0,0,1] neg_hi:[0,0,1]
	v_pk_fma_f32 v[28:29], v[28:29], v[136:137], v[18:19]
	v_add_f32_e32 v14, v68, v69
	v_pk_fma_f32 v[26:27], v[26:27], v[138:139], v[20:21]
	v_fma_f32 v8, -v108, v30, v14
	s_nop 1
	v_fmac_f32_e32 v8, v12, v109
	v_cndmask_b32_e64 v30, v31, v8, s[18:19]
	s_waitcnt lgkmcnt(8)
	v_pk_mul_f32 v[8:9], v[28:29], v[124:125]
	v_pk_mul_f32 v[18:19], v[26:27], v[126:127]
	v_pk_fma_f32 v[8:9], v[32:33], v[140:141], v[8:9]
	v_pk_fma_f32 v[22:23], v[34:35], v[142:143], v[18:19]
	s_nop 1
	s_waitcnt lgkmcnt(6)
	v_pk_mul_f32 v[18:19], v[28:29], v[128:129]
	v_pk_mul_f32 v[20:21], v[26:27], v[130:131]
	v_pk_fma_f32 v[14:15], v[32:33], v[152:153], v[18:19]
	v_pk_mov_b32 v[18:19], v[8:9], v[22:23] op_sel:[1,0]
	v_mov_b32_e32 v9, v23
	v_pk_fma_f32 v[16:17], v[34:35], v[154:155], v[20:21]
	v_pk_add_f32 v[8:9], v[18:19], v[8:9]
	v_add_f32_e32 v12, v16, v17
	v_add_f32_e32 v8, v8, v9
	v_add_f32_e32 v9, v14, v15
	s_nop 2
	v_add_f32_e32 v9, v9, v12
	v_add_f32_dpp v8, v8, v8 quad_perm:[1,0,3,2] row_mask:0xf bank_mask:0xf bound_ctrl:1
	v_mov_b32_e32 v12, v13
	v_add_f32_dpp v9, v9, v9 quad_perm:[1,0,3,2] row_mask:0xf bank_mask:0xf bound_ctrl:1
	v_add_f32_dpp v8, v8, v8 quad_perm:[2,3,0,1] row_mask:0xf bank_mask:0xf bound_ctrl:1
	s_nop 0
	v_add_f32_dpp v9, v9, v9 quad_perm:[2,3,0,1] row_mask:0xf bank_mask:0xf bound_ctrl:1
	v_add_f32_dpp v8, v8, v8 row_half_mirror row_mask:0xf bank_mask:0xf bound_ctrl:1
	s_waitcnt lgkmcnt(3)
	v_pk_mul_f32 v[24:25], v[8:9], v[182:183] op_sel_hi:[0,1]
	v_pk_mul_f32 v[22:23], v[8:9], v[180:181] op_sel_hi:[0,1]
	v_pk_fma_f32 v[18:19], v[12:13], v[132:133], v[22:23] op_sel_hi:[0,1,1] neg_lo:[0,0,1] neg_hi:[0,0,1]
	v_pk_fma_f32 v[20:21], v[12:13], v[134:135], v[24:25] op_sel_hi:[0,1,1] neg_lo:[0,0,1] neg_hi:[0,0,1]
	v_pk_fma_f32 v[34:35], v[34:35], v[170:171], v[20:21]
	v_pk_fma_f32 v[74:75], v[32:33], v[168:169], v[18:19]
	s_nop 2
	v_mov_b32_dpp v31, v9 row_half_mirror row_mask:0xf bank_mask:0xf bound_ctrl:1
	s_waitcnt lgkmcnt(0)
; DI void rwkv_scan_task(const Params& p, int srow0, int T, int h, int rq, const float* S0, float* Sout, int comb_bh, int comb_seg, unsigned char* smem) {
;     ...
;           for (int u = 0; u < 8; u++) {
;             const float* o = ops + (bsel * 16 + j * 8 + u) * 384;
;             const float v = o[192 + Rr];
;             const float br = sc[(bsel * 16 + j * 8 + u) * 2], kr = sc[(bsel * 16 + j * 8 + u) * 2 + 1];
;             f32x4v d1v = S[0] * *(const f32x4v*)(o + 256 + c0) + S[1] * *(const f32x4v*)(o + 256 + c0 + 4);
;             f32x4v d2v = S[0] * *(const f32x4v*)(o + 64 + c0) + S[1] * *(const f32x4v*)(o + 64 + c0 + 4);
;             float d1 = (d1v.x + d1v.y) + (d1v.z + d1v.w), d2 = (d2v.x + d2v.y) + (d2v.z + d2v.w);
;             d1 = dpp_add<0xB1>(d1); d2 = dpp_add<0xB1>(d2); d1 = dpp_add<0x4E>(d1); d2 = dpp_add<0x4E>(d2);
;             d1 = dpp_add<0x141>(d1); d2 = dpp_add<0x141>(d2);
; #pragma unroll
;             for (int m = 0; m < 2; m++) {
;               const f32x4v w = *(const f32x4v*)(o + c0 + 4 * m), kp = *(const f32x4v*)(o + 128 + c0 + 4 * m), bb = *(const f32x4v*)(o + 320 + c0 + 4 * m);
;               S[m] = S[m] * w + (kp * v - bb * d1);
;             }
;             const float y = d2 - d1 * br + v * kr;
;             yk = (u == c8) ? y : yk;
;           }
;           ybuf[bsel * 512 + (j * 8 + c8) * 32 + i] = yk;
	v_pk_mul_f32 v[22:23], v[8:9], v[208:209] op_sel_hi:[0,1]
	v_pk_mul_f32 v[24:25], v[8:9], v[210:211] op_sel_hi:[0,1]
	v_add_f32_e32 v9, v9, v31
	v_fma_f32 v8, -v110, v8, v9
	v_fmac_f32_e32 v8, v13, v111
	v_cndmask_b32_e64 v8, v30, v8, s[20:21]
	v_pk_fma_f32 v[20:21], v[12:13], v[150:151], v[24:25] op_sel_hi:[0,1,1] neg_lo:[0,0,1] neg_hi:[0,0,1]
	v_pk_fma_f32 v[18:19], v[12:13], v[148:149], v[22:23] op_sel_hi:[0,1,1] neg_lo:[0,0,1] neg_hi:[0,0,1]
	ds_write_b32 v83, v8 offset:49408
	v_pk_fma_f32 v[86:87], v[28:29], v[176:177], v[18:19]
	v_pk_fma_f32 v[88:89], v[26:27], v[178:179], v[20:21]
	ds_read2st64_b32 v[24:25], v77 offset0:51 offset1:57
	ds_read_b128 v[96:99], v163 offset:49216
	ds_read_b128 v[104:107], v163 offset:49232
	ds_read_b128 v[164:167], v163 offset:49248
	ds_read_b128 v[100:103], v163 offset:49264
	ds_read_b128 v[172:175], v36 offset:13312
	ds_read_b128 v[190:193], v36 offset:13328
	ds_read_b128 v[216:219], v36 offset:12544
	ds_read_b128 v[120:123], v36 offset:12560
	ds_read_b128 v[212:215], v36 offset:12288
	ds_read_b128 v[112:115], v36 offset:12304
	ds_read_b128 v[144:147], v36 offset:12800
	ds_read_b128 v[116:119], v36 offset:13568
	s_waitcnt lgkmcnt(6)
	ds_read_b128 v[136:139], v36 offset:12816
	ds_read_b128 v[124:127], v36 offset:13584
	ds_read_b128 v[140:143], v36 offset:14848
	ds_read_b128 v[128:131], v36 offset:14864
	ds_read_b128 v[152:155], v36 offset:14080
	ds_read_b128 v[180:183], v36 offset:14096
	ds_read_b128 v[132:135], v36 offset:13824
	ds_read_b128 v[168:171], v36 offset:14336
	v_pk_mul_f32 v[32:33], v[88:89], v[192:193]
	v_pk_mul_f32 v[30:31], v[86:87], v[190:191]
	v_pk_fma_f32 v[68:69], v[34:35], v[174:175], v[32:33]
	v_pk_fma_f32 v[66:67], v[74:75], v[172:173], v[30:31]
	s_nop 1
	s_waitcnt lgkmcnt(12)
	ds_read_b128 v[208:211], v36 offset:15104
	ds_read_b128 v[108:111], v36 offset:13840
	v_pk_mul_f32 v[30:31], v[86:87], v[120:121]
	v_pk_mul_f32 v[32:33], v[88:89], v[122:123]
	v_pk_fma_f32 v[26:27], v[74:75], v[216:217], v[30:31]
	v_pk_mov_b32 v[30:31], v[66:67], v[68:69] op_sel:[1,0]
	v_mov_b32_e32 v67, v69
	v_pk_fma_f32 v[28:29], v[34:35], v[218:219], v[32:33]
	v_pk_add_f32 v[30:31], v[30:31], v[66:67]
	v_add_f32_e32 v26, v26, v27
	v_add_f32_e32 v30, v30, v31
	v_add_f32_e32 v27, v28, v29
	v_add_f32_e32 v26, v26, v27
	s_nop 0
	v_add_f32_dpp v27, v30, v30 quad_perm:[1,0,3,2] row_mask:0xf bank_mask:0xf bound_ctrl:1
	v_add_f32_dpp v26, v26, v26 quad_perm:[1,0,3,2] row_mask:0xf bank_mask:0xf bound_ctrl:1
	s_nop 0
	v_add_f32_dpp v27, v27, v27 quad_perm:[2,3,0,1] row_mask:0xf bank_mask:0xf bound_ctrl:1
	v_add_f32_dpp v91, v26, v26 quad_perm:[2,3,0,1] row_mask:0xf bank_mask:0xf bound_ctrl:1
	s_nop 0
	v_add_f32_dpp v90, v27, v27 row_half_mirror row_mask:0xf bank_mask:0xf bound_ctrl:1
	s_nop 3
	v_mov_b32_dpp v92, v91 row_half_mirror row_mask:0xf bank_mask:0xf bound_ctrl:1
	s_waitcnt lgkmcnt(10)
	ds_read_b128 v[148:151], v36 offset:14352
	ds_read_b128 v[176:179], v36 offset:15120
	v_pk_mul_f32 v[70:71], v[90:91], v[116:117] op_sel_hi:[0,1]
	v_pk_mul_f32 v[72:73], v[90:91], v[118:119] op_sel_hi:[0,1]
	v_pk_fma_f32 v[68:69], v[24:25], v[146:147], v[72:73] op_sel_hi:[0,1,1] neg_lo:[0,0,1] neg_hi:[0,0,1]
	v_pk_fma_f32 v[66:67], v[24:25], v[144:145], v[70:71] op_sel_hi:[0,1,1] neg_lo:[0,0,1] neg_hi:[0,0,1]
	v_pk_fma_f32 v[70:71], v[74:75], v[212:213], v[66:67]
	v_pk_fma_f32 v[34:35], v[34:35], v[214:215], v[68:69]
	s_nop 1
	s_waitcnt lgkmcnt(10)
	v_pk_mul_f32 v[66:67], v[90:91], v[124:125] op_sel_hi:[0,1]
	v_pk_mul_f32 v[68:69], v[90:91], v[126:127] op_sel_hi:[0,1]
	v_pk_fma_f32 v[26:27], v[24:25], v[136:137], v[66:67] op_sel_hi:[0,1,1] neg_lo:[0,0,1] neg_hi:[0,0,1]
	v_pk_fma_f32 v[28:29], v[24:25], v[138:139], v[68:69] op_sel_hi:[0,1,1] neg_lo:[0,0,1] neg_hi:[0,0,1]
	v_pk_fma_f32 v[74:75], v[86:87], v[112:113], v[26:27]
	v_add_f32_e32 v26, v91, v92
	v_pk_fma_f32 v[72:73], v[88:89], v[114:115], v[28:29]
	v_fma_f32 v20, -v96, v90, v26
	s_nop 1
	v_fmac_f32_e32 v20, v24, v97
	v_cndmask_b32_e64 v86, 0, v20, s[6:7]
	v_lshlrev_b32_e32 v90, 16, v52
	v_and_b32_e32 v91, 0xffff0000, v52
	s_waitcnt lgkmcnt(8)
	v_pk_mul_f32 v[20:21], v[74:75], v[128:129]
	v_pk_mul_f32 v[30:31], v[72:73], v[130:131]
	v_pk_fma_f32 v[20:21], v[70:71], v[140:141], v[20:21]
	v_pk_fma_f32 v[66:67], v[34:35], v[142:143], v[30:31]
	s_nop 1
	v_lshlrev_b32_e32 v92, 16, v53
	s_waitcnt vmcnt(6)
	v_and_b32_e32 v52, 0xffff0000, v50
	v_lshlrev_b32_e32 v53, 16, v50
	v_lshlrev_b32_e32 v88, 16, v55
	s_waitcnt lgkmcnt(6)
	v_pk_mul_f32 v[30:31], v[74:75], v[180:181]
	v_pk_mul_f32 v[32:33], v[72:73], v[182:183]
	v_pk_fma_f32 v[26:27], v[70:71], v[152:153], v[30:31]
	v_pk_mov_b32 v[30:31], v[20:21], v[66:67] op_sel:[1,0]
	v_mov_b32_e32 v21, v67
	v_pk_fma_f32 v[28:29], v[34:35], v[154:155], v[32:33]
	v_pk_add_f32 v[20:21], v[30:31], v[20:21]
	v_add_f32_e32 v24, v28, v29
	v_add_f32_e32 v20, v20, v21
	v_add_f32_e32 v21, v26, v27
	s_nop 2
	v_add_f32_e32 v21, v21, v24
	v_add_f32_dpp v20, v20, v20 quad_perm:[1,0,3,2] row_mask:0xf bank_mask:0xf bound_ctrl:1
	v_mov_b32_e32 v24, v25
	v_add_f32_dpp v21, v21, v21 quad_perm:[1,0,3,2] row_mask:0xf bank_mask:0xf bound_ctrl:1
	v_add_f32_dpp v20, v20, v20 quad_perm:[2,3,0,1] row_mask:0xf bank_mask:0xf bound_ctrl:1
	v_and_b32_e32 v89, 0xffff0000, v55
	v_add_f32_dpp v21, v21, v21 quad_perm:[2,3,0,1] row_mask:0xf bank_mask:0xf bound_ctrl:1
	v_add_f32_dpp v20, v20, v20 row_half_mirror row_mask:0xf bank_mask:0xf bound_ctrl:1
	s_waitcnt lgkmcnt(3)
; DI void rwkv_scan_task(const Params& p, int srow0, int T, int h, int rq, const float* S0, float* Sout, int comb_bh, int comb_seg, unsigned char* smem) {
;     ...
;           for (int u = 0; u < 8; u++) {
;             const float* o = ops + (bsel * 16 + j * 8 + u) * 384;
;             const float v = o[192 + Rr];
;             const float br = sc[(bsel * 16 + j * 8 + u) * 2], kr = sc[(bsel * 16 + j * 8 + u) * 2 + 1];
;             f32x4v d1v = S[0] * *(const f32x4v*)(o + 256 + c0) + S[1] * *(const f32x4v*)(o + 256 + c0 + 4);
;             f32x4v d2v = S[0] * *(const f32x4v*)(o + 64 + c0) + S[1] * *(const f32x4v*)(o + 64 + c0 + 4);
;             float d1 = (d1v.x + d1v.y) + (d1v.z + d1v.w), d2 = (d2v.x + d2v.y) + (d2v.z + d2v.w);
;             d1 = dpp_add<0xB1>(d1); d2 = dpp_add<0xB1>(d2); d1 = dpp_add<0x4E>(d1); d2 = dpp_add<0x4E>(d2);
;             d1 = dpp_add<0x141>(d1); d2 = dpp_add<0x141>(d2);
; #pragma unroll
;             for (int m = 0; m < 2; m++) {
;               const f32x4v w = *(const f32x4v*)(o + c0 + 4 * m), kp = *(const f32x4v*)(o + 128 + c0 + 4 * m), bb = *(const f32x4v*)(o + 320 + c0 + 4 * m);
;               S[m] = S[m] * w + (kp * v - bb * d1);
;             }
;             const float y = d2 - d1 * br + v * kr;
;             yk = (u == c8) ? y : yk;
	v_pk_mul_f32 v[66:67], v[20:21], v[208:209] op_sel_hi:[0,1]
	v_pk_mul_f32 v[68:69], v[20:21], v[210:211] op_sel_hi:[0,1]
	v_pk_fma_f32 v[32:33], v[24:25], v[170:171], v[68:69] op_sel_hi:[0,1,1] neg_lo:[0,0,1] neg_hi:[0,0,1]
	v_pk_fma_f32 v[30:31], v[24:25], v[168:169], v[66:67] op_sel_hi:[0,1,1] neg_lo:[0,0,1] neg_hi:[0,0,1]
	v_pk_fma_f32 v[70:71], v[70:71], v[132:133], v[30:31]
	v_pk_fma_f32 v[34:35], v[34:35], v[134:135], v[32:33]
	s_nop 2
	v_mov_b32_dpp v87, v21 row_half_mirror row_mask:0xf bank_mask:0xf bound_ctrl:1
	v_and_b32_e32 v55, 0xffff0000, v46
	v_and_b32_e32 v50, 0xffff0000, v48
	s_waitcnt lgkmcnt(0)
	v_pk_mul_f32 v[68:69], v[20:21], v[178:179] op_sel_hi:[0,1]
	v_pk_mul_f32 v[66:67], v[20:21], v[176:177] op_sel_hi:[0,1]
	v_add_f32_e32 v21, v21, v87
	v_fma_f32 v20, -v98, v20, v21
	v_pk_fma_f32 v[30:31], v[24:25], v[148:149], v[66:67] op_sel_hi:[0,1,1] neg_lo:[0,0,1] neg_hi:[0,0,1]
	v_pk_fma_f32 v[32:33], v[24:25], v[150:151], v[68:69] op_sel_hi:[0,1,1] neg_lo:[0,0,1] neg_hi:[0,0,1]
	v_fmac_f32_e32 v20, v25, v99
	v_pk_fma_f32 v[66:67], v[72:73], v[110:111], v[32:33]
	v_pk_fma_f32 v[68:69], v[74:75], v[108:109], v[30:31]
	v_cndmask_b32_e64 v73, v86, v20, s[8:9]
	ds_read2st64_b32 v[20:21], v77 offset0:63 offset1:69
	ds_read_b128 v[190:193], v36 offset:16384
	ds_read_b128 v[172:175], v36 offset:16400
	ds_read_b128 v[120:123], v36 offset:15616
	ds_read_b128 v[216:219], v36 offset:15632
	ds_read_b128 v[116:119], v36 offset:15360
	ds_read_b128 v[144:147], v36 offset:15872
	ds_read_b128 v[212:215], v36 offset:16640
	ds_read_b128 v[124:127], v36 offset:15376
	ds_read_b128 v[136:139], v36 offset:15888
	ds_read_b128 v[112:115], v36 offset:16656
	ds_read_b128 v[128:131], v36 offset:17920
	ds_read_b128 v[140:143], v36 offset:17936
	ds_read_b128 v[180:183], v36 offset:17152
	v_and_b32_e32 v87, 0xffff0000, v54
	v_lshlrev_b32_e32 v86, 16, v54
	v_lshlrev_b32_e32 v54, 16, v48
	s_waitcnt lgkmcnt(11)
	ds_read_b128 v[152:155], v36 offset:17168
	ds_read_b128 v[208:211], v36 offset:16896
	ds_read_b128 v[168:171], v36 offset:17408
	v_pk_mul_f32 v[26:27], v[68:69], v[172:173]
	v_pk_mul_f32 v[28:29], v[66:67], v[174:175]
	v_pk_fma_f32 v[32:33], v[70:71], v[190:191], v[26:27]
	v_pk_fma_f32 v[30:31], v[34:35], v[192:193], v[28:29]
	s_nop 1
	s_waitcnt lgkmcnt(12)
	ds_read_b128 v[132:135], v36 offset:18176
	ds_read_b128 v[176:179], v36 offset:16912
	v_pk_mul_f32 v[26:27], v[68:69], v[216:217]
	v_pk_mul_f32 v[28:29], v[66:67], v[218:219]
	v_pk_fma_f32 v[22:23], v[70:71], v[120:121], v[26:27]
	v_pk_mov_b32 v[26:27], v[32:33], v[30:31] op_sel:[1,0]
	v_mov_b32_e32 v33, v31
	v_pk_fma_f32 v[24:25], v[34:35], v[122:123], v[28:29]
	v_pk_add_f32 v[26:27], v[26:27], v[32:33]
	v_add_f32_e32 v22, v22, v23
	v_add_f32_e32 v26, v26, v27
	v_add_f32_e32 v23, v24, v25
	v_add_f32_e32 v22, v22, v23
	s_nop 0
	v_add_f32_dpp v23, v26, v26 quad_perm:[1,0,3,2] row_mask:0xf bank_mask:0xf bound_ctrl:1
	v_add_f32_dpp v22, v22, v22 quad_perm:[1,0,3,2] row_mask:0xf bank_mask:0xf bound_ctrl:1
	s_nop 0
	v_add_f32_dpp v23, v23, v23 quad_perm:[2,3,0,1] row_mask:0xf bank_mask:0xf bound_ctrl:1
	v_add_f32_dpp v74, v22, v22 quad_perm:[2,3,0,1] row_mask:0xf bank_mask:0xf bound_ctrl:1
	s_nop 0
	v_add_f32_dpp v72, v23, v23 row_half_mirror row_mask:0xf bank_mask:0xf bound_ctrl:1
	s_nop 2
	v_mov_b32_dpp v75, v74 row_half_mirror row_mask:0xf bank_mask:0xf bound_ctrl:1
	s_waitcnt lgkmcnt(11)
	ds_read_b128 v[148:151], v36 offset:17424
	ds_read_b128 v[96:99], v36 offset:18192
	v_pk_mul_f32 v[30:31], v[72:73], v[212:213] op_sel_hi:[0,1]
	v_pk_mul_f32 v[32:33], v[72:73], v[214:215] op_sel_hi:[0,1]
	v_pk_fma_f32 v[28:29], v[20:21], v[146:147], v[32:33] op_sel_hi:[0,1,1] neg_lo:[0,0,1] neg_hi:[0,0,1]
	v_pk_fma_f32 v[26:27], v[20:21], v[144:145], v[30:31] op_sel_hi:[0,1,1] neg_lo:[0,0,1] neg_hi:[0,0,1]
	v_pk_fma_f32 v[70:71], v[70:71], v[116:117], v[26:27]
	v_pk_fma_f32 v[34:35], v[34:35], v[118:119], v[28:29]
	s_nop 2
	s_waitcnt lgkmcnt(10)
	v_pk_mul_f32 v[30:31], v[72:73], v[112:113] op_sel_hi:[0,1]
	v_pk_mul_f32 v[32:33], v[72:73], v[114:115] op_sel_hi:[0,1]
	v_pk_fma_f32 v[26:27], v[20:21], v[136:137], v[30:31] op_sel_hi:[0,1,1] neg_lo:[0,0,1] neg_hi:[0,0,1]
	v_pk_fma_f32 v[28:29], v[20:21], v[138:139], v[32:33] op_sel_hi:[0,1,1] neg_lo:[0,0,1] neg_hi:[0,0,1]
	v_pk_fma_f32 v[68:69], v[68:69], v[124:125], v[26:27]
	v_add_f32_e32 v22, v74, v75
	v_pk_fma_f32 v[66:67], v[66:67], v[126:127], v[28:29]
	v_fma_f32 v16, -v104, v72, v22
	s_nop 1
	v_fmac_f32_e32 v16, v20, v105
	v_cndmask_b32_e64 v72, v73, v16, s[10:11]
	s_waitcnt lgkmcnt(8)
	v_pk_mul_f32 v[16:17], v[68:69], v[140:141]
	v_pk_mul_f32 v[26:27], v[66:67], v[142:143]
	v_pk_fma_f32 v[16:17], v[70:71], v[128:129], v[16:17]
	v_pk_fma_f32 v[30:31], v[34:35], v[130:131], v[26:27]
	s_nop 1
	s_waitcnt lgkmcnt(6)
	v_pk_mul_f32 v[26:27], v[68:69], v[152:153]
	v_pk_mul_f32 v[28:29], v[66:67], v[154:155]
	v_pk_fma_f32 v[22:23], v[70:71], v[180:181], v[26:27]
	v_pk_mov_b32 v[26:27], v[16:17], v[30:31] op_sel:[1,0]
	v_mov_b32_e32 v17, v31
	v_pk_fma_f32 v[24:25], v[34:35], v[182:183], v[28:29]
	v_pk_add_f32 v[16:17], v[26:27], v[16:17]
	v_add_f32_e32 v20, v24, v25
	v_add_f32_e32 v16, v16, v17
	v_add_f32_e32 v17, v22, v23
	s_nop 2
	v_add_f32_e32 v17, v17, v20
	v_add_f32_dpp v16, v16, v16 quad_perm:[1,0,3,2] row_mask:0xf bank_mask:0xf bound_ctrl:1
	v_mov_b32_e32 v20, v21
	v_add_f32_dpp v17, v17, v17 quad_perm:[1,0,3,2] row_mask:0xf bank_mask:0xf bound_ctrl:1
	v_add_f32_dpp v16, v16, v16 quad_perm:[2,3,0,1] row_mask:0xf bank_mask:0xf bound_ctrl:1
	s_nop 0
	v_add_f32_dpp v17, v17, v17 quad_perm:[2,3,0,1] row_mask:0xf bank_mask:0xf bound_ctrl:1
	v_add_f32_dpp v16, v16, v16 row_half_mirror row_mask:0xf bank_mask:0xf bound_ctrl:1
	s_waitcnt lgkmcnt(3)
; DI void rwkv_scan_task(const Params& p, int srow0, int T, int h, int rq, const float* S0, float* Sout, int comb_bh, int comb_seg, unsigned char* smem) {
;     ...
;           for (int u = 0; u < 8; u++) {
;             const float* o = ops + (bsel * 16 + j * 8 + u) * 384;
;             const float v = o[192 + Rr];
;             const float br = sc[(bsel * 16 + j * 8 + u) * 2], kr = sc[(bsel * 16 + j * 8 + u) * 2 + 1];
;             f32x4v d1v = S[0] * *(const f32x4v*)(o + 256 + c0) + S[1] * *(const f32x4v*)(o + 256 + c0 + 4);
;             f32x4v d2v = S[0] * *(const f32x4v*)(o + 64 + c0) + S[1] * *(const f32x4v*)(o + 64 + c0 + 4);
;             float d1 = (d1v.x + d1v.y) + (d1v.z + d1v.w), d2 = (d2v.x + d2v.y) + (d2v.z + d2v.w);
;             d1 = dpp_add<0xB1>(d1); d2 = dpp_add<0xB1>(d2); d1 = dpp_add<0x4E>(d1); d2 = dpp_add<0x4E>(d2);
;             d1 = dpp_add<0x141>(d1); d2 = dpp_add<0x141>(d2);
; #pragma unroll
;             for (int m = 0; m < 2; m++) {
;               const f32x4v w = *(const f32x4v*)(o + c0 + 4 * m), kp = *(const f32x4v*)(o + 128 + c0 + 4 * m), bb = *(const f32x4v*)(o + 320 + c0 + 4 * m);
;               S[m] = S[m] * w + (kp * v - bb * d1);
;             }
;             const float y = d2 - d1 * br + v * kr;
;             yk = (u == c8) ? y : yk;
	v_pk_mul_f32 v[30:31], v[16:17], v[132:133] op_sel_hi:[0,1]
	v_pk_mul_f32 v[32:33], v[16:17], v[134:135] op_sel_hi:[0,1]
	v_pk_fma_f32 v[28:29], v[20:21], v[170:171], v[32:33] op_sel_hi:[0,1,1] neg_lo:[0,0,1] neg_hi:[0,0,1]
	v_pk_fma_f32 v[26:27], v[20:21], v[168:169], v[30:31] op_sel_hi:[0,1,1] neg_lo:[0,0,1] neg_hi:[0,0,1]
	v_pk_fma_f32 v[70:71], v[70:71], v[208:209], v[26:27]
	v_pk_fma_f32 v[34:35], v[34:35], v[210:211], v[28:29]
	s_nop 2
	v_mov_b32_dpp v73, v17 row_half_mirror row_mask:0xf bank_mask:0xf bound_ctrl:1
	s_waitcnt lgkmcnt(0)
	v_pk_mul_f32 v[32:33], v[16:17], v[98:99] op_sel_hi:[0,1]
	v_pk_mul_f32 v[30:31], v[16:17], v[96:97] op_sel_hi:[0,1]
	v_add_f32_e32 v17, v17, v73
	v_fma_f32 v16, -v106, v16, v17
	v_pk_fma_f32 v[26:27], v[20:21], v[148:149], v[30:31] op_sel_hi:[0,1,1] neg_lo:[0,0,1] neg_hi:[0,0,1]
	v_pk_fma_f32 v[28:29], v[20:21], v[150:151], v[32:33] op_sel_hi:[0,1,1] neg_lo:[0,0,1] neg_hi:[0,0,1]
	v_fmac_f32_e32 v16, v21, v107
	v_pk_fma_f32 v[30:31], v[66:67], v[178:179], v[28:29]
	v_pk_fma_f32 v[32:33], v[68:69], v[176:177], v[26:27]
	v_cndmask_b32_e64 v67, v72, v16, s[12:13]
	ds_read2st64_b32 v[16:17], v77 offset0:75 offset1:81
	ds_read_b128 v[108:111], v36 offset:19456
	ds_read_b128 v[172:175], v36 offset:19472
	ds_read_b128 v[190:193], v36 offset:18688
	ds_read_b128 v[216:219], v36 offset:18704
	ds_read_b128 v[120:123], v36 offset:18432
	ds_read_b128 v[212:215], v36 offset:18944
	ds_read_b128 v[144:147], v36 offset:19712
	ds_read_b128 v[116:119], v36 offset:18448
	ds_read_b128 v[112:115], v36 offset:18960
	ds_read_b128 v[136:139], v36 offset:19728
	ds_read_b128 v[124:127], v36 offset:20992
	ds_read_b128 v[140:143], v36 offset:21008
	ds_read_b128 v[128:131], v36 offset:20224
	s_waitcnt lgkmcnt(11)
	ds_read_b128 v[152:155], v36 offset:20240
	ds_read_b128 v[180:183], v36 offset:19968
	ds_read_b128 v[132:135], v36 offset:20480
	v_pk_mul_f32 v[22:23], v[32:33], v[172:173]
	v_pk_mul_f32 v[24:25], v[30:31], v[174:175]
	v_pk_fma_f32 v[28:29], v[70:71], v[108:109], v[22:23]
	v_pk_fma_f32 v[26:27], v[34:35], v[110:111], v[24:25]
	s_nop 1
	s_waitcnt lgkmcnt(12)
	ds_read_b128 v[168:171], v36 offset:21248
	ds_read_b128 v[208:211], v36 offset:19984
	v_pk_mul_f32 v[22:23], v[32:33], v[216:217]
	v_pk_mul_f32 v[24:25], v[30:31], v[218:219]
	v_pk_fma_f32 v[18:19], v[70:71], v[190:191], v[22:23]
	v_pk_mov_b32 v[22:23], v[28:29], v[26:27] op_sel:[1,0]
	v_mov_b32_e32 v29, v27
	v_pk_fma_f32 v[20:21], v[34:35], v[192:193], v[24:25]
	v_pk_add_f32 v[22:23], v[22:23], v[28:29]
	v_add_f32_e32 v18, v18, v19
	v_add_f32_e32 v22, v22, v23
	v_add_f32_e32 v19, v20, v21
	v_add_f32_e32 v18, v18, v19
	s_nop 0
	v_add_f32_dpp v19, v22, v22 quad_perm:[1,0,3,2] row_mask:0xf bank_mask:0xf bound_ctrl:1
	v_add_f32_dpp v18, v18, v18 quad_perm:[1,0,3,2] row_mask:0xf bank_mask:0xf bound_ctrl:1
	s_nop 0
	v_add_f32_dpp v19, v19, v19 quad_perm:[2,3,0,1] row_mask:0xf bank_mask:0xf bound_ctrl:1
	v_add_f32_dpp v72, v18, v18 quad_perm:[2,3,0,1] row_mask:0xf bank_mask:0xf bound_ctrl:1
	s_nop 0
	v_add_f32_dpp v66, v19, v19 row_half_mirror row_mask:0xf bank_mask:0xf bound_ctrl:1
	s_nop 2
	v_mov_b32_dpp v73, v72 row_half_mirror row_mask:0xf bank_mask:0xf bound_ctrl:1
	s_waitcnt lgkmcnt(11)
	ds_read_b128 v[96:99], v36 offset:20496
	ds_read_b128 v[148:151], v36 offset:21264
	v_pk_mul_f32 v[26:27], v[66:67], v[144:145] op_sel_hi:[0,1]
	v_pk_mul_f32 v[28:29], v[66:67], v[146:147] op_sel_hi:[0,1]
	v_pk_fma_f32 v[24:25], v[16:17], v[214:215], v[28:29] op_sel_hi:[0,1,1] neg_lo:[0,0,1] neg_hi:[0,0,1]
	v_pk_fma_f32 v[22:23], v[16:17], v[212:213], v[26:27] op_sel_hi:[0,1,1] neg_lo:[0,0,1] neg_hi:[0,0,1]
	v_pk_fma_f32 v[68:69], v[70:71], v[120:121], v[22:23]
	v_pk_fma_f32 v[34:35], v[34:35], v[122:123], v[24:25]
	s_nop 2
	s_waitcnt lgkmcnt(10)
	v_pk_mul_f32 v[26:27], v[66:67], v[136:137] op_sel_hi:[0,1]
	v_pk_mul_f32 v[28:29], v[66:67], v[138:139] op_sel_hi:[0,1]
	v_pk_fma_f32 v[22:23], v[16:17], v[112:113], v[26:27] op_sel_hi:[0,1,1] neg_lo:[0,0,1] neg_hi:[0,0,1]
	v_pk_fma_f32 v[24:25], v[16:17], v[114:115], v[28:29] op_sel_hi:[0,1,1] neg_lo:[0,0,1] neg_hi:[0,0,1]
	v_pk_fma_f32 v[32:33], v[32:33], v[116:117], v[22:23]
	v_add_f32_e32 v18, v72, v73
	v_pk_fma_f32 v[30:31], v[30:31], v[118:119], v[24:25]
	v_fma_f32 v12, -v164, v66, v18
	s_nop 1
	v_fmac_f32_e32 v12, v16, v165
	v_cndmask_b32_e64 v66, v67, v12, s[14:15]
	s_waitcnt lgkmcnt(8)
	v_pk_mul_f32 v[12:13], v[32:33], v[140:141]
	v_pk_mul_f32 v[22:23], v[30:31], v[142:143]
	v_pk_fma_f32 v[12:13], v[68:69], v[124:125], v[12:13]
	v_pk_fma_f32 v[26:27], v[34:35], v[126:127], v[22:23]
	s_nop 1
	s_waitcnt lgkmcnt(6)
	v_pk_mul_f32 v[22:23], v[32:33], v[152:153]
	v_pk_mul_f32 v[24:25], v[30:31], v[154:155]
	v_pk_fma_f32 v[18:19], v[68:69], v[128:129], v[22:23]
	v_pk_mov_b32 v[22:23], v[12:13], v[26:27] op_sel:[1,0]
	v_mov_b32_e32 v13, v27
	v_pk_fma_f32 v[20:21], v[34:35], v[130:131], v[24:25]
	v_pk_add_f32 v[12:13], v[22:23], v[12:13]
	v_add_f32_e32 v16, v20, v21
	v_add_f32_e32 v12, v12, v13
	v_add_f32_e32 v13, v18, v19
	s_nop 2
	v_add_f32_e32 v13, v13, v16
	v_add_f32_dpp v12, v12, v12 quad_perm:[1,0,3,2] row_mask:0xf bank_mask:0xf bound_ctrl:1
	v_mov_b32_e32 v16, v17
	v_add_f32_dpp v13, v13, v13 quad_perm:[1,0,3,2] row_mask:0xf bank_mask:0xf bound_ctrl:1
	v_add_f32_dpp v12, v12, v12 quad_perm:[2,3,0,1] row_mask:0xf bank_mask:0xf bound_ctrl:1
	s_nop 0
	v_add_f32_dpp v13, v13, v13 quad_perm:[2,3,0,1] row_mask:0xf bank_mask:0xf bound_ctrl:1
	v_add_f32_dpp v12, v12, v12 row_half_mirror row_mask:0xf bank_mask:0xf bound_ctrl:1
	s_waitcnt lgkmcnt(3)
; DI void rwkv_scan_task(const Params& p, int srow0, int T, int h, int rq, const float* S0, float* Sout, int comb_bh, int comb_seg, unsigned char* smem) {
;     ...
;           for (int u = 0; u < 8; u++) {
;             const float* o = ops + (bsel * 16 + j * 8 + u) * 384;
;             const float v = o[192 + Rr];
;             const float br = sc[(bsel * 16 + j * 8 + u) * 2], kr = sc[(bsel * 16 + j * 8 + u) * 2 + 1];
;             f32x4v d1v = S[0] * *(const f32x4v*)(o + 256 + c0) + S[1] * *(const f32x4v*)(o + 256 + c0 + 4);
;             f32x4v d2v = S[0] * *(const f32x4v*)(o + 64 + c0) + S[1] * *(const f32x4v*)(o + 64 + c0 + 4);
;             float d1 = (d1v.x + d1v.y) + (d1v.z + d1v.w), d2 = (d2v.x + d2v.y) + (d2v.z + d2v.w);
;             d1 = dpp_add<0xB1>(d1); d2 = dpp_add<0xB1>(d2); d1 = dpp_add<0x4E>(d1); d2 = dpp_add<0x4E>(d2);
;             d1 = dpp_add<0x141>(d1); d2 = dpp_add<0x141>(d2);
; #pragma unroll
;             for (int m = 0; m < 2; m++) {
;               const f32x4v w = *(const f32x4v*)(o + c0 + 4 * m), kp = *(const f32x4v*)(o + 128 + c0 + 4 * m), bb = *(const f32x4v*)(o + 320 + c0 + 4 * m);
;               S[m] = S[m] * w + (kp * v - bb * d1);
;             }
;             const float y = d2 - d1 * br + v * kr;
;             yk = (u == c8) ? y : yk;
	v_pk_mul_f32 v[26:27], v[12:13], v[168:169] op_sel_hi:[0,1]
	v_pk_mul_f32 v[28:29], v[12:13], v[170:171] op_sel_hi:[0,1]
	v_pk_fma_f32 v[24:25], v[16:17], v[134:135], v[28:29] op_sel_hi:[0,1,1] neg_lo:[0,0,1] neg_hi:[0,0,1]
	v_pk_fma_f32 v[22:23], v[16:17], v[132:133], v[26:27] op_sel_hi:[0,1,1] neg_lo:[0,0,1] neg_hi:[0,0,1]
	v_pk_fma_f32 v[70:71], v[68:69], v[180:181], v[22:23]
	v_pk_fma_f32 v[34:35], v[34:35], v[182:183], v[24:25]
	s_nop 2
	v_mov_b32_dpp v67, v13 row_half_mirror row_mask:0xf bank_mask:0xf bound_ctrl:1
	s_waitcnt lgkmcnt(0)
	v_pk_mul_f32 v[28:29], v[12:13], v[150:151] op_sel_hi:[0,1]
	v_pk_mul_f32 v[26:27], v[12:13], v[148:149] op_sel_hi:[0,1]
	v_add_f32_e32 v13, v13, v67
	v_fma_f32 v12, -v166, v12, v13
	v_pk_fma_f32 v[22:23], v[16:17], v[96:97], v[26:27] op_sel_hi:[0,1,1] neg_lo:[0,0,1] neg_hi:[0,0,1]
	v_fmac_f32_e32 v12, v17, v167
	v_pk_fma_f32 v[24:25], v[16:17], v[98:99], v[28:29] op_sel_hi:[0,1,1] neg_lo:[0,0,1] neg_hi:[0,0,1]
	v_pk_fma_f32 v[26:27], v[32:33], v[208:209], v[22:23]
	v_cndmask_b32_e64 v29, v66, v12, s[16:17]
	ds_read2st64_b32 v[66:67], v77 offset0:87 offset1:93
	ds_read_b128 v[104:107], v36 offset:22528
	ds_read_b128 v[176:179], v36 offset:22544
	ds_read_b128 v[172:175], v36 offset:21760
	ds_read_b128 v[108:111], v36 offset:21776
	ds_read_b128 v[216:219], v36 offset:21504
	ds_read_b128 v[190:193], v36 offset:22016
	ds_read_b128 v[144:147], v36 offset:22784
	ds_read_b128 v[212:215], v36 offset:21520
	ds_read_b128 v[120:123], v36 offset:22032
	ds_read_b128 v[136:139], v36 offset:22800
	ds_read_b128 v[112:115], v36 offset:24064
	ds_read_b128 v[116:119], v36 offset:24080
	ds_read_b128 v[140:143], v36 offset:23296
	v_pk_fma_f32 v[24:25], v[30:31], v[210:211], v[24:25]
	s_waitcnt lgkmcnt(11)
	ds_read_b128 v[124:127], v36 offset:23312
	v_pk_mul_f32 v[16:17], v[26:27], v[176:177]
	v_pk_mul_f32 v[18:19], v[24:25], v[178:179]
	v_pk_fma_f32 v[22:23], v[70:71], v[104:105], v[16:17]
	v_pk_fma_f32 v[20:21], v[34:35], v[106:107], v[18:19]
	s_nop 1
	s_waitcnt lgkmcnt(10)
	v_pk_mul_f32 v[16:17], v[26:27], v[108:109]
	v_pk_mul_f32 v[18:19], v[24:25], v[110:111]
	v_pk_fma_f32 v[12:13], v[70:71], v[172:173], v[16:17]
	v_pk_mov_b32 v[16:17], v[22:23], v[20:21] op_sel:[1,0]
	v_mov_b32_e32 v23, v21
	v_pk_fma_f32 v[14:15], v[34:35], v[174:175], v[18:19]
	v_pk_add_f32 v[16:17], v[16:17], v[22:23]
	v_add_f32_e32 v12, v12, v13
	v_add_f32_e32 v16, v16, v17
	v_add_f32_e32 v13, v14, v15
	v_add_f32_e32 v12, v12, v13
	s_nop 0
	v_add_f32_dpp v13, v16, v16 quad_perm:[1,0,3,2] row_mask:0xf bank_mask:0xf bound_ctrl:1
	v_add_f32_dpp v12, v12, v12 quad_perm:[1,0,3,2] row_mask:0xf bank_mask:0xf bound_ctrl:1
	s_nop 0
	v_add_f32_dpp v13, v13, v13 quad_perm:[2,3,0,1] row_mask:0xf bank_mask:0xf bound_ctrl:1
	v_add_f32_dpp v30, v12, v12 quad_perm:[2,3,0,1] row_mask:0xf bank_mask:0xf bound_ctrl:1
	s_nop 0
	v_add_f32_dpp v28, v13, v13 row_half_mirror row_mask:0xf bank_mask:0xf bound_ctrl:1
	s_nop 2
	v_mov_b32_dpp v31, v30 row_half_mirror row_mask:0xf bank_mask:0xf bound_ctrl:1
	s_waitcnt lgkmcnt(7)
	v_pk_mul_f32 v[22:23], v[28:29], v[146:147] op_sel_hi:[0,1]
	v_pk_mul_f32 v[20:21], v[28:29], v[144:145] op_sel_hi:[0,1]
	v_pk_fma_f32 v[16:17], v[66:67], v[190:191], v[20:21] op_sel_hi:[0,1,1] neg_lo:[0,0,1] neg_hi:[0,0,1]
	v_pk_fma_f32 v[18:19], v[66:67], v[192:193], v[22:23] op_sel_hi:[0,1,1] neg_lo:[0,0,1] neg_hi:[0,0,1]
	v_pk_fma_f32 v[68:69], v[34:35], v[218:219], v[18:19]
	v_pk_fma_f32 v[70:71], v[70:71], v[216:217], v[16:17]
	s_nop 2
	s_waitcnt lgkmcnt(4)
	v_pk_mul_f32 v[20:21], v[28:29], v[136:137] op_sel_hi:[0,1]
	v_pk_mul_f32 v[22:23], v[28:29], v[138:139] op_sel_hi:[0,1]
	v_pk_fma_f32 v[16:17], v[66:67], v[120:121], v[20:21] op_sel_hi:[0,1,1] neg_lo:[0,0,1] neg_hi:[0,0,1]
	v_pk_fma_f32 v[18:19], v[66:67], v[122:123], v[22:23] op_sel_hi:[0,1,1] neg_lo:[0,0,1] neg_hi:[0,0,1]
	v_pk_fma_f32 v[74:75], v[26:27], v[212:213], v[16:17]
	v_add_f32_e32 v12, v30, v31
	v_pk_fma_f32 v[72:73], v[24:25], v[214:215], v[18:19]
	v_fma_f32 v8, -v100, v28, v12
	s_nop 1
	v_fmac_f32_e32 v8, v66, v101
	v_cndmask_b32_e64 v66, v29, v8, s[18:19]
	s_waitcnt lgkmcnt(2)
; DI void rwkv_scan_task(const Params& p, int srow0, int T, int h, int rq, const float* S0, float* Sout, int comb_bh, int comb_seg, unsigned char* smem) {
;     ...
;           ybuf[bsel * 512 + (j * 8 + c8) * 32 + i] = yk;
;         }
;         SCAN_STAGE(((k + 1) & 1), (bsel ^ 1))
;         __syncthreads();
;         if (tid < 128) {
;           const int st = tid >> 3, i4 = (tid & 7) * 4;
;           *(f32x4v*)(YRAW + (size_t)(srow0 + cc * 16 + st) * 512 + h * 64 + rq * 16 + i4) = *(const f32x4v*)(ybuf + bsel * 512 + st * 32 + i4);
	v_pk_mul_f32 v[8:9], v[74:75], v[116:117]
	v_pk_mul_f32 v[16:17], v[72:73], v[118:119]
	v_pk_fma_f32 v[8:9], v[70:71], v[112:113], v[8:9]
	v_pk_fma_f32 v[20:21], v[68:69], v[114:115], v[16:17]
	s_nop 1
	s_waitcnt lgkmcnt(0)
	v_pk_mul_f32 v[16:17], v[74:75], v[124:125]
	v_pk_mul_f32 v[18:19], v[72:73], v[126:127]
	v_pk_fma_f32 v[12:13], v[70:71], v[140:141], v[16:17]
	v_pk_mov_b32 v[16:17], v[8:9], v[20:21] op_sel:[1,0]
	v_mov_b32_e32 v9, v21
	v_pk_fma_f32 v[14:15], v[68:69], v[142:143], v[18:19]
	v_pk_add_f32 v[8:9], v[16:17], v[8:9]
	s_nop 0
	v_add_f32_e32 v8, v8, v9
	v_add_f32_e32 v9, v12, v13
	v_add_f32_e32 v12, v14, v15
	v_add_f32_e32 v9, v9, v12
	v_add_f32_dpp v8, v8, v8 quad_perm:[1,0,3,2] row_mask:0xf bank_mask:0xf bound_ctrl:1
	ds_read_b128 v[16:19], v36 offset:23040
	ds_read_b128 v[24:27], v36 offset:23552
	ds_read_b128 v[32:35], v36 offset:24320
	ds_read_b128 v[12:15], v36 offset:23056
	ds_read_b128 v[20:23], v36 offset:23568
	ds_read_b128 v[28:31], v36 offset:24336
	v_add_f32_dpp v9, v9, v9 quad_perm:[1,0,3,2] row_mask:0xf bank_mask:0xf bound_ctrl:1
	v_add_f32_dpp v8, v8, v8 quad_perm:[2,3,0,1] row_mask:0xf bank_mask:0xf bound_ctrl:1
	s_nop 0
	v_add_f32_dpp v9, v9, v9 quad_perm:[2,3,0,1] row_mask:0xf bank_mask:0xf bound_ctrl:1
	v_add_f32_dpp v8, v8, v8 row_half_mirror row_mask:0xf bank_mask:0xf bound_ctrl:1
	s_nop 0
	v_add_f32_dpp v9, v9, v9 row_half_mirror row_mask:0xf bank_mask:0xf bound_ctrl:1
	v_fma_f32 v9, -v102, v8, v9
	v_fmac_f32_e32 v9, v67, v103
	v_cndmask_b32_e64 v9, v66, v9, s[20:21]
	v_lshlrev_b32_e32 v10, 16, v51
	v_and_b32_e32 v11, 0xffff0000, v51
	ds_write_b32 v83, v9 offset:50432
	ds_write_b128 v84, v[0:3]
	ds_write_b128 v84, v[86:89] offset:768
	ds_write_b128 v84, v[90:93] offset:1024
	v_lshlrev_b32_e32 v51, 16, v46
	v_lshlrev_b32_e32 v87, 16, v47
	v_and_b32_e32 v47, 0xffff0000, v47
	v_pk_mul_f32 v[2:3], v[2:3], v[10:11]
	v_pk_mul_f32 v[0:1], v[0:1], v[52:53] op_sel:[0,1] op_sel_hi:[1,0]
	v_lshlrev_b32_e32 v86, 16, v49
	v_and_b32_e32 v46, 0xffff0000, v49
	ds_write_b128 v84, v[0:3] offset:256
	v_mov_b32_e32 v0, v51
	v_mov_b32_e32 v1, v55
	v_mov_b32_e32 v2, v87
	v_mov_b32_e32 v3, v47
	ds_write_b128 v84, v[0:3] offset:512
	v_mov_b32_e32 v0, v54
	v_mov_b32_e32 v1, v50
	v_mov_b32_e32 v2, v86
	v_mov_b32_e32 v3, v46
	ds_write_b128 v84, v[0:3] offset:1280
	v_pk_mul_f32 v[0:1], v[52:53], v[54:55] op_sel:[1,0] op_sel_hi:[0,1]
	v_pk_fma_f32 v[0:1], v[50:51], v[52:53], v[0:1]
	v_mov_b32_e32 v2, v11
	v_pk_fma_f32 v[0:1], v[10:11], v[86:87], v[0:1] op_sel_hi:[0,1,1]
	v_pk_fma_f32 v[0:1], v[2:3], v[46:47], v[0:1] op_sel_hi:[0,1,1]
	s_nop 1
	v_mov_b32_dpp v2, v0 quad_perm:[1,0,3,2] row_mask:0xf bank_mask:0xf bound_ctrl:1
	v_mov_b32_dpp v3, v1 quad_perm:[1,0,3,2] row_mask:0xf bank_mask:0xf bound_ctrl:1
	v_pk_add_f32 v[0:1], v[0:1], v[2:3]
	s_nop 1
	v_mov_b32_dpp v2, v0 quad_perm:[2,3,0,1] row_mask:0xf bank_mask:0xf bound_ctrl:1
	v_mov_b32_dpp v3, v1 quad_perm:[2,3,0,1] row_mask:0xf bank_mask:0xf bound_ctrl:1
	v_pk_add_f32 v[0:1], v[0:1], v[2:3]
	s_nop 1
	v_mov_b32_dpp v2, v0 row_half_mirror row_mask:0xf bank_mask:0xf bound_ctrl:1
	v_mov_b32_dpp v3, v1 row_half_mirror row_mask:0xf bank_mask:0xf bound_ctrl:1
	v_pk_add_f32 v[0:1], v[0:1], v[2:3]
	s_nop 1
	v_mov_b32_dpp v2, v0 row_mirror row_mask:0xf bank_mask:0xf bound_ctrl:1
	v_mov_b32_dpp v3, v1 row_mirror row_mask:0xf bank_mask:0xf bound_ctrl:1
	s_and_saveexec_b64 s[2:3], vcc
	v_pk_add_f32 v[0:1], v[0:1], v[2:3]
	ds_write_b64 v78, v[0:1] offset:49152
	s_or_b64 exec, exec, s[2:3]
	s_waitcnt lgkmcnt(0)
	s_barrier
	s_and_saveexec_b64 s[2:3], s[4:5]
	s_cbranch_execz .LBB0_851
	v_add_u32_e32 v0, s27, v81
	v_ashrrev_i32_e32 v1, 31, v0
	v_lshlrev_b64 v[0:1], 11, v[0:1]
	v_lshl_add_u64 v[10:11], v[44:45], 0, v[0:1]
	ds_read_b128 v[0:3], v76 offset:49408
	s_waitcnt lgkmcnt(0)
	global_store_dwordx4 v[10:11], v[0:3], off

; #define MFMA32(a, b, c) __builtin_amdgcn_mfma_f32_32x32x16_bf16((a), (b), (c), 0, 0, 0)
; DI void gemm_mainloop(f32x16 (&acc)[2][2], const u16* A, int lda, const u16* Bt, int ldb, int K, unsigned char* smem) {
;     ...
;   for (int kt = 0; kt < nk; kt++) {
;     u16* sA = s0 + (kt & 1) * (256 * 72); u16* sB = sA + 128 * 72;
;     if (kt + 1 < nk) {
;       u16* nA = s0 + ((kt + 1) & 1) * (256 * 72); u16* nB = nA + 128 * 72;
; #pragma unroll
;       for (int i = 0; i < 4; i++) { *(u32x4*)(nA + (lr + 32 * i) * 72 + lc) = ra[i]; *(u32x4*)(nB + (lr + 32 * i) * 72 + lc) = rb[i]; }
;     }
;     if (kt + 2 < nk) { Ab += 128; Bb += 128; }
; #pragma unroll
;     for (int i = 0; i < 4; i++) { ra[i] = *(const u32x4*)(Ab + offA[i]); rb[i] = *(const u32x4*)(Bb + offB[i]); }
; #pragma unroll
;     for (int ks = 0; ks < 4; ks++) {
;       bf16x8 af[2], bfr[2];
; #pragma unroll
;       for (int b = 0; b < 2; b++) {
;         af[b] = *(const bf16x8*)(sA + (wm * 64 + b * 32 + r) * 72 + ks * 16 + hl * 8);
;         bfr[b] = *(const bf16x8*)(sB + (wn * 64 + b * 32 + r) * 72 + ks * 16 + hl * 8);
;       }
; #pragma unroll
;       for (int bm = 0; bm < 2; bm++)
; #pragma unroll
;         for (int bn = 0; bn < 2; bn++) acc[bm][bn] = MFMA32(af[bm], bfr[bn], acc[bm][bn]);
;     }
;     __syncthreads();
;   }
.LBB0_1004:
	s_bitcmp1_b32 s9, 0
	s_cselect_b32 s6, 0x9000, 0
	s_cselect_b32 s7, 0, 0x9000
	v_lshl_or_b32 v119, v114, 1, s6
	v_or_b32_e32 v120, s7, v113
	v_lshl_add_u32 v119, v118, 1, v119
	v_add_u32_e32 v128, v120, v115
	v_add_u32_e32 v129, v120, v112
	s_waitcnt vmcnt(7)
	ds_write_b128 v119, v[72:75]
	s_waitcnt vmcnt(6)
	ds_write_b128 v119, v[80:83] offset:18432
	s_waitcnt vmcnt(5)
	ds_write_b128 v119, v[68:71] offset:4608
	s_waitcnt vmcnt(4)
	ds_write_b128 v119, v[76:79] offset:23040
	s_waitcnt vmcnt(3)
	ds_write_b128 v119, v[64:67] offset:9216
	s_waitcnt vmcnt(2)
	ds_write_b128 v119, v[84:87] offset:27648
	s_waitcnt vmcnt(1)
	ds_write_b128 v119, v[88:91] offset:13824
	s_waitcnt vmcnt(0)
	ds_write_b128 v119, v[92:95] offset:32256
	ds_read_b128 v[134:137], v128
	ds_read_b128 v[138:141], v129 offset:18432
	ds_read_b128 v[142:145], v129 offset:23040
	ds_read_b128 v[146:149], v128 offset:4608
	ds_read_b128 v[150:153], v128 offset:32
	ds_read_b128 v[154:157], v129 offset:18464
	s_waitcnt lgkmcnt(4)
	ds_read_b128 v[164:167], v129 offset:23072
	ds_read_b128 v[168:171], v128 offset:4640
	ds_read_b128 v[172:175], v128 offset:64
	ds_read_b128 v[176:179], v129 offset:18496
	ds_read_b128 v[180:183], v129 offset:23104
	ds_read_b128 v[190:193], v128 offset:4672
	ds_read_b128 v[208:211], v128 offset:96
	v_mfma_f32_32x32x16_bf16 v[48:63], v[134:137], v[138:141], v[48:63]
	v_lshl_add_u64 v[76:77], v[102:103], 0, s[2:3]
	global_load_dwordx4 v[72:75], v[76:77], off
	v_lshl_add_u64 v[78:79], v[110:111], 0, s[2:3]
	global_load_dwordx4 v[80:83], v[78:79], off
	v_lshl_add_u64 v[92:93], v[100:101], 0, s[2:3]
	global_load_dwordx4 v[68:71], v[92:93], off
	v_lshl_add_u64 v[94:95], v[108:109], 0, s[2:3]
	global_load_dwordx4 v[76:79], v[94:95], off
	v_lshl_add_u64 v[120:121], v[98:99], 0, s[2:3]
	global_load_dwordx4 v[64:67], v[120:121], off
	v_lshl_add_u64 v[124:125], v[106:107], 0, s[2:3]
	global_load_dwordx4 v[84:87], v[124:125], off
	v_lshl_add_u64 v[126:127], v[96:97], 0, s[2:3]
	global_load_dwordx4 v[88:91], v[126:127], off
	s_waitcnt lgkmcnt(10)
	v_mfma_f32_32x32x16_bf16 v[32:47], v[134:137], v[142:145], v[32:47]
	s_nop 0
	v_lshl_add_u64 v[132:133], v[104:105], 0, s[2:3]
	global_load_dwordx4 v[92:95], v[132:133], off
	s_add_u32 s2, s2, 0x80
	s_addc_u32 s3, s3, 0
	s_add_i32 s9, s9, 1
	s_cmpk_lg_i32 s2, 0x700
	s_waitcnt lgkmcnt(9)
	v_mfma_f32_32x32x16_bf16 v[16:31], v[146:149], v[138:141], v[16:31]
	v_mfma_f32_32x32x16_bf16 v[0:15], v[146:149], v[142:145], v[0:15]
	s_nop 2
	s_waitcnt lgkmcnt(7)
	v_mfma_f32_32x32x16_bf16 v[48:63], v[150:153], v[154:157], v[48:63]
	s_waitcnt lgkmcnt(6)
	v_mfma_f32_32x32x16_bf16 v[32:47], v[150:153], v[164:167], v[32:47]
	s_nop 0
	s_waitcnt lgkmcnt(5)
	v_mfma_f32_32x32x16_bf16 v[16:31], v[168:171], v[154:157], v[16:31]
	v_mfma_f32_32x32x16_bf16 v[0:15], v[168:171], v[164:167], v[0:15]
	s_nop 3
	s_waitcnt lgkmcnt(3)
	v_mfma_f32_32x32x16_bf16 v[48:63], v[172:175], v[176:179], v[48:63]
	s_waitcnt lgkmcnt(2)
	v_mfma_f32_32x32x16_bf16 v[32:47], v[172:175], v[180:183], v[32:47]
	s_waitcnt lgkmcnt(1)
	v_mfma_f32_32x32x16_bf16 v[16:31], v[190:193], v[176:179], v[16:31]
	s_nop 2
	s_nop 0
	s_nop 2
	ds_read_b128 v[120:123], v129 offset:18528
	v_mfma_f32_32x32x16_bf16 v[0:15], v[190:193], v[180:183], v[0:15]
	s_nop 1
	ds_read_b128 v[124:127], v129 offset:23136
	ds_read_b128 v[128:131], v128 offset:4704
	s_waitcnt lgkmcnt(2)
	v_mfma_f32_32x32x16_bf16 v[48:63], v[208:211], v[120:123], v[48:63]
	s_waitcnt lgkmcnt(1)
	v_mfma_f32_32x32x16_bf16 v[32:47], v[208:211], v[124:127], v[32:47]
	s_nop 0
	s_waitcnt lgkmcnt(0)
	s_barrier
	v_mfma_f32_32x32x16_bf16 v[16:31], v[128:131], v[120:123], v[16:31]
	v_mfma_f32_32x32x16_bf16 v[0:15], v[128:131], v[124:127], v[0:15]
	s_cbranch_scc1 .LBB0_1004
; #define MFMA32(a, b, c) __builtin_amdgcn_mfma_f32_32x32x16_bf16((a), (b), (c), 0, 0, 0)
; DI void gemm_mainloop(f32x16 (&acc)[2][2], const u16* A, int lda, const u16* Bt, int ldb, int K, unsigned char* smem) {
;     ...
;   for (int kt = 0; kt < nk; kt++) {
;     u16* sA = s0 + (kt & 1) * (256 * 72); u16* sB = sA + 128 * 72;
;     if (kt + 1 < nk) {
;       u16* nA = s0 + ((kt + 1) & 1) * (256 * 72); u16* nB = nA + 128 * 72;
; #pragma unroll
;       for (int i = 0; i < 4; i++) { *(u32x4*)(nA + (lr + 32 * i) * 72 + lc) = ra[i]; *(u32x4*)(nB + (lr + 32 * i) * 72 + lc) = rb[i]; }
;     }
;     if (kt + 2 < nk) { Ab += 128; Bb += 128; }
; #pragma unroll
;     for (int i = 0; i < 4; i++) { ra[i] = *(const u32x4*)(Ab + offA[i]); rb[i] = *(const u32x4*)(Bb + offB[i]); }
; #pragma unroll
;     for (int ks = 0; ks < 4; ks++) {
;       bf16x8 af[2], bfr[2];
; #pragma unroll
;       for (int b = 0; b < 2; b++) {
;         af[b] = *(const bf16x8*)(sA + (wm * 64 + b * 32 + r) * 72 + ks * 16 + hl * 8);
;         bfr[b] = *(const bf16x8*)(sB + (wn * 64 + b * 32 + r) * 72 + ks * 16 + hl * 8);
;       }
; #pragma unroll
;       for (int bm = 0; bm < 2; bm++)
; #pragma unroll
;         for (int bn = 0; bn < 2; bn++) acc[bm][bn] = MFMA32(af[bm], bfr[bn], acc[bm][bn]);
;     }
;     __syncthreads();
;   }
; DI void phase7(const Params& p, int l, unsigned char* smem) {
;     ...
;     foreach_acc(acc, m0, n0, [&](int row, int col, float v) {
;       float xo = xrow_ptr(p, l, row)[col];
;       float gt = mod[(l * 10 + bidx_of(row)) * 3072 + 2048 + col];
	s_waitcnt vmcnt(7)
	ds_write_b128 v116, v[72:75] offset:36864
	s_waitcnt vmcnt(6)
	ds_write_b128 v116, v[80:83] offset:55296
	s_waitcnt vmcnt(5)
	ds_write_b128 v116, v[68:71] offset:41472
	s_waitcnt vmcnt(4)
	ds_write_b128 v116, v[76:79] offset:59904
	s_waitcnt vmcnt(3)
	ds_write_b128 v116, v[64:67] offset:46080
	s_waitcnt vmcnt(2)
	ds_write_b128 v116, v[84:87] offset:64512
	s_waitcnt vmcnt(1)
	ds_write_b128 v116, v[88:91] offset:50688
	s_waitcnt vmcnt(0)
	ds_write_b128 v117, v[92:95] offset:64512
	v_add_u32_e32 v88, v113, v115
	ds_read_b128 v[134:137], v88 offset:4608
	v_add3_u32 v89, s6, v113, v112
	ds_read_b128 v[138:141], v89 offset:23040
	ds_read_b128 v[142:145], v88
	ds_read_b128 v[146:149], v88 offset:32
	s_nop 3
	ds_read_b128 v[80:83], v89 offset:18432
	ds_read_b128 v[84:87], v89 offset:18464
	s_waitcnt lgkmcnt(3)
	ds_read_b128 v[150:153], v88 offset:4640
	ds_read_b128 v[154:157], v89 offset:23072
	ds_read_b128 v[164:167], v88 offset:64
	ds_read_b128 v[168:171], v89 offset:18496
	ds_read_b128 v[172:175], v88 offset:4672
	ds_read_b128 v[176:179], v89 offset:23104
	v_mfma_f32_32x32x16_bf16 v[32:47], v[142:145], v[138:141], v[32:47]
	s_mov_b64 s[2:3], -1
	s_and_b64 vcc, exec, s[20:21]
	s_waitcnt lgkmcnt(7)
	v_mfma_f32_32x32x16_bf16 v[48:63], v[142:145], v[80:83], v[48:63]
	v_mfma_f32_32x32x16_bf16 v[16:31], v[134:137], v[80:83], v[16:31]
	v_mfma_f32_32x32x16_bf16 v[0:15], v[134:137], v[138:141], v[0:15]
	s_nop 1
	s_waitcnt lgkmcnt(6)
	v_mfma_f32_32x32x16_bf16 v[48:63], v[146:149], v[84:87], v[48:63]
	s_waitcnt lgkmcnt(4)
	v_mfma_f32_32x32x16_bf16 v[32:47], v[146:149], v[154:157], v[32:47]
	v_mfma_f32_32x32x16_bf16 v[16:31], v[150:153], v[84:87], v[16:31]
	v_mfma_f32_32x32x16_bf16 v[0:15], v[150:153], v[154:157], v[0:15]
	s_nop 3
	s_waitcnt lgkmcnt(2)
	v_mfma_f32_32x32x16_bf16 v[48:63], v[164:167], v[168:171], v[48:63]
	s_waitcnt lgkmcnt(0)
	v_mfma_f32_32x32x16_bf16 v[32:47], v[164:167], v[176:179], v[32:47]
	v_mfma_f32_32x32x16_bf16 v[16:31], v[172:175], v[168:171], v[16:31]
	v_mfma_f32_32x32x16_bf16 v[0:15], v[172:175], v[176:179], v[0:15]
	ds_read_b128 v[64:67], v88 offset:96
	ds_read_b128 v[68:71], v89 offset:18528
	ds_read_b128 v[72:75], v88 offset:4704
	ds_read_b128 v[76:79], v89 offset:23136
	s_waitcnt lgkmcnt(0)
	s_barrier
	ds_read_b128 v[134:137], v88 offset:41472
	v_add_u32_e32 v89, v113, v112
	ds_read_b128 v[138:141], v89 offset:59904
	ds_read_b128 v[142:145], v88 offset:36864
	ds_read_b128 v[146:149], v88 offset:36896
	ds_read_b128 v[80:83], v89 offset:55296
	ds_read_b128 v[84:87], v89 offset:55328
	ds_read_b128 v[150:153], v88 offset:41504
	ds_read_b128 v[154:157], v89 offset:59936
	ds_read_b128 v[164:167], v88 offset:36928
	ds_read_b128 v[168:171], v89 offset:55360
	ds_read_b128 v[172:175], v88 offset:41536
	ds_read_b128 v[176:179], v89 offset:59968
	v_mfma_f32_32x32x16_bf16 v[48:63], v[64:67], v[68:71], v[48:63]
	v_mfma_f32_32x32x16_bf16 v[32:47], v[64:67], v[76:79], v[32:47]
	v_mfma_f32_32x32x16_bf16 v[16:31], v[72:75], v[68:71], v[16:31]
	v_mfma_f32_32x32x16_bf16 v[0:15], v[72:75], v[76:79], v[0:15]
	s_nop 5
	s_waitcnt lgkmcnt(7)
	v_mfma_f32_32x32x16_bf16 v[48:63], v[142:145], v[80:83], v[48:63]
	v_mfma_f32_32x32x16_bf16 v[32:47], v[142:145], v[138:141], v[32:47]
	v_mfma_f32_32x32x16_bf16 v[16:31], v[134:137], v[80:83], v[16:31]
	v_mfma_f32_32x32x16_bf16 v[0:15], v[134:137], v[138:141], v[0:15]
	s_nop 1
	s_waitcnt lgkmcnt(6)
	v_mfma_f32_32x32x16_bf16 v[48:63], v[146:149], v[84:87], v[48:63]
	s_waitcnt lgkmcnt(4)
	v_mfma_f32_32x32x16_bf16 v[32:47], v[146:149], v[154:157], v[32:47]
	v_mfma_f32_32x32x16_bf16 v[16:31], v[150:153], v[84:87], v[16:31]
	v_mfma_f32_32x32x16_bf16 v[0:15], v[150:153], v[154:157], v[0:15]
	s_nop 3
	s_waitcnt lgkmcnt(2)
	v_mfma_f32_32x32x16_bf16 v[48:63], v[164:167], v[168:171], v[48:63]
	s_waitcnt lgkmcnt(0)
	v_mfma_f32_32x32x16_bf16 v[32:47], v[164:167], v[176:179], v[32:47]
	v_mfma_f32_32x32x16_bf16 v[16:31], v[172:175], v[168:171], v[16:31]
	v_mfma_f32_32x32x16_bf16 v[0:15], v[172:175], v[176:179], v[0:15]
	ds_read_b128 v[64:67], v88 offset:36960
	ds_read_b128 v[68:71], v89 offset:55392
	ds_read_b128 v[72:75], v88 offset:41568
	ds_read_b128 v[76:79], v89 offset:60000
	s_waitcnt lgkmcnt(0)
	s_barrier
	v_mfma_f32_32x32x16_bf16 v[48:63], v[64:67], v[68:71], v[48:63]
	v_mfma_f32_32x32x16_bf16 v[32:47], v[64:67], v[76:79], v[32:47]
	v_mov_b32_e32 v64, v160
	v_mov_b32_e32 v65, v160
	s_nop 0
	v_ashrrev_i32_e32 v66, 1, v65
	v_and_b32_e32 v66, 0xffffffc0, v66
	v_mfma_f32_32x32x16_bf16 v[16:31], v[72:75], v[68:71], v[16:31]
	v_lshl_add_u32 v122, s8, 7, v66
	v_lshrrev_b32_e32 v66, 3, v64
	v_and_b32_e32 v123, 4, v66
	v_or_b32_e32 v66, v122, v123
	v_cmp_lt_i32_e64 s[6:7], s64, v66
	v_mfma_f32_32x32x16_bf16 v[0:15], v[72:75], v[76:79], v[0:15]
	s_cbranch_vccz .LBB0_1011
	s_and_saveexec_b64 s[2:3], s[6:7]
	s_xor_b64 s[2:3], exec, s[2:3]
	v_add_u32_e32 v162, 0xffffc000, v66
	v_mov_b32_e32 v67, v163
	v_mov_b64_e32 v[70:71], v[162:163]
	v_mov_b64_e32 v[68:69], v[66:67]
	s_or_saveexec_b64 s[2:3], s[2:3]
	v_readlane_b32 s6, v254, 2
	v_readlane_b32 s7, v254, 3
	s_nop 1
	v_mov_b64_e32 v[72:73], s[6:7]
	s_xor_b64 exec, exec, s[2:3]
	v_ashrrev_i32_e32 v67, 31, v66
	v_mov_b64_e32 v[72:73], s[0:1]
	v_mov_b64_e32 v[70:71], v[66:67]
	v_mov_b64_e32 v[68:69], v[66:67]
	s_or_b64 exec, exec, s[2:3]
	s_mov_b64 s[2:3], 0
